# dKdT stored in fragment order for linear dn_seq loads; batched phase-3 scans
# speedup vs baseline: 1.0198x; 1.0046x over previous
; __device__ __forceinline__ u32x2 pk4(f32x4 v) { u32x2 r; r.x = pk2(v[0], v[1]); r.y = pk2(v[2], v[3]); return r; }
; __device__ __forceinline__ f32x4 up4(u32x2 u) { return (f32x4){lo16(u.x), hi16(u.x), lo16(u.y), hi16(u.y)}; }
;     template <class Tp> __device__ __forceinline__ Tp* W(size_t off) const { return (Tp*)(ws + off); }
; __device__ void scan_ssd(const Ctx& c, int idx) {
;     bf16_t* sSt = c.W<bf16_t>(WS_SST); const float* sAcs = c.W<float>(WS_SACS);
;     const size_t e4 = (size_t)idx * 4; const int h = (int)(e4 >> 13);
;     f32x4 S = (f32x4){0.f, 0.f, 0.f, 0.f};
; #pragma unroll 4
;     for (int ck = 0; ck < NCH; ++ck) { u32x2* ad = (u32x2*)(sSt + (size_t)ck * 131072 + e4);
;         const f32x4 st = up4(__builtin_nontemporal_load(ad)); const float d = __expf(sAcs[(size_t)(ck * 16 + h) * 64 + 63]);
;         __builtin_nontemporal_store(pk4(S), ad); S = S * d + st; }
; }
; __device__ __forceinline__ void run_phase(int ph, unsigned char* ldsraw) {
;     ...
;         else { const int nbs = c.nb - 64, b2 = c.bid - 64;
;             for (int idx = b2 * 512 + c.tid; idx < 65536; idx += nbs * 512) { if (idx < 32768) scan_ssd(c, idx); else scan_gla(c, idx - 32768); }
.LBB0_429:
	s_and_b64 vcc, exec, s[0:1]
	s_cbranch_vccz .LBB0_605
	s_cmp_gt_i32 s92, 63
	s_mov_b64 s[0:1], -1
	s_cbranch_scc0 .LBB0_524
	s_sub_i32 s3, s92, 64
	s_waitcnt vmcnt(0)
	s_sub_i32 s2, s68, 64
	s_cmp_gt_u32 s3, 127
	s_cbranch_scc1 .Lscan_done
	s_load_dwordx2 s[4:5], s[94:95], 0xe8
	s_and_b32 s6, s3, 63
	v_lshl_add_u32 v0, s6, 9, v234
	v_lshlrev_b32_e32 v1, 3, v0
	s_waitcnt lgkmcnt(0)
	s_cmp_gt_u32 s3, 63
	s_cbranch_scc1 .Lscan_gla
	v_lshrrev_b32_e32 v2, 11, v0
	v_lshlrev_b32_e32 v2, 8, v2
	v_add_u32_e32 v2, 0xfc, v2
	s_add_u32 s6, s4, 0x2e501000
	s_addc_u32 s7, s5, 0
	s_add_u32 s8, s4, 0x30501000
	s_addc_u32 s9, s5, 0
	s_mov_b32 s12, s6
	s_mov_b32 s13, s7
	v_mov_b32_e32 v4, 0
	v_mov_b32_e32 v5, 0
	v_mov_b32_e32 v6, 0
	v_mov_b32_e32 v7, 0
	global_load_dwordx2 v[16:17], v1, s[6:7] nt
	global_load_dword v48, v2, s[8:9]
	s_add_u32 s8, s8, 0x1000
	s_addc_u32 s9, s9, 0
	s_add_u32 s6, s6, 0x40000
	s_addc_u32 s7, s7, 0
	global_load_dwordx2 v[18:19], v1, s[6:7] nt
	global_load_dword v49, v2, s[8:9]
	s_add_u32 s8, s8, 0x1000
	s_addc_u32 s9, s9, 0
	s_add_u32 s6, s6, 0x40000
	s_addc_u32 s7, s7, 0
	global_load_dwordx2 v[20:21], v1, s[6:7] nt
	global_load_dword v50, v2, s[8:9]
	s_add_u32 s8, s8, 0x1000
	s_addc_u32 s9, s9, 0
	s_add_u32 s6, s6, 0x40000
	s_addc_u32 s7, s7, 0
	global_load_dwordx2 v[22:23], v1, s[6:7] nt
	global_load_dword v51, v2, s[8:9]
	s_add_u32 s8, s8, 0x1000
	s_addc_u32 s9, s9, 0
	s_add_u32 s6, s6, 0x40000
	s_addc_u32 s7, s7, 0
	global_load_dwordx2 v[24:25], v1, s[6:7] nt
	global_load_dword v52, v2, s[8:9]
	s_add_u32 s8, s8, 0x1000
	s_addc_u32 s9, s9, 0
	s_add_u32 s6, s6, 0x40000
	s_addc_u32 s7, s7, 0
	global_load_dwordx2 v[26:27], v1, s[6:7] nt
	global_load_dword v53, v2, s[8:9]
	s_add_u32 s8, s8, 0x1000
	s_addc_u32 s9, s9, 0
	s_add_u32 s6, s6, 0x40000
	s_addc_u32 s7, s7, 0
	global_load_dwordx2 v[28:29], v1, s[6:7] nt
	global_load_dword v54, v2, s[8:9]
	s_add_u32 s8, s8, 0x1000
	s_addc_u32 s9, s9, 0
	s_add_u32 s6, s6, 0x40000
	s_addc_u32 s7, s7, 0
	global_load_dwordx2 v[30:31], v1, s[6:7] nt
	global_load_dword v55, v2, s[8:9]
	s_add_u32 s8, s8, 0x1000
	s_addc_u32 s9, s9, 0
	s_add_u32 s6, s6, 0x40000
	s_addc_u32 s7, s7, 0
	global_load_dwordx2 v[32:33], v1, s[6:7] nt
	global_load_dword v56, v2, s[8:9]
	s_add_u32 s8, s8, 0x1000
	s_addc_u32 s9, s9, 0
	s_add_u32 s6, s6, 0x40000
	s_addc_u32 s7, s7, 0
	global_load_dwordx2 v[34:35], v1, s[6:7] nt
	global_load_dword v57, v2, s[8:9]
	s_add_u32 s8, s8, 0x1000
	s_addc_u32 s9, s9, 0
	s_add_u32 s6, s6, 0x40000
	s_addc_u32 s7, s7, 0
	global_load_dwordx2 v[36:37], v1, s[6:7] nt
	global_load_dword v58, v2, s[8:9]
	s_add_u32 s8, s8, 0x1000
	s_addc_u32 s9, s9, 0
	s_add_u32 s6, s6, 0x40000
	s_addc_u32 s7, s7, 0
	global_load_dwordx2 v[38:39], v1, s[6:7] nt
	global_load_dword v59, v2, s[8:9]
	s_add_u32 s8, s8, 0x1000
	s_addc_u32 s9, s9, 0
	s_add_u32 s6, s6, 0x40000
	s_addc_u32 s7, s7, 0
	global_load_dwordx2 v[40:41], v1, s[6:7] nt
	global_load_dword v60, v2, s[8:9]
	s_add_u32 s8, s8, 0x1000
	s_addc_u32 s9, s9, 0
	s_add_u32 s6, s6, 0x40000
	s_addc_u32 s7, s7, 0
	global_load_dwordx2 v[42:43], v1, s[6:7] nt
	global_load_dword v61, v2, s[8:9]
	s_add_u32 s8, s8, 0x1000
	s_addc_u32 s9, s9, 0
	s_add_u32 s6, s6, 0x40000
	s_addc_u32 s7, s7, 0
	global_load_dwordx2 v[44:45], v1, s[6:7] nt
	global_load_dword v62, v2, s[8:9]
	s_add_u32 s8, s8, 0x1000
	s_addc_u32 s9, s9, 0
	s_add_u32 s6, s6, 0x40000
	s_addc_u32 s7, s7, 0
	global_load_dwordx2 v[46:47], v1, s[6:7] nt
	global_load_dword v63, v2, s[8:9]
	s_add_u32 s8, s8, 0x1000
	s_addc_u32 s9, s9, 0
	s_add_u32 s6, s6, 0x40000
	s_addc_u32 s7, s7, 0
	global_load_dwordx2 v[64:65], v1, s[6:7] nt
	global_load_dword v96, v2, s[8:9]
	s_add_u32 s8, s8, 0x1000
	s_addc_u32 s9, s9, 0
	s_add_u32 s6, s6, 0x40000
	s_addc_u32 s7, s7, 0
	global_load_dwordx2 v[66:67], v1, s[6:7] nt
	global_load_dword v97, v2, s[8:9]
	s_add_u32 s8, s8, 0x1000
	s_addc_u32 s9, s9, 0
	s_add_u32 s6, s6, 0x40000
	s_addc_u32 s7, s7, 0
	global_load_dwordx2 v[68:69], v1, s[6:7] nt
	global_load_dword v98, v2, s[8:9]
	s_add_u32 s8, s8, 0x1000
	s_addc_u32 s9, s9, 0
	s_add_u32 s6, s6, 0x40000
	s_addc_u32 s7, s7, 0
	global_load_dwordx2 v[70:71], v1, s[6:7] nt
	global_load_dword v99, v2, s[8:9]
	s_add_u32 s8, s8, 0x1000
	s_addc_u32 s9, s9, 0
	s_add_u32 s6, s6, 0x40000
	s_addc_u32 s7, s7, 0
	global_load_dwordx2 v[72:73], v1, s[6:7] nt
	global_load_dword v100, v2, s[8:9]
	s_add_u32 s8, s8, 0x1000
	s_addc_u32 s9, s9, 0
	s_add_u32 s6, s6, 0x40000
	s_addc_u32 s7, s7, 0
	global_load_dwordx2 v[74:75], v1, s[6:7] nt
	global_load_dword v101, v2, s[8:9]
	s_add_u32 s8, s8, 0x1000
	s_addc_u32 s9, s9, 0
	s_add_u32 s6, s6, 0x40000
	s_addc_u32 s7, s7, 0
	global_load_dwordx2 v[76:77], v1, s[6:7] nt
	global_load_dword v102, v2, s[8:9]
	s_add_u32 s8, s8, 0x1000
	s_addc_u32 s9, s9, 0
	s_add_u32 s6, s6, 0x40000
	s_addc_u32 s7, s7, 0
	global_load_dwordx2 v[78:79], v1, s[6:7] nt
	global_load_dword v103, v2, s[8:9]
	s_add_u32 s8, s8, 0x1000
	s_addc_u32 s9, s9, 0
	s_add_u32 s6, s6, 0x40000
	s_addc_u32 s7, s7, 0
	global_load_dwordx2 v[80:81], v1, s[6:7] nt
	global_load_dword v104, v2, s[8:9]
	s_add_u32 s8, s8, 0x1000
	s_addc_u32 s9, s9, 0
	s_add_u32 s6, s6, 0x40000
	s_addc_u32 s7, s7, 0
	global_load_dwordx2 v[82:83], v1, s[6:7] nt
	global_load_dword v105, v2, s[8:9]
	s_add_u32 s8, s8, 0x1000
	s_addc_u32 s9, s9, 0
	s_add_u32 s6, s6, 0x40000
	s_addc_u32 s7, s7, 0
	global_load_dwordx2 v[84:85], v1, s[6:7] nt
	global_load_dword v106, v2, s[8:9]
	s_add_u32 s8, s8, 0x1000
	s_addc_u32 s9, s9, 0
	s_add_u32 s6, s6, 0x40000
	s_addc_u32 s7, s7, 0
	global_load_dwordx2 v[86:87], v1, s[6:7] nt
	global_load_dword v107, v2, s[8:9]
	s_add_u32 s8, s8, 0x1000
	s_addc_u32 s9, s9, 0
	s_add_u32 s6, s6, 0x40000
	s_addc_u32 s7, s7, 0
	global_load_dwordx2 v[88:89], v1, s[6:7] nt
	global_load_dword v108, v2, s[8:9]
	s_add_u32 s8, s8, 0x1000
	s_addc_u32 s9, s9, 0
	s_add_u32 s6, s6, 0x40000
	s_addc_u32 s7, s7, 0
	global_load_dwordx2 v[90:91], v1, s[6:7] nt
	global_load_dword v109, v2, s[8:9]
	s_add_u32 s8, s8, 0x1000
	s_addc_u32 s9, s9, 0
	s_add_u32 s6, s6, 0x40000
	s_addc_u32 s7, s7, 0
	global_load_dwordx2 v[92:93], v1, s[6:7] nt
	global_load_dword v110, v2, s[8:9]
	s_add_u32 s8, s8, 0x1000
	s_addc_u32 s9, s9, 0
	s_add_u32 s6, s6, 0x40000
	s_addc_u32 s7, s7, 0
	global_load_dwordx2 v[94:95], v1, s[6:7] nt
	global_load_dword v111, v2, s[8:9]
	s_add_u32 s8, s8, 0x1000
	s_addc_u32 s9, s9, 0
	s_add_u32 s6, s6, 0x40000
	s_addc_u32 s7, s7, 0
	s_waitcnt vmcnt(32)
; __device__ __forceinline__ u32x2 pk4(f32x4 v) { u32x2 r; r.x = pk2(v[0], v[1]); r.y = pk2(v[2], v[3]); return r; }
; __device__ __forceinline__ f32x4 up4(u32x2 u) { return (f32x4){lo16(u.x), hi16(u.x), lo16(u.y), hi16(u.y)}; }
;     template <class Tp> __device__ __forceinline__ Tp* W(size_t off) const { return (Tp*)(ws + off); }
; __device__ void scan_ssd(const Ctx& c, int idx) {
;     bf16_t* sSt = c.W<bf16_t>(WS_SST); const float* sAcs = c.W<float>(WS_SACS);
;     const size_t e4 = (size_t)idx * 4; const int h = (int)(e4 >> 13);
;     f32x4 S = (f32x4){0.f, 0.f, 0.f, 0.f};
; #pragma unroll 4
;     for (int ck = 0; ck < NCH; ++ck) { u32x2* ad = (u32x2*)(sSt + (size_t)ck * 131072 + e4);
;         const f32x4 st = up4(__builtin_nontemporal_load(ad)); const float d = __expf(sAcs[(size_t)(ck * 16 + h) * 64 + 63]);
;         __builtin_nontemporal_store(pk4(S), ad); S = S * d + st; }
; }
	v_mul_f32_e32 v48, 0x3fb8aa3b, v48
	v_mul_f32_e32 v49, 0x3fb8aa3b, v49
	v_mul_f32_e32 v50, 0x3fb8aa3b, v50
	v_mul_f32_e32 v51, 0x3fb8aa3b, v51
	v_mul_f32_e32 v52, 0x3fb8aa3b, v52
	v_mul_f32_e32 v53, 0x3fb8aa3b, v53
	v_mul_f32_e32 v54, 0x3fb8aa3b, v54
	v_mul_f32_e32 v55, 0x3fb8aa3b, v55
	v_mul_f32_e32 v56, 0x3fb8aa3b, v56
	v_mul_f32_e32 v57, 0x3fb8aa3b, v57
	v_mul_f32_e32 v58, 0x3fb8aa3b, v58
	v_mul_f32_e32 v59, 0x3fb8aa3b, v59
	v_mul_f32_e32 v60, 0x3fb8aa3b, v60
	v_mul_f32_e32 v61, 0x3fb8aa3b, v61
	v_mul_f32_e32 v62, 0x3fb8aa3b, v62
	v_mul_f32_e32 v63, 0x3fb8aa3b, v63
	v_exp_f32_e32 v48, v48
	v_exp_f32_e32 v49, v49
	v_exp_f32_e32 v50, v50
	v_exp_f32_e32 v51, v51
	v_exp_f32_e32 v52, v52
	v_exp_f32_e32 v53, v53
	v_exp_f32_e32 v54, v54
	v_exp_f32_e32 v55, v55
	v_exp_f32_e32 v56, v56
	v_exp_f32_e32 v57, v57
	v_exp_f32_e32 v58, v58
	v_exp_f32_e32 v59, v59
	v_exp_f32_e32 v60, v60
	v_exp_f32_e32 v61, v61
	v_exp_f32_e32 v62, v62
	v_exp_f32_e32 v63, v63
	s_nop 0
	v_cvt_pk_bf16_f32 v8, v4, v5
	v_cvt_pk_bf16_f32 v9, v6, v7
	global_store_dwordx2 v1, v[8:9], s[12:13] nt
	s_add_u32 s12, s12, 0x40000
	s_addc_u32 s13, s13, 0
	v_lshlrev_b32_e32 v10, 16, v16
	v_and_b32_e32 v11, 0xffff0000, v16
	v_lshlrev_b32_e32 v12, 16, v17
	v_and_b32_e32 v13, 0xffff0000, v17
	v_fma_f32 v4, v4, v48, v10
	v_fma_f32 v5, v5, v48, v11
	v_fma_f32 v6, v6, v48, v12
	v_fma_f32 v7, v7, v48, v13
	v_cvt_pk_bf16_f32 v14, v4, v5
	v_cvt_pk_bf16_f32 v15, v6, v7
	global_store_dwordx2 v1, v[14:15], s[12:13] nt
	s_add_u32 s12, s12, 0x40000
	s_addc_u32 s13, s13, 0
	v_lshlrev_b32_e32 v10, 16, v18
	v_and_b32_e32 v11, 0xffff0000, v18
	v_lshlrev_b32_e32 v12, 16, v19
	v_and_b32_e32 v13, 0xffff0000, v19
	v_fma_f32 v4, v4, v49, v10
	v_fma_f32 v5, v5, v49, v11
	v_fma_f32 v6, v6, v49, v12
	v_fma_f32 v7, v7, v49, v13
	v_cvt_pk_bf16_f32 v8, v4, v5
	v_cvt_pk_bf16_f32 v9, v6, v7
	global_store_dwordx2 v1, v[8:9], s[12:13] nt
	s_add_u32 s12, s12, 0x40000
	s_addc_u32 s13, s13, 0
	v_lshlrev_b32_e32 v10, 16, v20
	v_and_b32_e32 v11, 0xffff0000, v20
	v_lshlrev_b32_e32 v12, 16, v21
	v_and_b32_e32 v13, 0xffff0000, v21
	v_fma_f32 v4, v4, v50, v10
	v_fma_f32 v5, v5, v50, v11
	v_fma_f32 v6, v6, v50, v12
	v_fma_f32 v7, v7, v50, v13
	v_cvt_pk_bf16_f32 v14, v4, v5
	v_cvt_pk_bf16_f32 v15, v6, v7
	global_store_dwordx2 v1, v[14:15], s[12:13] nt
	s_add_u32 s12, s12, 0x40000
	s_addc_u32 s13, s13, 0
	v_lshlrev_b32_e32 v10, 16, v22
	v_and_b32_e32 v11, 0xffff0000, v22
	v_lshlrev_b32_e32 v12, 16, v23
	v_and_b32_e32 v13, 0xffff0000, v23
	v_fma_f32 v4, v4, v51, v10
	v_fma_f32 v5, v5, v51, v11
	v_fma_f32 v6, v6, v51, v12
	v_fma_f32 v7, v7, v51, v13
	v_cvt_pk_bf16_f32 v8, v4, v5
	v_cvt_pk_bf16_f32 v9, v6, v7
	global_store_dwordx2 v1, v[8:9], s[12:13] nt
	s_add_u32 s12, s12, 0x40000
	s_addc_u32 s13, s13, 0
	v_lshlrev_b32_e32 v10, 16, v24
	v_and_b32_e32 v11, 0xffff0000, v24
	v_lshlrev_b32_e32 v12, 16, v25
	v_and_b32_e32 v13, 0xffff0000, v25
	v_fma_f32 v4, v4, v52, v10
	v_fma_f32 v5, v5, v52, v11
	v_fma_f32 v6, v6, v52, v12
	v_fma_f32 v7, v7, v52, v13
	v_cvt_pk_bf16_f32 v14, v4, v5
	v_cvt_pk_bf16_f32 v15, v6, v7
	global_store_dwordx2 v1, v[14:15], s[12:13] nt
	s_add_u32 s12, s12, 0x40000
	s_addc_u32 s13, s13, 0
	v_lshlrev_b32_e32 v10, 16, v26
	v_and_b32_e32 v11, 0xffff0000, v26
	v_lshlrev_b32_e32 v12, 16, v27
	v_and_b32_e32 v13, 0xffff0000, v27
	v_fma_f32 v4, v4, v53, v10
	v_fma_f32 v5, v5, v53, v11
	v_fma_f32 v6, v6, v53, v12
	v_fma_f32 v7, v7, v53, v13
	v_cvt_pk_bf16_f32 v8, v4, v5
	v_cvt_pk_bf16_f32 v9, v6, v7
	global_store_dwordx2 v1, v[8:9], s[12:13] nt
	s_add_u32 s12, s12, 0x40000
	s_addc_u32 s13, s13, 0
	v_lshlrev_b32_e32 v10, 16, v28
	v_and_b32_e32 v11, 0xffff0000, v28
	v_lshlrev_b32_e32 v12, 16, v29
	v_and_b32_e32 v13, 0xffff0000, v29
	v_fma_f32 v4, v4, v54, v10
	v_fma_f32 v5, v5, v54, v11
	v_fma_f32 v6, v6, v54, v12
	v_fma_f32 v7, v7, v54, v13
	v_cvt_pk_bf16_f32 v14, v4, v5
	v_cvt_pk_bf16_f32 v15, v6, v7
	global_store_dwordx2 v1, v[14:15], s[12:13] nt
	s_add_u32 s12, s12, 0x40000
	s_addc_u32 s13, s13, 0
	v_lshlrev_b32_e32 v10, 16, v30
	v_and_b32_e32 v11, 0xffff0000, v30
	v_lshlrev_b32_e32 v12, 16, v31
	v_and_b32_e32 v13, 0xffff0000, v31
	v_fma_f32 v4, v4, v55, v10
	v_fma_f32 v5, v5, v55, v11
	v_fma_f32 v6, v6, v55, v12
	v_fma_f32 v7, v7, v55, v13
	v_cvt_pk_bf16_f32 v8, v4, v5
	v_cvt_pk_bf16_f32 v9, v6, v7
	global_store_dwordx2 v1, v[8:9], s[12:13] nt
	s_add_u32 s12, s12, 0x40000
	s_addc_u32 s13, s13, 0
	v_lshlrev_b32_e32 v10, 16, v32
	v_and_b32_e32 v11, 0xffff0000, v32
	v_lshlrev_b32_e32 v12, 16, v33
	v_and_b32_e32 v13, 0xffff0000, v33
	v_fma_f32 v4, v4, v56, v10
	v_fma_f32 v5, v5, v56, v11
	v_fma_f32 v6, v6, v56, v12
	v_fma_f32 v7, v7, v56, v13
	v_cvt_pk_bf16_f32 v14, v4, v5
	v_cvt_pk_bf16_f32 v15, v6, v7
	global_store_dwordx2 v1, v[14:15], s[12:13] nt
	s_add_u32 s12, s12, 0x40000
	s_addc_u32 s13, s13, 0
	v_lshlrev_b32_e32 v10, 16, v34
	v_and_b32_e32 v11, 0xffff0000, v34
	v_lshlrev_b32_e32 v12, 16, v35
	v_and_b32_e32 v13, 0xffff0000, v35
	v_fma_f32 v4, v4, v57, v10
	v_fma_f32 v5, v5, v57, v11
	v_fma_f32 v6, v6, v57, v12
	v_fma_f32 v7, v7, v57, v13
	v_cvt_pk_bf16_f32 v8, v4, v5
	v_cvt_pk_bf16_f32 v9, v6, v7
	global_store_dwordx2 v1, v[8:9], s[12:13] nt
	s_add_u32 s12, s12, 0x40000
	s_addc_u32 s13, s13, 0
	v_lshlrev_b32_e32 v10, 16, v36
	v_and_b32_e32 v11, 0xffff0000, v36
	v_lshlrev_b32_e32 v12, 16, v37
	v_and_b32_e32 v13, 0xffff0000, v37
	v_fma_f32 v4, v4, v58, v10
	v_fma_f32 v5, v5, v58, v11
	v_fma_f32 v6, v6, v58, v12
	v_fma_f32 v7, v7, v58, v13
	v_cvt_pk_bf16_f32 v14, v4, v5
	v_cvt_pk_bf16_f32 v15, v6, v7
	global_store_dwordx2 v1, v[14:15], s[12:13] nt
	s_add_u32 s12, s12, 0x40000
	s_addc_u32 s13, s13, 0
; __device__ __forceinline__ u32x2 pk4(f32x4 v) { u32x2 r; r.x = pk2(v[0], v[1]); r.y = pk2(v[2], v[3]); return r; }
; __device__ __forceinline__ f32x4 up4(u32x2 u) { return (f32x4){lo16(u.x), hi16(u.x), lo16(u.y), hi16(u.y)}; }
;     template <class Tp> __device__ __forceinline__ Tp* W(size_t off) const { return (Tp*)(ws + off); }
; __device__ void scan_ssd(const Ctx& c, int idx) {
;     bf16_t* sSt = c.W<bf16_t>(WS_SST); const float* sAcs = c.W<float>(WS_SACS);
;     const size_t e4 = (size_t)idx * 4; const int h = (int)(e4 >> 13);
;     f32x4 S = (f32x4){0.f, 0.f, 0.f, 0.f};
; #pragma unroll 4
;     for (int ck = 0; ck < NCH; ++ck) { u32x2* ad = (u32x2*)(sSt + (size_t)ck * 131072 + e4);
;         const f32x4 st = up4(__builtin_nontemporal_load(ad)); const float d = __expf(sAcs[(size_t)(ck * 16 + h) * 64 + 63]);
;         __builtin_nontemporal_store(pk4(S), ad); S = S * d + st; }
; }
	v_lshlrev_b32_e32 v10, 16, v38
	v_and_b32_e32 v11, 0xffff0000, v38
	v_lshlrev_b32_e32 v12, 16, v39
	v_and_b32_e32 v13, 0xffff0000, v39
	v_fma_f32 v4, v4, v59, v10
	v_fma_f32 v5, v5, v59, v11
	v_fma_f32 v6, v6, v59, v12
	v_fma_f32 v7, v7, v59, v13
	v_cvt_pk_bf16_f32 v8, v4, v5
	v_cvt_pk_bf16_f32 v9, v6, v7
	global_store_dwordx2 v1, v[8:9], s[12:13] nt
	s_add_u32 s12, s12, 0x40000
	s_addc_u32 s13, s13, 0
	v_lshlrev_b32_e32 v10, 16, v40
	v_and_b32_e32 v11, 0xffff0000, v40
	v_lshlrev_b32_e32 v12, 16, v41
	v_and_b32_e32 v13, 0xffff0000, v41
	v_fma_f32 v4, v4, v60, v10
	v_fma_f32 v5, v5, v60, v11
	v_fma_f32 v6, v6, v60, v12
	v_fma_f32 v7, v7, v60, v13
	v_cvt_pk_bf16_f32 v14, v4, v5
	v_cvt_pk_bf16_f32 v15, v6, v7
	global_store_dwordx2 v1, v[14:15], s[12:13] nt
	s_add_u32 s12, s12, 0x40000
	s_addc_u32 s13, s13, 0
	v_lshlrev_b32_e32 v10, 16, v42
	v_and_b32_e32 v11, 0xffff0000, v42
	v_lshlrev_b32_e32 v12, 16, v43
	v_and_b32_e32 v13, 0xffff0000, v43
	v_fma_f32 v4, v4, v61, v10
	v_fma_f32 v5, v5, v61, v11
	v_fma_f32 v6, v6, v61, v12
	v_fma_f32 v7, v7, v61, v13
	v_cvt_pk_bf16_f32 v8, v4, v5
	v_cvt_pk_bf16_f32 v9, v6, v7
	global_store_dwordx2 v1, v[8:9], s[12:13] nt
	s_add_u32 s12, s12, 0x40000
	s_addc_u32 s13, s13, 0
	v_lshlrev_b32_e32 v10, 16, v44
	v_and_b32_e32 v11, 0xffff0000, v44
	v_lshlrev_b32_e32 v12, 16, v45
	v_and_b32_e32 v13, 0xffff0000, v45
	v_fma_f32 v4, v4, v62, v10
	v_fma_f32 v5, v5, v62, v11
	v_fma_f32 v6, v6, v62, v12
	v_fma_f32 v7, v7, v62, v13
	v_cvt_pk_bf16_f32 v14, v4, v5
	v_cvt_pk_bf16_f32 v15, v6, v7
	global_store_dwordx2 v1, v[14:15], s[12:13] nt
	s_add_u32 s12, s12, 0x40000
	s_addc_u32 s13, s13, 0
	v_lshlrev_b32_e32 v10, 16, v46
	v_and_b32_e32 v11, 0xffff0000, v46
	v_lshlrev_b32_e32 v12, 16, v47
	v_and_b32_e32 v13, 0xffff0000, v47
	v_fma_f32 v4, v4, v63, v10
	v_fma_f32 v5, v5, v63, v11
	v_fma_f32 v6, v6, v63, v12
	v_fma_f32 v7, v7, v63, v13
	global_load_dwordx2 v[16:17], v1, s[6:7] nt
	global_load_dword v48, v2, s[8:9]
	s_add_u32 s8, s8, 0x1000
	s_addc_u32 s9, s9, 0
	s_add_u32 s6, s6, 0x40000
	s_addc_u32 s7, s7, 0
	global_load_dwordx2 v[18:19], v1, s[6:7] nt
	global_load_dword v49, v2, s[8:9]
	s_add_u32 s8, s8, 0x1000
	s_addc_u32 s9, s9, 0
	s_add_u32 s6, s6, 0x40000
	s_addc_u32 s7, s7, 0
	global_load_dwordx2 v[20:21], v1, s[6:7] nt
	global_load_dword v50, v2, s[8:9]
	s_add_u32 s8, s8, 0x1000
	s_addc_u32 s9, s9, 0
	s_add_u32 s6, s6, 0x40000
	s_addc_u32 s7, s7, 0
	global_load_dwordx2 v[22:23], v1, s[6:7] nt
	global_load_dword v51, v2, s[8:9]
	s_add_u32 s8, s8, 0x1000
	s_addc_u32 s9, s9, 0
	s_add_u32 s6, s6, 0x40000
	s_addc_u32 s7, s7, 0
	global_load_dwordx2 v[24:25], v1, s[6:7] nt
	global_load_dword v52, v2, s[8:9]
	s_add_u32 s8, s8, 0x1000
	s_addc_u32 s9, s9, 0
	s_add_u32 s6, s6, 0x40000
	s_addc_u32 s7, s7, 0
	global_load_dwordx2 v[26:27], v1, s[6:7] nt
	global_load_dword v53, v2, s[8:9]
	s_add_u32 s8, s8, 0x1000
	s_addc_u32 s9, s9, 0
	s_add_u32 s6, s6, 0x40000
	s_addc_u32 s7, s7, 0
	global_load_dwordx2 v[28:29], v1, s[6:7] nt
	global_load_dword v54, v2, s[8:9]
	s_add_u32 s8, s8, 0x1000
	s_addc_u32 s9, s9, 0
	s_add_u32 s6, s6, 0x40000
	s_addc_u32 s7, s7, 0
	global_load_dwordx2 v[30:31], v1, s[6:7] nt
	global_load_dword v55, v2, s[8:9]
	s_add_u32 s8, s8, 0x1000
	s_addc_u32 s9, s9, 0
	s_add_u32 s6, s6, 0x40000
	s_addc_u32 s7, s7, 0
	global_load_dwordx2 v[32:33], v1, s[6:7] nt
	global_load_dword v56, v2, s[8:9]
	s_add_u32 s8, s8, 0x1000
	s_addc_u32 s9, s9, 0
	s_add_u32 s6, s6, 0x40000
	s_addc_u32 s7, s7, 0
	global_load_dwordx2 v[34:35], v1, s[6:7] nt
	global_load_dword v57, v2, s[8:9]
	s_add_u32 s8, s8, 0x1000
	s_addc_u32 s9, s9, 0
	s_add_u32 s6, s6, 0x40000
	s_addc_u32 s7, s7, 0
	global_load_dwordx2 v[36:37], v1, s[6:7] nt
	global_load_dword v58, v2, s[8:9]
	s_add_u32 s8, s8, 0x1000
	s_addc_u32 s9, s9, 0
	s_add_u32 s6, s6, 0x40000
	s_addc_u32 s7, s7, 0
	global_load_dwordx2 v[38:39], v1, s[6:7] nt
	global_load_dword v59, v2, s[8:9]
	s_add_u32 s8, s8, 0x1000
	s_addc_u32 s9, s9, 0
	s_add_u32 s6, s6, 0x40000
	s_addc_u32 s7, s7, 0
	global_load_dwordx2 v[40:41], v1, s[6:7] nt
	global_load_dword v60, v2, s[8:9]
	s_add_u32 s8, s8, 0x1000
	s_addc_u32 s9, s9, 0
	s_add_u32 s6, s6, 0x40000
	s_addc_u32 s7, s7, 0
	global_load_dwordx2 v[42:43], v1, s[6:7] nt
	global_load_dword v61, v2, s[8:9]
	s_add_u32 s8, s8, 0x1000
	s_addc_u32 s9, s9, 0
	s_add_u32 s6, s6, 0x40000
	s_addc_u32 s7, s7, 0
	global_load_dwordx2 v[44:45], v1, s[6:7] nt
	global_load_dword v62, v2, s[8:9]
	s_add_u32 s8, s8, 0x1000
	s_addc_u32 s9, s9, 0
	s_add_u32 s6, s6, 0x40000
	s_addc_u32 s7, s7, 0
	global_load_dwordx2 v[46:47], v1, s[6:7] nt
	global_load_dword v63, v2, s[8:9]
	s_add_u32 s8, s8, 0x1000
	s_addc_u32 s9, s9, 0
	s_add_u32 s6, s6, 0x40000
	s_addc_u32 s7, s7, 0
	s_waitcnt vmcnt(48)
; __device__ __forceinline__ u32x2 pk4(f32x4 v) { u32x2 r; r.x = pk2(v[0], v[1]); r.y = pk2(v[2], v[3]); return r; }
; __device__ __forceinline__ f32x4 up4(u32x2 u) { return (f32x4){lo16(u.x), hi16(u.x), lo16(u.y), hi16(u.y)}; }
;     template <class Tp> __device__ __forceinline__ Tp* W(size_t off) const { return (Tp*)(ws + off); }
; __device__ void scan_ssd(const Ctx& c, int idx) {
;     bf16_t* sSt = c.W<bf16_t>(WS_SST); const float* sAcs = c.W<float>(WS_SACS);
;     const size_t e4 = (size_t)idx * 4; const int h = (int)(e4 >> 13);
;     f32x4 S = (f32x4){0.f, 0.f, 0.f, 0.f};
; #pragma unroll 4
;     for (int ck = 0; ck < NCH; ++ck) { u32x2* ad = (u32x2*)(sSt + (size_t)ck * 131072 + e4);
;         const f32x4 st = up4(__builtin_nontemporal_load(ad)); const float d = __expf(sAcs[(size_t)(ck * 16 + h) * 64 + 63]);
;         __builtin_nontemporal_store(pk4(S), ad); S = S * d + st; }
; }
	v_mul_f32_e32 v96, 0x3fb8aa3b, v96
	v_mul_f32_e32 v97, 0x3fb8aa3b, v97
	v_mul_f32_e32 v98, 0x3fb8aa3b, v98
	v_mul_f32_e32 v99, 0x3fb8aa3b, v99
	v_mul_f32_e32 v100, 0x3fb8aa3b, v100
	v_mul_f32_e32 v101, 0x3fb8aa3b, v101
	v_mul_f32_e32 v102, 0x3fb8aa3b, v102
	v_mul_f32_e32 v103, 0x3fb8aa3b, v103
	v_mul_f32_e32 v104, 0x3fb8aa3b, v104
	v_mul_f32_e32 v105, 0x3fb8aa3b, v105
	v_mul_f32_e32 v106, 0x3fb8aa3b, v106
	v_mul_f32_e32 v107, 0x3fb8aa3b, v107
	v_mul_f32_e32 v108, 0x3fb8aa3b, v108
	v_mul_f32_e32 v109, 0x3fb8aa3b, v109
	v_mul_f32_e32 v110, 0x3fb8aa3b, v110
	v_mul_f32_e32 v111, 0x3fb8aa3b, v111
	v_exp_f32_e32 v96, v96
	v_exp_f32_e32 v97, v97
	v_exp_f32_e32 v98, v98
	v_exp_f32_e32 v99, v99
	v_exp_f32_e32 v100, v100
	v_exp_f32_e32 v101, v101
	v_exp_f32_e32 v102, v102
	v_exp_f32_e32 v103, v103
	v_exp_f32_e32 v104, v104
	v_exp_f32_e32 v105, v105
	v_exp_f32_e32 v106, v106
	v_exp_f32_e32 v107, v107
	v_exp_f32_e32 v108, v108
	v_exp_f32_e32 v109, v109
	v_exp_f32_e32 v110, v110
	v_exp_f32_e32 v111, v111
	s_nop 0
	v_cvt_pk_bf16_f32 v8, v4, v5
	v_cvt_pk_bf16_f32 v9, v6, v7
	global_store_dwordx2 v1, v[8:9], s[12:13] nt
	s_add_u32 s12, s12, 0x40000
	s_addc_u32 s13, s13, 0
	v_lshlrev_b32_e32 v10, 16, v64
	v_and_b32_e32 v11, 0xffff0000, v64
	v_lshlrev_b32_e32 v12, 16, v65
	v_and_b32_e32 v13, 0xffff0000, v65
	v_fma_f32 v4, v4, v96, v10
	v_fma_f32 v5, v5, v96, v11
	v_fma_f32 v6, v6, v96, v12
	v_fma_f32 v7, v7, v96, v13
	v_cvt_pk_bf16_f32 v14, v4, v5
	v_cvt_pk_bf16_f32 v15, v6, v7
	global_store_dwordx2 v1, v[14:15], s[12:13] nt
	s_add_u32 s12, s12, 0x40000
	s_addc_u32 s13, s13, 0
	v_lshlrev_b32_e32 v10, 16, v66
	v_and_b32_e32 v11, 0xffff0000, v66
	v_lshlrev_b32_e32 v12, 16, v67
	v_and_b32_e32 v13, 0xffff0000, v67
	v_fma_f32 v4, v4, v97, v10
	v_fma_f32 v5, v5, v97, v11
	v_fma_f32 v6, v6, v97, v12
	v_fma_f32 v7, v7, v97, v13
	v_cvt_pk_bf16_f32 v8, v4, v5
	v_cvt_pk_bf16_f32 v9, v6, v7
	global_store_dwordx2 v1, v[8:9], s[12:13] nt
	s_add_u32 s12, s12, 0x40000
	s_addc_u32 s13, s13, 0
	v_lshlrev_b32_e32 v10, 16, v68
	v_and_b32_e32 v11, 0xffff0000, v68
	v_lshlrev_b32_e32 v12, 16, v69
	v_and_b32_e32 v13, 0xffff0000, v69
	v_fma_f32 v4, v4, v98, v10
	v_fma_f32 v5, v5, v98, v11
	v_fma_f32 v6, v6, v98, v12
	v_fma_f32 v7, v7, v98, v13
	v_cvt_pk_bf16_f32 v14, v4, v5
	v_cvt_pk_bf16_f32 v15, v6, v7
	global_store_dwordx2 v1, v[14:15], s[12:13] nt
	s_add_u32 s12, s12, 0x40000
	s_addc_u32 s13, s13, 0
	v_lshlrev_b32_e32 v10, 16, v70
	v_and_b32_e32 v11, 0xffff0000, v70
	v_lshlrev_b32_e32 v12, 16, v71
	v_and_b32_e32 v13, 0xffff0000, v71
	v_fma_f32 v4, v4, v99, v10
	v_fma_f32 v5, v5, v99, v11
	v_fma_f32 v6, v6, v99, v12
	v_fma_f32 v7, v7, v99, v13
	v_cvt_pk_bf16_f32 v8, v4, v5
	v_cvt_pk_bf16_f32 v9, v6, v7
	global_store_dwordx2 v1, v[8:9], s[12:13] nt
	s_add_u32 s12, s12, 0x40000
	s_addc_u32 s13, s13, 0
	v_lshlrev_b32_e32 v10, 16, v72
	v_and_b32_e32 v11, 0xffff0000, v72
	v_lshlrev_b32_e32 v12, 16, v73
	v_and_b32_e32 v13, 0xffff0000, v73
	v_fma_f32 v4, v4, v100, v10
	v_fma_f32 v5, v5, v100, v11
	v_fma_f32 v6, v6, v100, v12
	v_fma_f32 v7, v7, v100, v13
	v_cvt_pk_bf16_f32 v14, v4, v5
	v_cvt_pk_bf16_f32 v15, v6, v7
	global_store_dwordx2 v1, v[14:15], s[12:13] nt
	s_add_u32 s12, s12, 0x40000
	s_addc_u32 s13, s13, 0
	v_lshlrev_b32_e32 v10, 16, v74
	v_and_b32_e32 v11, 0xffff0000, v74
	v_lshlrev_b32_e32 v12, 16, v75
	v_and_b32_e32 v13, 0xffff0000, v75
	v_fma_f32 v4, v4, v101, v10
	v_fma_f32 v5, v5, v101, v11
	v_fma_f32 v6, v6, v101, v12
	v_fma_f32 v7, v7, v101, v13
	v_cvt_pk_bf16_f32 v8, v4, v5
	v_cvt_pk_bf16_f32 v9, v6, v7
	global_store_dwordx2 v1, v[8:9], s[12:13] nt
	s_add_u32 s12, s12, 0x40000
	s_addc_u32 s13, s13, 0
	v_lshlrev_b32_e32 v10, 16, v76
	v_and_b32_e32 v11, 0xffff0000, v76
	v_lshlrev_b32_e32 v12, 16, v77
	v_and_b32_e32 v13, 0xffff0000, v77
	v_fma_f32 v4, v4, v102, v10
	v_fma_f32 v5, v5, v102, v11
	v_fma_f32 v6, v6, v102, v12
	v_fma_f32 v7, v7, v102, v13
	v_cvt_pk_bf16_f32 v14, v4, v5
	v_cvt_pk_bf16_f32 v15, v6, v7
	global_store_dwordx2 v1, v[14:15], s[12:13] nt
	s_add_u32 s12, s12, 0x40000
	s_addc_u32 s13, s13, 0
	v_lshlrev_b32_e32 v10, 16, v78
	v_and_b32_e32 v11, 0xffff0000, v78
	v_lshlrev_b32_e32 v12, 16, v79
	v_and_b32_e32 v13, 0xffff0000, v79
	v_fma_f32 v4, v4, v103, v10
	v_fma_f32 v5, v5, v103, v11
	v_fma_f32 v6, v6, v103, v12
	v_fma_f32 v7, v7, v103, v13
	v_cvt_pk_bf16_f32 v8, v4, v5
	v_cvt_pk_bf16_f32 v9, v6, v7
	global_store_dwordx2 v1, v[8:9], s[12:13] nt
	s_add_u32 s12, s12, 0x40000
	s_addc_u32 s13, s13, 0
	v_lshlrev_b32_e32 v10, 16, v80
	v_and_b32_e32 v11, 0xffff0000, v80
	v_lshlrev_b32_e32 v12, 16, v81
	v_and_b32_e32 v13, 0xffff0000, v81
	v_fma_f32 v4, v4, v104, v10
	v_fma_f32 v5, v5, v104, v11
	v_fma_f32 v6, v6, v104, v12
	v_fma_f32 v7, v7, v104, v13
	v_cvt_pk_bf16_f32 v14, v4, v5
	v_cvt_pk_bf16_f32 v15, v6, v7
	global_store_dwordx2 v1, v[14:15], s[12:13] nt
	s_add_u32 s12, s12, 0x40000
	s_addc_u32 s13, s13, 0
	v_lshlrev_b32_e32 v10, 16, v82
	v_and_b32_e32 v11, 0xffff0000, v82
	v_lshlrev_b32_e32 v12, 16, v83
	v_and_b32_e32 v13, 0xffff0000, v83
	v_fma_f32 v4, v4, v105, v10
	v_fma_f32 v5, v5, v105, v11
	v_fma_f32 v6, v6, v105, v12
	v_fma_f32 v7, v7, v105, v13
	v_cvt_pk_bf16_f32 v8, v4, v5
	v_cvt_pk_bf16_f32 v9, v6, v7
	global_store_dwordx2 v1, v[8:9], s[12:13] nt
	s_add_u32 s12, s12, 0x40000
	s_addc_u32 s13, s13, 0
	v_lshlrev_b32_e32 v10, 16, v84
	v_and_b32_e32 v11, 0xffff0000, v84
	v_lshlrev_b32_e32 v12, 16, v85
	v_and_b32_e32 v13, 0xffff0000, v85
	v_fma_f32 v4, v4, v106, v10
	v_fma_f32 v5, v5, v106, v11
	v_fma_f32 v6, v6, v106, v12
	v_fma_f32 v7, v7, v106, v13
	v_cvt_pk_bf16_f32 v14, v4, v5
	v_cvt_pk_bf16_f32 v15, v6, v7
	global_store_dwordx2 v1, v[14:15], s[12:13] nt
; __device__ __forceinline__ u32x2 pk4(f32x4 v) { u32x2 r; r.x = pk2(v[0], v[1]); r.y = pk2(v[2], v[3]); return r; }
; __device__ __forceinline__ f32x4 up4(u32x2 u) { return (f32x4){lo16(u.x), hi16(u.x), lo16(u.y), hi16(u.y)}; }
;     template <class Tp> __device__ __forceinline__ Tp* W(size_t off) const { return (Tp*)(ws + off); }
; __device__ void scan_ssd(const Ctx& c, int idx) {
;     bf16_t* sSt = c.W<bf16_t>(WS_SST); const float* sAcs = c.W<float>(WS_SACS);
;     const size_t e4 = (size_t)idx * 4; const int h = (int)(e4 >> 13);
;     f32x4 S = (f32x4){0.f, 0.f, 0.f, 0.f};
; #pragma unroll 4
;     for (int ck = 0; ck < NCH; ++ck) { u32x2* ad = (u32x2*)(sSt + (size_t)ck * 131072 + e4);
;         const f32x4 st = up4(__builtin_nontemporal_load(ad)); const float d = __expf(sAcs[(size_t)(ck * 16 + h) * 64 + 63]);
;         __builtin_nontemporal_store(pk4(S), ad); S = S * d + st; }
; }
	s_add_u32 s12, s12, 0x40000
	s_addc_u32 s13, s13, 0
	v_lshlrev_b32_e32 v10, 16, v86
	v_and_b32_e32 v11, 0xffff0000, v86
	v_lshlrev_b32_e32 v12, 16, v87
	v_and_b32_e32 v13, 0xffff0000, v87
	v_fma_f32 v4, v4, v107, v10
	v_fma_f32 v5, v5, v107, v11
	v_fma_f32 v6, v6, v107, v12
	v_fma_f32 v7, v7, v107, v13
	v_cvt_pk_bf16_f32 v8, v4, v5
	v_cvt_pk_bf16_f32 v9, v6, v7
	global_store_dwordx2 v1, v[8:9], s[12:13] nt
	s_add_u32 s12, s12, 0x40000
	s_addc_u32 s13, s13, 0
	v_lshlrev_b32_e32 v10, 16, v88
	v_and_b32_e32 v11, 0xffff0000, v88
	v_lshlrev_b32_e32 v12, 16, v89
	v_and_b32_e32 v13, 0xffff0000, v89
	v_fma_f32 v4, v4, v108, v10
	v_fma_f32 v5, v5, v108, v11
	v_fma_f32 v6, v6, v108, v12
	v_fma_f32 v7, v7, v108, v13
	v_cvt_pk_bf16_f32 v14, v4, v5
	v_cvt_pk_bf16_f32 v15, v6, v7
	global_store_dwordx2 v1, v[14:15], s[12:13] nt
	s_add_u32 s12, s12, 0x40000
	s_addc_u32 s13, s13, 0
	v_lshlrev_b32_e32 v10, 16, v90
	v_and_b32_e32 v11, 0xffff0000, v90
	v_lshlrev_b32_e32 v12, 16, v91
	v_and_b32_e32 v13, 0xffff0000, v91
	v_fma_f32 v4, v4, v109, v10
	v_fma_f32 v5, v5, v109, v11
	v_fma_f32 v6, v6, v109, v12
	v_fma_f32 v7, v7, v109, v13
	v_cvt_pk_bf16_f32 v8, v4, v5
	v_cvt_pk_bf16_f32 v9, v6, v7
	global_store_dwordx2 v1, v[8:9], s[12:13] nt
	s_add_u32 s12, s12, 0x40000
	s_addc_u32 s13, s13, 0
	v_lshlrev_b32_e32 v10, 16, v92
	v_and_b32_e32 v11, 0xffff0000, v92
	v_lshlrev_b32_e32 v12, 16, v93
	v_and_b32_e32 v13, 0xffff0000, v93
	v_fma_f32 v4, v4, v110, v10
	v_fma_f32 v5, v5, v110, v11
	v_fma_f32 v6, v6, v110, v12
	v_fma_f32 v7, v7, v110, v13
	v_cvt_pk_bf16_f32 v14, v4, v5
	v_cvt_pk_bf16_f32 v15, v6, v7
	global_store_dwordx2 v1, v[14:15], s[12:13] nt
	s_add_u32 s12, s12, 0x40000
	s_addc_u32 s13, s13, 0
	v_lshlrev_b32_e32 v10, 16, v94
	v_and_b32_e32 v11, 0xffff0000, v94
	v_lshlrev_b32_e32 v12, 16, v95
	v_and_b32_e32 v13, 0xffff0000, v95
	v_fma_f32 v4, v4, v111, v10
	v_fma_f32 v5, v5, v111, v11
	v_fma_f32 v6, v6, v111, v12
	v_fma_f32 v7, v7, v111, v13
	global_load_dwordx2 v[64:65], v1, s[6:7] nt
	global_load_dword v96, v2, s[8:9]
	s_add_u32 s8, s8, 0x1000
	s_addc_u32 s9, s9, 0
	s_add_u32 s6, s6, 0x40000
	s_addc_u32 s7, s7, 0
	global_load_dwordx2 v[66:67], v1, s[6:7] nt
	global_load_dword v97, v2, s[8:9]
	s_add_u32 s8, s8, 0x1000
	s_addc_u32 s9, s9, 0
	s_add_u32 s6, s6, 0x40000
	s_addc_u32 s7, s7, 0
	global_load_dwordx2 v[68:69], v1, s[6:7] nt
	global_load_dword v98, v2, s[8:9]
	s_add_u32 s8, s8, 0x1000
	s_addc_u32 s9, s9, 0
	s_add_u32 s6, s6, 0x40000
	s_addc_u32 s7, s7, 0
	global_load_dwordx2 v[70:71], v1, s[6:7] nt
	global_load_dword v99, v2, s[8:9]
	s_add_u32 s8, s8, 0x1000
	s_addc_u32 s9, s9, 0
	s_add_u32 s6, s6, 0x40000
	s_addc_u32 s7, s7, 0
	global_load_dwordx2 v[72:73], v1, s[6:7] nt
	global_load_dword v100, v2, s[8:9]
	s_add_u32 s8, s8, 0x1000
	s_addc_u32 s9, s9, 0
	s_add_u32 s6, s6, 0x40000
	s_addc_u32 s7, s7, 0
	global_load_dwordx2 v[74:75], v1, s[6:7] nt
	global_load_dword v101, v2, s[8:9]
	s_add_u32 s8, s8, 0x1000
	s_addc_u32 s9, s9, 0
	s_add_u32 s6, s6, 0x40000
	s_addc_u32 s7, s7, 0
	global_load_dwordx2 v[76:77], v1, s[6:7] nt
	global_load_dword v102, v2, s[8:9]
	s_add_u32 s8, s8, 0x1000
	s_addc_u32 s9, s9, 0
	s_add_u32 s6, s6, 0x40000
	s_addc_u32 s7, s7, 0
	global_load_dwordx2 v[78:79], v1, s[6:7] nt
	global_load_dword v103, v2, s[8:9]
	s_add_u32 s8, s8, 0x1000
	s_addc_u32 s9, s9, 0
	s_add_u32 s6, s6, 0x40000
	s_addc_u32 s7, s7, 0
	global_load_dwordx2 v[80:81], v1, s[6:7] nt
	global_load_dword v104, v2, s[8:9]
	s_add_u32 s8, s8, 0x1000
	s_addc_u32 s9, s9, 0
	s_add_u32 s6, s6, 0x40000
	s_addc_u32 s7, s7, 0
	global_load_dwordx2 v[82:83], v1, s[6:7] nt
	global_load_dword v105, v2, s[8:9]
	s_add_u32 s8, s8, 0x1000
	s_addc_u32 s9, s9, 0
	s_add_u32 s6, s6, 0x40000
	s_addc_u32 s7, s7, 0
	global_load_dwordx2 v[84:85], v1, s[6:7] nt
	global_load_dword v106, v2, s[8:9]
	s_add_u32 s8, s8, 0x1000
	s_addc_u32 s9, s9, 0
	s_add_u32 s6, s6, 0x40000
	s_addc_u32 s7, s7, 0
	global_load_dwordx2 v[86:87], v1, s[6:7] nt
	global_load_dword v107, v2, s[8:9]
	s_add_u32 s8, s8, 0x1000
	s_addc_u32 s9, s9, 0
	s_add_u32 s6, s6, 0x40000
	s_addc_u32 s7, s7, 0
	global_load_dwordx2 v[88:89], v1, s[6:7] nt
	global_load_dword v108, v2, s[8:9]
	s_add_u32 s8, s8, 0x1000
	s_addc_u32 s9, s9, 0
	s_add_u32 s6, s6, 0x40000
	s_addc_u32 s7, s7, 0
	global_load_dwordx2 v[90:91], v1, s[6:7] nt
	global_load_dword v109, v2, s[8:9]
	s_add_u32 s8, s8, 0x1000
	s_addc_u32 s9, s9, 0
	s_add_u32 s6, s6, 0x40000
	s_addc_u32 s7, s7, 0
	global_load_dwordx2 v[92:93], v1, s[6:7] nt
	global_load_dword v110, v2, s[8:9]
	s_add_u32 s8, s8, 0x1000
	s_addc_u32 s9, s9, 0
	s_add_u32 s6, s6, 0x40000
	s_addc_u32 s7, s7, 0
	global_load_dwordx2 v[94:95], v1, s[6:7] nt
	global_load_dword v111, v2, s[8:9]
	s_add_u32 s8, s8, 0x1000
	s_addc_u32 s9, s9, 0
	s_add_u32 s6, s6, 0x40000
	s_addc_u32 s7, s7, 0
	s_waitcnt vmcnt(48)
; __device__ __forceinline__ u32x2 pk4(f32x4 v) { u32x2 r; r.x = pk2(v[0], v[1]); r.y = pk2(v[2], v[3]); return r; }
; __device__ __forceinline__ f32x4 up4(u32x2 u) { return (f32x4){lo16(u.x), hi16(u.x), lo16(u.y), hi16(u.y)}; }
;     template <class Tp> __device__ __forceinline__ Tp* W(size_t off) const { return (Tp*)(ws + off); }
; __device__ void scan_ssd(const Ctx& c, int idx) {
;     bf16_t* sSt = c.W<bf16_t>(WS_SST); const float* sAcs = c.W<float>(WS_SACS);
;     const size_t e4 = (size_t)idx * 4; const int h = (int)(e4 >> 13);
;     f32x4 S = (f32x4){0.f, 0.f, 0.f, 0.f};
; #pragma unroll 4
;     for (int ck = 0; ck < NCH; ++ck) { u32x2* ad = (u32x2*)(sSt + (size_t)ck * 131072 + e4);
;         const f32x4 st = up4(__builtin_nontemporal_load(ad)); const float d = __expf(sAcs[(size_t)(ck * 16 + h) * 64 + 63]);
;         __builtin_nontemporal_store(pk4(S), ad); S = S * d + st; }
; }
	v_mul_f32_e32 v48, 0x3fb8aa3b, v48
	v_mul_f32_e32 v49, 0x3fb8aa3b, v49
	v_mul_f32_e32 v50, 0x3fb8aa3b, v50
	v_mul_f32_e32 v51, 0x3fb8aa3b, v51
	v_mul_f32_e32 v52, 0x3fb8aa3b, v52
	v_mul_f32_e32 v53, 0x3fb8aa3b, v53
	v_mul_f32_e32 v54, 0x3fb8aa3b, v54
	v_mul_f32_e32 v55, 0x3fb8aa3b, v55
	v_mul_f32_e32 v56, 0x3fb8aa3b, v56
	v_mul_f32_e32 v57, 0x3fb8aa3b, v57
	v_mul_f32_e32 v58, 0x3fb8aa3b, v58
	v_mul_f32_e32 v59, 0x3fb8aa3b, v59
	v_mul_f32_e32 v60, 0x3fb8aa3b, v60
	v_mul_f32_e32 v61, 0x3fb8aa3b, v61
	v_mul_f32_e32 v62, 0x3fb8aa3b, v62
	v_mul_f32_e32 v63, 0x3fb8aa3b, v63
	v_exp_f32_e32 v48, v48
	v_exp_f32_e32 v49, v49
	v_exp_f32_e32 v50, v50
	v_exp_f32_e32 v51, v51
	v_exp_f32_e32 v52, v52
	v_exp_f32_e32 v53, v53
	v_exp_f32_e32 v54, v54
	v_exp_f32_e32 v55, v55
	v_exp_f32_e32 v56, v56
	v_exp_f32_e32 v57, v57
	v_exp_f32_e32 v58, v58
	v_exp_f32_e32 v59, v59
	v_exp_f32_e32 v60, v60
	v_exp_f32_e32 v61, v61
	v_exp_f32_e32 v62, v62
	v_exp_f32_e32 v63, v63
	s_nop 0
	v_cvt_pk_bf16_f32 v8, v4, v5
	v_cvt_pk_bf16_f32 v9, v6, v7
	global_store_dwordx2 v1, v[8:9], s[12:13] nt
	s_add_u32 s12, s12, 0x40000
	s_addc_u32 s13, s13, 0
	v_lshlrev_b32_e32 v10, 16, v16
	v_and_b32_e32 v11, 0xffff0000, v16
	v_lshlrev_b32_e32 v12, 16, v17
	v_and_b32_e32 v13, 0xffff0000, v17
	v_fma_f32 v4, v4, v48, v10
	v_fma_f32 v5, v5, v48, v11
	v_fma_f32 v6, v6, v48, v12
	v_fma_f32 v7, v7, v48, v13
	v_cvt_pk_bf16_f32 v14, v4, v5
	v_cvt_pk_bf16_f32 v15, v6, v7
	global_store_dwordx2 v1, v[14:15], s[12:13] nt
	s_add_u32 s12, s12, 0x40000
	s_addc_u32 s13, s13, 0
	v_lshlrev_b32_e32 v10, 16, v18
	v_and_b32_e32 v11, 0xffff0000, v18
	v_lshlrev_b32_e32 v12, 16, v19
	v_and_b32_e32 v13, 0xffff0000, v19
	v_fma_f32 v4, v4, v49, v10
	v_fma_f32 v5, v5, v49, v11
	v_fma_f32 v6, v6, v49, v12
	v_fma_f32 v7, v7, v49, v13
	v_cvt_pk_bf16_f32 v8, v4, v5
	v_cvt_pk_bf16_f32 v9, v6, v7
	global_store_dwordx2 v1, v[8:9], s[12:13] nt
	s_add_u32 s12, s12, 0x40000
	s_addc_u32 s13, s13, 0
	v_lshlrev_b32_e32 v10, 16, v20
	v_and_b32_e32 v11, 0xffff0000, v20
	v_lshlrev_b32_e32 v12, 16, v21
	v_and_b32_e32 v13, 0xffff0000, v21
	v_fma_f32 v4, v4, v50, v10
	v_fma_f32 v5, v5, v50, v11
	v_fma_f32 v6, v6, v50, v12
	v_fma_f32 v7, v7, v50, v13
	v_cvt_pk_bf16_f32 v14, v4, v5
	v_cvt_pk_bf16_f32 v15, v6, v7
	global_store_dwordx2 v1, v[14:15], s[12:13] nt
	s_add_u32 s12, s12, 0x40000
	s_addc_u32 s13, s13, 0
	v_lshlrev_b32_e32 v10, 16, v22
	v_and_b32_e32 v11, 0xffff0000, v22
	v_lshlrev_b32_e32 v12, 16, v23
	v_and_b32_e32 v13, 0xffff0000, v23
	v_fma_f32 v4, v4, v51, v10
	v_fma_f32 v5, v5, v51, v11
	v_fma_f32 v6, v6, v51, v12
	v_fma_f32 v7, v7, v51, v13
	v_cvt_pk_bf16_f32 v8, v4, v5
	v_cvt_pk_bf16_f32 v9, v6, v7
	global_store_dwordx2 v1, v[8:9], s[12:13] nt
	s_add_u32 s12, s12, 0x40000
	s_addc_u32 s13, s13, 0
	v_lshlrev_b32_e32 v10, 16, v24
	v_and_b32_e32 v11, 0xffff0000, v24
	v_lshlrev_b32_e32 v12, 16, v25
	v_and_b32_e32 v13, 0xffff0000, v25
	v_fma_f32 v4, v4, v52, v10
	v_fma_f32 v5, v5, v52, v11
	v_fma_f32 v6, v6, v52, v12
	v_fma_f32 v7, v7, v52, v13
	v_cvt_pk_bf16_f32 v14, v4, v5
	v_cvt_pk_bf16_f32 v15, v6, v7
	global_store_dwordx2 v1, v[14:15], s[12:13] nt
	s_add_u32 s12, s12, 0x40000
	s_addc_u32 s13, s13, 0
	v_lshlrev_b32_e32 v10, 16, v26
	v_and_b32_e32 v11, 0xffff0000, v26
	v_lshlrev_b32_e32 v12, 16, v27
	v_and_b32_e32 v13, 0xffff0000, v27
	v_fma_f32 v4, v4, v53, v10
	v_fma_f32 v5, v5, v53, v11
	v_fma_f32 v6, v6, v53, v12
	v_fma_f32 v7, v7, v53, v13
	v_cvt_pk_bf16_f32 v8, v4, v5
	v_cvt_pk_bf16_f32 v9, v6, v7
	global_store_dwordx2 v1, v[8:9], s[12:13] nt
	s_add_u32 s12, s12, 0x40000
	s_addc_u32 s13, s13, 0
	v_lshlrev_b32_e32 v10, 16, v28
	v_and_b32_e32 v11, 0xffff0000, v28
	v_lshlrev_b32_e32 v12, 16, v29
	v_and_b32_e32 v13, 0xffff0000, v29
	v_fma_f32 v4, v4, v54, v10
	v_fma_f32 v5, v5, v54, v11
	v_fma_f32 v6, v6, v54, v12
	v_fma_f32 v7, v7, v54, v13
	v_cvt_pk_bf16_f32 v14, v4, v5
	v_cvt_pk_bf16_f32 v15, v6, v7
	global_store_dwordx2 v1, v[14:15], s[12:13] nt
	s_add_u32 s12, s12, 0x40000
	s_addc_u32 s13, s13, 0
	v_lshlrev_b32_e32 v10, 16, v30
	v_and_b32_e32 v11, 0xffff0000, v30
	v_lshlrev_b32_e32 v12, 16, v31
	v_and_b32_e32 v13, 0xffff0000, v31
	v_fma_f32 v4, v4, v55, v10
	v_fma_f32 v5, v5, v55, v11
	v_fma_f32 v6, v6, v55, v12
	v_fma_f32 v7, v7, v55, v13
	v_cvt_pk_bf16_f32 v8, v4, v5
	v_cvt_pk_bf16_f32 v9, v6, v7
	global_store_dwordx2 v1, v[8:9], s[12:13] nt
	s_add_u32 s12, s12, 0x40000
	s_addc_u32 s13, s13, 0
	v_lshlrev_b32_e32 v10, 16, v32
	v_and_b32_e32 v11, 0xffff0000, v32
	v_lshlrev_b32_e32 v12, 16, v33
	v_and_b32_e32 v13, 0xffff0000, v33
	v_fma_f32 v4, v4, v56, v10
	v_fma_f32 v5, v5, v56, v11
	v_fma_f32 v6, v6, v56, v12
	v_fma_f32 v7, v7, v56, v13
	v_cvt_pk_bf16_f32 v14, v4, v5
	v_cvt_pk_bf16_f32 v15, v6, v7
	global_store_dwordx2 v1, v[14:15], s[12:13] nt
	s_add_u32 s12, s12, 0x40000
	s_addc_u32 s13, s13, 0
	v_lshlrev_b32_e32 v10, 16, v34
	v_and_b32_e32 v11, 0xffff0000, v34
	v_lshlrev_b32_e32 v12, 16, v35
	v_and_b32_e32 v13, 0xffff0000, v35
	v_fma_f32 v4, v4, v57, v10
	v_fma_f32 v5, v5, v57, v11
	v_fma_f32 v6, v6, v57, v12
	v_fma_f32 v7, v7, v57, v13
	v_cvt_pk_bf16_f32 v8, v4, v5
	v_cvt_pk_bf16_f32 v9, v6, v7
	global_store_dwordx2 v1, v[8:9], s[12:13] nt
	s_add_u32 s12, s12, 0x40000
	s_addc_u32 s13, s13, 0
	v_lshlrev_b32_e32 v10, 16, v36
	v_and_b32_e32 v11, 0xffff0000, v36
	v_lshlrev_b32_e32 v12, 16, v37
	v_and_b32_e32 v13, 0xffff0000, v37
	v_fma_f32 v4, v4, v58, v10
	v_fma_f32 v5, v5, v58, v11
	v_fma_f32 v6, v6, v58, v12
	v_fma_f32 v7, v7, v58, v13
	v_cvt_pk_bf16_f32 v14, v4, v5
	v_cvt_pk_bf16_f32 v15, v6, v7
	global_store_dwordx2 v1, v[14:15], s[12:13] nt
	s_add_u32 s12, s12, 0x40000
	s_addc_u32 s13, s13, 0
; __device__ __forceinline__ u32x2 pk4(f32x4 v) { u32x2 r; r.x = pk2(v[0], v[1]); r.y = pk2(v[2], v[3]); return r; }
; __device__ __forceinline__ f32x4 up4(u32x2 u) { return (f32x4){lo16(u.x), hi16(u.x), lo16(u.y), hi16(u.y)}; }
;     template <class Tp> __device__ __forceinline__ Tp* W(size_t off) const { return (Tp*)(ws + off); }
; __device__ void scan_ssd(const Ctx& c, int idx) {
;     bf16_t* sSt = c.W<bf16_t>(WS_SST); const float* sAcs = c.W<float>(WS_SACS);
;     const size_t e4 = (size_t)idx * 4; const int h = (int)(e4 >> 13);
;     f32x4 S = (f32x4){0.f, 0.f, 0.f, 0.f};
; #pragma unroll 4
;     for (int ck = 0; ck < NCH; ++ck) { u32x2* ad = (u32x2*)(sSt + (size_t)ck * 131072 + e4);
;         const f32x4 st = up4(__builtin_nontemporal_load(ad)); const float d = __expf(sAcs[(size_t)(ck * 16 + h) * 64 + 63]);
;         __builtin_nontemporal_store(pk4(S), ad); S = S * d + st; }
; }
	v_lshlrev_b32_e32 v10, 16, v38
	v_and_b32_e32 v11, 0xffff0000, v38
	v_lshlrev_b32_e32 v12, 16, v39
	v_and_b32_e32 v13, 0xffff0000, v39
	v_fma_f32 v4, v4, v59, v10
	v_fma_f32 v5, v5, v59, v11
	v_fma_f32 v6, v6, v59, v12
	v_fma_f32 v7, v7, v59, v13
	v_cvt_pk_bf16_f32 v8, v4, v5
	v_cvt_pk_bf16_f32 v9, v6, v7
	global_store_dwordx2 v1, v[8:9], s[12:13] nt
	s_add_u32 s12, s12, 0x40000
	s_addc_u32 s13, s13, 0
	v_lshlrev_b32_e32 v10, 16, v40
	v_and_b32_e32 v11, 0xffff0000, v40
	v_lshlrev_b32_e32 v12, 16, v41
	v_and_b32_e32 v13, 0xffff0000, v41
	v_fma_f32 v4, v4, v60, v10
	v_fma_f32 v5, v5, v60, v11
	v_fma_f32 v6, v6, v60, v12
	v_fma_f32 v7, v7, v60, v13
	v_cvt_pk_bf16_f32 v14, v4, v5
	v_cvt_pk_bf16_f32 v15, v6, v7
	global_store_dwordx2 v1, v[14:15], s[12:13] nt
	s_add_u32 s12, s12, 0x40000
	s_addc_u32 s13, s13, 0
	v_lshlrev_b32_e32 v10, 16, v42
	v_and_b32_e32 v11, 0xffff0000, v42
	v_lshlrev_b32_e32 v12, 16, v43
	v_and_b32_e32 v13, 0xffff0000, v43
	v_fma_f32 v4, v4, v61, v10
	v_fma_f32 v5, v5, v61, v11
	v_fma_f32 v6, v6, v61, v12
	v_fma_f32 v7, v7, v61, v13
	v_cvt_pk_bf16_f32 v8, v4, v5
	v_cvt_pk_bf16_f32 v9, v6, v7
	global_store_dwordx2 v1, v[8:9], s[12:13] nt
	s_add_u32 s12, s12, 0x40000
	s_addc_u32 s13, s13, 0
	v_lshlrev_b32_e32 v10, 16, v44
	v_and_b32_e32 v11, 0xffff0000, v44
	v_lshlrev_b32_e32 v12, 16, v45
	v_and_b32_e32 v13, 0xffff0000, v45
	v_fma_f32 v4, v4, v62, v10
	v_fma_f32 v5, v5, v62, v11
	v_fma_f32 v6, v6, v62, v12
	v_fma_f32 v7, v7, v62, v13
	v_cvt_pk_bf16_f32 v14, v4, v5
	v_cvt_pk_bf16_f32 v15, v6, v7
	global_store_dwordx2 v1, v[14:15], s[12:13] nt
	s_add_u32 s12, s12, 0x40000
	s_addc_u32 s13, s13, 0
	v_lshlrev_b32_e32 v10, 16, v46
	v_and_b32_e32 v11, 0xffff0000, v46
	v_lshlrev_b32_e32 v12, 16, v47
	v_and_b32_e32 v13, 0xffff0000, v47
	v_fma_f32 v4, v4, v63, v10
	v_fma_f32 v5, v5, v63, v11
	v_fma_f32 v6, v6, v63, v12
	v_fma_f32 v7, v7, v63, v13
	global_load_dwordx2 v[16:17], v1, s[6:7] nt
	global_load_dword v48, v2, s[8:9]
	s_add_u32 s8, s8, 0x1000
	s_addc_u32 s9, s9, 0
	s_add_u32 s6, s6, 0x40000
	s_addc_u32 s7, s7, 0
	global_load_dwordx2 v[18:19], v1, s[6:7] nt
	global_load_dword v49, v2, s[8:9]
	s_add_u32 s8, s8, 0x1000
	s_addc_u32 s9, s9, 0
	s_add_u32 s6, s6, 0x40000
	s_addc_u32 s7, s7, 0
	global_load_dwordx2 v[20:21], v1, s[6:7] nt
	global_load_dword v50, v2, s[8:9]
	s_add_u32 s8, s8, 0x1000
	s_addc_u32 s9, s9, 0
	s_add_u32 s6, s6, 0x40000
	s_addc_u32 s7, s7, 0
	global_load_dwordx2 v[22:23], v1, s[6:7] nt
	global_load_dword v51, v2, s[8:9]
	s_add_u32 s8, s8, 0x1000
	s_addc_u32 s9, s9, 0
	s_add_u32 s6, s6, 0x40000
	s_addc_u32 s7, s7, 0
	global_load_dwordx2 v[24:25], v1, s[6:7] nt
	global_load_dword v52, v2, s[8:9]
	s_add_u32 s8, s8, 0x1000
	s_addc_u32 s9, s9, 0
	s_add_u32 s6, s6, 0x40000
	s_addc_u32 s7, s7, 0
	global_load_dwordx2 v[26:27], v1, s[6:7] nt
	global_load_dword v53, v2, s[8:9]
	s_add_u32 s8, s8, 0x1000
	s_addc_u32 s9, s9, 0
	s_add_u32 s6, s6, 0x40000
	s_addc_u32 s7, s7, 0
	global_load_dwordx2 v[28:29], v1, s[6:7] nt
	global_load_dword v54, v2, s[8:9]
	s_add_u32 s8, s8, 0x1000
	s_addc_u32 s9, s9, 0
	s_add_u32 s6, s6, 0x40000
	s_addc_u32 s7, s7, 0
	global_load_dwordx2 v[30:31], v1, s[6:7] nt
	global_load_dword v55, v2, s[8:9]
	s_add_u32 s8, s8, 0x1000
	s_addc_u32 s9, s9, 0
	s_add_u32 s6, s6, 0x40000
	s_addc_u32 s7, s7, 0
	global_load_dwordx2 v[32:33], v1, s[6:7] nt
	global_load_dword v56, v2, s[8:9]
	s_add_u32 s8, s8, 0x1000
	s_addc_u32 s9, s9, 0
	s_add_u32 s6, s6, 0x40000
	s_addc_u32 s7, s7, 0
	global_load_dwordx2 v[34:35], v1, s[6:7] nt
	global_load_dword v57, v2, s[8:9]
	s_add_u32 s8, s8, 0x1000
	s_addc_u32 s9, s9, 0
	s_add_u32 s6, s6, 0x40000
	s_addc_u32 s7, s7, 0
	global_load_dwordx2 v[36:37], v1, s[6:7] nt
	global_load_dword v58, v2, s[8:9]
	s_add_u32 s8, s8, 0x1000
	s_addc_u32 s9, s9, 0
	s_add_u32 s6, s6, 0x40000
	s_addc_u32 s7, s7, 0
	global_load_dwordx2 v[38:39], v1, s[6:7] nt
	global_load_dword v59, v2, s[8:9]
	s_add_u32 s8, s8, 0x1000
	s_addc_u32 s9, s9, 0
	s_add_u32 s6, s6, 0x40000
	s_addc_u32 s7, s7, 0
	global_load_dwordx2 v[40:41], v1, s[6:7] nt
	global_load_dword v60, v2, s[8:9]
	s_add_u32 s8, s8, 0x1000
	s_addc_u32 s9, s9, 0
	s_add_u32 s6, s6, 0x40000
	s_addc_u32 s7, s7, 0
	global_load_dwordx2 v[42:43], v1, s[6:7] nt
	global_load_dword v61, v2, s[8:9]
	s_add_u32 s8, s8, 0x1000
	s_addc_u32 s9, s9, 0
	s_add_u32 s6, s6, 0x40000
	s_addc_u32 s7, s7, 0
	global_load_dwordx2 v[44:45], v1, s[6:7] nt
	global_load_dword v62, v2, s[8:9]
	s_add_u32 s8, s8, 0x1000
	s_addc_u32 s9, s9, 0
	s_add_u32 s6, s6, 0x40000
	s_addc_u32 s7, s7, 0
	global_load_dwordx2 v[46:47], v1, s[6:7] nt
	global_load_dword v63, v2, s[8:9]
	s_add_u32 s8, s8, 0x1000
	s_addc_u32 s9, s9, 0
	s_add_u32 s6, s6, 0x40000
	s_addc_u32 s7, s7, 0
	s_waitcnt vmcnt(48)
; __device__ __forceinline__ u32x2 pk4(f32x4 v) { u32x2 r; r.x = pk2(v[0], v[1]); r.y = pk2(v[2], v[3]); return r; }
; __device__ __forceinline__ f32x4 up4(u32x2 u) { return (f32x4){lo16(u.x), hi16(u.x), lo16(u.y), hi16(u.y)}; }
;     template <class Tp> __device__ __forceinline__ Tp* W(size_t off) const { return (Tp*)(ws + off); }
; __device__ void scan_ssd(const Ctx& c, int idx) {
;     bf16_t* sSt = c.W<bf16_t>(WS_SST); const float* sAcs = c.W<float>(WS_SACS);
;     const size_t e4 = (size_t)idx * 4; const int h = (int)(e4 >> 13);
;     f32x4 S = (f32x4){0.f, 0.f, 0.f, 0.f};
; #pragma unroll 4
;     for (int ck = 0; ck < NCH; ++ck) { u32x2* ad = (u32x2*)(sSt + (size_t)ck * 131072 + e4);
;         const f32x4 st = up4(__builtin_nontemporal_load(ad)); const float d = __expf(sAcs[(size_t)(ck * 16 + h) * 64 + 63]);
;         __builtin_nontemporal_store(pk4(S), ad); S = S * d + st; }
; }
	v_mul_f32_e32 v96, 0x3fb8aa3b, v96
	v_mul_f32_e32 v97, 0x3fb8aa3b, v97
	v_mul_f32_e32 v98, 0x3fb8aa3b, v98
	v_mul_f32_e32 v99, 0x3fb8aa3b, v99
	v_mul_f32_e32 v100, 0x3fb8aa3b, v100
	v_mul_f32_e32 v101, 0x3fb8aa3b, v101
	v_mul_f32_e32 v102, 0x3fb8aa3b, v102
	v_mul_f32_e32 v103, 0x3fb8aa3b, v103
	v_mul_f32_e32 v104, 0x3fb8aa3b, v104
	v_mul_f32_e32 v105, 0x3fb8aa3b, v105
	v_mul_f32_e32 v106, 0x3fb8aa3b, v106
	v_mul_f32_e32 v107, 0x3fb8aa3b, v107
	v_mul_f32_e32 v108, 0x3fb8aa3b, v108
	v_mul_f32_e32 v109, 0x3fb8aa3b, v109
	v_mul_f32_e32 v110, 0x3fb8aa3b, v110
	v_mul_f32_e32 v111, 0x3fb8aa3b, v111
	v_exp_f32_e32 v96, v96
	v_exp_f32_e32 v97, v97
	v_exp_f32_e32 v98, v98
	v_exp_f32_e32 v99, v99
	v_exp_f32_e32 v100, v100
	v_exp_f32_e32 v101, v101
	v_exp_f32_e32 v102, v102
	v_exp_f32_e32 v103, v103
	v_exp_f32_e32 v104, v104
	v_exp_f32_e32 v105, v105
	v_exp_f32_e32 v106, v106
	v_exp_f32_e32 v107, v107
	v_exp_f32_e32 v108, v108
	v_exp_f32_e32 v109, v109
	v_exp_f32_e32 v110, v110
	v_exp_f32_e32 v111, v111
	s_nop 0
	v_cvt_pk_bf16_f32 v8, v4, v5
	v_cvt_pk_bf16_f32 v9, v6, v7
	global_store_dwordx2 v1, v[8:9], s[12:13] nt
	s_add_u32 s12, s12, 0x40000
	s_addc_u32 s13, s13, 0
	v_lshlrev_b32_e32 v10, 16, v64
	v_and_b32_e32 v11, 0xffff0000, v64
	v_lshlrev_b32_e32 v12, 16, v65
	v_and_b32_e32 v13, 0xffff0000, v65
	v_fma_f32 v4, v4, v96, v10
	v_fma_f32 v5, v5, v96, v11
	v_fma_f32 v6, v6, v96, v12
	v_fma_f32 v7, v7, v96, v13
	v_cvt_pk_bf16_f32 v14, v4, v5
	v_cvt_pk_bf16_f32 v15, v6, v7
	global_store_dwordx2 v1, v[14:15], s[12:13] nt
	s_add_u32 s12, s12, 0x40000
	s_addc_u32 s13, s13, 0
	v_lshlrev_b32_e32 v10, 16, v66
	v_and_b32_e32 v11, 0xffff0000, v66
	v_lshlrev_b32_e32 v12, 16, v67
	v_and_b32_e32 v13, 0xffff0000, v67
	v_fma_f32 v4, v4, v97, v10
	v_fma_f32 v5, v5, v97, v11
	v_fma_f32 v6, v6, v97, v12
	v_fma_f32 v7, v7, v97, v13
	v_cvt_pk_bf16_f32 v8, v4, v5
	v_cvt_pk_bf16_f32 v9, v6, v7
	global_store_dwordx2 v1, v[8:9], s[12:13] nt
	s_add_u32 s12, s12, 0x40000
	s_addc_u32 s13, s13, 0
	v_lshlrev_b32_e32 v10, 16, v68
	v_and_b32_e32 v11, 0xffff0000, v68
	v_lshlrev_b32_e32 v12, 16, v69
	v_and_b32_e32 v13, 0xffff0000, v69
	v_fma_f32 v4, v4, v98, v10
	v_fma_f32 v5, v5, v98, v11
	v_fma_f32 v6, v6, v98, v12
	v_fma_f32 v7, v7, v98, v13
	v_cvt_pk_bf16_f32 v14, v4, v5
	v_cvt_pk_bf16_f32 v15, v6, v7
	global_store_dwordx2 v1, v[14:15], s[12:13] nt
	s_add_u32 s12, s12, 0x40000
	s_addc_u32 s13, s13, 0
	v_lshlrev_b32_e32 v10, 16, v70
	v_and_b32_e32 v11, 0xffff0000, v70
	v_lshlrev_b32_e32 v12, 16, v71
	v_and_b32_e32 v13, 0xffff0000, v71
	v_fma_f32 v4, v4, v99, v10
	v_fma_f32 v5, v5, v99, v11
	v_fma_f32 v6, v6, v99, v12
	v_fma_f32 v7, v7, v99, v13
	v_cvt_pk_bf16_f32 v8, v4, v5
	v_cvt_pk_bf16_f32 v9, v6, v7
	global_store_dwordx2 v1, v[8:9], s[12:13] nt
	s_add_u32 s12, s12, 0x40000
	s_addc_u32 s13, s13, 0
	v_lshlrev_b32_e32 v10, 16, v72
	v_and_b32_e32 v11, 0xffff0000, v72
	v_lshlrev_b32_e32 v12, 16, v73
	v_and_b32_e32 v13, 0xffff0000, v73
	v_fma_f32 v4, v4, v100, v10
	v_fma_f32 v5, v5, v100, v11
	v_fma_f32 v6, v6, v100, v12
	v_fma_f32 v7, v7, v100, v13
	v_cvt_pk_bf16_f32 v14, v4, v5
	v_cvt_pk_bf16_f32 v15, v6, v7
	global_store_dwordx2 v1, v[14:15], s[12:13] nt
	s_add_u32 s12, s12, 0x40000
	s_addc_u32 s13, s13, 0
	v_lshlrev_b32_e32 v10, 16, v74
	v_and_b32_e32 v11, 0xffff0000, v74
	v_lshlrev_b32_e32 v12, 16, v75
	v_and_b32_e32 v13, 0xffff0000, v75
	v_fma_f32 v4, v4, v101, v10
	v_fma_f32 v5, v5, v101, v11
	v_fma_f32 v6, v6, v101, v12
	v_fma_f32 v7, v7, v101, v13
	v_cvt_pk_bf16_f32 v8, v4, v5
	v_cvt_pk_bf16_f32 v9, v6, v7
	global_store_dwordx2 v1, v[8:9], s[12:13] nt
	s_add_u32 s12, s12, 0x40000
	s_addc_u32 s13, s13, 0
	v_lshlrev_b32_e32 v10, 16, v76
	v_and_b32_e32 v11, 0xffff0000, v76
	v_lshlrev_b32_e32 v12, 16, v77
	v_and_b32_e32 v13, 0xffff0000, v77
	v_fma_f32 v4, v4, v102, v10
	v_fma_f32 v5, v5, v102, v11
	v_fma_f32 v6, v6, v102, v12
	v_fma_f32 v7, v7, v102, v13
	v_cvt_pk_bf16_f32 v14, v4, v5
	v_cvt_pk_bf16_f32 v15, v6, v7
	global_store_dwordx2 v1, v[14:15], s[12:13] nt
	s_add_u32 s12, s12, 0x40000
	s_addc_u32 s13, s13, 0
	v_lshlrev_b32_e32 v10, 16, v78
	v_and_b32_e32 v11, 0xffff0000, v78
	v_lshlrev_b32_e32 v12, 16, v79
	v_and_b32_e32 v13, 0xffff0000, v79
	v_fma_f32 v4, v4, v103, v10
	v_fma_f32 v5, v5, v103, v11
	v_fma_f32 v6, v6, v103, v12
	v_fma_f32 v7, v7, v103, v13
	v_cvt_pk_bf16_f32 v8, v4, v5
	v_cvt_pk_bf16_f32 v9, v6, v7
	global_store_dwordx2 v1, v[8:9], s[12:13] nt
	s_add_u32 s12, s12, 0x40000
	s_addc_u32 s13, s13, 0
	v_lshlrev_b32_e32 v10, 16, v80
	v_and_b32_e32 v11, 0xffff0000, v80
	v_lshlrev_b32_e32 v12, 16, v81
	v_and_b32_e32 v13, 0xffff0000, v81
	v_fma_f32 v4, v4, v104, v10
	v_fma_f32 v5, v5, v104, v11
	v_fma_f32 v6, v6, v104, v12
	v_fma_f32 v7, v7, v104, v13
	v_cvt_pk_bf16_f32 v14, v4, v5
	v_cvt_pk_bf16_f32 v15, v6, v7
	global_store_dwordx2 v1, v[14:15], s[12:13] nt
	s_add_u32 s12, s12, 0x40000
	s_addc_u32 s13, s13, 0
	v_lshlrev_b32_e32 v10, 16, v82
	v_and_b32_e32 v11, 0xffff0000, v82
	v_lshlrev_b32_e32 v12, 16, v83
	v_and_b32_e32 v13, 0xffff0000, v83
	v_fma_f32 v4, v4, v105, v10
	v_fma_f32 v5, v5, v105, v11
	v_fma_f32 v6, v6, v105, v12
	v_fma_f32 v7, v7, v105, v13
	v_cvt_pk_bf16_f32 v8, v4, v5
	v_cvt_pk_bf16_f32 v9, v6, v7
	global_store_dwordx2 v1, v[8:9], s[12:13] nt
	s_add_u32 s12, s12, 0x40000
	s_addc_u32 s13, s13, 0
	v_lshlrev_b32_e32 v10, 16, v84
	v_and_b32_e32 v11, 0xffff0000, v84
	v_lshlrev_b32_e32 v12, 16, v85
	v_and_b32_e32 v13, 0xffff0000, v85
	v_fma_f32 v4, v4, v106, v10
	v_fma_f32 v5, v5, v106, v11
	v_fma_f32 v6, v6, v106, v12
	v_fma_f32 v7, v7, v106, v13
	v_cvt_pk_bf16_f32 v14, v4, v5
	v_cvt_pk_bf16_f32 v15, v6, v7
	global_store_dwordx2 v1, v[14:15], s[12:13] nt
; __device__ __forceinline__ u32x2 pk4(f32x4 v) { u32x2 r; r.x = pk2(v[0], v[1]); r.y = pk2(v[2], v[3]); return r; }
; __device__ __forceinline__ f32x4 up4(u32x2 u) { return (f32x4){lo16(u.x), hi16(u.x), lo16(u.y), hi16(u.y)}; }
; __device__ void scan_ssd(const Ctx& c, int idx) {
;     ...
;     for (int ck = 0; ck < NCH; ++ck) { u32x2* ad = (u32x2*)(sSt + (size_t)ck * 131072 + e4);
;         const f32x4 st = up4(__builtin_nontemporal_load(ad)); const float d = __expf(sAcs[(size_t)(ck * 16 + h) * 64 + 63]);
;         __builtin_nontemporal_store(pk4(S), ad); S = S * d + st; }
	s_add_u32 s12, s12, 0x40000
	s_addc_u32 s13, s13, 0
	v_lshlrev_b32_e32 v10, 16, v86
	v_and_b32_e32 v11, 0xffff0000, v86
	v_lshlrev_b32_e32 v12, 16, v87
	v_and_b32_e32 v13, 0xffff0000, v87
	v_fma_f32 v4, v4, v107, v10
	v_fma_f32 v5, v5, v107, v11
	v_fma_f32 v6, v6, v107, v12
	v_fma_f32 v7, v7, v107, v13
	v_cvt_pk_bf16_f32 v8, v4, v5
	v_cvt_pk_bf16_f32 v9, v6, v7
	global_store_dwordx2 v1, v[8:9], s[12:13] nt
	s_add_u32 s12, s12, 0x40000
	s_addc_u32 s13, s13, 0
	v_lshlrev_b32_e32 v10, 16, v88
	v_and_b32_e32 v11, 0xffff0000, v88
	v_lshlrev_b32_e32 v12, 16, v89
	v_and_b32_e32 v13, 0xffff0000, v89
	v_fma_f32 v4, v4, v108, v10
	v_fma_f32 v5, v5, v108, v11
	v_fma_f32 v6, v6, v108, v12
	v_fma_f32 v7, v7, v108, v13
	v_cvt_pk_bf16_f32 v14, v4, v5
	v_cvt_pk_bf16_f32 v15, v6, v7
	global_store_dwordx2 v1, v[14:15], s[12:13] nt
	s_add_u32 s12, s12, 0x40000
	s_addc_u32 s13, s13, 0
	v_lshlrev_b32_e32 v10, 16, v90
	v_and_b32_e32 v11, 0xffff0000, v90
	v_lshlrev_b32_e32 v12, 16, v91
	v_and_b32_e32 v13, 0xffff0000, v91
	v_fma_f32 v4, v4, v109, v10
	v_fma_f32 v5, v5, v109, v11
	v_fma_f32 v6, v6, v109, v12
	v_fma_f32 v7, v7, v109, v13
	v_cvt_pk_bf16_f32 v8, v4, v5
	v_cvt_pk_bf16_f32 v9, v6, v7
	global_store_dwordx2 v1, v[8:9], s[12:13] nt
	s_add_u32 s12, s12, 0x40000
	s_addc_u32 s13, s13, 0
	v_lshlrev_b32_e32 v10, 16, v92
	v_and_b32_e32 v11, 0xffff0000, v92
	v_lshlrev_b32_e32 v12, 16, v93
	v_and_b32_e32 v13, 0xffff0000, v93
	v_fma_f32 v4, v4, v110, v10
	v_fma_f32 v5, v5, v110, v11
	v_fma_f32 v6, v6, v110, v12
	v_fma_f32 v7, v7, v110, v13
	v_cvt_pk_bf16_f32 v14, v4, v5
	v_cvt_pk_bf16_f32 v15, v6, v7
	global_store_dwordx2 v1, v[14:15], s[12:13] nt
	s_add_u32 s12, s12, 0x40000
	s_addc_u32 s13, s13, 0
	v_lshlrev_b32_e32 v10, 16, v94
	v_and_b32_e32 v11, 0xffff0000, v94
	v_lshlrev_b32_e32 v12, 16, v95
	v_and_b32_e32 v13, 0xffff0000, v95
	v_fma_f32 v4, v4, v111, v10
	v_fma_f32 v5, v5, v111, v11
	v_fma_f32 v6, v6, v111, v12
	v_fma_f32 v7, v7, v111, v13
	global_load_dwordx2 v[64:65], v1, s[6:7] nt
	global_load_dword v96, v2, s[8:9]
	s_add_u32 s8, s8, 0x1000
	s_addc_u32 s9, s9, 0
	s_add_u32 s6, s6, 0x40000
	s_addc_u32 s7, s7, 0
	global_load_dwordx2 v[66:67], v1, s[6:7] nt
	global_load_dword v97, v2, s[8:9]
	s_add_u32 s8, s8, 0x1000
	s_addc_u32 s9, s9, 0
	s_add_u32 s6, s6, 0x40000
	s_addc_u32 s7, s7, 0
	global_load_dwordx2 v[68:69], v1, s[6:7] nt
	global_load_dword v98, v2, s[8:9]
	s_add_u32 s8, s8, 0x1000
	s_addc_u32 s9, s9, 0
	s_add_u32 s6, s6, 0x40000
	s_addc_u32 s7, s7, 0
	global_load_dwordx2 v[70:71], v1, s[6:7] nt
	global_load_dword v99, v2, s[8:9]
	s_add_u32 s8, s8, 0x1000
	s_addc_u32 s9, s9, 0
	s_add_u32 s6, s6, 0x40000
	s_addc_u32 s7, s7, 0
	global_load_dwordx2 v[72:73], v1, s[6:7] nt
	global_load_dword v100, v2, s[8:9]
	s_add_u32 s8, s8, 0x1000
	s_addc_u32 s9, s9, 0
	s_add_u32 s6, s6, 0x40000
	s_addc_u32 s7, s7, 0
	global_load_dwordx2 v[74:75], v1, s[6:7] nt
	global_load_dword v101, v2, s[8:9]
	s_add_u32 s8, s8, 0x1000
	s_addc_u32 s9, s9, 0
	s_add_u32 s6, s6, 0x40000
	s_addc_u32 s7, s7, 0
	global_load_dwordx2 v[76:77], v1, s[6:7] nt
	global_load_dword v102, v2, s[8:9]
	s_add_u32 s8, s8, 0x1000
	s_addc_u32 s9, s9, 0
	s_add_u32 s6, s6, 0x40000
	s_addc_u32 s7, s7, 0
	global_load_dwordx2 v[78:79], v1, s[6:7] nt
	global_load_dword v103, v2, s[8:9]
	s_add_u32 s8, s8, 0x1000
	s_addc_u32 s9, s9, 0
	s_add_u32 s6, s6, 0x40000
	s_addc_u32 s7, s7, 0
	global_load_dwordx2 v[80:81], v1, s[6:7] nt
	global_load_dword v104, v2, s[8:9]
	s_add_u32 s8, s8, 0x1000
	s_addc_u32 s9, s9, 0
	s_add_u32 s6, s6, 0x40000
	s_addc_u32 s7, s7, 0
	global_load_dwordx2 v[82:83], v1, s[6:7] nt
	global_load_dword v105, v2, s[8:9]
	s_add_u32 s8, s8, 0x1000
	s_addc_u32 s9, s9, 0
	s_add_u32 s6, s6, 0x40000
	s_addc_u32 s7, s7, 0
	global_load_dwordx2 v[84:85], v1, s[6:7] nt
	global_load_dword v106, v2, s[8:9]
	s_add_u32 s8, s8, 0x1000
	s_addc_u32 s9, s9, 0
	s_add_u32 s6, s6, 0x40000
	s_addc_u32 s7, s7, 0
	global_load_dwordx2 v[86:87], v1, s[6:7] nt
	global_load_dword v107, v2, s[8:9]
	s_add_u32 s8, s8, 0x1000
	s_addc_u32 s9, s9, 0
	s_add_u32 s6, s6, 0x40000
	s_addc_u32 s7, s7, 0
	global_load_dwordx2 v[88:89], v1, s[6:7] nt
	global_load_dword v108, v2, s[8:9]
	s_add_u32 s8, s8, 0x1000
	s_addc_u32 s9, s9, 0
	s_add_u32 s6, s6, 0x40000
	s_addc_u32 s7, s7, 0
	global_load_dwordx2 v[90:91], v1, s[6:7] nt
	global_load_dword v109, v2, s[8:9]
	s_add_u32 s8, s8, 0x1000
	s_addc_u32 s9, s9, 0
	s_add_u32 s6, s6, 0x40000
	s_addc_u32 s7, s7, 0
	global_load_dwordx2 v[92:93], v1, s[6:7] nt
	global_load_dword v110, v2, s[8:9]
	s_add_u32 s8, s8, 0x1000
	s_addc_u32 s9, s9, 0
	s_add_u32 s6, s6, 0x40000
	s_addc_u32 s7, s7, 0
	global_load_dwordx2 v[94:95], v1, s[6:7] nt
	global_load_dword v111, v2, s[8:9]
	s_add_u32 s8, s8, 0x1000
	s_addc_u32 s9, s9, 0
	s_add_u32 s6, s6, 0x40000
	s_addc_u32 s7, s7, 0
	s_waitcnt vmcnt(48)
; __device__ __forceinline__ u32x2 pk4(f32x4 v) { u32x2 r; r.x = pk2(v[0], v[1]); r.y = pk2(v[2], v[3]); return r; }
; __device__ __forceinline__ f32x4 up4(u32x2 u) { return (f32x4){lo16(u.x), hi16(u.x), lo16(u.y), hi16(u.y)}; }
; __device__ void scan_ssd(const Ctx& c, int idx) {
;     ...
;     for (int ck = 0; ck < NCH; ++ck) { u32x2* ad = (u32x2*)(sSt + (size_t)ck * 131072 + e4);
;         const f32x4 st = up4(__builtin_nontemporal_load(ad)); const float d = __expf(sAcs[(size_t)(ck * 16 + h) * 64 + 63]);
;         __builtin_nontemporal_store(pk4(S), ad); S = S * d + st; }
	v_mul_f32_e32 v48, 0x3fb8aa3b, v48
	v_mul_f32_e32 v49, 0x3fb8aa3b, v49
	v_mul_f32_e32 v50, 0x3fb8aa3b, v50
	v_mul_f32_e32 v51, 0x3fb8aa3b, v51
	v_mul_f32_e32 v52, 0x3fb8aa3b, v52
	v_mul_f32_e32 v53, 0x3fb8aa3b, v53
	v_mul_f32_e32 v54, 0x3fb8aa3b, v54
	v_mul_f32_e32 v55, 0x3fb8aa3b, v55
	v_mul_f32_e32 v56, 0x3fb8aa3b, v56
	v_mul_f32_e32 v57, 0x3fb8aa3b, v57
	v_mul_f32_e32 v58, 0x3fb8aa3b, v58
	v_mul_f32_e32 v59, 0x3fb8aa3b, v59
	v_mul_f32_e32 v60, 0x3fb8aa3b, v60
	v_mul_f32_e32 v61, 0x3fb8aa3b, v61
	v_mul_f32_e32 v62, 0x3fb8aa3b, v62
	v_mul_f32_e32 v63, 0x3fb8aa3b, v63
	v_exp_f32_e32 v48, v48
	v_exp_f32_e32 v49, v49
	v_exp_f32_e32 v50, v50
	v_exp_f32_e32 v51, v51
	v_exp_f32_e32 v52, v52
	v_exp_f32_e32 v53, v53
	v_exp_f32_e32 v54, v54
	v_exp_f32_e32 v55, v55
	v_exp_f32_e32 v56, v56
	v_exp_f32_e32 v57, v57
	v_exp_f32_e32 v58, v58
	v_exp_f32_e32 v59, v59
	v_exp_f32_e32 v60, v60
	v_exp_f32_e32 v61, v61
	v_exp_f32_e32 v62, v62
	v_exp_f32_e32 v63, v63
	s_nop 0
	v_cvt_pk_bf16_f32 v8, v4, v5
	v_cvt_pk_bf16_f32 v9, v6, v7
	global_store_dwordx2 v1, v[8:9], s[12:13] nt
	s_add_u32 s12, s12, 0x40000
	s_addc_u32 s13, s13, 0
	v_lshlrev_b32_e32 v10, 16, v16
	v_and_b32_e32 v11, 0xffff0000, v16
	v_lshlrev_b32_e32 v12, 16, v17
	v_and_b32_e32 v13, 0xffff0000, v17
	v_fma_f32 v4, v4, v48, v10
	v_fma_f32 v5, v5, v48, v11
	v_fma_f32 v6, v6, v48, v12
	v_fma_f32 v7, v7, v48, v13
	v_cvt_pk_bf16_f32 v14, v4, v5
	v_cvt_pk_bf16_f32 v15, v6, v7
	global_store_dwordx2 v1, v[14:15], s[12:13] nt
	s_add_u32 s12, s12, 0x40000
	s_addc_u32 s13, s13, 0
	v_lshlrev_b32_e32 v10, 16, v18
	v_and_b32_e32 v11, 0xffff0000, v18
	v_lshlrev_b32_e32 v12, 16, v19
	v_and_b32_e32 v13, 0xffff0000, v19
	v_fma_f32 v4, v4, v49, v10
	v_fma_f32 v5, v5, v49, v11
	v_fma_f32 v6, v6, v49, v12
	v_fma_f32 v7, v7, v49, v13
	v_cvt_pk_bf16_f32 v8, v4, v5
	v_cvt_pk_bf16_f32 v9, v6, v7
	global_store_dwordx2 v1, v[8:9], s[12:13] nt
	s_add_u32 s12, s12, 0x40000
	s_addc_u32 s13, s13, 0
	v_lshlrev_b32_e32 v10, 16, v20
	v_and_b32_e32 v11, 0xffff0000, v20
	v_lshlrev_b32_e32 v12, 16, v21
	v_and_b32_e32 v13, 0xffff0000, v21
	v_fma_f32 v4, v4, v50, v10
	v_fma_f32 v5, v5, v50, v11
	v_fma_f32 v6, v6, v50, v12
	v_fma_f32 v7, v7, v50, v13
	v_cvt_pk_bf16_f32 v14, v4, v5
	v_cvt_pk_bf16_f32 v15, v6, v7
	global_store_dwordx2 v1, v[14:15], s[12:13] nt
	s_add_u32 s12, s12, 0x40000
	s_addc_u32 s13, s13, 0
	v_lshlrev_b32_e32 v10, 16, v22
	v_and_b32_e32 v11, 0xffff0000, v22
	v_lshlrev_b32_e32 v12, 16, v23
	v_and_b32_e32 v13, 0xffff0000, v23
	v_fma_f32 v4, v4, v51, v10
	v_fma_f32 v5, v5, v51, v11
	v_fma_f32 v6, v6, v51, v12
	v_fma_f32 v7, v7, v51, v13
	v_cvt_pk_bf16_f32 v8, v4, v5
	v_cvt_pk_bf16_f32 v9, v6, v7
	global_store_dwordx2 v1, v[8:9], s[12:13] nt
	s_add_u32 s12, s12, 0x40000
	s_addc_u32 s13, s13, 0
	v_lshlrev_b32_e32 v10, 16, v24
	v_and_b32_e32 v11, 0xffff0000, v24
	v_lshlrev_b32_e32 v12, 16, v25
	v_and_b32_e32 v13, 0xffff0000, v25
	v_fma_f32 v4, v4, v52, v10
	v_fma_f32 v5, v5, v52, v11
	v_fma_f32 v6, v6, v52, v12
	v_fma_f32 v7, v7, v52, v13
	v_cvt_pk_bf16_f32 v14, v4, v5
	v_cvt_pk_bf16_f32 v15, v6, v7
	global_store_dwordx2 v1, v[14:15], s[12:13] nt
	s_add_u32 s12, s12, 0x40000
	s_addc_u32 s13, s13, 0
	v_lshlrev_b32_e32 v10, 16, v26
	v_and_b32_e32 v11, 0xffff0000, v26
	v_lshlrev_b32_e32 v12, 16, v27
	v_and_b32_e32 v13, 0xffff0000, v27
	v_fma_f32 v4, v4, v53, v10
	v_fma_f32 v5, v5, v53, v11
	v_fma_f32 v6, v6, v53, v12
	v_fma_f32 v7, v7, v53, v13
	v_cvt_pk_bf16_f32 v8, v4, v5
	v_cvt_pk_bf16_f32 v9, v6, v7
	global_store_dwordx2 v1, v[8:9], s[12:13] nt
	s_add_u32 s12, s12, 0x40000
	s_addc_u32 s13, s13, 0
	v_lshlrev_b32_e32 v10, 16, v28
	v_and_b32_e32 v11, 0xffff0000, v28
	v_lshlrev_b32_e32 v12, 16, v29
	v_and_b32_e32 v13, 0xffff0000, v29
	v_fma_f32 v4, v4, v54, v10
	v_fma_f32 v5, v5, v54, v11
	v_fma_f32 v6, v6, v54, v12
	v_fma_f32 v7, v7, v54, v13
	v_cvt_pk_bf16_f32 v14, v4, v5
	v_cvt_pk_bf16_f32 v15, v6, v7
	global_store_dwordx2 v1, v[14:15], s[12:13] nt
	s_add_u32 s12, s12, 0x40000
	s_addc_u32 s13, s13, 0
	v_lshlrev_b32_e32 v10, 16, v30
	v_and_b32_e32 v11, 0xffff0000, v30
	v_lshlrev_b32_e32 v12, 16, v31
	v_and_b32_e32 v13, 0xffff0000, v31
	v_fma_f32 v4, v4, v55, v10
	v_fma_f32 v5, v5, v55, v11
	v_fma_f32 v6, v6, v55, v12
	v_fma_f32 v7, v7, v55, v13
	v_cvt_pk_bf16_f32 v8, v4, v5
	v_cvt_pk_bf16_f32 v9, v6, v7
	global_store_dwordx2 v1, v[8:9], s[12:13] nt
	s_add_u32 s12, s12, 0x40000
	s_addc_u32 s13, s13, 0
	v_lshlrev_b32_e32 v10, 16, v32
	v_and_b32_e32 v11, 0xffff0000, v32
	v_lshlrev_b32_e32 v12, 16, v33
	v_and_b32_e32 v13, 0xffff0000, v33
	v_fma_f32 v4, v4, v56, v10
	v_fma_f32 v5, v5, v56, v11
	v_fma_f32 v6, v6, v56, v12
	v_fma_f32 v7, v7, v56, v13
	v_cvt_pk_bf16_f32 v14, v4, v5
	v_cvt_pk_bf16_f32 v15, v6, v7
	global_store_dwordx2 v1, v[14:15], s[12:13] nt
	s_add_u32 s12, s12, 0x40000
	s_addc_u32 s13, s13, 0
	v_lshlrev_b32_e32 v10, 16, v34
	v_and_b32_e32 v11, 0xffff0000, v34
	v_lshlrev_b32_e32 v12, 16, v35
	v_and_b32_e32 v13, 0xffff0000, v35
	v_fma_f32 v4, v4, v57, v10
	v_fma_f32 v5, v5, v57, v11
	v_fma_f32 v6, v6, v57, v12
	v_fma_f32 v7, v7, v57, v13
	v_cvt_pk_bf16_f32 v8, v4, v5
	v_cvt_pk_bf16_f32 v9, v6, v7
	global_store_dwordx2 v1, v[8:9], s[12:13] nt
	s_add_u32 s12, s12, 0x40000
	s_addc_u32 s13, s13, 0
	v_lshlrev_b32_e32 v10, 16, v36
	v_and_b32_e32 v11, 0xffff0000, v36
	v_lshlrev_b32_e32 v12, 16, v37
	v_and_b32_e32 v13, 0xffff0000, v37
	v_fma_f32 v4, v4, v58, v10
	v_fma_f32 v5, v5, v58, v11
	v_fma_f32 v6, v6, v58, v12
	v_fma_f32 v7, v7, v58, v13
	v_cvt_pk_bf16_f32 v14, v4, v5
	v_cvt_pk_bf16_f32 v15, v6, v7
	global_store_dwordx2 v1, v[14:15], s[12:13] nt
	s_add_u32 s12, s12, 0x40000
	s_addc_u32 s13, s13, 0
; __device__ __forceinline__ u32x2 pk4(f32x4 v) { u32x2 r; r.x = pk2(v[0], v[1]); r.y = pk2(v[2], v[3]); return r; }
; __device__ __forceinline__ f32x4 up4(u32x2 u) { return (f32x4){lo16(u.x), hi16(u.x), lo16(u.y), hi16(u.y)}; }
; __device__ void scan_ssd(const Ctx& c, int idx) {
;     ...
;     for (int ck = 0; ck < NCH; ++ck) { u32x2* ad = (u32x2*)(sSt + (size_t)ck * 131072 + e4);
;         const f32x4 st = up4(__builtin_nontemporal_load(ad)); const float d = __expf(sAcs[(size_t)(ck * 16 + h) * 64 + 63]);
;         __builtin_nontemporal_store(pk4(S), ad); S = S * d + st; }
	v_lshlrev_b32_e32 v10, 16, v38
	v_and_b32_e32 v11, 0xffff0000, v38
	v_lshlrev_b32_e32 v12, 16, v39
	v_and_b32_e32 v13, 0xffff0000, v39
	v_fma_f32 v4, v4, v59, v10
	v_fma_f32 v5, v5, v59, v11
	v_fma_f32 v6, v6, v59, v12
	v_fma_f32 v7, v7, v59, v13
	v_cvt_pk_bf16_f32 v8, v4, v5
	v_cvt_pk_bf16_f32 v9, v6, v7
	global_store_dwordx2 v1, v[8:9], s[12:13] nt
	s_add_u32 s12, s12, 0x40000
	s_addc_u32 s13, s13, 0
	v_lshlrev_b32_e32 v10, 16, v40
	v_and_b32_e32 v11, 0xffff0000, v40
	v_lshlrev_b32_e32 v12, 16, v41
	v_and_b32_e32 v13, 0xffff0000, v41
	v_fma_f32 v4, v4, v60, v10
	v_fma_f32 v5, v5, v60, v11
	v_fma_f32 v6, v6, v60, v12
	v_fma_f32 v7, v7, v60, v13
	v_cvt_pk_bf16_f32 v14, v4, v5
	v_cvt_pk_bf16_f32 v15, v6, v7
	global_store_dwordx2 v1, v[14:15], s[12:13] nt
	s_add_u32 s12, s12, 0x40000
	s_addc_u32 s13, s13, 0
	v_lshlrev_b32_e32 v10, 16, v42
	v_and_b32_e32 v11, 0xffff0000, v42
	v_lshlrev_b32_e32 v12, 16, v43
	v_and_b32_e32 v13, 0xffff0000, v43
	v_fma_f32 v4, v4, v61, v10
	v_fma_f32 v5, v5, v61, v11
	v_fma_f32 v6, v6, v61, v12
	v_fma_f32 v7, v7, v61, v13
	v_cvt_pk_bf16_f32 v8, v4, v5
	v_cvt_pk_bf16_f32 v9, v6, v7
	global_store_dwordx2 v1, v[8:9], s[12:13] nt
	s_add_u32 s12, s12, 0x40000
	s_addc_u32 s13, s13, 0
	v_lshlrev_b32_e32 v10, 16, v44
	v_and_b32_e32 v11, 0xffff0000, v44
	v_lshlrev_b32_e32 v12, 16, v45
	v_and_b32_e32 v13, 0xffff0000, v45
	v_fma_f32 v4, v4, v62, v10
	v_fma_f32 v5, v5, v62, v11
	v_fma_f32 v6, v6, v62, v12
	v_fma_f32 v7, v7, v62, v13
	v_cvt_pk_bf16_f32 v14, v4, v5
	v_cvt_pk_bf16_f32 v15, v6, v7
	global_store_dwordx2 v1, v[14:15], s[12:13] nt
	s_add_u32 s12, s12, 0x40000
	s_addc_u32 s13, s13, 0
	v_lshlrev_b32_e32 v10, 16, v46
	v_and_b32_e32 v11, 0xffff0000, v46
	v_lshlrev_b32_e32 v12, 16, v47
	v_and_b32_e32 v13, 0xffff0000, v47
	v_fma_f32 v4, v4, v63, v10
	v_fma_f32 v5, v5, v63, v11
	v_fma_f32 v6, v6, v63, v12
	v_fma_f32 v7, v7, v63, v13
	global_load_dwordx2 v[16:17], v1, s[6:7] nt
	global_load_dword v48, v2, s[8:9]
	s_add_u32 s8, s8, 0x1000
	s_addc_u32 s9, s9, 0
	s_add_u32 s6, s6, 0x40000
	s_addc_u32 s7, s7, 0
	global_load_dwordx2 v[18:19], v1, s[6:7] nt
	global_load_dword v49, v2, s[8:9]
	s_add_u32 s8, s8, 0x1000
	s_addc_u32 s9, s9, 0
	s_add_u32 s6, s6, 0x40000
	s_addc_u32 s7, s7, 0
	global_load_dwordx2 v[20:21], v1, s[6:7] nt
	global_load_dword v50, v2, s[8:9]
	s_add_u32 s8, s8, 0x1000
	s_addc_u32 s9, s9, 0
	s_add_u32 s6, s6, 0x40000
	s_addc_u32 s7, s7, 0
	global_load_dwordx2 v[22:23], v1, s[6:7] nt
	global_load_dword v51, v2, s[8:9]
	s_add_u32 s8, s8, 0x1000
	s_addc_u32 s9, s9, 0
	s_add_u32 s6, s6, 0x40000
	s_addc_u32 s7, s7, 0
	global_load_dwordx2 v[24:25], v1, s[6:7] nt
	global_load_dword v52, v2, s[8:9]
	s_add_u32 s8, s8, 0x1000
	s_addc_u32 s9, s9, 0
	s_add_u32 s6, s6, 0x40000
	s_addc_u32 s7, s7, 0
	global_load_dwordx2 v[26:27], v1, s[6:7] nt
	global_load_dword v53, v2, s[8:9]
	s_add_u32 s8, s8, 0x1000
	s_addc_u32 s9, s9, 0
	s_add_u32 s6, s6, 0x40000
	s_addc_u32 s7, s7, 0
	global_load_dwordx2 v[28:29], v1, s[6:7] nt
	global_load_dword v54, v2, s[8:9]
	s_add_u32 s8, s8, 0x1000
	s_addc_u32 s9, s9, 0
	s_add_u32 s6, s6, 0x40000
	s_addc_u32 s7, s7, 0
	global_load_dwordx2 v[30:31], v1, s[6:7] nt
	global_load_dword v55, v2, s[8:9]
	s_add_u32 s8, s8, 0x1000
	s_addc_u32 s9, s9, 0
	s_add_u32 s6, s6, 0x40000
	s_addc_u32 s7, s7, 0
	global_load_dwordx2 v[32:33], v1, s[6:7] nt
	global_load_dword v56, v2, s[8:9]
	s_add_u32 s8, s8, 0x1000
	s_addc_u32 s9, s9, 0
	s_add_u32 s6, s6, 0x40000
	s_addc_u32 s7, s7, 0
	global_load_dwordx2 v[34:35], v1, s[6:7] nt
	global_load_dword v57, v2, s[8:9]
	s_add_u32 s8, s8, 0x1000
	s_addc_u32 s9, s9, 0
	s_add_u32 s6, s6, 0x40000
	s_addc_u32 s7, s7, 0
	global_load_dwordx2 v[36:37], v1, s[6:7] nt
	global_load_dword v58, v2, s[8:9]
	s_add_u32 s8, s8, 0x1000
	s_addc_u32 s9, s9, 0
	s_add_u32 s6, s6, 0x40000
	s_addc_u32 s7, s7, 0
	global_load_dwordx2 v[38:39], v1, s[6:7] nt
	global_load_dword v59, v2, s[8:9]
	s_add_u32 s8, s8, 0x1000
	s_addc_u32 s9, s9, 0
	s_add_u32 s6, s6, 0x40000
	s_addc_u32 s7, s7, 0
	global_load_dwordx2 v[40:41], v1, s[6:7] nt
	global_load_dword v60, v2, s[8:9]
	s_add_u32 s8, s8, 0x1000
	s_addc_u32 s9, s9, 0
	s_add_u32 s6, s6, 0x40000
	s_addc_u32 s7, s7, 0
	global_load_dwordx2 v[42:43], v1, s[6:7] nt
	global_load_dword v61, v2, s[8:9]
	s_add_u32 s8, s8, 0x1000
	s_addc_u32 s9, s9, 0
	s_add_u32 s6, s6, 0x40000
	s_addc_u32 s7, s7, 0
	global_load_dwordx2 v[44:45], v1, s[6:7] nt
	global_load_dword v62, v2, s[8:9]
	s_add_u32 s8, s8, 0x1000
	s_addc_u32 s9, s9, 0
	s_add_u32 s6, s6, 0x40000
	s_addc_u32 s7, s7, 0
	global_load_dwordx2 v[46:47], v1, s[6:7] nt
	global_load_dword v63, v2, s[8:9]
	s_add_u32 s8, s8, 0x1000
	s_addc_u32 s9, s9, 0
	s_add_u32 s6, s6, 0x40000
	s_addc_u32 s7, s7, 0
	s_waitcnt vmcnt(48)
; __device__ __forceinline__ u32x2 pk4(f32x4 v) { u32x2 r; r.x = pk2(v[0], v[1]); r.y = pk2(v[2], v[3]); return r; }
; __device__ __forceinline__ f32x4 up4(u32x2 u) { return (f32x4){lo16(u.x), hi16(u.x), lo16(u.y), hi16(u.y)}; }
; __device__ void scan_ssd(const Ctx& c, int idx) {
;     ...
;     for (int ck = 0; ck < NCH; ++ck) { u32x2* ad = (u32x2*)(sSt + (size_t)ck * 131072 + e4);
;         const f32x4 st = up4(__builtin_nontemporal_load(ad)); const float d = __expf(sAcs[(size_t)(ck * 16 + h) * 64 + 63]);
;         __builtin_nontemporal_store(pk4(S), ad); S = S * d + st; }
	v_mul_f32_e32 v96, 0x3fb8aa3b, v96
	v_mul_f32_e32 v97, 0x3fb8aa3b, v97
	v_mul_f32_e32 v98, 0x3fb8aa3b, v98
	v_mul_f32_e32 v99, 0x3fb8aa3b, v99
	v_mul_f32_e32 v100, 0x3fb8aa3b, v100
	v_mul_f32_e32 v101, 0x3fb8aa3b, v101
	v_mul_f32_e32 v102, 0x3fb8aa3b, v102
	v_mul_f32_e32 v103, 0x3fb8aa3b, v103
	v_mul_f32_e32 v104, 0x3fb8aa3b, v104
	v_mul_f32_e32 v105, 0x3fb8aa3b, v105
	v_mul_f32_e32 v106, 0x3fb8aa3b, v106
	v_mul_f32_e32 v107, 0x3fb8aa3b, v107
	v_mul_f32_e32 v108, 0x3fb8aa3b, v108
	v_mul_f32_e32 v109, 0x3fb8aa3b, v109
	v_mul_f32_e32 v110, 0x3fb8aa3b, v110
	v_mul_f32_e32 v111, 0x3fb8aa3b, v111
	v_exp_f32_e32 v96, v96
	v_exp_f32_e32 v97, v97
	v_exp_f32_e32 v98, v98
	v_exp_f32_e32 v99, v99
	v_exp_f32_e32 v100, v100
	v_exp_f32_e32 v101, v101
	v_exp_f32_e32 v102, v102
	v_exp_f32_e32 v103, v103
	v_exp_f32_e32 v104, v104
	v_exp_f32_e32 v105, v105
	v_exp_f32_e32 v106, v106
	v_exp_f32_e32 v107, v107
	v_exp_f32_e32 v108, v108
	v_exp_f32_e32 v109, v109
	v_exp_f32_e32 v110, v110
	v_exp_f32_e32 v111, v111
	s_nop 0
	v_cvt_pk_bf16_f32 v8, v4, v5
	v_cvt_pk_bf16_f32 v9, v6, v7
	global_store_dwordx2 v1, v[8:9], s[12:13] nt
	s_add_u32 s12, s12, 0x40000
	s_addc_u32 s13, s13, 0
	v_lshlrev_b32_e32 v10, 16, v64
	v_and_b32_e32 v11, 0xffff0000, v64
	v_lshlrev_b32_e32 v12, 16, v65
	v_and_b32_e32 v13, 0xffff0000, v65
	v_fma_f32 v4, v4, v96, v10
	v_fma_f32 v5, v5, v96, v11
	v_fma_f32 v6, v6, v96, v12
	v_fma_f32 v7, v7, v96, v13
	v_cvt_pk_bf16_f32 v14, v4, v5
	v_cvt_pk_bf16_f32 v15, v6, v7
	global_store_dwordx2 v1, v[14:15], s[12:13] nt
	s_add_u32 s12, s12, 0x40000
	s_addc_u32 s13, s13, 0
	v_lshlrev_b32_e32 v10, 16, v66
	v_and_b32_e32 v11, 0xffff0000, v66
	v_lshlrev_b32_e32 v12, 16, v67
	v_and_b32_e32 v13, 0xffff0000, v67
	v_fma_f32 v4, v4, v97, v10
	v_fma_f32 v5, v5, v97, v11
	v_fma_f32 v6, v6, v97, v12
	v_fma_f32 v7, v7, v97, v13
	v_cvt_pk_bf16_f32 v8, v4, v5
	v_cvt_pk_bf16_f32 v9, v6, v7
	global_store_dwordx2 v1, v[8:9], s[12:13] nt
	s_add_u32 s12, s12, 0x40000
	s_addc_u32 s13, s13, 0
	v_lshlrev_b32_e32 v10, 16, v68
	v_and_b32_e32 v11, 0xffff0000, v68
	v_lshlrev_b32_e32 v12, 16, v69
	v_and_b32_e32 v13, 0xffff0000, v69
	v_fma_f32 v4, v4, v98, v10
	v_fma_f32 v5, v5, v98, v11
	v_fma_f32 v6, v6, v98, v12
	v_fma_f32 v7, v7, v98, v13
	v_cvt_pk_bf16_f32 v14, v4, v5
	v_cvt_pk_bf16_f32 v15, v6, v7
	global_store_dwordx2 v1, v[14:15], s[12:13] nt
	s_add_u32 s12, s12, 0x40000
	s_addc_u32 s13, s13, 0
	v_lshlrev_b32_e32 v10, 16, v70
	v_and_b32_e32 v11, 0xffff0000, v70
	v_lshlrev_b32_e32 v12, 16, v71
	v_and_b32_e32 v13, 0xffff0000, v71
	v_fma_f32 v4, v4, v99, v10
	v_fma_f32 v5, v5, v99, v11
	v_fma_f32 v6, v6, v99, v12
	v_fma_f32 v7, v7, v99, v13
	v_cvt_pk_bf16_f32 v8, v4, v5
	v_cvt_pk_bf16_f32 v9, v6, v7
	global_store_dwordx2 v1, v[8:9], s[12:13] nt
	s_add_u32 s12, s12, 0x40000
	s_addc_u32 s13, s13, 0
	v_lshlrev_b32_e32 v10, 16, v72
	v_and_b32_e32 v11, 0xffff0000, v72
	v_lshlrev_b32_e32 v12, 16, v73
	v_and_b32_e32 v13, 0xffff0000, v73
	v_fma_f32 v4, v4, v100, v10
	v_fma_f32 v5, v5, v100, v11
	v_fma_f32 v6, v6, v100, v12
	v_fma_f32 v7, v7, v100, v13
	v_cvt_pk_bf16_f32 v14, v4, v5
	v_cvt_pk_bf16_f32 v15, v6, v7
	global_store_dwordx2 v1, v[14:15], s[12:13] nt
	s_add_u32 s12, s12, 0x40000
	s_addc_u32 s13, s13, 0
	v_lshlrev_b32_e32 v10, 16, v74
	v_and_b32_e32 v11, 0xffff0000, v74
	v_lshlrev_b32_e32 v12, 16, v75
	v_and_b32_e32 v13, 0xffff0000, v75
	v_fma_f32 v4, v4, v101, v10
	v_fma_f32 v5, v5, v101, v11
	v_fma_f32 v6, v6, v101, v12
	v_fma_f32 v7, v7, v101, v13
	v_cvt_pk_bf16_f32 v8, v4, v5
	v_cvt_pk_bf16_f32 v9, v6, v7
	global_store_dwordx2 v1, v[8:9], s[12:13] nt
	s_add_u32 s12, s12, 0x40000
	s_addc_u32 s13, s13, 0
	v_lshlrev_b32_e32 v10, 16, v76
	v_and_b32_e32 v11, 0xffff0000, v76
	v_lshlrev_b32_e32 v12, 16, v77
	v_and_b32_e32 v13, 0xffff0000, v77
	v_fma_f32 v4, v4, v102, v10
	v_fma_f32 v5, v5, v102, v11
	v_fma_f32 v6, v6, v102, v12
	v_fma_f32 v7, v7, v102, v13
	v_cvt_pk_bf16_f32 v14, v4, v5
	v_cvt_pk_bf16_f32 v15, v6, v7
	global_store_dwordx2 v1, v[14:15], s[12:13] nt
	s_add_u32 s12, s12, 0x40000
	s_addc_u32 s13, s13, 0
	v_lshlrev_b32_e32 v10, 16, v78
	v_and_b32_e32 v11, 0xffff0000, v78
	v_lshlrev_b32_e32 v12, 16, v79
	v_and_b32_e32 v13, 0xffff0000, v79
	v_fma_f32 v4, v4, v103, v10
	v_fma_f32 v5, v5, v103, v11
	v_fma_f32 v6, v6, v103, v12
	v_fma_f32 v7, v7, v103, v13
	v_cvt_pk_bf16_f32 v8, v4, v5
	v_cvt_pk_bf16_f32 v9, v6, v7
	global_store_dwordx2 v1, v[8:9], s[12:13] nt
	s_add_u32 s12, s12, 0x40000
	s_addc_u32 s13, s13, 0
	v_lshlrev_b32_e32 v10, 16, v80
	v_and_b32_e32 v11, 0xffff0000, v80
	v_lshlrev_b32_e32 v12, 16, v81
	v_and_b32_e32 v13, 0xffff0000, v81
	v_fma_f32 v4, v4, v104, v10
	v_fma_f32 v5, v5, v104, v11
	v_fma_f32 v6, v6, v104, v12
	v_fma_f32 v7, v7, v104, v13
	v_cvt_pk_bf16_f32 v14, v4, v5
	v_cvt_pk_bf16_f32 v15, v6, v7
	global_store_dwordx2 v1, v[14:15], s[12:13] nt
	s_add_u32 s12, s12, 0x40000
	s_addc_u32 s13, s13, 0
	v_lshlrev_b32_e32 v10, 16, v82
	v_and_b32_e32 v11, 0xffff0000, v82
	v_lshlrev_b32_e32 v12, 16, v83
	v_and_b32_e32 v13, 0xffff0000, v83
	v_fma_f32 v4, v4, v105, v10
	v_fma_f32 v5, v5, v105, v11
	v_fma_f32 v6, v6, v105, v12
	v_fma_f32 v7, v7, v105, v13
	v_cvt_pk_bf16_f32 v8, v4, v5
	v_cvt_pk_bf16_f32 v9, v6, v7
	global_store_dwordx2 v1, v[8:9], s[12:13] nt
	s_add_u32 s12, s12, 0x40000
	s_addc_u32 s13, s13, 0
	v_lshlrev_b32_e32 v10, 16, v84
	v_and_b32_e32 v11, 0xffff0000, v84
	v_lshlrev_b32_e32 v12, 16, v85
	v_and_b32_e32 v13, 0xffff0000, v85
	v_fma_f32 v4, v4, v106, v10
	v_fma_f32 v5, v5, v106, v11
	v_fma_f32 v6, v6, v106, v12
	v_fma_f32 v7, v7, v106, v13
	v_cvt_pk_bf16_f32 v14, v4, v5
	v_cvt_pk_bf16_f32 v15, v6, v7
	global_store_dwordx2 v1, v[14:15], s[12:13] nt
; __device__ __forceinline__ u32x2 pk4(f32x4 v) { u32x2 r; r.x = pk2(v[0], v[1]); r.y = pk2(v[2], v[3]); return r; }
; __device__ __forceinline__ f32x4 up4(u32x2 u) { return (f32x4){lo16(u.x), hi16(u.x), lo16(u.y), hi16(u.y)}; }
; __device__ void scan_ssd(const Ctx& c, int idx) {
;     ...
;     for (int ck = 0; ck < NCH; ++ck) { u32x2* ad = (u32x2*)(sSt + (size_t)ck * 131072 + e4);
;         const f32x4 st = up4(__builtin_nontemporal_load(ad)); const float d = __expf(sAcs[(size_t)(ck * 16 + h) * 64 + 63]);
;         __builtin_nontemporal_store(pk4(S), ad); S = S * d + st; }
	s_add_u32 s12, s12, 0x40000
	s_addc_u32 s13, s13, 0
	v_lshlrev_b32_e32 v10, 16, v86
	v_and_b32_e32 v11, 0xffff0000, v86
	v_lshlrev_b32_e32 v12, 16, v87
	v_and_b32_e32 v13, 0xffff0000, v87
	v_fma_f32 v4, v4, v107, v10
	v_fma_f32 v5, v5, v107, v11
	v_fma_f32 v6, v6, v107, v12
	v_fma_f32 v7, v7, v107, v13
	v_cvt_pk_bf16_f32 v8, v4, v5
	v_cvt_pk_bf16_f32 v9, v6, v7
	global_store_dwordx2 v1, v[8:9], s[12:13] nt
	s_add_u32 s12, s12, 0x40000
	s_addc_u32 s13, s13, 0
	v_lshlrev_b32_e32 v10, 16, v88
	v_and_b32_e32 v11, 0xffff0000, v88
	v_lshlrev_b32_e32 v12, 16, v89
	v_and_b32_e32 v13, 0xffff0000, v89
	v_fma_f32 v4, v4, v108, v10
	v_fma_f32 v5, v5, v108, v11
	v_fma_f32 v6, v6, v108, v12
	v_fma_f32 v7, v7, v108, v13
	v_cvt_pk_bf16_f32 v14, v4, v5
	v_cvt_pk_bf16_f32 v15, v6, v7
	global_store_dwordx2 v1, v[14:15], s[12:13] nt
	s_add_u32 s12, s12, 0x40000
	s_addc_u32 s13, s13, 0
	v_lshlrev_b32_e32 v10, 16, v90
	v_and_b32_e32 v11, 0xffff0000, v90
	v_lshlrev_b32_e32 v12, 16, v91
	v_and_b32_e32 v13, 0xffff0000, v91
	v_fma_f32 v4, v4, v109, v10
	v_fma_f32 v5, v5, v109, v11
	v_fma_f32 v6, v6, v109, v12
	v_fma_f32 v7, v7, v109, v13
	v_cvt_pk_bf16_f32 v8, v4, v5
	v_cvt_pk_bf16_f32 v9, v6, v7
	global_store_dwordx2 v1, v[8:9], s[12:13] nt
	s_add_u32 s12, s12, 0x40000
	s_addc_u32 s13, s13, 0
	v_lshlrev_b32_e32 v10, 16, v92
	v_and_b32_e32 v11, 0xffff0000, v92
	v_lshlrev_b32_e32 v12, 16, v93
	v_and_b32_e32 v13, 0xffff0000, v93
	v_fma_f32 v4, v4, v110, v10
	v_fma_f32 v5, v5, v110, v11
	v_fma_f32 v6, v6, v110, v12
	v_fma_f32 v7, v7, v110, v13
	v_cvt_pk_bf16_f32 v14, v4, v5
	v_cvt_pk_bf16_f32 v15, v6, v7
	global_store_dwordx2 v1, v[14:15], s[12:13] nt
	s_add_u32 s12, s12, 0x40000
	s_addc_u32 s13, s13, 0
	v_lshlrev_b32_e32 v10, 16, v94
	v_and_b32_e32 v11, 0xffff0000, v94
	v_lshlrev_b32_e32 v12, 16, v95
	v_and_b32_e32 v13, 0xffff0000, v95
	v_fma_f32 v4, v4, v111, v10
	v_fma_f32 v5, v5, v111, v11
	v_fma_f32 v6, v6, v111, v12
	v_fma_f32 v7, v7, v111, v13
	global_load_dwordx2 v[64:65], v1, s[6:7] nt
	global_load_dword v96, v2, s[8:9]
	s_add_u32 s8, s8, 0x1000
	s_addc_u32 s9, s9, 0
	s_add_u32 s6, s6, 0x40000
	s_addc_u32 s7, s7, 0
	global_load_dwordx2 v[66:67], v1, s[6:7] nt
	global_load_dword v97, v2, s[8:9]
	s_add_u32 s8, s8, 0x1000
	s_addc_u32 s9, s9, 0
	s_add_u32 s6, s6, 0x40000
	s_addc_u32 s7, s7, 0
	global_load_dwordx2 v[68:69], v1, s[6:7] nt
	global_load_dword v98, v2, s[8:9]
	s_add_u32 s8, s8, 0x1000
	s_addc_u32 s9, s9, 0
	s_add_u32 s6, s6, 0x40000
	s_addc_u32 s7, s7, 0
	global_load_dwordx2 v[70:71], v1, s[6:7] nt
	global_load_dword v99, v2, s[8:9]
	s_add_u32 s8, s8, 0x1000
	s_addc_u32 s9, s9, 0
	s_add_u32 s6, s6, 0x40000
	s_addc_u32 s7, s7, 0
	global_load_dwordx2 v[72:73], v1, s[6:7] nt
	global_load_dword v100, v2, s[8:9]
	s_add_u32 s8, s8, 0x1000
	s_addc_u32 s9, s9, 0
	s_add_u32 s6, s6, 0x40000
	s_addc_u32 s7, s7, 0
	global_load_dwordx2 v[74:75], v1, s[6:7] nt
	global_load_dword v101, v2, s[8:9]
	s_add_u32 s8, s8, 0x1000
	s_addc_u32 s9, s9, 0
	s_add_u32 s6, s6, 0x40000
	s_addc_u32 s7, s7, 0
	global_load_dwordx2 v[76:77], v1, s[6:7] nt
	global_load_dword v102, v2, s[8:9]
	s_add_u32 s8, s8, 0x1000
	s_addc_u32 s9, s9, 0
	s_add_u32 s6, s6, 0x40000
	s_addc_u32 s7, s7, 0
	global_load_dwordx2 v[78:79], v1, s[6:7] nt
	global_load_dword v103, v2, s[8:9]
	s_add_u32 s8, s8, 0x1000
	s_addc_u32 s9, s9, 0
	s_add_u32 s6, s6, 0x40000
	s_addc_u32 s7, s7, 0
	global_load_dwordx2 v[80:81], v1, s[6:7] nt
	global_load_dword v104, v2, s[8:9]
	s_add_u32 s8, s8, 0x1000
	s_addc_u32 s9, s9, 0
	s_add_u32 s6, s6, 0x40000
	s_addc_u32 s7, s7, 0
	global_load_dwordx2 v[82:83], v1, s[6:7] nt
	global_load_dword v105, v2, s[8:9]
	s_add_u32 s8, s8, 0x1000
	s_addc_u32 s9, s9, 0
	s_add_u32 s6, s6, 0x40000
	s_addc_u32 s7, s7, 0
	global_load_dwordx2 v[84:85], v1, s[6:7] nt
	global_load_dword v106, v2, s[8:9]
	s_add_u32 s8, s8, 0x1000
	s_addc_u32 s9, s9, 0
	s_add_u32 s6, s6, 0x40000
	s_addc_u32 s7, s7, 0
	global_load_dwordx2 v[86:87], v1, s[6:7] nt
	global_load_dword v107, v2, s[8:9]
	s_add_u32 s8, s8, 0x1000
	s_addc_u32 s9, s9, 0
	s_add_u32 s6, s6, 0x40000
	s_addc_u32 s7, s7, 0
	global_load_dwordx2 v[88:89], v1, s[6:7] nt
	global_load_dword v108, v2, s[8:9]
	s_add_u32 s8, s8, 0x1000
	s_addc_u32 s9, s9, 0
	s_add_u32 s6, s6, 0x40000
	s_addc_u32 s7, s7, 0
	global_load_dwordx2 v[90:91], v1, s[6:7] nt
	global_load_dword v109, v2, s[8:9]
	s_add_u32 s8, s8, 0x1000
	s_addc_u32 s9, s9, 0
	s_add_u32 s6, s6, 0x40000
	s_addc_u32 s7, s7, 0
	global_load_dwordx2 v[92:93], v1, s[6:7] nt
	global_load_dword v110, v2, s[8:9]
	s_add_u32 s8, s8, 0x1000
	s_addc_u32 s9, s9, 0
	s_add_u32 s6, s6, 0x40000
	s_addc_u32 s7, s7, 0
	global_load_dwordx2 v[94:95], v1, s[6:7] nt
	global_load_dword v111, v2, s[8:9]
	s_add_u32 s8, s8, 0x1000
	s_addc_u32 s9, s9, 0
	s_add_u32 s6, s6, 0x40000
	s_addc_u32 s7, s7, 0
	s_waitcnt vmcnt(48)
; __device__ __forceinline__ u32x2 pk4(f32x4 v) { u32x2 r; r.x = pk2(v[0], v[1]); r.y = pk2(v[2], v[3]); return r; }
; __device__ __forceinline__ f32x4 up4(u32x2 u) { return (f32x4){lo16(u.x), hi16(u.x), lo16(u.y), hi16(u.y)}; }
; __device__ void scan_ssd(const Ctx& c, int idx) {
;     ...
;     for (int ck = 0; ck < NCH; ++ck) { u32x2* ad = (u32x2*)(sSt + (size_t)ck * 131072 + e4);
;         const f32x4 st = up4(__builtin_nontemporal_load(ad)); const float d = __expf(sAcs[(size_t)(ck * 16 + h) * 64 + 63]);
;         __builtin_nontemporal_store(pk4(S), ad); S = S * d + st; }
	v_mul_f32_e32 v48, 0x3fb8aa3b, v48
	v_mul_f32_e32 v49, 0x3fb8aa3b, v49
	v_mul_f32_e32 v50, 0x3fb8aa3b, v50
	v_mul_f32_e32 v51, 0x3fb8aa3b, v51
	v_mul_f32_e32 v52, 0x3fb8aa3b, v52
	v_mul_f32_e32 v53, 0x3fb8aa3b, v53
	v_mul_f32_e32 v54, 0x3fb8aa3b, v54
	v_mul_f32_e32 v55, 0x3fb8aa3b, v55
	v_mul_f32_e32 v56, 0x3fb8aa3b, v56
	v_mul_f32_e32 v57, 0x3fb8aa3b, v57
	v_mul_f32_e32 v58, 0x3fb8aa3b, v58
	v_mul_f32_e32 v59, 0x3fb8aa3b, v59
	v_mul_f32_e32 v60, 0x3fb8aa3b, v60
	v_mul_f32_e32 v61, 0x3fb8aa3b, v61
	v_mul_f32_e32 v62, 0x3fb8aa3b, v62
	v_mul_f32_e32 v63, 0x3fb8aa3b, v63
	v_exp_f32_e32 v48, v48
	v_exp_f32_e32 v49, v49
	v_exp_f32_e32 v50, v50
	v_exp_f32_e32 v51, v51
	v_exp_f32_e32 v52, v52
	v_exp_f32_e32 v53, v53
	v_exp_f32_e32 v54, v54
	v_exp_f32_e32 v55, v55
	v_exp_f32_e32 v56, v56
	v_exp_f32_e32 v57, v57
	v_exp_f32_e32 v58, v58
	v_exp_f32_e32 v59, v59
	v_exp_f32_e32 v60, v60
	v_exp_f32_e32 v61, v61
	v_exp_f32_e32 v62, v62
	v_exp_f32_e32 v63, v63
	s_nop 0
	v_cvt_pk_bf16_f32 v8, v4, v5
	v_cvt_pk_bf16_f32 v9, v6, v7
	global_store_dwordx2 v1, v[8:9], s[12:13] nt
	s_add_u32 s12, s12, 0x40000
	s_addc_u32 s13, s13, 0
	v_lshlrev_b32_e32 v10, 16, v16
	v_and_b32_e32 v11, 0xffff0000, v16
	v_lshlrev_b32_e32 v12, 16, v17
	v_and_b32_e32 v13, 0xffff0000, v17
	v_fma_f32 v4, v4, v48, v10
	v_fma_f32 v5, v5, v48, v11
	v_fma_f32 v6, v6, v48, v12
	v_fma_f32 v7, v7, v48, v13
	v_cvt_pk_bf16_f32 v14, v4, v5
	v_cvt_pk_bf16_f32 v15, v6, v7
	global_store_dwordx2 v1, v[14:15], s[12:13] nt
	s_add_u32 s12, s12, 0x40000
	s_addc_u32 s13, s13, 0
	v_lshlrev_b32_e32 v10, 16, v18
	v_and_b32_e32 v11, 0xffff0000, v18
	v_lshlrev_b32_e32 v12, 16, v19
	v_and_b32_e32 v13, 0xffff0000, v19
	v_fma_f32 v4, v4, v49, v10
	v_fma_f32 v5, v5, v49, v11
	v_fma_f32 v6, v6, v49, v12
	v_fma_f32 v7, v7, v49, v13
	v_cvt_pk_bf16_f32 v8, v4, v5
	v_cvt_pk_bf16_f32 v9, v6, v7
	global_store_dwordx2 v1, v[8:9], s[12:13] nt
	s_add_u32 s12, s12, 0x40000
	s_addc_u32 s13, s13, 0
	v_lshlrev_b32_e32 v10, 16, v20
	v_and_b32_e32 v11, 0xffff0000, v20
	v_lshlrev_b32_e32 v12, 16, v21
	v_and_b32_e32 v13, 0xffff0000, v21
	v_fma_f32 v4, v4, v50, v10
	v_fma_f32 v5, v5, v50, v11
	v_fma_f32 v6, v6, v50, v12
	v_fma_f32 v7, v7, v50, v13
	v_cvt_pk_bf16_f32 v14, v4, v5
	v_cvt_pk_bf16_f32 v15, v6, v7
	global_store_dwordx2 v1, v[14:15], s[12:13] nt
	s_add_u32 s12, s12, 0x40000
	s_addc_u32 s13, s13, 0
	v_lshlrev_b32_e32 v10, 16, v22
	v_and_b32_e32 v11, 0xffff0000, v22
	v_lshlrev_b32_e32 v12, 16, v23
	v_and_b32_e32 v13, 0xffff0000, v23
	v_fma_f32 v4, v4, v51, v10
	v_fma_f32 v5, v5, v51, v11
	v_fma_f32 v6, v6, v51, v12
	v_fma_f32 v7, v7, v51, v13
	v_cvt_pk_bf16_f32 v8, v4, v5
	v_cvt_pk_bf16_f32 v9, v6, v7
	global_store_dwordx2 v1, v[8:9], s[12:13] nt
	s_add_u32 s12, s12, 0x40000
	s_addc_u32 s13, s13, 0
	v_lshlrev_b32_e32 v10, 16, v24
	v_and_b32_e32 v11, 0xffff0000, v24
	v_lshlrev_b32_e32 v12, 16, v25
	v_and_b32_e32 v13, 0xffff0000, v25
	v_fma_f32 v4, v4, v52, v10
	v_fma_f32 v5, v5, v52, v11
	v_fma_f32 v6, v6, v52, v12
	v_fma_f32 v7, v7, v52, v13
	v_cvt_pk_bf16_f32 v14, v4, v5
	v_cvt_pk_bf16_f32 v15, v6, v7
	global_store_dwordx2 v1, v[14:15], s[12:13] nt
	s_add_u32 s12, s12, 0x40000
	s_addc_u32 s13, s13, 0
	v_lshlrev_b32_e32 v10, 16, v26
	v_and_b32_e32 v11, 0xffff0000, v26
	v_lshlrev_b32_e32 v12, 16, v27
	v_and_b32_e32 v13, 0xffff0000, v27
	v_fma_f32 v4, v4, v53, v10
	v_fma_f32 v5, v5, v53, v11
	v_fma_f32 v6, v6, v53, v12
	v_fma_f32 v7, v7, v53, v13
	v_cvt_pk_bf16_f32 v8, v4, v5
	v_cvt_pk_bf16_f32 v9, v6, v7
	global_store_dwordx2 v1, v[8:9], s[12:13] nt
	s_add_u32 s12, s12, 0x40000
	s_addc_u32 s13, s13, 0
	v_lshlrev_b32_e32 v10, 16, v28
	v_and_b32_e32 v11, 0xffff0000, v28
	v_lshlrev_b32_e32 v12, 16, v29
	v_and_b32_e32 v13, 0xffff0000, v29
	v_fma_f32 v4, v4, v54, v10
	v_fma_f32 v5, v5, v54, v11
	v_fma_f32 v6, v6, v54, v12
	v_fma_f32 v7, v7, v54, v13
	v_cvt_pk_bf16_f32 v14, v4, v5
	v_cvt_pk_bf16_f32 v15, v6, v7
	global_store_dwordx2 v1, v[14:15], s[12:13] nt
	s_add_u32 s12, s12, 0x40000
	s_addc_u32 s13, s13, 0
	v_lshlrev_b32_e32 v10, 16, v30
	v_and_b32_e32 v11, 0xffff0000, v30
	v_lshlrev_b32_e32 v12, 16, v31
	v_and_b32_e32 v13, 0xffff0000, v31
	v_fma_f32 v4, v4, v55, v10
	v_fma_f32 v5, v5, v55, v11
	v_fma_f32 v6, v6, v55, v12
	v_fma_f32 v7, v7, v55, v13
	v_cvt_pk_bf16_f32 v8, v4, v5
	v_cvt_pk_bf16_f32 v9, v6, v7
	global_store_dwordx2 v1, v[8:9], s[12:13] nt
	s_add_u32 s12, s12, 0x40000
	s_addc_u32 s13, s13, 0
	v_lshlrev_b32_e32 v10, 16, v32
	v_and_b32_e32 v11, 0xffff0000, v32
	v_lshlrev_b32_e32 v12, 16, v33
	v_and_b32_e32 v13, 0xffff0000, v33
	v_fma_f32 v4, v4, v56, v10
	v_fma_f32 v5, v5, v56, v11
	v_fma_f32 v6, v6, v56, v12
	v_fma_f32 v7, v7, v56, v13
	v_cvt_pk_bf16_f32 v14, v4, v5
	v_cvt_pk_bf16_f32 v15, v6, v7
	global_store_dwordx2 v1, v[14:15], s[12:13] nt
	s_add_u32 s12, s12, 0x40000
	s_addc_u32 s13, s13, 0
	v_lshlrev_b32_e32 v10, 16, v34
	v_and_b32_e32 v11, 0xffff0000, v34
	v_lshlrev_b32_e32 v12, 16, v35
	v_and_b32_e32 v13, 0xffff0000, v35
	v_fma_f32 v4, v4, v57, v10
	v_fma_f32 v5, v5, v57, v11
	v_fma_f32 v6, v6, v57, v12
	v_fma_f32 v7, v7, v57, v13
	v_cvt_pk_bf16_f32 v8, v4, v5
	v_cvt_pk_bf16_f32 v9, v6, v7
	global_store_dwordx2 v1, v[8:9], s[12:13] nt
	s_add_u32 s12, s12, 0x40000
	s_addc_u32 s13, s13, 0
	v_lshlrev_b32_e32 v10, 16, v36
	v_and_b32_e32 v11, 0xffff0000, v36
	v_lshlrev_b32_e32 v12, 16, v37
	v_and_b32_e32 v13, 0xffff0000, v37
	v_fma_f32 v4, v4, v58, v10
	v_fma_f32 v5, v5, v58, v11
	v_fma_f32 v6, v6, v58, v12
	v_fma_f32 v7, v7, v58, v13
	v_cvt_pk_bf16_f32 v14, v4, v5
	v_cvt_pk_bf16_f32 v15, v6, v7
	global_store_dwordx2 v1, v[14:15], s[12:13] nt
	s_add_u32 s12, s12, 0x40000
	s_addc_u32 s13, s13, 0
; __device__ __forceinline__ u32x2 pk4(f32x4 v) { u32x2 r; r.x = pk2(v[0], v[1]); r.y = pk2(v[2], v[3]); return r; }
; __device__ __forceinline__ f32x4 up4(u32x2 u) { return (f32x4){lo16(u.x), hi16(u.x), lo16(u.y), hi16(u.y)}; }
; __device__ void scan_ssd(const Ctx& c, int idx) {
;     ...
;     for (int ck = 0; ck < NCH; ++ck) { u32x2* ad = (u32x2*)(sSt + (size_t)ck * 131072 + e4);
;         const f32x4 st = up4(__builtin_nontemporal_load(ad)); const float d = __expf(sAcs[(size_t)(ck * 16 + h) * 64 + 63]);
;         __builtin_nontemporal_store(pk4(S), ad); S = S * d + st; }
	v_lshlrev_b32_e32 v10, 16, v38
	v_and_b32_e32 v11, 0xffff0000, v38
	v_lshlrev_b32_e32 v12, 16, v39
	v_and_b32_e32 v13, 0xffff0000, v39
	v_fma_f32 v4, v4, v59, v10
	v_fma_f32 v5, v5, v59, v11
	v_fma_f32 v6, v6, v59, v12
	v_fma_f32 v7, v7, v59, v13
	v_cvt_pk_bf16_f32 v8, v4, v5
	v_cvt_pk_bf16_f32 v9, v6, v7
	global_store_dwordx2 v1, v[8:9], s[12:13] nt
	s_add_u32 s12, s12, 0x40000
	s_addc_u32 s13, s13, 0
	v_lshlrev_b32_e32 v10, 16, v40
	v_and_b32_e32 v11, 0xffff0000, v40
	v_lshlrev_b32_e32 v12, 16, v41
	v_and_b32_e32 v13, 0xffff0000, v41
	v_fma_f32 v4, v4, v60, v10
	v_fma_f32 v5, v5, v60, v11
	v_fma_f32 v6, v6, v60, v12
	v_fma_f32 v7, v7, v60, v13
	v_cvt_pk_bf16_f32 v14, v4, v5
	v_cvt_pk_bf16_f32 v15, v6, v7
	global_store_dwordx2 v1, v[14:15], s[12:13] nt
	s_add_u32 s12, s12, 0x40000
	s_addc_u32 s13, s13, 0
	v_lshlrev_b32_e32 v10, 16, v42
	v_and_b32_e32 v11, 0xffff0000, v42
	v_lshlrev_b32_e32 v12, 16, v43
	v_and_b32_e32 v13, 0xffff0000, v43
	v_fma_f32 v4, v4, v61, v10
	v_fma_f32 v5, v5, v61, v11
	v_fma_f32 v6, v6, v61, v12
	v_fma_f32 v7, v7, v61, v13
	v_cvt_pk_bf16_f32 v8, v4, v5
	v_cvt_pk_bf16_f32 v9, v6, v7
	global_store_dwordx2 v1, v[8:9], s[12:13] nt
	s_add_u32 s12, s12, 0x40000
	s_addc_u32 s13, s13, 0
	v_lshlrev_b32_e32 v10, 16, v44
	v_and_b32_e32 v11, 0xffff0000, v44
	v_lshlrev_b32_e32 v12, 16, v45
	v_and_b32_e32 v13, 0xffff0000, v45
	v_fma_f32 v4, v4, v62, v10
	v_fma_f32 v5, v5, v62, v11
	v_fma_f32 v6, v6, v62, v12
	v_fma_f32 v7, v7, v62, v13
	v_cvt_pk_bf16_f32 v14, v4, v5
	v_cvt_pk_bf16_f32 v15, v6, v7
	global_store_dwordx2 v1, v[14:15], s[12:13] nt
	s_add_u32 s12, s12, 0x40000
	s_addc_u32 s13, s13, 0
	v_lshlrev_b32_e32 v10, 16, v46
	v_and_b32_e32 v11, 0xffff0000, v46
	v_lshlrev_b32_e32 v12, 16, v47
	v_and_b32_e32 v13, 0xffff0000, v47
	v_fma_f32 v4, v4, v63, v10
	v_fma_f32 v5, v5, v63, v11
	v_fma_f32 v6, v6, v63, v12
	v_fma_f32 v7, v7, v63, v13
	s_waitcnt vmcnt(16)
	v_mul_f32_e32 v96, 0x3fb8aa3b, v96
	v_mul_f32_e32 v97, 0x3fb8aa3b, v97
	v_mul_f32_e32 v98, 0x3fb8aa3b, v98
	v_mul_f32_e32 v99, 0x3fb8aa3b, v99
	v_mul_f32_e32 v100, 0x3fb8aa3b, v100
	v_mul_f32_e32 v101, 0x3fb8aa3b, v101
	v_mul_f32_e32 v102, 0x3fb8aa3b, v102
	v_mul_f32_e32 v103, 0x3fb8aa3b, v103
	v_mul_f32_e32 v104, 0x3fb8aa3b, v104
	v_mul_f32_e32 v105, 0x3fb8aa3b, v105
	v_mul_f32_e32 v106, 0x3fb8aa3b, v106
	v_mul_f32_e32 v107, 0x3fb8aa3b, v107
	v_mul_f32_e32 v108, 0x3fb8aa3b, v108
	v_mul_f32_e32 v109, 0x3fb8aa3b, v109
	v_mul_f32_e32 v110, 0x3fb8aa3b, v110
	v_mul_f32_e32 v111, 0x3fb8aa3b, v111
	v_exp_f32_e32 v96, v96
	v_exp_f32_e32 v97, v97
	v_exp_f32_e32 v98, v98
	v_exp_f32_e32 v99, v99
	v_exp_f32_e32 v100, v100
	v_exp_f32_e32 v101, v101
	v_exp_f32_e32 v102, v102
	v_exp_f32_e32 v103, v103
	v_exp_f32_e32 v104, v104
	v_exp_f32_e32 v105, v105
	v_exp_f32_e32 v106, v106
	v_exp_f32_e32 v107, v107
	v_exp_f32_e32 v108, v108
	v_exp_f32_e32 v109, v109
	v_exp_f32_e32 v110, v110
	v_exp_f32_e32 v111, v111
	s_nop 0
	v_cvt_pk_bf16_f32 v8, v4, v5
	v_cvt_pk_bf16_f32 v9, v6, v7
	global_store_dwordx2 v1, v[8:9], s[12:13] nt
	s_add_u32 s12, s12, 0x40000
	s_addc_u32 s13, s13, 0
	v_lshlrev_b32_e32 v10, 16, v64
	v_and_b32_e32 v11, 0xffff0000, v64
	v_lshlrev_b32_e32 v12, 16, v65
	v_and_b32_e32 v13, 0xffff0000, v65
	v_fma_f32 v4, v4, v96, v10
	v_fma_f32 v5, v5, v96, v11
	v_fma_f32 v6, v6, v96, v12
	v_fma_f32 v7, v7, v96, v13
	v_cvt_pk_bf16_f32 v14, v4, v5
	v_cvt_pk_bf16_f32 v15, v6, v7
	global_store_dwordx2 v1, v[14:15], s[12:13] nt
	s_add_u32 s12, s12, 0x40000
	s_addc_u32 s13, s13, 0
	v_lshlrev_b32_e32 v10, 16, v66
	v_and_b32_e32 v11, 0xffff0000, v66
	v_lshlrev_b32_e32 v12, 16, v67
	v_and_b32_e32 v13, 0xffff0000, v67
	v_fma_f32 v4, v4, v97, v10
	v_fma_f32 v5, v5, v97, v11
	v_fma_f32 v6, v6, v97, v12
	v_fma_f32 v7, v7, v97, v13
	v_cvt_pk_bf16_f32 v8, v4, v5
	v_cvt_pk_bf16_f32 v9, v6, v7
	global_store_dwordx2 v1, v[8:9], s[12:13] nt
	s_add_u32 s12, s12, 0x40000
	s_addc_u32 s13, s13, 0
	v_lshlrev_b32_e32 v10, 16, v68
	v_and_b32_e32 v11, 0xffff0000, v68
	v_lshlrev_b32_e32 v12, 16, v69
	v_and_b32_e32 v13, 0xffff0000, v69
	v_fma_f32 v4, v4, v98, v10
	v_fma_f32 v5, v5, v98, v11
	v_fma_f32 v6, v6, v98, v12
	v_fma_f32 v7, v7, v98, v13
	v_cvt_pk_bf16_f32 v14, v4, v5
	v_cvt_pk_bf16_f32 v15, v6, v7
	global_store_dwordx2 v1, v[14:15], s[12:13] nt
	s_add_u32 s12, s12, 0x40000
	s_addc_u32 s13, s13, 0
	v_lshlrev_b32_e32 v10, 16, v70
	v_and_b32_e32 v11, 0xffff0000, v70
	v_lshlrev_b32_e32 v12, 16, v71
	v_and_b32_e32 v13, 0xffff0000, v71
	v_fma_f32 v4, v4, v99, v10
	v_fma_f32 v5, v5, v99, v11
	v_fma_f32 v6, v6, v99, v12
	v_fma_f32 v7, v7, v99, v13
	v_cvt_pk_bf16_f32 v8, v4, v5
	v_cvt_pk_bf16_f32 v9, v6, v7
	global_store_dwordx2 v1, v[8:9], s[12:13] nt
	s_add_u32 s12, s12, 0x40000
	s_addc_u32 s13, s13, 0
	v_lshlrev_b32_e32 v10, 16, v72
	v_and_b32_e32 v11, 0xffff0000, v72
	v_lshlrev_b32_e32 v12, 16, v73
	v_and_b32_e32 v13, 0xffff0000, v73
	v_fma_f32 v4, v4, v100, v10
	v_fma_f32 v5, v5, v100, v11
	v_fma_f32 v6, v6, v100, v12
	v_fma_f32 v7, v7, v100, v13
	v_cvt_pk_bf16_f32 v14, v4, v5
	v_cvt_pk_bf16_f32 v15, v6, v7
	global_store_dwordx2 v1, v[14:15], s[12:13] nt
	s_add_u32 s12, s12, 0x40000
	s_addc_u32 s13, s13, 0
	v_lshlrev_b32_e32 v10, 16, v74
	v_and_b32_e32 v11, 0xffff0000, v74
	v_lshlrev_b32_e32 v12, 16, v75
	v_and_b32_e32 v13, 0xffff0000, v75
	v_fma_f32 v4, v4, v101, v10
	v_fma_f32 v5, v5, v101, v11
	v_fma_f32 v6, v6, v101, v12
	v_fma_f32 v7, v7, v101, v13
	v_cvt_pk_bf16_f32 v8, v4, v5
	v_cvt_pk_bf16_f32 v9, v6, v7
	global_store_dwordx2 v1, v[8:9], s[12:13] nt
	s_add_u32 s12, s12, 0x40000
	s_addc_u32 s13, s13, 0
	v_lshlrev_b32_e32 v10, 16, v76
	v_and_b32_e32 v11, 0xffff0000, v76
	v_lshlrev_b32_e32 v12, 16, v77
; __device__ __forceinline__ u32x2 pk4(f32x4 v) { u32x2 r; r.x = pk2(v[0], v[1]); r.y = pk2(v[2], v[3]); return r; }
; __device__ __forceinline__ f32x4 up4(u32x2 u) { return (f32x4){lo16(u.x), hi16(u.x), lo16(u.y), hi16(u.y)}; }
;     template <class Tp> __device__ __forceinline__ Tp* W(size_t off) const { return (Tp*)(ws + off); }
; __device__ void scan_ssd(const Ctx& c, int idx) {
;     ...
;     for (int ck = 0; ck < NCH; ++ck) { u32x2* ad = (u32x2*)(sSt + (size_t)ck * 131072 + e4);
;         const f32x4 st = up4(__builtin_nontemporal_load(ad)); const float d = __expf(sAcs[(size_t)(ck * 16 + h) * 64 + 63]);
;         __builtin_nontemporal_store(pk4(S), ad); S = S * d + st; }
; __device__ void scan_gla(const Ctx& c, int idx) {
;     bf16_t* gSt = c.W<bf16_t>(WS_GST); const float* gDec = c.W<float>(WS_GDEC);
;     const size_t e4 = (size_t)idx * 4; const int h = (int)(e4 >> 15), k4 = (int)(e4 & 127);
;     f32x4 S = (f32x4){0.f, 0.f, 0.f, 0.f};
; #pragma unroll 4
;     for (int ck = 0; ck < NCH; ++ck) { u32x2* ad = (u32x2*)(gSt + (size_t)ck * 131072 + e4);
;         const f32x4 st = up4(__builtin_nontemporal_load(ad)); const f32x4 d = *(const f32x4*)(gDec + (size_t)ck * 512 + h * 128 + k4);
;         __builtin_nontemporal_store(pk4(S), ad); S = S * d + st; }
	v_and_b32_e32 v13, 0xffff0000, v77
	v_fma_f32 v4, v4, v102, v10
	v_fma_f32 v5, v5, v102, v11
	v_fma_f32 v6, v6, v102, v12
	v_fma_f32 v7, v7, v102, v13
	v_cvt_pk_bf16_f32 v14, v4, v5
	v_cvt_pk_bf16_f32 v15, v6, v7
	global_store_dwordx2 v1, v[14:15], s[12:13] nt
	s_add_u32 s12, s12, 0x40000
	s_addc_u32 s13, s13, 0
	v_lshlrev_b32_e32 v10, 16, v78
	v_and_b32_e32 v11, 0xffff0000, v78
	v_lshlrev_b32_e32 v12, 16, v79
	v_and_b32_e32 v13, 0xffff0000, v79
	v_fma_f32 v4, v4, v103, v10
	v_fma_f32 v5, v5, v103, v11
	v_fma_f32 v6, v6, v103, v12
	v_fma_f32 v7, v7, v103, v13
	v_cvt_pk_bf16_f32 v8, v4, v5
	v_cvt_pk_bf16_f32 v9, v6, v7
	global_store_dwordx2 v1, v[8:9], s[12:13] nt
	s_add_u32 s12, s12, 0x40000
	s_addc_u32 s13, s13, 0
	v_lshlrev_b32_e32 v10, 16, v80
	v_and_b32_e32 v11, 0xffff0000, v80
	v_lshlrev_b32_e32 v12, 16, v81
	v_and_b32_e32 v13, 0xffff0000, v81
	v_fma_f32 v4, v4, v104, v10
	v_fma_f32 v5, v5, v104, v11
	v_fma_f32 v6, v6, v104, v12
	v_fma_f32 v7, v7, v104, v13
	v_cvt_pk_bf16_f32 v14, v4, v5
	v_cvt_pk_bf16_f32 v15, v6, v7
	global_store_dwordx2 v1, v[14:15], s[12:13] nt
	s_add_u32 s12, s12, 0x40000
	s_addc_u32 s13, s13, 0
	v_lshlrev_b32_e32 v10, 16, v82
	v_and_b32_e32 v11, 0xffff0000, v82
	v_lshlrev_b32_e32 v12, 16, v83
	v_and_b32_e32 v13, 0xffff0000, v83
	v_fma_f32 v4, v4, v105, v10
	v_fma_f32 v5, v5, v105, v11
	v_fma_f32 v6, v6, v105, v12
	v_fma_f32 v7, v7, v105, v13
	v_cvt_pk_bf16_f32 v8, v4, v5
	v_cvt_pk_bf16_f32 v9, v6, v7
	global_store_dwordx2 v1, v[8:9], s[12:13] nt
	s_add_u32 s12, s12, 0x40000
	s_addc_u32 s13, s13, 0
	v_lshlrev_b32_e32 v10, 16, v84
	v_and_b32_e32 v11, 0xffff0000, v84
	v_lshlrev_b32_e32 v12, 16, v85
	v_and_b32_e32 v13, 0xffff0000, v85
	v_fma_f32 v4, v4, v106, v10
	v_fma_f32 v5, v5, v106, v11
	v_fma_f32 v6, v6, v106, v12
	v_fma_f32 v7, v7, v106, v13
	v_cvt_pk_bf16_f32 v14, v4, v5
	v_cvt_pk_bf16_f32 v15, v6, v7
	global_store_dwordx2 v1, v[14:15], s[12:13] nt
	s_add_u32 s12, s12, 0x40000
	s_addc_u32 s13, s13, 0
	v_lshlrev_b32_e32 v10, 16, v86
	v_and_b32_e32 v11, 0xffff0000, v86
	v_lshlrev_b32_e32 v12, 16, v87
	v_and_b32_e32 v13, 0xffff0000, v87
	v_fma_f32 v4, v4, v107, v10
	v_fma_f32 v5, v5, v107, v11
	v_fma_f32 v6, v6, v107, v12
	v_fma_f32 v7, v7, v107, v13
	v_cvt_pk_bf16_f32 v8, v4, v5
	v_cvt_pk_bf16_f32 v9, v6, v7
	global_store_dwordx2 v1, v[8:9], s[12:13] nt
	s_add_u32 s12, s12, 0x40000
	s_addc_u32 s13, s13, 0
	v_lshlrev_b32_e32 v10, 16, v88
	v_and_b32_e32 v11, 0xffff0000, v88
	v_lshlrev_b32_e32 v12, 16, v89
	v_and_b32_e32 v13, 0xffff0000, v89
	v_fma_f32 v4, v4, v108, v10
	v_fma_f32 v5, v5, v108, v11
	v_fma_f32 v6, v6, v108, v12
	v_fma_f32 v7, v7, v108, v13
	v_cvt_pk_bf16_f32 v14, v4, v5
	v_cvt_pk_bf16_f32 v15, v6, v7
	global_store_dwordx2 v1, v[14:15], s[12:13] nt
	s_add_u32 s12, s12, 0x40000
	s_addc_u32 s13, s13, 0
	v_lshlrev_b32_e32 v10, 16, v90
	v_and_b32_e32 v11, 0xffff0000, v90
	v_lshlrev_b32_e32 v12, 16, v91
	v_and_b32_e32 v13, 0xffff0000, v91
	v_fma_f32 v4, v4, v109, v10
	v_fma_f32 v5, v5, v109, v11
	v_fma_f32 v6, v6, v109, v12
	v_fma_f32 v7, v7, v109, v13
	v_cvt_pk_bf16_f32 v8, v4, v5
	v_cvt_pk_bf16_f32 v9, v6, v7
	global_store_dwordx2 v1, v[8:9], s[12:13] nt
	s_add_u32 s12, s12, 0x40000
	s_addc_u32 s13, s13, 0
	v_lshlrev_b32_e32 v10, 16, v92
	v_and_b32_e32 v11, 0xffff0000, v92
	v_lshlrev_b32_e32 v12, 16, v93
	v_and_b32_e32 v13, 0xffff0000, v93
	v_fma_f32 v4, v4, v110, v10
	v_fma_f32 v5, v5, v110, v11
	v_fma_f32 v6, v6, v110, v12
	v_fma_f32 v7, v7, v110, v13
	v_cvt_pk_bf16_f32 v14, v4, v5
	v_cvt_pk_bf16_f32 v15, v6, v7
	global_store_dwordx2 v1, v[14:15], s[12:13] nt
	s_add_u32 s12, s12, 0x40000
	s_addc_u32 s13, s13, 0
	v_lshlrev_b32_e32 v10, 16, v94
	v_and_b32_e32 v11, 0xffff0000, v94
	v_lshlrev_b32_e32 v12, 16, v95
	v_and_b32_e32 v13, 0xffff0000, v95
	v_fma_f32 v4, v4, v111, v10
	v_fma_f32 v5, v5, v111, v11
	v_fma_f32 v6, v6, v111, v12
	v_fma_f32 v7, v7, v111, v13
	s_branch .Lscan_done
.Lscan_gla:
	v_lshrrev_b32_e32 v2, 13, v0
	v_lshlrev_b32_e32 v2, 9, v2
	v_and_b32_e32 v3, 31, v0
	v_lshl_or_b32 v2, v3, 4, v2
	s_add_u32 s6, s4, 0x33181000
	s_addc_u32 s7, s5, 0
	s_add_u32 s8, s4, 0x35181000
	s_addc_u32 s9, s5, 0
	s_mov_b32 s12, s6
	s_mov_b32 s13, s7
	v_mov_b32_e32 v4, 0
	v_mov_b32_e32 v5, 0
	v_mov_b32_e32 v6, 0
	v_mov_b32_e32 v7, 0
	global_load_dwordx2 v[16:17], v1, s[6:7] nt
	global_load_dwordx4 v[32:35], v2, s[8:9] offset:0
	s_add_u32 s6, s6, 0x40000
	s_addc_u32 s7, s7, 0
	global_load_dwordx2 v[18:19], v1, s[6:7] nt
	global_load_dwordx4 v[36:39], v2, s[8:9] offset:2048
	s_add_u32 s8, s8, 0x1000
	s_addc_u32 s9, s9, 0
	s_add_u32 s6, s6, 0x40000
	s_addc_u32 s7, s7, 0
	global_load_dwordx2 v[20:21], v1, s[6:7] nt
	global_load_dwordx4 v[40:43], v2, s[8:9] offset:0
	s_add_u32 s6, s6, 0x40000
	s_addc_u32 s7, s7, 0
	global_load_dwordx2 v[22:23], v1, s[6:7] nt
	global_load_dwordx4 v[44:47], v2, s[8:9] offset:2048
	s_add_u32 s8, s8, 0x1000
	s_addc_u32 s9, s9, 0
	s_add_u32 s6, s6, 0x40000
	s_addc_u32 s7, s7, 0
	global_load_dwordx2 v[24:25], v1, s[6:7] nt
	global_load_dwordx4 v[48:51], v2, s[8:9] offset:0
	s_add_u32 s6, s6, 0x40000
	s_addc_u32 s7, s7, 0
	global_load_dwordx2 v[26:27], v1, s[6:7] nt
	global_load_dwordx4 v[52:55], v2, s[8:9] offset:2048
	s_add_u32 s8, s8, 0x1000
	s_addc_u32 s9, s9, 0
	s_add_u32 s6, s6, 0x40000
	s_addc_u32 s7, s7, 0
	global_load_dwordx2 v[28:29], v1, s[6:7] nt
	global_load_dwordx4 v[56:59], v2, s[8:9] offset:0
	s_add_u32 s6, s6, 0x40000
	s_addc_u32 s7, s7, 0
	global_load_dwordx2 v[30:31], v1, s[6:7] nt
	global_load_dwordx4 v[60:63], v2, s[8:9] offset:2048
	s_add_u32 s8, s8, 0x1000
	s_addc_u32 s9, s9, 0
	s_add_u32 s6, s6, 0x40000
	s_addc_u32 s7, s7, 0
	global_load_dwordx2 v[64:65], v1, s[6:7] nt
	global_load_dwordx4 v[80:83], v2, s[8:9] offset:0
	s_add_u32 s6, s6, 0x40000
	s_addc_u32 s7, s7, 0
	global_load_dwordx2 v[66:67], v1, s[6:7] nt
	global_load_dwordx4 v[84:87], v2, s[8:9] offset:2048
	s_add_u32 s8, s8, 0x1000
	s_addc_u32 s9, s9, 0
	s_add_u32 s6, s6, 0x40000
	s_addc_u32 s7, s7, 0
	global_load_dwordx2 v[68:69], v1, s[6:7] nt
	global_load_dwordx4 v[88:91], v2, s[8:9] offset:0
	s_add_u32 s6, s6, 0x40000
	s_addc_u32 s7, s7, 0
	global_load_dwordx2 v[70:71], v1, s[6:7] nt
	global_load_dwordx4 v[92:95], v2, s[8:9] offset:2048
	s_add_u32 s8, s8, 0x1000
	s_addc_u32 s9, s9, 0
	s_add_u32 s6, s6, 0x40000
	s_addc_u32 s7, s7, 0
	global_load_dwordx2 v[72:73], v1, s[6:7] nt
	global_load_dwordx4 v[96:99], v2, s[8:9] offset:0
	s_add_u32 s6, s6, 0x40000
	s_addc_u32 s7, s7, 0
	global_load_dwordx2 v[74:75], v1, s[6:7] nt
	global_load_dwordx4 v[100:103], v2, s[8:9] offset:2048
	s_add_u32 s8, s8, 0x1000
	s_addc_u32 s9, s9, 0
	s_add_u32 s6, s6, 0x40000
	s_addc_u32 s7, s7, 0
	global_load_dwordx2 v[76:77], v1, s[6:7] nt
	global_load_dwordx4 v[104:107], v2, s[8:9] offset:0
	s_add_u32 s6, s6, 0x40000
	s_addc_u32 s7, s7, 0
	global_load_dwordx2 v[78:79], v1, s[6:7] nt
	global_load_dwordx4 v[108:111], v2, s[8:9] offset:2048
	s_add_u32 s8, s8, 0x1000
	s_addc_u32 s9, s9, 0
	s_add_u32 s6, s6, 0x40000
	s_addc_u32 s7, s7, 0
	s_waitcnt vmcnt(16)
; __device__ __forceinline__ u32x2 pk4(f32x4 v) { u32x2 r; r.x = pk2(v[0], v[1]); r.y = pk2(v[2], v[3]); return r; }
; __device__ __forceinline__ f32x4 up4(u32x2 u) { return (f32x4){lo16(u.x), hi16(u.x), lo16(u.y), hi16(u.y)}; }
; __device__ void scan_gla(const Ctx& c, int idx) {
;     ...
;     for (int ck = 0; ck < NCH; ++ck) { u32x2* ad = (u32x2*)(gSt + (size_t)ck * 131072 + e4);
;         const f32x4 st = up4(__builtin_nontemporal_load(ad)); const f32x4 d = *(const f32x4*)(gDec + (size_t)ck * 512 + h * 128 + k4);
;         __builtin_nontemporal_store(pk4(S), ad); S = S * d + st; }
	v_cvt_pk_bf16_f32 v8, v4, v5
	v_cvt_pk_bf16_f32 v9, v6, v7
	global_store_dwordx2 v1, v[8:9], s[12:13] nt
	s_add_u32 s12, s12, 0x40000
	s_addc_u32 s13, s13, 0
	v_lshlrev_b32_e32 v10, 16, v16
	v_and_b32_e32 v11, 0xffff0000, v16
	v_lshlrev_b32_e32 v12, 16, v17
	v_and_b32_e32 v13, 0xffff0000, v17
	v_fma_f32 v4, v4, v32, v10
	v_fma_f32 v5, v5, v33, v11
	v_fma_f32 v6, v6, v34, v12
	v_fma_f32 v7, v7, v35, v13
	v_cvt_pk_bf16_f32 v14, v4, v5
	v_cvt_pk_bf16_f32 v15, v6, v7
	global_store_dwordx2 v1, v[14:15], s[12:13] nt
	s_add_u32 s12, s12, 0x40000
	s_addc_u32 s13, s13, 0
	v_lshlrev_b32_e32 v10, 16, v18
	v_and_b32_e32 v11, 0xffff0000, v18
	v_lshlrev_b32_e32 v12, 16, v19
	v_and_b32_e32 v13, 0xffff0000, v19
	v_fma_f32 v4, v4, v36, v10
	v_fma_f32 v5, v5, v37, v11
	v_fma_f32 v6, v6, v38, v12
	v_fma_f32 v7, v7, v39, v13
	v_cvt_pk_bf16_f32 v8, v4, v5
	v_cvt_pk_bf16_f32 v9, v6, v7
	global_store_dwordx2 v1, v[8:9], s[12:13] nt
	s_add_u32 s12, s12, 0x40000
	s_addc_u32 s13, s13, 0
	v_lshlrev_b32_e32 v10, 16, v20
	v_and_b32_e32 v11, 0xffff0000, v20
	v_lshlrev_b32_e32 v12, 16, v21
	v_and_b32_e32 v13, 0xffff0000, v21
	v_fma_f32 v4, v4, v40, v10
	v_fma_f32 v5, v5, v41, v11
	v_fma_f32 v6, v6, v42, v12
	v_fma_f32 v7, v7, v43, v13
	v_cvt_pk_bf16_f32 v14, v4, v5
	v_cvt_pk_bf16_f32 v15, v6, v7
	global_store_dwordx2 v1, v[14:15], s[12:13] nt
	s_add_u32 s12, s12, 0x40000
	s_addc_u32 s13, s13, 0
	v_lshlrev_b32_e32 v10, 16, v22
	v_and_b32_e32 v11, 0xffff0000, v22
	v_lshlrev_b32_e32 v12, 16, v23
	v_and_b32_e32 v13, 0xffff0000, v23
	v_fma_f32 v4, v4, v44, v10
	v_fma_f32 v5, v5, v45, v11
	v_fma_f32 v6, v6, v46, v12
	v_fma_f32 v7, v7, v47, v13
	v_cvt_pk_bf16_f32 v8, v4, v5
	v_cvt_pk_bf16_f32 v9, v6, v7
	global_store_dwordx2 v1, v[8:9], s[12:13] nt
	s_add_u32 s12, s12, 0x40000
	s_addc_u32 s13, s13, 0
	v_lshlrev_b32_e32 v10, 16, v24
	v_and_b32_e32 v11, 0xffff0000, v24
	v_lshlrev_b32_e32 v12, 16, v25
	v_and_b32_e32 v13, 0xffff0000, v25
	v_fma_f32 v4, v4, v48, v10
	v_fma_f32 v5, v5, v49, v11
	v_fma_f32 v6, v6, v50, v12
	v_fma_f32 v7, v7, v51, v13
	v_cvt_pk_bf16_f32 v14, v4, v5
	v_cvt_pk_bf16_f32 v15, v6, v7
	global_store_dwordx2 v1, v[14:15], s[12:13] nt
	s_add_u32 s12, s12, 0x40000
	s_addc_u32 s13, s13, 0
	v_lshlrev_b32_e32 v10, 16, v26
	v_and_b32_e32 v11, 0xffff0000, v26
	v_lshlrev_b32_e32 v12, 16, v27
	v_and_b32_e32 v13, 0xffff0000, v27
	v_fma_f32 v4, v4, v52, v10
	v_fma_f32 v5, v5, v53, v11
	v_fma_f32 v6, v6, v54, v12
	v_fma_f32 v7, v7, v55, v13
	v_cvt_pk_bf16_f32 v8, v4, v5
	v_cvt_pk_bf16_f32 v9, v6, v7
	global_store_dwordx2 v1, v[8:9], s[12:13] nt
	s_add_u32 s12, s12, 0x40000
	s_addc_u32 s13, s13, 0
	v_lshlrev_b32_e32 v10, 16, v28
	v_and_b32_e32 v11, 0xffff0000, v28
	v_lshlrev_b32_e32 v12, 16, v29
	v_and_b32_e32 v13, 0xffff0000, v29
	v_fma_f32 v4, v4, v56, v10
	v_fma_f32 v5, v5, v57, v11
	v_fma_f32 v6, v6, v58, v12
	v_fma_f32 v7, v7, v59, v13
	v_cvt_pk_bf16_f32 v14, v4, v5
	v_cvt_pk_bf16_f32 v15, v6, v7
	global_store_dwordx2 v1, v[14:15], s[12:13] nt
	s_add_u32 s12, s12, 0x40000
	s_addc_u32 s13, s13, 0
	v_lshlrev_b32_e32 v10, 16, v30
	v_and_b32_e32 v11, 0xffff0000, v30
	v_lshlrev_b32_e32 v12, 16, v31
	v_and_b32_e32 v13, 0xffff0000, v31
	v_fma_f32 v4, v4, v60, v10
	v_fma_f32 v5, v5, v61, v11
	v_fma_f32 v6, v6, v62, v12
	v_fma_f32 v7, v7, v63, v13
	global_load_dwordx2 v[16:17], v1, s[6:7] nt
	global_load_dwordx4 v[32:35], v2, s[8:9] offset:0
	s_add_u32 s6, s6, 0x40000
	s_addc_u32 s7, s7, 0
	global_load_dwordx2 v[18:19], v1, s[6:7] nt
	global_load_dwordx4 v[36:39], v2, s[8:9] offset:2048
	s_add_u32 s8, s8, 0x1000
	s_addc_u32 s9, s9, 0
	s_add_u32 s6, s6, 0x40000
	s_addc_u32 s7, s7, 0
	global_load_dwordx2 v[20:21], v1, s[6:7] nt
	global_load_dwordx4 v[40:43], v2, s[8:9] offset:0
	s_add_u32 s6, s6, 0x40000
	s_addc_u32 s7, s7, 0
	global_load_dwordx2 v[22:23], v1, s[6:7] nt
	global_load_dwordx4 v[44:47], v2, s[8:9] offset:2048
	s_add_u32 s8, s8, 0x1000
	s_addc_u32 s9, s9, 0
	s_add_u32 s6, s6, 0x40000
	s_addc_u32 s7, s7, 0
	global_load_dwordx2 v[24:25], v1, s[6:7] nt
	global_load_dwordx4 v[48:51], v2, s[8:9] offset:0
	s_add_u32 s6, s6, 0x40000
	s_addc_u32 s7, s7, 0
	global_load_dwordx2 v[26:27], v1, s[6:7] nt
	global_load_dwordx4 v[52:55], v2, s[8:9] offset:2048
	s_add_u32 s8, s8, 0x1000
	s_addc_u32 s9, s9, 0
	s_add_u32 s6, s6, 0x40000
	s_addc_u32 s7, s7, 0
	global_load_dwordx2 v[28:29], v1, s[6:7] nt
	global_load_dwordx4 v[56:59], v2, s[8:9] offset:0
	s_add_u32 s6, s6, 0x40000
	s_addc_u32 s7, s7, 0
	global_load_dwordx2 v[30:31], v1, s[6:7] nt
	global_load_dwordx4 v[60:63], v2, s[8:9] offset:2048
	s_add_u32 s8, s8, 0x1000
	s_addc_u32 s9, s9, 0
	s_add_u32 s6, s6, 0x40000
	s_addc_u32 s7, s7, 0
	s_waitcnt vmcnt(24)
; __device__ __forceinline__ u32x2 pk4(f32x4 v) { u32x2 r; r.x = pk2(v[0], v[1]); r.y = pk2(v[2], v[3]); return r; }
; __device__ __forceinline__ f32x4 up4(u32x2 u) { return (f32x4){lo16(u.x), hi16(u.x), lo16(u.y), hi16(u.y)}; }
; __device__ void scan_gla(const Ctx& c, int idx) {
;     ...
;     for (int ck = 0; ck < NCH; ++ck) { u32x2* ad = (u32x2*)(gSt + (size_t)ck * 131072 + e4);
;         const f32x4 st = up4(__builtin_nontemporal_load(ad)); const f32x4 d = *(const f32x4*)(gDec + (size_t)ck * 512 + h * 128 + k4);
;         __builtin_nontemporal_store(pk4(S), ad); S = S * d + st; }
	v_cvt_pk_bf16_f32 v8, v4, v5
	v_cvt_pk_bf16_f32 v9, v6, v7
	global_store_dwordx2 v1, v[8:9], s[12:13] nt
	s_add_u32 s12, s12, 0x40000
	s_addc_u32 s13, s13, 0
	v_lshlrev_b32_e32 v10, 16, v64
	v_and_b32_e32 v11, 0xffff0000, v64
	v_lshlrev_b32_e32 v12, 16, v65
	v_and_b32_e32 v13, 0xffff0000, v65
	v_fma_f32 v4, v4, v80, v10
	v_fma_f32 v5, v5, v81, v11
	v_fma_f32 v6, v6, v82, v12
	v_fma_f32 v7, v7, v83, v13
	v_cvt_pk_bf16_f32 v14, v4, v5
	v_cvt_pk_bf16_f32 v15, v6, v7
	global_store_dwordx2 v1, v[14:15], s[12:13] nt
	s_add_u32 s12, s12, 0x40000
	s_addc_u32 s13, s13, 0
	v_lshlrev_b32_e32 v10, 16, v66
	v_and_b32_e32 v11, 0xffff0000, v66
	v_lshlrev_b32_e32 v12, 16, v67
	v_and_b32_e32 v13, 0xffff0000, v67
	v_fma_f32 v4, v4, v84, v10
	v_fma_f32 v5, v5, v85, v11
	v_fma_f32 v6, v6, v86, v12
	v_fma_f32 v7, v7, v87, v13
	v_cvt_pk_bf16_f32 v8, v4, v5
	v_cvt_pk_bf16_f32 v9, v6, v7
	global_store_dwordx2 v1, v[8:9], s[12:13] nt
	s_add_u32 s12, s12, 0x40000
	s_addc_u32 s13, s13, 0
	v_lshlrev_b32_e32 v10, 16, v68
	v_and_b32_e32 v11, 0xffff0000, v68
	v_lshlrev_b32_e32 v12, 16, v69
	v_and_b32_e32 v13, 0xffff0000, v69
	v_fma_f32 v4, v4, v88, v10
	v_fma_f32 v5, v5, v89, v11
	v_fma_f32 v6, v6, v90, v12
	v_fma_f32 v7, v7, v91, v13
	v_cvt_pk_bf16_f32 v14, v4, v5
	v_cvt_pk_bf16_f32 v15, v6, v7
	global_store_dwordx2 v1, v[14:15], s[12:13] nt
	s_add_u32 s12, s12, 0x40000
	s_addc_u32 s13, s13, 0
	v_lshlrev_b32_e32 v10, 16, v70
	v_and_b32_e32 v11, 0xffff0000, v70
	v_lshlrev_b32_e32 v12, 16, v71
	v_and_b32_e32 v13, 0xffff0000, v71
	v_fma_f32 v4, v4, v92, v10
	v_fma_f32 v5, v5, v93, v11
	v_fma_f32 v6, v6, v94, v12
	v_fma_f32 v7, v7, v95, v13
	v_cvt_pk_bf16_f32 v8, v4, v5
	v_cvt_pk_bf16_f32 v9, v6, v7
	global_store_dwordx2 v1, v[8:9], s[12:13] nt
	s_add_u32 s12, s12, 0x40000
	s_addc_u32 s13, s13, 0
	v_lshlrev_b32_e32 v10, 16, v72
	v_and_b32_e32 v11, 0xffff0000, v72
	v_lshlrev_b32_e32 v12, 16, v73
	v_and_b32_e32 v13, 0xffff0000, v73
	v_fma_f32 v4, v4, v96, v10
	v_fma_f32 v5, v5, v97, v11
	v_fma_f32 v6, v6, v98, v12
	v_fma_f32 v7, v7, v99, v13
	v_cvt_pk_bf16_f32 v14, v4, v5
	v_cvt_pk_bf16_f32 v15, v6, v7
	global_store_dwordx2 v1, v[14:15], s[12:13] nt
	s_add_u32 s12, s12, 0x40000
	s_addc_u32 s13, s13, 0
	v_lshlrev_b32_e32 v10, 16, v74
	v_and_b32_e32 v11, 0xffff0000, v74
	v_lshlrev_b32_e32 v12, 16, v75
	v_and_b32_e32 v13, 0xffff0000, v75
	v_fma_f32 v4, v4, v100, v10
	v_fma_f32 v5, v5, v101, v11
	v_fma_f32 v6, v6, v102, v12
	v_fma_f32 v7, v7, v103, v13
	v_cvt_pk_bf16_f32 v8, v4, v5
	v_cvt_pk_bf16_f32 v9, v6, v7
	global_store_dwordx2 v1, v[8:9], s[12:13] nt
	s_add_u32 s12, s12, 0x40000
	s_addc_u32 s13, s13, 0
	v_lshlrev_b32_e32 v10, 16, v76
	v_and_b32_e32 v11, 0xffff0000, v76
	v_lshlrev_b32_e32 v12, 16, v77
	v_and_b32_e32 v13, 0xffff0000, v77
	v_fma_f32 v4, v4, v104, v10
	v_fma_f32 v5, v5, v105, v11
	v_fma_f32 v6, v6, v106, v12
	v_fma_f32 v7, v7, v107, v13
	v_cvt_pk_bf16_f32 v14, v4, v5
	v_cvt_pk_bf16_f32 v15, v6, v7
	global_store_dwordx2 v1, v[14:15], s[12:13] nt
	s_add_u32 s12, s12, 0x40000
	s_addc_u32 s13, s13, 0
	v_lshlrev_b32_e32 v10, 16, v78
	v_and_b32_e32 v11, 0xffff0000, v78
	v_lshlrev_b32_e32 v12, 16, v79
	v_and_b32_e32 v13, 0xffff0000, v79
	v_fma_f32 v4, v4, v108, v10
	v_fma_f32 v5, v5, v109, v11
	v_fma_f32 v6, v6, v110, v12
	v_fma_f32 v7, v7, v111, v13
	global_load_dwordx2 v[64:65], v1, s[6:7] nt
	global_load_dwordx4 v[80:83], v2, s[8:9] offset:0
	s_add_u32 s6, s6, 0x40000
	s_addc_u32 s7, s7, 0
	global_load_dwordx2 v[66:67], v1, s[6:7] nt
	global_load_dwordx4 v[84:87], v2, s[8:9] offset:2048
	s_add_u32 s8, s8, 0x1000
	s_addc_u32 s9, s9, 0
	s_add_u32 s6, s6, 0x40000
	s_addc_u32 s7, s7, 0
	global_load_dwordx2 v[68:69], v1, s[6:7] nt
	global_load_dwordx4 v[88:91], v2, s[8:9] offset:0
	s_add_u32 s6, s6, 0x40000
	s_addc_u32 s7, s7, 0
	global_load_dwordx2 v[70:71], v1, s[6:7] nt
	global_load_dwordx4 v[92:95], v2, s[8:9] offset:2048
	s_add_u32 s8, s8, 0x1000
	s_addc_u32 s9, s9, 0
	s_add_u32 s6, s6, 0x40000
	s_addc_u32 s7, s7, 0
	global_load_dwordx2 v[72:73], v1, s[6:7] nt
	global_load_dwordx4 v[96:99], v2, s[8:9] offset:0
	s_add_u32 s6, s6, 0x40000
	s_addc_u32 s7, s7, 0
	global_load_dwordx2 v[74:75], v1, s[6:7] nt
	global_load_dwordx4 v[100:103], v2, s[8:9] offset:2048
	s_add_u32 s8, s8, 0x1000
	s_addc_u32 s9, s9, 0
	s_add_u32 s6, s6, 0x40000
	s_addc_u32 s7, s7, 0
	global_load_dwordx2 v[76:77], v1, s[6:7] nt
	global_load_dwordx4 v[104:107], v2, s[8:9] offset:0
	s_add_u32 s6, s6, 0x40000
	s_addc_u32 s7, s7, 0
	global_load_dwordx2 v[78:79], v1, s[6:7] nt
	global_load_dwordx4 v[108:111], v2, s[8:9] offset:2048
	s_add_u32 s8, s8, 0x1000
	s_addc_u32 s9, s9, 0
	s_add_u32 s6, s6, 0x40000
	s_addc_u32 s7, s7, 0
	s_waitcnt vmcnt(24)
; __device__ __forceinline__ u32x2 pk4(f32x4 v) { u32x2 r; r.x = pk2(v[0], v[1]); r.y = pk2(v[2], v[3]); return r; }
; __device__ __forceinline__ f32x4 up4(u32x2 u) { return (f32x4){lo16(u.x), hi16(u.x), lo16(u.y), hi16(u.y)}; }
; __device__ void scan_gla(const Ctx& c, int idx) {
;     ...
;     for (int ck = 0; ck < NCH; ++ck) { u32x2* ad = (u32x2*)(gSt + (size_t)ck * 131072 + e4);
;         const f32x4 st = up4(__builtin_nontemporal_load(ad)); const f32x4 d = *(const f32x4*)(gDec + (size_t)ck * 512 + h * 128 + k4);
;         __builtin_nontemporal_store(pk4(S), ad); S = S * d + st; }
	v_cvt_pk_bf16_f32 v8, v4, v5
	v_cvt_pk_bf16_f32 v9, v6, v7
	global_store_dwordx2 v1, v[8:9], s[12:13] nt
	s_add_u32 s12, s12, 0x40000
	s_addc_u32 s13, s13, 0
	v_lshlrev_b32_e32 v10, 16, v16
	v_and_b32_e32 v11, 0xffff0000, v16
	v_lshlrev_b32_e32 v12, 16, v17
	v_and_b32_e32 v13, 0xffff0000, v17
	v_fma_f32 v4, v4, v32, v10
	v_fma_f32 v5, v5, v33, v11
	v_fma_f32 v6, v6, v34, v12
	v_fma_f32 v7, v7, v35, v13
	v_cvt_pk_bf16_f32 v14, v4, v5
	v_cvt_pk_bf16_f32 v15, v6, v7
	global_store_dwordx2 v1, v[14:15], s[12:13] nt
	s_add_u32 s12, s12, 0x40000
	s_addc_u32 s13, s13, 0
	v_lshlrev_b32_e32 v10, 16, v18
	v_and_b32_e32 v11, 0xffff0000, v18
	v_lshlrev_b32_e32 v12, 16, v19
	v_and_b32_e32 v13, 0xffff0000, v19
	v_fma_f32 v4, v4, v36, v10
	v_fma_f32 v5, v5, v37, v11
	v_fma_f32 v6, v6, v38, v12
	v_fma_f32 v7, v7, v39, v13
	v_cvt_pk_bf16_f32 v8, v4, v5
	v_cvt_pk_bf16_f32 v9, v6, v7
	global_store_dwordx2 v1, v[8:9], s[12:13] nt
	s_add_u32 s12, s12, 0x40000
	s_addc_u32 s13, s13, 0
	v_lshlrev_b32_e32 v10, 16, v20
	v_and_b32_e32 v11, 0xffff0000, v20
	v_lshlrev_b32_e32 v12, 16, v21
	v_and_b32_e32 v13, 0xffff0000, v21
	v_fma_f32 v4, v4, v40, v10
	v_fma_f32 v5, v5, v41, v11
	v_fma_f32 v6, v6, v42, v12
	v_fma_f32 v7, v7, v43, v13
	v_cvt_pk_bf16_f32 v14, v4, v5
	v_cvt_pk_bf16_f32 v15, v6, v7
	global_store_dwordx2 v1, v[14:15], s[12:13] nt
	s_add_u32 s12, s12, 0x40000
	s_addc_u32 s13, s13, 0
	v_lshlrev_b32_e32 v10, 16, v22
	v_and_b32_e32 v11, 0xffff0000, v22
	v_lshlrev_b32_e32 v12, 16, v23
	v_and_b32_e32 v13, 0xffff0000, v23
	v_fma_f32 v4, v4, v44, v10
	v_fma_f32 v5, v5, v45, v11
	v_fma_f32 v6, v6, v46, v12
	v_fma_f32 v7, v7, v47, v13
	v_cvt_pk_bf16_f32 v8, v4, v5
	v_cvt_pk_bf16_f32 v9, v6, v7
	global_store_dwordx2 v1, v[8:9], s[12:13] nt
	s_add_u32 s12, s12, 0x40000
	s_addc_u32 s13, s13, 0
	v_lshlrev_b32_e32 v10, 16, v24
	v_and_b32_e32 v11, 0xffff0000, v24
	v_lshlrev_b32_e32 v12, 16, v25
	v_and_b32_e32 v13, 0xffff0000, v25
	v_fma_f32 v4, v4, v48, v10
	v_fma_f32 v5, v5, v49, v11
	v_fma_f32 v6, v6, v50, v12
	v_fma_f32 v7, v7, v51, v13
	v_cvt_pk_bf16_f32 v14, v4, v5
	v_cvt_pk_bf16_f32 v15, v6, v7
	global_store_dwordx2 v1, v[14:15], s[12:13] nt
	s_add_u32 s12, s12, 0x40000
	s_addc_u32 s13, s13, 0
	v_lshlrev_b32_e32 v10, 16, v26
	v_and_b32_e32 v11, 0xffff0000, v26
	v_lshlrev_b32_e32 v12, 16, v27
	v_and_b32_e32 v13, 0xffff0000, v27
	v_fma_f32 v4, v4, v52, v10
	v_fma_f32 v5, v5, v53, v11
	v_fma_f32 v6, v6, v54, v12
	v_fma_f32 v7, v7, v55, v13
	v_cvt_pk_bf16_f32 v8, v4, v5
	v_cvt_pk_bf16_f32 v9, v6, v7
	global_store_dwordx2 v1, v[8:9], s[12:13] nt
	s_add_u32 s12, s12, 0x40000
	s_addc_u32 s13, s13, 0
	v_lshlrev_b32_e32 v10, 16, v28
	v_and_b32_e32 v11, 0xffff0000, v28
	v_lshlrev_b32_e32 v12, 16, v29
	v_and_b32_e32 v13, 0xffff0000, v29
	v_fma_f32 v4, v4, v56, v10
	v_fma_f32 v5, v5, v57, v11
	v_fma_f32 v6, v6, v58, v12
	v_fma_f32 v7, v7, v59, v13
	v_cvt_pk_bf16_f32 v14, v4, v5
	v_cvt_pk_bf16_f32 v15, v6, v7
	global_store_dwordx2 v1, v[14:15], s[12:13] nt
	s_add_u32 s12, s12, 0x40000
	s_addc_u32 s13, s13, 0
	v_lshlrev_b32_e32 v10, 16, v30
	v_and_b32_e32 v11, 0xffff0000, v30
	v_lshlrev_b32_e32 v12, 16, v31
	v_and_b32_e32 v13, 0xffff0000, v31
	v_fma_f32 v4, v4, v60, v10
	v_fma_f32 v5, v5, v61, v11
	v_fma_f32 v6, v6, v62, v12
	v_fma_f32 v7, v7, v63, v13
	global_load_dwordx2 v[16:17], v1, s[6:7] nt
	global_load_dwordx4 v[32:35], v2, s[8:9] offset:0
	s_add_u32 s6, s6, 0x40000
	s_addc_u32 s7, s7, 0
	global_load_dwordx2 v[18:19], v1, s[6:7] nt
	global_load_dwordx4 v[36:39], v2, s[8:9] offset:2048
	s_add_u32 s8, s8, 0x1000
	s_addc_u32 s9, s9, 0
	s_add_u32 s6, s6, 0x40000
	s_addc_u32 s7, s7, 0
	global_load_dwordx2 v[20:21], v1, s[6:7] nt
	global_load_dwordx4 v[40:43], v2, s[8:9] offset:0
	s_add_u32 s6, s6, 0x40000
	s_addc_u32 s7, s7, 0
	global_load_dwordx2 v[22:23], v1, s[6:7] nt
	global_load_dwordx4 v[44:47], v2, s[8:9] offset:2048
	s_add_u32 s8, s8, 0x1000
	s_addc_u32 s9, s9, 0
	s_add_u32 s6, s6, 0x40000
	s_addc_u32 s7, s7, 0
	global_load_dwordx2 v[24:25], v1, s[6:7] nt
	global_load_dwordx4 v[48:51], v2, s[8:9] offset:0
	s_add_u32 s6, s6, 0x40000
	s_addc_u32 s7, s7, 0
	global_load_dwordx2 v[26:27], v1, s[6:7] nt
	global_load_dwordx4 v[52:55], v2, s[8:9] offset:2048
	s_add_u32 s8, s8, 0x1000
	s_addc_u32 s9, s9, 0
	s_add_u32 s6, s6, 0x40000
	s_addc_u32 s7, s7, 0
	global_load_dwordx2 v[28:29], v1, s[6:7] nt
	global_load_dwordx4 v[56:59], v2, s[8:9] offset:0
	s_add_u32 s6, s6, 0x40000
	s_addc_u32 s7, s7, 0
	global_load_dwordx2 v[30:31], v1, s[6:7] nt
	global_load_dwordx4 v[60:63], v2, s[8:9] offset:2048
	s_add_u32 s8, s8, 0x1000
	s_addc_u32 s9, s9, 0
	s_add_u32 s6, s6, 0x40000
	s_addc_u32 s7, s7, 0
	s_waitcnt vmcnt(24)
; __device__ __forceinline__ u32x2 pk4(f32x4 v) { u32x2 r; r.x = pk2(v[0], v[1]); r.y = pk2(v[2], v[3]); return r; }
; __device__ __forceinline__ f32x4 up4(u32x2 u) { return (f32x4){lo16(u.x), hi16(u.x), lo16(u.y), hi16(u.y)}; }
; __device__ void scan_gla(const Ctx& c, int idx) {
;     ...
;     for (int ck = 0; ck < NCH; ++ck) { u32x2* ad = (u32x2*)(gSt + (size_t)ck * 131072 + e4);
;         const f32x4 st = up4(__builtin_nontemporal_load(ad)); const f32x4 d = *(const f32x4*)(gDec + (size_t)ck * 512 + h * 128 + k4);
;         __builtin_nontemporal_store(pk4(S), ad); S = S * d + st; }
	v_cvt_pk_bf16_f32 v8, v4, v5
	v_cvt_pk_bf16_f32 v9, v6, v7
	global_store_dwordx2 v1, v[8:9], s[12:13] nt
	s_add_u32 s12, s12, 0x40000
	s_addc_u32 s13, s13, 0
	v_lshlrev_b32_e32 v10, 16, v64
	v_and_b32_e32 v11, 0xffff0000, v64
	v_lshlrev_b32_e32 v12, 16, v65
	v_and_b32_e32 v13, 0xffff0000, v65
	v_fma_f32 v4, v4, v80, v10
	v_fma_f32 v5, v5, v81, v11
	v_fma_f32 v6, v6, v82, v12
	v_fma_f32 v7, v7, v83, v13
	v_cvt_pk_bf16_f32 v14, v4, v5
	v_cvt_pk_bf16_f32 v15, v6, v7
	global_store_dwordx2 v1, v[14:15], s[12:13] nt
	s_add_u32 s12, s12, 0x40000
	s_addc_u32 s13, s13, 0
	v_lshlrev_b32_e32 v10, 16, v66
	v_and_b32_e32 v11, 0xffff0000, v66
	v_lshlrev_b32_e32 v12, 16, v67
	v_and_b32_e32 v13, 0xffff0000, v67
	v_fma_f32 v4, v4, v84, v10
	v_fma_f32 v5, v5, v85, v11
	v_fma_f32 v6, v6, v86, v12
	v_fma_f32 v7, v7, v87, v13
	v_cvt_pk_bf16_f32 v8, v4, v5
	v_cvt_pk_bf16_f32 v9, v6, v7
	global_store_dwordx2 v1, v[8:9], s[12:13] nt
	s_add_u32 s12, s12, 0x40000
	s_addc_u32 s13, s13, 0
	v_lshlrev_b32_e32 v10, 16, v68
	v_and_b32_e32 v11, 0xffff0000, v68
	v_lshlrev_b32_e32 v12, 16, v69
	v_and_b32_e32 v13, 0xffff0000, v69
	v_fma_f32 v4, v4, v88, v10
	v_fma_f32 v5, v5, v89, v11
	v_fma_f32 v6, v6, v90, v12
	v_fma_f32 v7, v7, v91, v13
	v_cvt_pk_bf16_f32 v14, v4, v5
	v_cvt_pk_bf16_f32 v15, v6, v7
	global_store_dwordx2 v1, v[14:15], s[12:13] nt
	s_add_u32 s12, s12, 0x40000
	s_addc_u32 s13, s13, 0
	v_lshlrev_b32_e32 v10, 16, v70
	v_and_b32_e32 v11, 0xffff0000, v70
	v_lshlrev_b32_e32 v12, 16, v71
	v_and_b32_e32 v13, 0xffff0000, v71
	v_fma_f32 v4, v4, v92, v10
	v_fma_f32 v5, v5, v93, v11
	v_fma_f32 v6, v6, v94, v12
	v_fma_f32 v7, v7, v95, v13
	v_cvt_pk_bf16_f32 v8, v4, v5
	v_cvt_pk_bf16_f32 v9, v6, v7
	global_store_dwordx2 v1, v[8:9], s[12:13] nt
	s_add_u32 s12, s12, 0x40000
	s_addc_u32 s13, s13, 0
	v_lshlrev_b32_e32 v10, 16, v72
	v_and_b32_e32 v11, 0xffff0000, v72
	v_lshlrev_b32_e32 v12, 16, v73
	v_and_b32_e32 v13, 0xffff0000, v73
	v_fma_f32 v4, v4, v96, v10
	v_fma_f32 v5, v5, v97, v11
	v_fma_f32 v6, v6, v98, v12
	v_fma_f32 v7, v7, v99, v13
	v_cvt_pk_bf16_f32 v14, v4, v5
	v_cvt_pk_bf16_f32 v15, v6, v7
	global_store_dwordx2 v1, v[14:15], s[12:13] nt
	s_add_u32 s12, s12, 0x40000
	s_addc_u32 s13, s13, 0
	v_lshlrev_b32_e32 v10, 16, v74
	v_and_b32_e32 v11, 0xffff0000, v74
	v_lshlrev_b32_e32 v12, 16, v75
	v_and_b32_e32 v13, 0xffff0000, v75
	v_fma_f32 v4, v4, v100, v10
	v_fma_f32 v5, v5, v101, v11
	v_fma_f32 v6, v6, v102, v12
	v_fma_f32 v7, v7, v103, v13
	v_cvt_pk_bf16_f32 v8, v4, v5
	v_cvt_pk_bf16_f32 v9, v6, v7
	global_store_dwordx2 v1, v[8:9], s[12:13] nt
	s_add_u32 s12, s12, 0x40000
	s_addc_u32 s13, s13, 0
	v_lshlrev_b32_e32 v10, 16, v76
	v_and_b32_e32 v11, 0xffff0000, v76
	v_lshlrev_b32_e32 v12, 16, v77
	v_and_b32_e32 v13, 0xffff0000, v77
	v_fma_f32 v4, v4, v104, v10
	v_fma_f32 v5, v5, v105, v11
	v_fma_f32 v6, v6, v106, v12
	v_fma_f32 v7, v7, v107, v13
	v_cvt_pk_bf16_f32 v14, v4, v5
	v_cvt_pk_bf16_f32 v15, v6, v7
	global_store_dwordx2 v1, v[14:15], s[12:13] nt
	s_add_u32 s12, s12, 0x40000
	s_addc_u32 s13, s13, 0
	v_lshlrev_b32_e32 v10, 16, v78
	v_and_b32_e32 v11, 0xffff0000, v78
	v_lshlrev_b32_e32 v12, 16, v79
	v_and_b32_e32 v13, 0xffff0000, v79
	v_fma_f32 v4, v4, v108, v10
	v_fma_f32 v5, v5, v109, v11
	v_fma_f32 v6, v6, v110, v12
	v_fma_f32 v7, v7, v111, v13
	global_load_dwordx2 v[64:65], v1, s[6:7] nt
	global_load_dwordx4 v[80:83], v2, s[8:9] offset:0
	s_add_u32 s6, s6, 0x40000
	s_addc_u32 s7, s7, 0
	global_load_dwordx2 v[66:67], v1, s[6:7] nt
	global_load_dwordx4 v[84:87], v2, s[8:9] offset:2048
	s_add_u32 s8, s8, 0x1000
	s_addc_u32 s9, s9, 0
	s_add_u32 s6, s6, 0x40000
	s_addc_u32 s7, s7, 0
	global_load_dwordx2 v[68:69], v1, s[6:7] nt
	global_load_dwordx4 v[88:91], v2, s[8:9] offset:0
	s_add_u32 s6, s6, 0x40000
	s_addc_u32 s7, s7, 0
	global_load_dwordx2 v[70:71], v1, s[6:7] nt
	global_load_dwordx4 v[92:95], v2, s[8:9] offset:2048
	s_add_u32 s8, s8, 0x1000
	s_addc_u32 s9, s9, 0
	s_add_u32 s6, s6, 0x40000
	s_addc_u32 s7, s7, 0
	global_load_dwordx2 v[72:73], v1, s[6:7] nt
	global_load_dwordx4 v[96:99], v2, s[8:9] offset:0
	s_add_u32 s6, s6, 0x40000
	s_addc_u32 s7, s7, 0
	global_load_dwordx2 v[74:75], v1, s[6:7] nt
	global_load_dwordx4 v[100:103], v2, s[8:9] offset:2048
	s_add_u32 s8, s8, 0x1000
	s_addc_u32 s9, s9, 0
	s_add_u32 s6, s6, 0x40000
	s_addc_u32 s7, s7, 0
	global_load_dwordx2 v[76:77], v1, s[6:7] nt
	global_load_dwordx4 v[104:107], v2, s[8:9] offset:0
	s_add_u32 s6, s6, 0x40000
	s_addc_u32 s7, s7, 0
	global_load_dwordx2 v[78:79], v1, s[6:7] nt
	global_load_dwordx4 v[108:111], v2, s[8:9] offset:2048
	s_add_u32 s8, s8, 0x1000
	s_addc_u32 s9, s9, 0
	s_add_u32 s6, s6, 0x40000
	s_addc_u32 s7, s7, 0
	s_waitcnt vmcnt(24)
; __device__ __forceinline__ u32x2 pk4(f32x4 v) { u32x2 r; r.x = pk2(v[0], v[1]); r.y = pk2(v[2], v[3]); return r; }
; __device__ __forceinline__ f32x4 up4(u32x2 u) { return (f32x4){lo16(u.x), hi16(u.x), lo16(u.y), hi16(u.y)}; }
; __device__ void scan_gla(const Ctx& c, int idx) {
;     ...
;     for (int ck = 0; ck < NCH; ++ck) { u32x2* ad = (u32x2*)(gSt + (size_t)ck * 131072 + e4);
;         const f32x4 st = up4(__builtin_nontemporal_load(ad)); const f32x4 d = *(const f32x4*)(gDec + (size_t)ck * 512 + h * 128 + k4);
;         __builtin_nontemporal_store(pk4(S), ad); S = S * d + st; }
	v_cvt_pk_bf16_f32 v8, v4, v5
	v_cvt_pk_bf16_f32 v9, v6, v7
	global_store_dwordx2 v1, v[8:9], s[12:13] nt
	s_add_u32 s12, s12, 0x40000
	s_addc_u32 s13, s13, 0
	v_lshlrev_b32_e32 v10, 16, v16
	v_and_b32_e32 v11, 0xffff0000, v16
	v_lshlrev_b32_e32 v12, 16, v17
	v_and_b32_e32 v13, 0xffff0000, v17
	v_fma_f32 v4, v4, v32, v10
	v_fma_f32 v5, v5, v33, v11
	v_fma_f32 v6, v6, v34, v12
	v_fma_f32 v7, v7, v35, v13
	v_cvt_pk_bf16_f32 v14, v4, v5
	v_cvt_pk_bf16_f32 v15, v6, v7
	global_store_dwordx2 v1, v[14:15], s[12:13] nt
	s_add_u32 s12, s12, 0x40000
	s_addc_u32 s13, s13, 0
	v_lshlrev_b32_e32 v10, 16, v18
	v_and_b32_e32 v11, 0xffff0000, v18
	v_lshlrev_b32_e32 v12, 16, v19
	v_and_b32_e32 v13, 0xffff0000, v19
	v_fma_f32 v4, v4, v36, v10
	v_fma_f32 v5, v5, v37, v11
	v_fma_f32 v6, v6, v38, v12
	v_fma_f32 v7, v7, v39, v13
	v_cvt_pk_bf16_f32 v8, v4, v5
	v_cvt_pk_bf16_f32 v9, v6, v7
	global_store_dwordx2 v1, v[8:9], s[12:13] nt
	s_add_u32 s12, s12, 0x40000
	s_addc_u32 s13, s13, 0
	v_lshlrev_b32_e32 v10, 16, v20
	v_and_b32_e32 v11, 0xffff0000, v20
	v_lshlrev_b32_e32 v12, 16, v21
	v_and_b32_e32 v13, 0xffff0000, v21
	v_fma_f32 v4, v4, v40, v10
	v_fma_f32 v5, v5, v41, v11
	v_fma_f32 v6, v6, v42, v12
	v_fma_f32 v7, v7, v43, v13
	v_cvt_pk_bf16_f32 v14, v4, v5
	v_cvt_pk_bf16_f32 v15, v6, v7
	global_store_dwordx2 v1, v[14:15], s[12:13] nt
	s_add_u32 s12, s12, 0x40000
	s_addc_u32 s13, s13, 0
	v_lshlrev_b32_e32 v10, 16, v22
	v_and_b32_e32 v11, 0xffff0000, v22
	v_lshlrev_b32_e32 v12, 16, v23
	v_and_b32_e32 v13, 0xffff0000, v23
	v_fma_f32 v4, v4, v44, v10
	v_fma_f32 v5, v5, v45, v11
	v_fma_f32 v6, v6, v46, v12
	v_fma_f32 v7, v7, v47, v13
	v_cvt_pk_bf16_f32 v8, v4, v5
	v_cvt_pk_bf16_f32 v9, v6, v7
	global_store_dwordx2 v1, v[8:9], s[12:13] nt
	s_add_u32 s12, s12, 0x40000
	s_addc_u32 s13, s13, 0
	v_lshlrev_b32_e32 v10, 16, v24
	v_and_b32_e32 v11, 0xffff0000, v24
	v_lshlrev_b32_e32 v12, 16, v25
	v_and_b32_e32 v13, 0xffff0000, v25
	v_fma_f32 v4, v4, v48, v10
	v_fma_f32 v5, v5, v49, v11
	v_fma_f32 v6, v6, v50, v12
	v_fma_f32 v7, v7, v51, v13
	v_cvt_pk_bf16_f32 v14, v4, v5
	v_cvt_pk_bf16_f32 v15, v6, v7
	global_store_dwordx2 v1, v[14:15], s[12:13] nt
	s_add_u32 s12, s12, 0x40000
	s_addc_u32 s13, s13, 0
	v_lshlrev_b32_e32 v10, 16, v26
	v_and_b32_e32 v11, 0xffff0000, v26
	v_lshlrev_b32_e32 v12, 16, v27
	v_and_b32_e32 v13, 0xffff0000, v27
	v_fma_f32 v4, v4, v52, v10
	v_fma_f32 v5, v5, v53, v11
	v_fma_f32 v6, v6, v54, v12
	v_fma_f32 v7, v7, v55, v13
	v_cvt_pk_bf16_f32 v8, v4, v5
	v_cvt_pk_bf16_f32 v9, v6, v7
	global_store_dwordx2 v1, v[8:9], s[12:13] nt
	s_add_u32 s12, s12, 0x40000
	s_addc_u32 s13, s13, 0
	v_lshlrev_b32_e32 v10, 16, v28
	v_and_b32_e32 v11, 0xffff0000, v28
	v_lshlrev_b32_e32 v12, 16, v29
	v_and_b32_e32 v13, 0xffff0000, v29
	v_fma_f32 v4, v4, v56, v10
	v_fma_f32 v5, v5, v57, v11
	v_fma_f32 v6, v6, v58, v12
	v_fma_f32 v7, v7, v59, v13
	v_cvt_pk_bf16_f32 v14, v4, v5
	v_cvt_pk_bf16_f32 v15, v6, v7
	global_store_dwordx2 v1, v[14:15], s[12:13] nt
	s_add_u32 s12, s12, 0x40000
	s_addc_u32 s13, s13, 0
	v_lshlrev_b32_e32 v10, 16, v30
	v_and_b32_e32 v11, 0xffff0000, v30
	v_lshlrev_b32_e32 v12, 16, v31
	v_and_b32_e32 v13, 0xffff0000, v31
	v_fma_f32 v4, v4, v60, v10
	v_fma_f32 v5, v5, v61, v11
	v_fma_f32 v6, v6, v62, v12
	v_fma_f32 v7, v7, v63, v13
	global_load_dwordx2 v[16:17], v1, s[6:7] nt
	global_load_dwordx4 v[32:35], v2, s[8:9] offset:0
	s_add_u32 s6, s6, 0x40000
	s_addc_u32 s7, s7, 0
	global_load_dwordx2 v[18:19], v1, s[6:7] nt
	global_load_dwordx4 v[36:39], v2, s[8:9] offset:2048
	s_add_u32 s8, s8, 0x1000
	s_addc_u32 s9, s9, 0
	s_add_u32 s6, s6, 0x40000
	s_addc_u32 s7, s7, 0
	global_load_dwordx2 v[20:21], v1, s[6:7] nt
	global_load_dwordx4 v[40:43], v2, s[8:9] offset:0
	s_add_u32 s6, s6, 0x40000
	s_addc_u32 s7, s7, 0
	global_load_dwordx2 v[22:23], v1, s[6:7] nt
	global_load_dwordx4 v[44:47], v2, s[8:9] offset:2048
	s_add_u32 s8, s8, 0x1000
	s_addc_u32 s9, s9, 0
	s_add_u32 s6, s6, 0x40000
	s_addc_u32 s7, s7, 0
	global_load_dwordx2 v[24:25], v1, s[6:7] nt
	global_load_dwordx4 v[48:51], v2, s[8:9] offset:0
	s_add_u32 s6, s6, 0x40000
	s_addc_u32 s7, s7, 0
	global_load_dwordx2 v[26:27], v1, s[6:7] nt
	global_load_dwordx4 v[52:55], v2, s[8:9] offset:2048
	s_add_u32 s8, s8, 0x1000
	s_addc_u32 s9, s9, 0
	s_add_u32 s6, s6, 0x40000
	s_addc_u32 s7, s7, 0
	global_load_dwordx2 v[28:29], v1, s[6:7] nt
	global_load_dwordx4 v[56:59], v2, s[8:9] offset:0
	s_add_u32 s6, s6, 0x40000
	s_addc_u32 s7, s7, 0
	global_load_dwordx2 v[30:31], v1, s[6:7] nt
	global_load_dwordx4 v[60:63], v2, s[8:9] offset:2048
	s_add_u32 s8, s8, 0x1000
	s_addc_u32 s9, s9, 0
	s_add_u32 s6, s6, 0x40000
	s_addc_u32 s7, s7, 0
	s_waitcnt vmcnt(24)
; __device__ __forceinline__ u32x2 pk4(f32x4 v) { u32x2 r; r.x = pk2(v[0], v[1]); r.y = pk2(v[2], v[3]); return r; }
; __device__ __forceinline__ f32x4 up4(u32x2 u) { return (f32x4){lo16(u.x), hi16(u.x), lo16(u.y), hi16(u.y)}; }
; __device__ void scan_gla(const Ctx& c, int idx) {
;     ...
;     for (int ck = 0; ck < NCH; ++ck) { u32x2* ad = (u32x2*)(gSt + (size_t)ck * 131072 + e4);
;         const f32x4 st = up4(__builtin_nontemporal_load(ad)); const f32x4 d = *(const f32x4*)(gDec + (size_t)ck * 512 + h * 128 + k4);
;         __builtin_nontemporal_store(pk4(S), ad); S = S * d + st; }
	v_cvt_pk_bf16_f32 v8, v4, v5
	v_cvt_pk_bf16_f32 v9, v6, v7
	global_store_dwordx2 v1, v[8:9], s[12:13] nt
	s_add_u32 s12, s12, 0x40000
	s_addc_u32 s13, s13, 0
	v_lshlrev_b32_e32 v10, 16, v64
	v_and_b32_e32 v11, 0xffff0000, v64
	v_lshlrev_b32_e32 v12, 16, v65
	v_and_b32_e32 v13, 0xffff0000, v65
	v_fma_f32 v4, v4, v80, v10
	v_fma_f32 v5, v5, v81, v11
	v_fma_f32 v6, v6, v82, v12
	v_fma_f32 v7, v7, v83, v13
	v_cvt_pk_bf16_f32 v14, v4, v5
	v_cvt_pk_bf16_f32 v15, v6, v7
	global_store_dwordx2 v1, v[14:15], s[12:13] nt
	s_add_u32 s12, s12, 0x40000
	s_addc_u32 s13, s13, 0
	v_lshlrev_b32_e32 v10, 16, v66
	v_and_b32_e32 v11, 0xffff0000, v66
	v_lshlrev_b32_e32 v12, 16, v67
	v_and_b32_e32 v13, 0xffff0000, v67
	v_fma_f32 v4, v4, v84, v10
	v_fma_f32 v5, v5, v85, v11
	v_fma_f32 v6, v6, v86, v12
	v_fma_f32 v7, v7, v87, v13
	v_cvt_pk_bf16_f32 v8, v4, v5
	v_cvt_pk_bf16_f32 v9, v6, v7
	global_store_dwordx2 v1, v[8:9], s[12:13] nt
	s_add_u32 s12, s12, 0x40000
	s_addc_u32 s13, s13, 0
	v_lshlrev_b32_e32 v10, 16, v68
	v_and_b32_e32 v11, 0xffff0000, v68
	v_lshlrev_b32_e32 v12, 16, v69
	v_and_b32_e32 v13, 0xffff0000, v69
	v_fma_f32 v4, v4, v88, v10
	v_fma_f32 v5, v5, v89, v11
	v_fma_f32 v6, v6, v90, v12
	v_fma_f32 v7, v7, v91, v13
	v_cvt_pk_bf16_f32 v14, v4, v5
	v_cvt_pk_bf16_f32 v15, v6, v7
	global_store_dwordx2 v1, v[14:15], s[12:13] nt
	s_add_u32 s12, s12, 0x40000
	s_addc_u32 s13, s13, 0
	v_lshlrev_b32_e32 v10, 16, v70
	v_and_b32_e32 v11, 0xffff0000, v70
	v_lshlrev_b32_e32 v12, 16, v71
	v_and_b32_e32 v13, 0xffff0000, v71
	v_fma_f32 v4, v4, v92, v10
	v_fma_f32 v5, v5, v93, v11
	v_fma_f32 v6, v6, v94, v12
	v_fma_f32 v7, v7, v95, v13
	v_cvt_pk_bf16_f32 v8, v4, v5
	v_cvt_pk_bf16_f32 v9, v6, v7
	global_store_dwordx2 v1, v[8:9], s[12:13] nt
	s_add_u32 s12, s12, 0x40000
	s_addc_u32 s13, s13, 0
	v_lshlrev_b32_e32 v10, 16, v72
	v_and_b32_e32 v11, 0xffff0000, v72
	v_lshlrev_b32_e32 v12, 16, v73
	v_and_b32_e32 v13, 0xffff0000, v73
	v_fma_f32 v4, v4, v96, v10
	v_fma_f32 v5, v5, v97, v11
	v_fma_f32 v6, v6, v98, v12
	v_fma_f32 v7, v7, v99, v13
	v_cvt_pk_bf16_f32 v14, v4, v5
	v_cvt_pk_bf16_f32 v15, v6, v7
	global_store_dwordx2 v1, v[14:15], s[12:13] nt
	s_add_u32 s12, s12, 0x40000
	s_addc_u32 s13, s13, 0
	v_lshlrev_b32_e32 v10, 16, v74
	v_and_b32_e32 v11, 0xffff0000, v74
	v_lshlrev_b32_e32 v12, 16, v75
	v_and_b32_e32 v13, 0xffff0000, v75
	v_fma_f32 v4, v4, v100, v10
	v_fma_f32 v5, v5, v101, v11
	v_fma_f32 v6, v6, v102, v12
	v_fma_f32 v7, v7, v103, v13
	v_cvt_pk_bf16_f32 v8, v4, v5
	v_cvt_pk_bf16_f32 v9, v6, v7
	global_store_dwordx2 v1, v[8:9], s[12:13] nt
	s_add_u32 s12, s12, 0x40000
	s_addc_u32 s13, s13, 0
	v_lshlrev_b32_e32 v10, 16, v76
	v_and_b32_e32 v11, 0xffff0000, v76
	v_lshlrev_b32_e32 v12, 16, v77
	v_and_b32_e32 v13, 0xffff0000, v77
	v_fma_f32 v4, v4, v104, v10
	v_fma_f32 v5, v5, v105, v11
	v_fma_f32 v6, v6, v106, v12
	v_fma_f32 v7, v7, v107, v13
	v_cvt_pk_bf16_f32 v14, v4, v5
	v_cvt_pk_bf16_f32 v15, v6, v7
	global_store_dwordx2 v1, v[14:15], s[12:13] nt
	s_add_u32 s12, s12, 0x40000
	s_addc_u32 s13, s13, 0
	v_lshlrev_b32_e32 v10, 16, v78
	v_and_b32_e32 v11, 0xffff0000, v78
	v_lshlrev_b32_e32 v12, 16, v79
	v_and_b32_e32 v13, 0xffff0000, v79
	v_fma_f32 v4, v4, v108, v10
	v_fma_f32 v5, v5, v109, v11
	v_fma_f32 v6, v6, v110, v12
	v_fma_f32 v7, v7, v111, v13
	global_load_dwordx2 v[64:65], v1, s[6:7] nt
	global_load_dwordx4 v[80:83], v2, s[8:9] offset:0
	s_add_u32 s6, s6, 0x40000
	s_addc_u32 s7, s7, 0
	global_load_dwordx2 v[66:67], v1, s[6:7] nt
	global_load_dwordx4 v[84:87], v2, s[8:9] offset:2048
	s_add_u32 s8, s8, 0x1000
	s_addc_u32 s9, s9, 0
	s_add_u32 s6, s6, 0x40000
	s_addc_u32 s7, s7, 0
	global_load_dwordx2 v[68:69], v1, s[6:7] nt
	global_load_dwordx4 v[88:91], v2, s[8:9] offset:0
	s_add_u32 s6, s6, 0x40000
	s_addc_u32 s7, s7, 0
	global_load_dwordx2 v[70:71], v1, s[6:7] nt
	global_load_dwordx4 v[92:95], v2, s[8:9] offset:2048
	s_add_u32 s8, s8, 0x1000
	s_addc_u32 s9, s9, 0
	s_add_u32 s6, s6, 0x40000
	s_addc_u32 s7, s7, 0
	global_load_dwordx2 v[72:73], v1, s[6:7] nt
	global_load_dwordx4 v[96:99], v2, s[8:9] offset:0
	s_add_u32 s6, s6, 0x40000
	s_addc_u32 s7, s7, 0
	global_load_dwordx2 v[74:75], v1, s[6:7] nt
	global_load_dwordx4 v[100:103], v2, s[8:9] offset:2048
	s_add_u32 s8, s8, 0x1000
	s_addc_u32 s9, s9, 0
	s_add_u32 s6, s6, 0x40000
	s_addc_u32 s7, s7, 0
	global_load_dwordx2 v[76:77], v1, s[6:7] nt
	global_load_dwordx4 v[104:107], v2, s[8:9] offset:0
	s_add_u32 s6, s6, 0x40000
	s_addc_u32 s7, s7, 0
	global_load_dwordx2 v[78:79], v1, s[6:7] nt
	global_load_dwordx4 v[108:111], v2, s[8:9] offset:2048
	s_add_u32 s8, s8, 0x1000
	s_addc_u32 s9, s9, 0
	s_add_u32 s6, s6, 0x40000
	s_addc_u32 s7, s7, 0
	s_waitcnt vmcnt(24)
; __device__ __forceinline__ u32x2 pk4(f32x4 v) { u32x2 r; r.x = pk2(v[0], v[1]); r.y = pk2(v[2], v[3]); return r; }
; __device__ __forceinline__ f32x4 up4(u32x2 u) { return (f32x4){lo16(u.x), hi16(u.x), lo16(u.y), hi16(u.y)}; }
; __device__ void scan_gla(const Ctx& c, int idx) {
;     ...
;     for (int ck = 0; ck < NCH; ++ck) { u32x2* ad = (u32x2*)(gSt + (size_t)ck * 131072 + e4);
;         const f32x4 st = up4(__builtin_nontemporal_load(ad)); const f32x4 d = *(const f32x4*)(gDec + (size_t)ck * 512 + h * 128 + k4);
;         __builtin_nontemporal_store(pk4(S), ad); S = S * d + st; }
	v_cvt_pk_bf16_f32 v8, v4, v5
	v_cvt_pk_bf16_f32 v9, v6, v7
	global_store_dwordx2 v1, v[8:9], s[12:13] nt
	s_add_u32 s12, s12, 0x40000
	s_addc_u32 s13, s13, 0
	v_lshlrev_b32_e32 v10, 16, v16
	v_and_b32_e32 v11, 0xffff0000, v16
	v_lshlrev_b32_e32 v12, 16, v17
	v_and_b32_e32 v13, 0xffff0000, v17
	v_fma_f32 v4, v4, v32, v10
	v_fma_f32 v5, v5, v33, v11
	v_fma_f32 v6, v6, v34, v12
	v_fma_f32 v7, v7, v35, v13
	v_cvt_pk_bf16_f32 v14, v4, v5
	v_cvt_pk_bf16_f32 v15, v6, v7
	global_store_dwordx2 v1, v[14:15], s[12:13] nt
	s_add_u32 s12, s12, 0x40000
	s_addc_u32 s13, s13, 0
	v_lshlrev_b32_e32 v10, 16, v18
	v_and_b32_e32 v11, 0xffff0000, v18
	v_lshlrev_b32_e32 v12, 16, v19
	v_and_b32_e32 v13, 0xffff0000, v19
	v_fma_f32 v4, v4, v36, v10
	v_fma_f32 v5, v5, v37, v11
	v_fma_f32 v6, v6, v38, v12
	v_fma_f32 v7, v7, v39, v13
	v_cvt_pk_bf16_f32 v8, v4, v5
	v_cvt_pk_bf16_f32 v9, v6, v7
	global_store_dwordx2 v1, v[8:9], s[12:13] nt
	s_add_u32 s12, s12, 0x40000
	s_addc_u32 s13, s13, 0
	v_lshlrev_b32_e32 v10, 16, v20
	v_and_b32_e32 v11, 0xffff0000, v20
	v_lshlrev_b32_e32 v12, 16, v21
	v_and_b32_e32 v13, 0xffff0000, v21
	v_fma_f32 v4, v4, v40, v10
	v_fma_f32 v5, v5, v41, v11
	v_fma_f32 v6, v6, v42, v12
	v_fma_f32 v7, v7, v43, v13
	v_cvt_pk_bf16_f32 v14, v4, v5
	v_cvt_pk_bf16_f32 v15, v6, v7
	global_store_dwordx2 v1, v[14:15], s[12:13] nt
	s_add_u32 s12, s12, 0x40000
	s_addc_u32 s13, s13, 0
	v_lshlrev_b32_e32 v10, 16, v22
	v_and_b32_e32 v11, 0xffff0000, v22
	v_lshlrev_b32_e32 v12, 16, v23
	v_and_b32_e32 v13, 0xffff0000, v23
	v_fma_f32 v4, v4, v44, v10
	v_fma_f32 v5, v5, v45, v11
	v_fma_f32 v6, v6, v46, v12
	v_fma_f32 v7, v7, v47, v13
	v_cvt_pk_bf16_f32 v8, v4, v5
	v_cvt_pk_bf16_f32 v9, v6, v7
	global_store_dwordx2 v1, v[8:9], s[12:13] nt
	s_add_u32 s12, s12, 0x40000
	s_addc_u32 s13, s13, 0
	v_lshlrev_b32_e32 v10, 16, v24
	v_and_b32_e32 v11, 0xffff0000, v24
	v_lshlrev_b32_e32 v12, 16, v25
	v_and_b32_e32 v13, 0xffff0000, v25
	v_fma_f32 v4, v4, v48, v10
	v_fma_f32 v5, v5, v49, v11
	v_fma_f32 v6, v6, v50, v12
	v_fma_f32 v7, v7, v51, v13
	v_cvt_pk_bf16_f32 v14, v4, v5
	v_cvt_pk_bf16_f32 v15, v6, v7
	global_store_dwordx2 v1, v[14:15], s[12:13] nt
	s_add_u32 s12, s12, 0x40000
	s_addc_u32 s13, s13, 0
	v_lshlrev_b32_e32 v10, 16, v26
	v_and_b32_e32 v11, 0xffff0000, v26
	v_lshlrev_b32_e32 v12, 16, v27
	v_and_b32_e32 v13, 0xffff0000, v27
	v_fma_f32 v4, v4, v52, v10
	v_fma_f32 v5, v5, v53, v11
	v_fma_f32 v6, v6, v54, v12
	v_fma_f32 v7, v7, v55, v13
	v_cvt_pk_bf16_f32 v8, v4, v5
	v_cvt_pk_bf16_f32 v9, v6, v7
	global_store_dwordx2 v1, v[8:9], s[12:13] nt
	s_add_u32 s12, s12, 0x40000
	s_addc_u32 s13, s13, 0
	v_lshlrev_b32_e32 v10, 16, v28
	v_and_b32_e32 v11, 0xffff0000, v28
	v_lshlrev_b32_e32 v12, 16, v29
	v_and_b32_e32 v13, 0xffff0000, v29
	v_fma_f32 v4, v4, v56, v10
	v_fma_f32 v5, v5, v57, v11
	v_fma_f32 v6, v6, v58, v12
	v_fma_f32 v7, v7, v59, v13
	v_cvt_pk_bf16_f32 v14, v4, v5
	v_cvt_pk_bf16_f32 v15, v6, v7
	global_store_dwordx2 v1, v[14:15], s[12:13] nt
	s_add_u32 s12, s12, 0x40000
	s_addc_u32 s13, s13, 0
	v_lshlrev_b32_e32 v10, 16, v30
	v_and_b32_e32 v11, 0xffff0000, v30
	v_lshlrev_b32_e32 v12, 16, v31
	v_and_b32_e32 v13, 0xffff0000, v31
	v_fma_f32 v4, v4, v60, v10
	v_fma_f32 v5, v5, v61, v11
	v_fma_f32 v6, v6, v62, v12
	v_fma_f32 v7, v7, v63, v13
	global_load_dwordx2 v[16:17], v1, s[6:7] nt
	global_load_dwordx4 v[32:35], v2, s[8:9] offset:0
	s_add_u32 s6, s6, 0x40000
	s_addc_u32 s7, s7, 0
	global_load_dwordx2 v[18:19], v1, s[6:7] nt
	global_load_dwordx4 v[36:39], v2, s[8:9] offset:2048
	s_add_u32 s8, s8, 0x1000
	s_addc_u32 s9, s9, 0
	s_add_u32 s6, s6, 0x40000
	s_addc_u32 s7, s7, 0
	global_load_dwordx2 v[20:21], v1, s[6:7] nt
	global_load_dwordx4 v[40:43], v2, s[8:9] offset:0
	s_add_u32 s6, s6, 0x40000
	s_addc_u32 s7, s7, 0
	global_load_dwordx2 v[22:23], v1, s[6:7] nt
	global_load_dwordx4 v[44:47], v2, s[8:9] offset:2048
	s_add_u32 s8, s8, 0x1000
	s_addc_u32 s9, s9, 0
	s_add_u32 s6, s6, 0x40000
	s_addc_u32 s7, s7, 0
	global_load_dwordx2 v[24:25], v1, s[6:7] nt
	global_load_dwordx4 v[48:51], v2, s[8:9] offset:0
	s_add_u32 s6, s6, 0x40000
	s_addc_u32 s7, s7, 0
	global_load_dwordx2 v[26:27], v1, s[6:7] nt
	global_load_dwordx4 v[52:55], v2, s[8:9] offset:2048
	s_add_u32 s8, s8, 0x1000
	s_addc_u32 s9, s9, 0
	s_add_u32 s6, s6, 0x40000
	s_addc_u32 s7, s7, 0
	global_load_dwordx2 v[28:29], v1, s[6:7] nt
	global_load_dwordx4 v[56:59], v2, s[8:9] offset:0
	s_add_u32 s6, s6, 0x40000
	s_addc_u32 s7, s7, 0
	global_load_dwordx2 v[30:31], v1, s[6:7] nt
	global_load_dwordx4 v[60:63], v2, s[8:9] offset:2048
	s_add_u32 s8, s8, 0x1000
	s_addc_u32 s9, s9, 0
	s_add_u32 s6, s6, 0x40000
	s_addc_u32 s7, s7, 0
	s_waitcnt vmcnt(24)
; __device__ __forceinline__ u32x2 pk4(f32x4 v) { u32x2 r; r.x = pk2(v[0], v[1]); r.y = pk2(v[2], v[3]); return r; }
; __device__ __forceinline__ f32x4 up4(u32x2 u) { return (f32x4){lo16(u.x), hi16(u.x), lo16(u.y), hi16(u.y)}; }
; __device__ void scan_gla(const Ctx& c, int idx) {
;     ...
;     for (int ck = 0; ck < NCH; ++ck) { u32x2* ad = (u32x2*)(gSt + (size_t)ck * 131072 + e4);
;         const f32x4 st = up4(__builtin_nontemporal_load(ad)); const f32x4 d = *(const f32x4*)(gDec + (size_t)ck * 512 + h * 128 + k4);
;         __builtin_nontemporal_store(pk4(S), ad); S = S * d + st; }
	v_cvt_pk_bf16_f32 v8, v4, v5
	v_cvt_pk_bf16_f32 v9, v6, v7
	global_store_dwordx2 v1, v[8:9], s[12:13] nt
	s_add_u32 s12, s12, 0x40000
	s_addc_u32 s13, s13, 0
	v_lshlrev_b32_e32 v10, 16, v64
	v_and_b32_e32 v11, 0xffff0000, v64
	v_lshlrev_b32_e32 v12, 16, v65
	v_and_b32_e32 v13, 0xffff0000, v65
	v_fma_f32 v4, v4, v80, v10
	v_fma_f32 v5, v5, v81, v11
	v_fma_f32 v6, v6, v82, v12
	v_fma_f32 v7, v7, v83, v13
	v_cvt_pk_bf16_f32 v14, v4, v5
	v_cvt_pk_bf16_f32 v15, v6, v7
	global_store_dwordx2 v1, v[14:15], s[12:13] nt
	s_add_u32 s12, s12, 0x40000
	s_addc_u32 s13, s13, 0
	v_lshlrev_b32_e32 v10, 16, v66
	v_and_b32_e32 v11, 0xffff0000, v66
	v_lshlrev_b32_e32 v12, 16, v67
	v_and_b32_e32 v13, 0xffff0000, v67
	v_fma_f32 v4, v4, v84, v10
	v_fma_f32 v5, v5, v85, v11
	v_fma_f32 v6, v6, v86, v12
	v_fma_f32 v7, v7, v87, v13
	v_cvt_pk_bf16_f32 v8, v4, v5
	v_cvt_pk_bf16_f32 v9, v6, v7
	global_store_dwordx2 v1, v[8:9], s[12:13] nt
	s_add_u32 s12, s12, 0x40000
	s_addc_u32 s13, s13, 0
	v_lshlrev_b32_e32 v10, 16, v68
	v_and_b32_e32 v11, 0xffff0000, v68
	v_lshlrev_b32_e32 v12, 16, v69
	v_and_b32_e32 v13, 0xffff0000, v69
	v_fma_f32 v4, v4, v88, v10
	v_fma_f32 v5, v5, v89, v11
	v_fma_f32 v6, v6, v90, v12
	v_fma_f32 v7, v7, v91, v13
	v_cvt_pk_bf16_f32 v14, v4, v5
	v_cvt_pk_bf16_f32 v15, v6, v7
	global_store_dwordx2 v1, v[14:15], s[12:13] nt
	s_add_u32 s12, s12, 0x40000
	s_addc_u32 s13, s13, 0
	v_lshlrev_b32_e32 v10, 16, v70
	v_and_b32_e32 v11, 0xffff0000, v70
	v_lshlrev_b32_e32 v12, 16, v71
	v_and_b32_e32 v13, 0xffff0000, v71
	v_fma_f32 v4, v4, v92, v10
	v_fma_f32 v5, v5, v93, v11
	v_fma_f32 v6, v6, v94, v12
	v_fma_f32 v7, v7, v95, v13
	v_cvt_pk_bf16_f32 v8, v4, v5
	v_cvt_pk_bf16_f32 v9, v6, v7
	global_store_dwordx2 v1, v[8:9], s[12:13] nt
	s_add_u32 s12, s12, 0x40000
	s_addc_u32 s13, s13, 0
	v_lshlrev_b32_e32 v10, 16, v72
	v_and_b32_e32 v11, 0xffff0000, v72
	v_lshlrev_b32_e32 v12, 16, v73
	v_and_b32_e32 v13, 0xffff0000, v73
	v_fma_f32 v4, v4, v96, v10
	v_fma_f32 v5, v5, v97, v11
	v_fma_f32 v6, v6, v98, v12
	v_fma_f32 v7, v7, v99, v13
	v_cvt_pk_bf16_f32 v14, v4, v5
	v_cvt_pk_bf16_f32 v15, v6, v7
	global_store_dwordx2 v1, v[14:15], s[12:13] nt
	s_add_u32 s12, s12, 0x40000
	s_addc_u32 s13, s13, 0
	v_lshlrev_b32_e32 v10, 16, v74
	v_and_b32_e32 v11, 0xffff0000, v74
	v_lshlrev_b32_e32 v12, 16, v75
	v_and_b32_e32 v13, 0xffff0000, v75
	v_fma_f32 v4, v4, v100, v10
	v_fma_f32 v5, v5, v101, v11
	v_fma_f32 v6, v6, v102, v12
	v_fma_f32 v7, v7, v103, v13
	v_cvt_pk_bf16_f32 v8, v4, v5
	v_cvt_pk_bf16_f32 v9, v6, v7
	global_store_dwordx2 v1, v[8:9], s[12:13] nt
	s_add_u32 s12, s12, 0x40000
	s_addc_u32 s13, s13, 0
	v_lshlrev_b32_e32 v10, 16, v76
	v_and_b32_e32 v11, 0xffff0000, v76
	v_lshlrev_b32_e32 v12, 16, v77
	v_and_b32_e32 v13, 0xffff0000, v77
	v_fma_f32 v4, v4, v104, v10
	v_fma_f32 v5, v5, v105, v11
	v_fma_f32 v6, v6, v106, v12
	v_fma_f32 v7, v7, v107, v13
	v_cvt_pk_bf16_f32 v14, v4, v5
	v_cvt_pk_bf16_f32 v15, v6, v7
	global_store_dwordx2 v1, v[14:15], s[12:13] nt
	s_add_u32 s12, s12, 0x40000
	s_addc_u32 s13, s13, 0
	v_lshlrev_b32_e32 v10, 16, v78
	v_and_b32_e32 v11, 0xffff0000, v78
	v_lshlrev_b32_e32 v12, 16, v79
	v_and_b32_e32 v13, 0xffff0000, v79
	v_fma_f32 v4, v4, v108, v10
	v_fma_f32 v5, v5, v109, v11
	v_fma_f32 v6, v6, v110, v12
	v_fma_f32 v7, v7, v111, v13
	global_load_dwordx2 v[64:65], v1, s[6:7] nt
	global_load_dwordx4 v[80:83], v2, s[8:9] offset:0
	s_add_u32 s6, s6, 0x40000
	s_addc_u32 s7, s7, 0
	global_load_dwordx2 v[66:67], v1, s[6:7] nt
	global_load_dwordx4 v[84:87], v2, s[8:9] offset:2048
	s_add_u32 s8, s8, 0x1000
	s_addc_u32 s9, s9, 0
	s_add_u32 s6, s6, 0x40000
	s_addc_u32 s7, s7, 0
	global_load_dwordx2 v[68:69], v1, s[6:7] nt
	global_load_dwordx4 v[88:91], v2, s[8:9] offset:0
	s_add_u32 s6, s6, 0x40000
	s_addc_u32 s7, s7, 0
	global_load_dwordx2 v[70:71], v1, s[6:7] nt
	global_load_dwordx4 v[92:95], v2, s[8:9] offset:2048
	s_add_u32 s8, s8, 0x1000
	s_addc_u32 s9, s9, 0
	s_add_u32 s6, s6, 0x40000
	s_addc_u32 s7, s7, 0
	global_load_dwordx2 v[72:73], v1, s[6:7] nt
	global_load_dwordx4 v[96:99], v2, s[8:9] offset:0
	s_add_u32 s6, s6, 0x40000
	s_addc_u32 s7, s7, 0
	global_load_dwordx2 v[74:75], v1, s[6:7] nt
	global_load_dwordx4 v[100:103], v2, s[8:9] offset:2048
	s_add_u32 s8, s8, 0x1000
	s_addc_u32 s9, s9, 0
	s_add_u32 s6, s6, 0x40000
	s_addc_u32 s7, s7, 0
	global_load_dwordx2 v[76:77], v1, s[6:7] nt
	global_load_dwordx4 v[104:107], v2, s[8:9] offset:0
	s_add_u32 s6, s6, 0x40000
	s_addc_u32 s7, s7, 0
	global_load_dwordx2 v[78:79], v1, s[6:7] nt
	global_load_dwordx4 v[108:111], v2, s[8:9] offset:2048
	s_add_u32 s8, s8, 0x1000
	s_addc_u32 s9, s9, 0
	s_add_u32 s6, s6, 0x40000
	s_addc_u32 s7, s7, 0
	s_waitcnt vmcnt(24)
; __device__ __forceinline__ u32x2 pk4(f32x4 v) { u32x2 r; r.x = pk2(v[0], v[1]); r.y = pk2(v[2], v[3]); return r; }
; __device__ __forceinline__ f32x4 up4(u32x2 u) { return (f32x4){lo16(u.x), hi16(u.x), lo16(u.y), hi16(u.y)}; }
; __device__ void scan_gla(const Ctx& c, int idx) {
;     ...
;     for (int ck = 0; ck < NCH; ++ck) { u32x2* ad = (u32x2*)(gSt + (size_t)ck * 131072 + e4);
;         const f32x4 st = up4(__builtin_nontemporal_load(ad)); const f32x4 d = *(const f32x4*)(gDec + (size_t)ck * 512 + h * 128 + k4);
;         __builtin_nontemporal_store(pk4(S), ad); S = S * d + st; }
	v_cvt_pk_bf16_f32 v8, v4, v5
	v_cvt_pk_bf16_f32 v9, v6, v7
	global_store_dwordx2 v1, v[8:9], s[12:13] nt
	s_add_u32 s12, s12, 0x40000
	s_addc_u32 s13, s13, 0
	v_lshlrev_b32_e32 v10, 16, v16
	v_and_b32_e32 v11, 0xffff0000, v16
	v_lshlrev_b32_e32 v12, 16, v17
	v_and_b32_e32 v13, 0xffff0000, v17
	v_fma_f32 v4, v4, v32, v10
	v_fma_f32 v5, v5, v33, v11
	v_fma_f32 v6, v6, v34, v12
	v_fma_f32 v7, v7, v35, v13
	v_cvt_pk_bf16_f32 v14, v4, v5
	v_cvt_pk_bf16_f32 v15, v6, v7
	global_store_dwordx2 v1, v[14:15], s[12:13] nt
	s_add_u32 s12, s12, 0x40000
	s_addc_u32 s13, s13, 0
	v_lshlrev_b32_e32 v10, 16, v18
	v_and_b32_e32 v11, 0xffff0000, v18
	v_lshlrev_b32_e32 v12, 16, v19
	v_and_b32_e32 v13, 0xffff0000, v19
	v_fma_f32 v4, v4, v36, v10
	v_fma_f32 v5, v5, v37, v11
	v_fma_f32 v6, v6, v38, v12
	v_fma_f32 v7, v7, v39, v13
	v_cvt_pk_bf16_f32 v8, v4, v5
	v_cvt_pk_bf16_f32 v9, v6, v7
	global_store_dwordx2 v1, v[8:9], s[12:13] nt
	s_add_u32 s12, s12, 0x40000
	s_addc_u32 s13, s13, 0
	v_lshlrev_b32_e32 v10, 16, v20
	v_and_b32_e32 v11, 0xffff0000, v20
	v_lshlrev_b32_e32 v12, 16, v21
	v_and_b32_e32 v13, 0xffff0000, v21
	v_fma_f32 v4, v4, v40, v10
	v_fma_f32 v5, v5, v41, v11
	v_fma_f32 v6, v6, v42, v12
	v_fma_f32 v7, v7, v43, v13
	v_cvt_pk_bf16_f32 v14, v4, v5
	v_cvt_pk_bf16_f32 v15, v6, v7
	global_store_dwordx2 v1, v[14:15], s[12:13] nt
	s_add_u32 s12, s12, 0x40000
	s_addc_u32 s13, s13, 0
	v_lshlrev_b32_e32 v10, 16, v22
	v_and_b32_e32 v11, 0xffff0000, v22
	v_lshlrev_b32_e32 v12, 16, v23
	v_and_b32_e32 v13, 0xffff0000, v23
	v_fma_f32 v4, v4, v44, v10
	v_fma_f32 v5, v5, v45, v11
	v_fma_f32 v6, v6, v46, v12
	v_fma_f32 v7, v7, v47, v13
	v_cvt_pk_bf16_f32 v8, v4, v5
	v_cvt_pk_bf16_f32 v9, v6, v7
	global_store_dwordx2 v1, v[8:9], s[12:13] nt
	s_add_u32 s12, s12, 0x40000
	s_addc_u32 s13, s13, 0
	v_lshlrev_b32_e32 v10, 16, v24
	v_and_b32_e32 v11, 0xffff0000, v24
	v_lshlrev_b32_e32 v12, 16, v25
	v_and_b32_e32 v13, 0xffff0000, v25
	v_fma_f32 v4, v4, v48, v10
	v_fma_f32 v5, v5, v49, v11
	v_fma_f32 v6, v6, v50, v12
	v_fma_f32 v7, v7, v51, v13
	v_cvt_pk_bf16_f32 v14, v4, v5
	v_cvt_pk_bf16_f32 v15, v6, v7
	global_store_dwordx2 v1, v[14:15], s[12:13] nt
	s_add_u32 s12, s12, 0x40000
	s_addc_u32 s13, s13, 0
	v_lshlrev_b32_e32 v10, 16, v26
	v_and_b32_e32 v11, 0xffff0000, v26
	v_lshlrev_b32_e32 v12, 16, v27
	v_and_b32_e32 v13, 0xffff0000, v27
	v_fma_f32 v4, v4, v52, v10
	v_fma_f32 v5, v5, v53, v11
	v_fma_f32 v6, v6, v54, v12
	v_fma_f32 v7, v7, v55, v13
	v_cvt_pk_bf16_f32 v8, v4, v5
	v_cvt_pk_bf16_f32 v9, v6, v7
	global_store_dwordx2 v1, v[8:9], s[12:13] nt
	s_add_u32 s12, s12, 0x40000
	s_addc_u32 s13, s13, 0
	v_lshlrev_b32_e32 v10, 16, v28
	v_and_b32_e32 v11, 0xffff0000, v28
	v_lshlrev_b32_e32 v12, 16, v29
	v_and_b32_e32 v13, 0xffff0000, v29
	v_fma_f32 v4, v4, v56, v10
	v_fma_f32 v5, v5, v57, v11
	v_fma_f32 v6, v6, v58, v12
	v_fma_f32 v7, v7, v59, v13
	v_cvt_pk_bf16_f32 v14, v4, v5
	v_cvt_pk_bf16_f32 v15, v6, v7
	global_store_dwordx2 v1, v[14:15], s[12:13] nt
	s_add_u32 s12, s12, 0x40000
	s_addc_u32 s13, s13, 0
	v_lshlrev_b32_e32 v10, 16, v30
	v_and_b32_e32 v11, 0xffff0000, v30
	v_lshlrev_b32_e32 v12, 16, v31
	v_and_b32_e32 v13, 0xffff0000, v31
	v_fma_f32 v4, v4, v60, v10
	v_fma_f32 v5, v5, v61, v11
	v_fma_f32 v6, v6, v62, v12
	v_fma_f32 v7, v7, v63, v13
	global_load_dwordx2 v[16:17], v1, s[6:7] nt
	global_load_dwordx4 v[32:35], v2, s[8:9] offset:0
	s_add_u32 s6, s6, 0x40000
	s_addc_u32 s7, s7, 0
	global_load_dwordx2 v[18:19], v1, s[6:7] nt
	global_load_dwordx4 v[36:39], v2, s[8:9] offset:2048
	s_add_u32 s8, s8, 0x1000
	s_addc_u32 s9, s9, 0
	s_add_u32 s6, s6, 0x40000
	s_addc_u32 s7, s7, 0
	global_load_dwordx2 v[20:21], v1, s[6:7] nt
	global_load_dwordx4 v[40:43], v2, s[8:9] offset:0
	s_add_u32 s6, s6, 0x40000
	s_addc_u32 s7, s7, 0
	global_load_dwordx2 v[22:23], v1, s[6:7] nt
	global_load_dwordx4 v[44:47], v2, s[8:9] offset:2048
	s_add_u32 s8, s8, 0x1000
	s_addc_u32 s9, s9, 0
	s_add_u32 s6, s6, 0x40000
	s_addc_u32 s7, s7, 0
	global_load_dwordx2 v[24:25], v1, s[6:7] nt
	global_load_dwordx4 v[48:51], v2, s[8:9] offset:0
	s_add_u32 s6, s6, 0x40000
	s_addc_u32 s7, s7, 0
	global_load_dwordx2 v[26:27], v1, s[6:7] nt
	global_load_dwordx4 v[52:55], v2, s[8:9] offset:2048
	s_add_u32 s8, s8, 0x1000
	s_addc_u32 s9, s9, 0
	s_add_u32 s6, s6, 0x40000
	s_addc_u32 s7, s7, 0
	global_load_dwordx2 v[28:29], v1, s[6:7] nt
	global_load_dwordx4 v[56:59], v2, s[8:9] offset:0
	s_add_u32 s6, s6, 0x40000
	s_addc_u32 s7, s7, 0
	global_load_dwordx2 v[30:31], v1, s[6:7] nt
	global_load_dwordx4 v[60:63], v2, s[8:9] offset:2048
	s_add_u32 s8, s8, 0x1000
	s_addc_u32 s9, s9, 0
	s_add_u32 s6, s6, 0x40000
	s_addc_u32 s7, s7, 0
	s_waitcnt vmcnt(24)
; __device__ __forceinline__ u32x2 pk4(f32x4 v) { u32x2 r; r.x = pk2(v[0], v[1]); r.y = pk2(v[2], v[3]); return r; }
; __device__ __forceinline__ f32x4 up4(u32x2 u) { return (f32x4){lo16(u.x), hi16(u.x), lo16(u.y), hi16(u.y)}; }
; __device__ void scan_gla(const Ctx& c, int idx) {
;     ...
;     for (int ck = 0; ck < NCH; ++ck) { u32x2* ad = (u32x2*)(gSt + (size_t)ck * 131072 + e4);
;         const f32x4 st = up4(__builtin_nontemporal_load(ad)); const f32x4 d = *(const f32x4*)(gDec + (size_t)ck * 512 + h * 128 + k4);
;         __builtin_nontemporal_store(pk4(S), ad); S = S * d + st; }
	v_cvt_pk_bf16_f32 v8, v4, v5
	v_cvt_pk_bf16_f32 v9, v6, v7
	global_store_dwordx2 v1, v[8:9], s[12:13] nt
	s_add_u32 s12, s12, 0x40000
	s_addc_u32 s13, s13, 0
	v_lshlrev_b32_e32 v10, 16, v64
	v_and_b32_e32 v11, 0xffff0000, v64
	v_lshlrev_b32_e32 v12, 16, v65
	v_and_b32_e32 v13, 0xffff0000, v65
	v_fma_f32 v4, v4, v80, v10
	v_fma_f32 v5, v5, v81, v11
	v_fma_f32 v6, v6, v82, v12
	v_fma_f32 v7, v7, v83, v13
	v_cvt_pk_bf16_f32 v14, v4, v5
	v_cvt_pk_bf16_f32 v15, v6, v7
	global_store_dwordx2 v1, v[14:15], s[12:13] nt
	s_add_u32 s12, s12, 0x40000
	s_addc_u32 s13, s13, 0
	v_lshlrev_b32_e32 v10, 16, v66
	v_and_b32_e32 v11, 0xffff0000, v66
	v_lshlrev_b32_e32 v12, 16, v67
	v_and_b32_e32 v13, 0xffff0000, v67
	v_fma_f32 v4, v4, v84, v10
	v_fma_f32 v5, v5, v85, v11
	v_fma_f32 v6, v6, v86, v12
	v_fma_f32 v7, v7, v87, v13
	v_cvt_pk_bf16_f32 v8, v4, v5
	v_cvt_pk_bf16_f32 v9, v6, v7
	global_store_dwordx2 v1, v[8:9], s[12:13] nt
	s_add_u32 s12, s12, 0x40000
	s_addc_u32 s13, s13, 0
	v_lshlrev_b32_e32 v10, 16, v68
	v_and_b32_e32 v11, 0xffff0000, v68
	v_lshlrev_b32_e32 v12, 16, v69
	v_and_b32_e32 v13, 0xffff0000, v69
	v_fma_f32 v4, v4, v88, v10
	v_fma_f32 v5, v5, v89, v11
	v_fma_f32 v6, v6, v90, v12
	v_fma_f32 v7, v7, v91, v13
	v_cvt_pk_bf16_f32 v14, v4, v5
	v_cvt_pk_bf16_f32 v15, v6, v7
	global_store_dwordx2 v1, v[14:15], s[12:13] nt
	s_add_u32 s12, s12, 0x40000
	s_addc_u32 s13, s13, 0
	v_lshlrev_b32_e32 v10, 16, v70
	v_and_b32_e32 v11, 0xffff0000, v70
	v_lshlrev_b32_e32 v12, 16, v71
	v_and_b32_e32 v13, 0xffff0000, v71
	v_fma_f32 v4, v4, v92, v10
	v_fma_f32 v5, v5, v93, v11
	v_fma_f32 v6, v6, v94, v12
	v_fma_f32 v7, v7, v95, v13
	v_cvt_pk_bf16_f32 v8, v4, v5
	v_cvt_pk_bf16_f32 v9, v6, v7
	global_store_dwordx2 v1, v[8:9], s[12:13] nt
	s_add_u32 s12, s12, 0x40000
	s_addc_u32 s13, s13, 0
	v_lshlrev_b32_e32 v10, 16, v72
	v_and_b32_e32 v11, 0xffff0000, v72
	v_lshlrev_b32_e32 v12, 16, v73
	v_and_b32_e32 v13, 0xffff0000, v73
	v_fma_f32 v4, v4, v96, v10
	v_fma_f32 v5, v5, v97, v11
	v_fma_f32 v6, v6, v98, v12
	v_fma_f32 v7, v7, v99, v13
	v_cvt_pk_bf16_f32 v14, v4, v5
	v_cvt_pk_bf16_f32 v15, v6, v7
	global_store_dwordx2 v1, v[14:15], s[12:13] nt
	s_add_u32 s12, s12, 0x40000
	s_addc_u32 s13, s13, 0
	v_lshlrev_b32_e32 v10, 16, v74
	v_and_b32_e32 v11, 0xffff0000, v74
	v_lshlrev_b32_e32 v12, 16, v75
	v_and_b32_e32 v13, 0xffff0000, v75
	v_fma_f32 v4, v4, v100, v10
	v_fma_f32 v5, v5, v101, v11
	v_fma_f32 v6, v6, v102, v12
	v_fma_f32 v7, v7, v103, v13
	v_cvt_pk_bf16_f32 v8, v4, v5
	v_cvt_pk_bf16_f32 v9, v6, v7
	global_store_dwordx2 v1, v[8:9], s[12:13] nt
	s_add_u32 s12, s12, 0x40000
	s_addc_u32 s13, s13, 0
	v_lshlrev_b32_e32 v10, 16, v76
	v_and_b32_e32 v11, 0xffff0000, v76
	v_lshlrev_b32_e32 v12, 16, v77
	v_and_b32_e32 v13, 0xffff0000, v77
	v_fma_f32 v4, v4, v104, v10
	v_fma_f32 v5, v5, v105, v11
	v_fma_f32 v6, v6, v106, v12
	v_fma_f32 v7, v7, v107, v13
	v_cvt_pk_bf16_f32 v14, v4, v5
	v_cvt_pk_bf16_f32 v15, v6, v7
	global_store_dwordx2 v1, v[14:15], s[12:13] nt
	s_add_u32 s12, s12, 0x40000
	s_addc_u32 s13, s13, 0
	v_lshlrev_b32_e32 v10, 16, v78
	v_and_b32_e32 v11, 0xffff0000, v78
	v_lshlrev_b32_e32 v12, 16, v79
	v_and_b32_e32 v13, 0xffff0000, v79
	v_fma_f32 v4, v4, v108, v10
	v_fma_f32 v5, v5, v109, v11
	v_fma_f32 v6, v6, v110, v12
	v_fma_f32 v7, v7, v111, v13
	global_load_dwordx2 v[64:65], v1, s[6:7] nt
	global_load_dwordx4 v[80:83], v2, s[8:9] offset:0
	s_add_u32 s6, s6, 0x40000
	s_addc_u32 s7, s7, 0
	global_load_dwordx2 v[66:67], v1, s[6:7] nt
	global_load_dwordx4 v[84:87], v2, s[8:9] offset:2048
	s_add_u32 s8, s8, 0x1000
	s_addc_u32 s9, s9, 0
	s_add_u32 s6, s6, 0x40000
	s_addc_u32 s7, s7, 0
	global_load_dwordx2 v[68:69], v1, s[6:7] nt
	global_load_dwordx4 v[88:91], v2, s[8:9] offset:0
	s_add_u32 s6, s6, 0x40000
	s_addc_u32 s7, s7, 0
	global_load_dwordx2 v[70:71], v1, s[6:7] nt
	global_load_dwordx4 v[92:95], v2, s[8:9] offset:2048
	s_add_u32 s8, s8, 0x1000
	s_addc_u32 s9, s9, 0
	s_add_u32 s6, s6, 0x40000
	s_addc_u32 s7, s7, 0
	global_load_dwordx2 v[72:73], v1, s[6:7] nt
	global_load_dwordx4 v[96:99], v2, s[8:9] offset:0
	s_add_u32 s6, s6, 0x40000
	s_addc_u32 s7, s7, 0
	global_load_dwordx2 v[74:75], v1, s[6:7] nt
	global_load_dwordx4 v[100:103], v2, s[8:9] offset:2048
	s_add_u32 s8, s8, 0x1000
	s_addc_u32 s9, s9, 0
	s_add_u32 s6, s6, 0x40000
	s_addc_u32 s7, s7, 0
	global_load_dwordx2 v[76:77], v1, s[6:7] nt
	global_load_dwordx4 v[104:107], v2, s[8:9] offset:0
	s_add_u32 s6, s6, 0x40000
	s_addc_u32 s7, s7, 0
	global_load_dwordx2 v[78:79], v1, s[6:7] nt
	global_load_dwordx4 v[108:111], v2, s[8:9] offset:2048
	s_add_u32 s8, s8, 0x1000
	s_addc_u32 s9, s9, 0
	s_add_u32 s6, s6, 0x40000
	s_addc_u32 s7, s7, 0
	s_waitcnt vmcnt(24)
; __device__ __forceinline__ u32x2 pk4(f32x4 v) { u32x2 r; r.x = pk2(v[0], v[1]); r.y = pk2(v[2], v[3]); return r; }
; __device__ __forceinline__ f32x4 up4(u32x2 u) { return (f32x4){lo16(u.x), hi16(u.x), lo16(u.y), hi16(u.y)}; }
; __device__ void scan_gla(const Ctx& c, int idx) {
;     ...
;     for (int ck = 0; ck < NCH; ++ck) { u32x2* ad = (u32x2*)(gSt + (size_t)ck * 131072 + e4);
;         const f32x4 st = up4(__builtin_nontemporal_load(ad)); const f32x4 d = *(const f32x4*)(gDec + (size_t)ck * 512 + h * 128 + k4);
;         __builtin_nontemporal_store(pk4(S), ad); S = S * d + st; }
	v_cvt_pk_bf16_f32 v8, v4, v5
	v_cvt_pk_bf16_f32 v9, v6, v7
	global_store_dwordx2 v1, v[8:9], s[12:13] nt
	s_add_u32 s12, s12, 0x40000
	s_addc_u32 s13, s13, 0
	v_lshlrev_b32_e32 v10, 16, v16
	v_and_b32_e32 v11, 0xffff0000, v16
	v_lshlrev_b32_e32 v12, 16, v17
	v_and_b32_e32 v13, 0xffff0000, v17
	v_fma_f32 v4, v4, v32, v10
	v_fma_f32 v5, v5, v33, v11
	v_fma_f32 v6, v6, v34, v12
	v_fma_f32 v7, v7, v35, v13
	v_cvt_pk_bf16_f32 v14, v4, v5
	v_cvt_pk_bf16_f32 v15, v6, v7
	global_store_dwordx2 v1, v[14:15], s[12:13] nt
	s_add_u32 s12, s12, 0x40000
	s_addc_u32 s13, s13, 0
	v_lshlrev_b32_e32 v10, 16, v18
	v_and_b32_e32 v11, 0xffff0000, v18
	v_lshlrev_b32_e32 v12, 16, v19
	v_and_b32_e32 v13, 0xffff0000, v19
	v_fma_f32 v4, v4, v36, v10
	v_fma_f32 v5, v5, v37, v11
	v_fma_f32 v6, v6, v38, v12
	v_fma_f32 v7, v7, v39, v13
	v_cvt_pk_bf16_f32 v8, v4, v5
	v_cvt_pk_bf16_f32 v9, v6, v7
	global_store_dwordx2 v1, v[8:9], s[12:13] nt
	s_add_u32 s12, s12, 0x40000
	s_addc_u32 s13, s13, 0
	v_lshlrev_b32_e32 v10, 16, v20
	v_and_b32_e32 v11, 0xffff0000, v20
	v_lshlrev_b32_e32 v12, 16, v21
	v_and_b32_e32 v13, 0xffff0000, v21
	v_fma_f32 v4, v4, v40, v10
	v_fma_f32 v5, v5, v41, v11
	v_fma_f32 v6, v6, v42, v12
	v_fma_f32 v7, v7, v43, v13
	v_cvt_pk_bf16_f32 v14, v4, v5
	v_cvt_pk_bf16_f32 v15, v6, v7
	global_store_dwordx2 v1, v[14:15], s[12:13] nt
	s_add_u32 s12, s12, 0x40000
	s_addc_u32 s13, s13, 0
	v_lshlrev_b32_e32 v10, 16, v22
	v_and_b32_e32 v11, 0xffff0000, v22
	v_lshlrev_b32_e32 v12, 16, v23
	v_and_b32_e32 v13, 0xffff0000, v23
	v_fma_f32 v4, v4, v44, v10
	v_fma_f32 v5, v5, v45, v11
	v_fma_f32 v6, v6, v46, v12
	v_fma_f32 v7, v7, v47, v13
	v_cvt_pk_bf16_f32 v8, v4, v5
	v_cvt_pk_bf16_f32 v9, v6, v7
	global_store_dwordx2 v1, v[8:9], s[12:13] nt
	s_add_u32 s12, s12, 0x40000
	s_addc_u32 s13, s13, 0
	v_lshlrev_b32_e32 v10, 16, v24
	v_and_b32_e32 v11, 0xffff0000, v24
	v_lshlrev_b32_e32 v12, 16, v25
	v_and_b32_e32 v13, 0xffff0000, v25
	v_fma_f32 v4, v4, v48, v10
	v_fma_f32 v5, v5, v49, v11
	v_fma_f32 v6, v6, v50, v12
	v_fma_f32 v7, v7, v51, v13
	v_cvt_pk_bf16_f32 v14, v4, v5
	v_cvt_pk_bf16_f32 v15, v6, v7
	global_store_dwordx2 v1, v[14:15], s[12:13] nt
	s_add_u32 s12, s12, 0x40000
	s_addc_u32 s13, s13, 0
	v_lshlrev_b32_e32 v10, 16, v26
	v_and_b32_e32 v11, 0xffff0000, v26
	v_lshlrev_b32_e32 v12, 16, v27
	v_and_b32_e32 v13, 0xffff0000, v27
	v_fma_f32 v4, v4, v52, v10
	v_fma_f32 v5, v5, v53, v11
	v_fma_f32 v6, v6, v54, v12
	v_fma_f32 v7, v7, v55, v13
	v_cvt_pk_bf16_f32 v8, v4, v5
	v_cvt_pk_bf16_f32 v9, v6, v7
	global_store_dwordx2 v1, v[8:9], s[12:13] nt
	s_add_u32 s12, s12, 0x40000
	s_addc_u32 s13, s13, 0
	v_lshlrev_b32_e32 v10, 16, v28
	v_and_b32_e32 v11, 0xffff0000, v28
	v_lshlrev_b32_e32 v12, 16, v29
	v_and_b32_e32 v13, 0xffff0000, v29
	v_fma_f32 v4, v4, v56, v10
	v_fma_f32 v5, v5, v57, v11
	v_fma_f32 v6, v6, v58, v12
	v_fma_f32 v7, v7, v59, v13
	v_cvt_pk_bf16_f32 v14, v4, v5
	v_cvt_pk_bf16_f32 v15, v6, v7
	global_store_dwordx2 v1, v[14:15], s[12:13] nt
	s_add_u32 s12, s12, 0x40000
	s_addc_u32 s13, s13, 0
	v_lshlrev_b32_e32 v10, 16, v30
	v_and_b32_e32 v11, 0xffff0000, v30
	v_lshlrev_b32_e32 v12, 16, v31
	v_and_b32_e32 v13, 0xffff0000, v31
	v_fma_f32 v4, v4, v60, v10
	v_fma_f32 v5, v5, v61, v11
	v_fma_f32 v6, v6, v62, v12
	v_fma_f32 v7, v7, v63, v13
	global_load_dwordx2 v[16:17], v1, s[6:7] nt
	global_load_dwordx4 v[32:35], v2, s[8:9] offset:0
	s_add_u32 s6, s6, 0x40000
	s_addc_u32 s7, s7, 0
	global_load_dwordx2 v[18:19], v1, s[6:7] nt
	global_load_dwordx4 v[36:39], v2, s[8:9] offset:2048
	s_add_u32 s8, s8, 0x1000
	s_addc_u32 s9, s9, 0
	s_add_u32 s6, s6, 0x40000
	s_addc_u32 s7, s7, 0
	global_load_dwordx2 v[20:21], v1, s[6:7] nt
	global_load_dwordx4 v[40:43], v2, s[8:9] offset:0
	s_add_u32 s6, s6, 0x40000
	s_addc_u32 s7, s7, 0
	global_load_dwordx2 v[22:23], v1, s[6:7] nt
	global_load_dwordx4 v[44:47], v2, s[8:9] offset:2048
	s_add_u32 s8, s8, 0x1000
	s_addc_u32 s9, s9, 0
	s_add_u32 s6, s6, 0x40000
	s_addc_u32 s7, s7, 0
	global_load_dwordx2 v[24:25], v1, s[6:7] nt
	global_load_dwordx4 v[48:51], v2, s[8:9] offset:0
	s_add_u32 s6, s6, 0x40000
	s_addc_u32 s7, s7, 0
	global_load_dwordx2 v[26:27], v1, s[6:7] nt
	global_load_dwordx4 v[52:55], v2, s[8:9] offset:2048
	s_add_u32 s8, s8, 0x1000
	s_addc_u32 s9, s9, 0
	s_add_u32 s6, s6, 0x40000
	s_addc_u32 s7, s7, 0
	global_load_dwordx2 v[28:29], v1, s[6:7] nt
	global_load_dwordx4 v[56:59], v2, s[8:9] offset:0
	s_add_u32 s6, s6, 0x40000
	s_addc_u32 s7, s7, 0
	global_load_dwordx2 v[30:31], v1, s[6:7] nt
	global_load_dwordx4 v[60:63], v2, s[8:9] offset:2048
	s_add_u32 s8, s8, 0x1000
	s_addc_u32 s9, s9, 0
	s_add_u32 s6, s6, 0x40000
	s_addc_u32 s7, s7, 0
	s_waitcnt vmcnt(24)
; __device__ __forceinline__ u32x2 pk4(f32x4 v) { u32x2 r; r.x = pk2(v[0], v[1]); r.y = pk2(v[2], v[3]); return r; }
; __device__ __forceinline__ f32x4 up4(u32x2 u) { return (f32x4){lo16(u.x), hi16(u.x), lo16(u.y), hi16(u.y)}; }
; __device__ void scan_gla(const Ctx& c, int idx) {
;     ...
;     for (int ck = 0; ck < NCH; ++ck) { u32x2* ad = (u32x2*)(gSt + (size_t)ck * 131072 + e4);
;         const f32x4 st = up4(__builtin_nontemporal_load(ad)); const f32x4 d = *(const f32x4*)(gDec + (size_t)ck * 512 + h * 128 + k4);
;         __builtin_nontemporal_store(pk4(S), ad); S = S * d + st; }
	v_cvt_pk_bf16_f32 v8, v4, v5
	v_cvt_pk_bf16_f32 v9, v6, v7
	global_store_dwordx2 v1, v[8:9], s[12:13] nt
	s_add_u32 s12, s12, 0x40000
	s_addc_u32 s13, s13, 0
	v_lshlrev_b32_e32 v10, 16, v64
	v_and_b32_e32 v11, 0xffff0000, v64
	v_lshlrev_b32_e32 v12, 16, v65
	v_and_b32_e32 v13, 0xffff0000, v65
	v_fma_f32 v4, v4, v80, v10
	v_fma_f32 v5, v5, v81, v11
	v_fma_f32 v6, v6, v82, v12
	v_fma_f32 v7, v7, v83, v13
	v_cvt_pk_bf16_f32 v14, v4, v5
	v_cvt_pk_bf16_f32 v15, v6, v7
	global_store_dwordx2 v1, v[14:15], s[12:13] nt
	s_add_u32 s12, s12, 0x40000
	s_addc_u32 s13, s13, 0
	v_lshlrev_b32_e32 v10, 16, v66
	v_and_b32_e32 v11, 0xffff0000, v66
	v_lshlrev_b32_e32 v12, 16, v67
	v_and_b32_e32 v13, 0xffff0000, v67
	v_fma_f32 v4, v4, v84, v10
	v_fma_f32 v5, v5, v85, v11
	v_fma_f32 v6, v6, v86, v12
	v_fma_f32 v7, v7, v87, v13
	v_cvt_pk_bf16_f32 v8, v4, v5
	v_cvt_pk_bf16_f32 v9, v6, v7
	global_store_dwordx2 v1, v[8:9], s[12:13] nt
	s_add_u32 s12, s12, 0x40000
	s_addc_u32 s13, s13, 0
	v_lshlrev_b32_e32 v10, 16, v68
	v_and_b32_e32 v11, 0xffff0000, v68
	v_lshlrev_b32_e32 v12, 16, v69
	v_and_b32_e32 v13, 0xffff0000, v69
	v_fma_f32 v4, v4, v88, v10
	v_fma_f32 v5, v5, v89, v11
	v_fma_f32 v6, v6, v90, v12
	v_fma_f32 v7, v7, v91, v13
	v_cvt_pk_bf16_f32 v14, v4, v5
	v_cvt_pk_bf16_f32 v15, v6, v7
	global_store_dwordx2 v1, v[14:15], s[12:13] nt
	s_add_u32 s12, s12, 0x40000
	s_addc_u32 s13, s13, 0
	v_lshlrev_b32_e32 v10, 16, v70
	v_and_b32_e32 v11, 0xffff0000, v70
	v_lshlrev_b32_e32 v12, 16, v71
	v_and_b32_e32 v13, 0xffff0000, v71
	v_fma_f32 v4, v4, v92, v10
	v_fma_f32 v5, v5, v93, v11
	v_fma_f32 v6, v6, v94, v12
	v_fma_f32 v7, v7, v95, v13
	v_cvt_pk_bf16_f32 v8, v4, v5
	v_cvt_pk_bf16_f32 v9, v6, v7
	global_store_dwordx2 v1, v[8:9], s[12:13] nt
	s_add_u32 s12, s12, 0x40000
	s_addc_u32 s13, s13, 0
	v_lshlrev_b32_e32 v10, 16, v72
	v_and_b32_e32 v11, 0xffff0000, v72
	v_lshlrev_b32_e32 v12, 16, v73
	v_and_b32_e32 v13, 0xffff0000, v73
	v_fma_f32 v4, v4, v96, v10
	v_fma_f32 v5, v5, v97, v11
	v_fma_f32 v6, v6, v98, v12
	v_fma_f32 v7, v7, v99, v13
	v_cvt_pk_bf16_f32 v14, v4, v5
	v_cvt_pk_bf16_f32 v15, v6, v7
	global_store_dwordx2 v1, v[14:15], s[12:13] nt
	s_add_u32 s12, s12, 0x40000
	s_addc_u32 s13, s13, 0
	v_lshlrev_b32_e32 v10, 16, v74
	v_and_b32_e32 v11, 0xffff0000, v74
	v_lshlrev_b32_e32 v12, 16, v75
	v_and_b32_e32 v13, 0xffff0000, v75
	v_fma_f32 v4, v4, v100, v10
	v_fma_f32 v5, v5, v101, v11
	v_fma_f32 v6, v6, v102, v12
	v_fma_f32 v7, v7, v103, v13
	v_cvt_pk_bf16_f32 v8, v4, v5
	v_cvt_pk_bf16_f32 v9, v6, v7
	global_store_dwordx2 v1, v[8:9], s[12:13] nt
	s_add_u32 s12, s12, 0x40000
	s_addc_u32 s13, s13, 0
	v_lshlrev_b32_e32 v10, 16, v76
	v_and_b32_e32 v11, 0xffff0000, v76
	v_lshlrev_b32_e32 v12, 16, v77
	v_and_b32_e32 v13, 0xffff0000, v77
	v_fma_f32 v4, v4, v104, v10
	v_fma_f32 v5, v5, v105, v11
	v_fma_f32 v6, v6, v106, v12
	v_fma_f32 v7, v7, v107, v13
	v_cvt_pk_bf16_f32 v14, v4, v5
	v_cvt_pk_bf16_f32 v15, v6, v7
	global_store_dwordx2 v1, v[14:15], s[12:13] nt
	s_add_u32 s12, s12, 0x40000
	s_addc_u32 s13, s13, 0
	v_lshlrev_b32_e32 v10, 16, v78
	v_and_b32_e32 v11, 0xffff0000, v78
	v_lshlrev_b32_e32 v12, 16, v79
	v_and_b32_e32 v13, 0xffff0000, v79
	v_fma_f32 v4, v4, v108, v10
	v_fma_f32 v5, v5, v109, v11
	v_fma_f32 v6, v6, v110, v12
	v_fma_f32 v7, v7, v111, v13
	global_load_dwordx2 v[64:65], v1, s[6:7] nt
	global_load_dwordx4 v[80:83], v2, s[8:9] offset:0
	s_add_u32 s6, s6, 0x40000
	s_addc_u32 s7, s7, 0
	global_load_dwordx2 v[66:67], v1, s[6:7] nt
	global_load_dwordx4 v[84:87], v2, s[8:9] offset:2048
	s_add_u32 s8, s8, 0x1000
	s_addc_u32 s9, s9, 0
	s_add_u32 s6, s6, 0x40000
	s_addc_u32 s7, s7, 0
	global_load_dwordx2 v[68:69], v1, s[6:7] nt
	global_load_dwordx4 v[88:91], v2, s[8:9] offset:0
	s_add_u32 s6, s6, 0x40000
	s_addc_u32 s7, s7, 0
	global_load_dwordx2 v[70:71], v1, s[6:7] nt
	global_load_dwordx4 v[92:95], v2, s[8:9] offset:2048
	s_add_u32 s8, s8, 0x1000
	s_addc_u32 s9, s9, 0
	s_add_u32 s6, s6, 0x40000
	s_addc_u32 s7, s7, 0
	global_load_dwordx2 v[72:73], v1, s[6:7] nt
	global_load_dwordx4 v[96:99], v2, s[8:9] offset:0
	s_add_u32 s6, s6, 0x40000
	s_addc_u32 s7, s7, 0
	global_load_dwordx2 v[74:75], v1, s[6:7] nt
	global_load_dwordx4 v[100:103], v2, s[8:9] offset:2048
	s_add_u32 s8, s8, 0x1000
	s_addc_u32 s9, s9, 0
	s_add_u32 s6, s6, 0x40000
	s_addc_u32 s7, s7, 0
	global_load_dwordx2 v[76:77], v1, s[6:7] nt
	global_load_dwordx4 v[104:107], v2, s[8:9] offset:0
	s_add_u32 s6, s6, 0x40000
	s_addc_u32 s7, s7, 0
	global_load_dwordx2 v[78:79], v1, s[6:7] nt
	global_load_dwordx4 v[108:111], v2, s[8:9] offset:2048
	s_add_u32 s8, s8, 0x1000
	s_addc_u32 s9, s9, 0
	s_add_u32 s6, s6, 0x40000
	s_addc_u32 s7, s7, 0
	s_waitcnt vmcnt(24)
; __device__ __forceinline__ u32x2 pk4(f32x4 v) { u32x2 r; r.x = pk2(v[0], v[1]); r.y = pk2(v[2], v[3]); return r; }
; __device__ __forceinline__ f32x4 up4(u32x2 u) { return (f32x4){lo16(u.x), hi16(u.x), lo16(u.y), hi16(u.y)}; }
; __device__ void scan_gla(const Ctx& c, int idx) {
;     ...
;     for (int ck = 0; ck < NCH; ++ck) { u32x2* ad = (u32x2*)(gSt + (size_t)ck * 131072 + e4);
;         const f32x4 st = up4(__builtin_nontemporal_load(ad)); const f32x4 d = *(const f32x4*)(gDec + (size_t)ck * 512 + h * 128 + k4);
;         __builtin_nontemporal_store(pk4(S), ad); S = S * d + st; }
	v_cvt_pk_bf16_f32 v8, v4, v5
	v_cvt_pk_bf16_f32 v9, v6, v7
	global_store_dwordx2 v1, v[8:9], s[12:13] nt
	s_add_u32 s12, s12, 0x40000
	s_addc_u32 s13, s13, 0
	v_lshlrev_b32_e32 v10, 16, v16
	v_and_b32_e32 v11, 0xffff0000, v16
	v_lshlrev_b32_e32 v12, 16, v17
	v_and_b32_e32 v13, 0xffff0000, v17
	v_fma_f32 v4, v4, v32, v10
	v_fma_f32 v5, v5, v33, v11
	v_fma_f32 v6, v6, v34, v12
	v_fma_f32 v7, v7, v35, v13
	v_cvt_pk_bf16_f32 v14, v4, v5
	v_cvt_pk_bf16_f32 v15, v6, v7
	global_store_dwordx2 v1, v[14:15], s[12:13] nt
	s_add_u32 s12, s12, 0x40000
	s_addc_u32 s13, s13, 0
	v_lshlrev_b32_e32 v10, 16, v18
	v_and_b32_e32 v11, 0xffff0000, v18
	v_lshlrev_b32_e32 v12, 16, v19
	v_and_b32_e32 v13, 0xffff0000, v19
	v_fma_f32 v4, v4, v36, v10
	v_fma_f32 v5, v5, v37, v11
	v_fma_f32 v6, v6, v38, v12
	v_fma_f32 v7, v7, v39, v13
	v_cvt_pk_bf16_f32 v8, v4, v5
	v_cvt_pk_bf16_f32 v9, v6, v7
	global_store_dwordx2 v1, v[8:9], s[12:13] nt
	s_add_u32 s12, s12, 0x40000
	s_addc_u32 s13, s13, 0
	v_lshlrev_b32_e32 v10, 16, v20
	v_and_b32_e32 v11, 0xffff0000, v20
	v_lshlrev_b32_e32 v12, 16, v21
	v_and_b32_e32 v13, 0xffff0000, v21
	v_fma_f32 v4, v4, v40, v10
	v_fma_f32 v5, v5, v41, v11
	v_fma_f32 v6, v6, v42, v12
	v_fma_f32 v7, v7, v43, v13
	v_cvt_pk_bf16_f32 v14, v4, v5
	v_cvt_pk_bf16_f32 v15, v6, v7
	global_store_dwordx2 v1, v[14:15], s[12:13] nt
	s_add_u32 s12, s12, 0x40000
	s_addc_u32 s13, s13, 0
	v_lshlrev_b32_e32 v10, 16, v22
	v_and_b32_e32 v11, 0xffff0000, v22
	v_lshlrev_b32_e32 v12, 16, v23
	v_and_b32_e32 v13, 0xffff0000, v23
	v_fma_f32 v4, v4, v44, v10
	v_fma_f32 v5, v5, v45, v11
	v_fma_f32 v6, v6, v46, v12
	v_fma_f32 v7, v7, v47, v13
	v_cvt_pk_bf16_f32 v8, v4, v5
	v_cvt_pk_bf16_f32 v9, v6, v7
	global_store_dwordx2 v1, v[8:9], s[12:13] nt
	s_add_u32 s12, s12, 0x40000
	s_addc_u32 s13, s13, 0
	v_lshlrev_b32_e32 v10, 16, v24
	v_and_b32_e32 v11, 0xffff0000, v24
	v_lshlrev_b32_e32 v12, 16, v25
	v_and_b32_e32 v13, 0xffff0000, v25
	v_fma_f32 v4, v4, v48, v10
	v_fma_f32 v5, v5, v49, v11
	v_fma_f32 v6, v6, v50, v12
	v_fma_f32 v7, v7, v51, v13
	v_cvt_pk_bf16_f32 v14, v4, v5
	v_cvt_pk_bf16_f32 v15, v6, v7
	global_store_dwordx2 v1, v[14:15], s[12:13] nt
	s_add_u32 s12, s12, 0x40000
	s_addc_u32 s13, s13, 0
	v_lshlrev_b32_e32 v10, 16, v26
	v_and_b32_e32 v11, 0xffff0000, v26
	v_lshlrev_b32_e32 v12, 16, v27
	v_and_b32_e32 v13, 0xffff0000, v27
	v_fma_f32 v4, v4, v52, v10
	v_fma_f32 v5, v5, v53, v11
	v_fma_f32 v6, v6, v54, v12
	v_fma_f32 v7, v7, v55, v13
	v_cvt_pk_bf16_f32 v8, v4, v5
	v_cvt_pk_bf16_f32 v9, v6, v7
	global_store_dwordx2 v1, v[8:9], s[12:13] nt
	s_add_u32 s12, s12, 0x40000
	s_addc_u32 s13, s13, 0
	v_lshlrev_b32_e32 v10, 16, v28
	v_and_b32_e32 v11, 0xffff0000, v28
	v_lshlrev_b32_e32 v12, 16, v29
	v_and_b32_e32 v13, 0xffff0000, v29
	v_fma_f32 v4, v4, v56, v10
	v_fma_f32 v5, v5, v57, v11
	v_fma_f32 v6, v6, v58, v12
	v_fma_f32 v7, v7, v59, v13
	v_cvt_pk_bf16_f32 v14, v4, v5
	v_cvt_pk_bf16_f32 v15, v6, v7
	global_store_dwordx2 v1, v[14:15], s[12:13] nt
	s_add_u32 s12, s12, 0x40000
	s_addc_u32 s13, s13, 0
	v_lshlrev_b32_e32 v10, 16, v30
	v_and_b32_e32 v11, 0xffff0000, v30
	v_lshlrev_b32_e32 v12, 16, v31
	v_and_b32_e32 v13, 0xffff0000, v31
	v_fma_f32 v4, v4, v60, v10
	v_fma_f32 v5, v5, v61, v11
	v_fma_f32 v6, v6, v62, v12
	v_fma_f32 v7, v7, v63, v13
	global_load_dwordx2 v[16:17], v1, s[6:7] nt
	global_load_dwordx4 v[32:35], v2, s[8:9] offset:0
	s_add_u32 s6, s6, 0x40000
	s_addc_u32 s7, s7, 0
	global_load_dwordx2 v[18:19], v1, s[6:7] nt
	global_load_dwordx4 v[36:39], v2, s[8:9] offset:2048
	s_add_u32 s8, s8, 0x1000
	s_addc_u32 s9, s9, 0
	s_add_u32 s6, s6, 0x40000
	s_addc_u32 s7, s7, 0
	global_load_dwordx2 v[20:21], v1, s[6:7] nt
	global_load_dwordx4 v[40:43], v2, s[8:9] offset:0
	s_add_u32 s6, s6, 0x40000
	s_addc_u32 s7, s7, 0
	global_load_dwordx2 v[22:23], v1, s[6:7] nt
	global_load_dwordx4 v[44:47], v2, s[8:9] offset:2048
	s_add_u32 s8, s8, 0x1000
	s_addc_u32 s9, s9, 0
	s_add_u32 s6, s6, 0x40000
	s_addc_u32 s7, s7, 0
	global_load_dwordx2 v[24:25], v1, s[6:7] nt
	global_load_dwordx4 v[48:51], v2, s[8:9] offset:0
	s_add_u32 s6, s6, 0x40000
	s_addc_u32 s7, s7, 0
	global_load_dwordx2 v[26:27], v1, s[6:7] nt
	global_load_dwordx4 v[52:55], v2, s[8:9] offset:2048
	s_add_u32 s8, s8, 0x1000
	s_addc_u32 s9, s9, 0
	s_add_u32 s6, s6, 0x40000
	s_addc_u32 s7, s7, 0
	global_load_dwordx2 v[28:29], v1, s[6:7] nt
	global_load_dwordx4 v[56:59], v2, s[8:9] offset:0
	s_add_u32 s6, s6, 0x40000
	s_addc_u32 s7, s7, 0
	global_load_dwordx2 v[30:31], v1, s[6:7] nt
	global_load_dwordx4 v[60:63], v2, s[8:9] offset:2048
	s_add_u32 s8, s8, 0x1000
	s_addc_u32 s9, s9, 0
	s_add_u32 s6, s6, 0x40000
	s_addc_u32 s7, s7, 0
	s_waitcnt vmcnt(24)
; __device__ __forceinline__ u32x2 pk4(f32x4 v) { u32x2 r; r.x = pk2(v[0], v[1]); r.y = pk2(v[2], v[3]); return r; }
; __device__ __forceinline__ f32x4 up4(u32x2 u) { return (f32x4){lo16(u.x), hi16(u.x), lo16(u.y), hi16(u.y)}; }
; __device__ void scan_gla(const Ctx& c, int idx) {
;     ...
;     for (int ck = 0; ck < NCH; ++ck) { u32x2* ad = (u32x2*)(gSt + (size_t)ck * 131072 + e4);
;         const f32x4 st = up4(__builtin_nontemporal_load(ad)); const f32x4 d = *(const f32x4*)(gDec + (size_t)ck * 512 + h * 128 + k4);
;         __builtin_nontemporal_store(pk4(S), ad); S = S * d + st; }
	v_cvt_pk_bf16_f32 v8, v4, v5
	v_cvt_pk_bf16_f32 v9, v6, v7
	global_store_dwordx2 v1, v[8:9], s[12:13] nt
	s_add_u32 s12, s12, 0x40000
	s_addc_u32 s13, s13, 0
	v_lshlrev_b32_e32 v10, 16, v64
	v_and_b32_e32 v11, 0xffff0000, v64
	v_lshlrev_b32_e32 v12, 16, v65
	v_and_b32_e32 v13, 0xffff0000, v65
	v_fma_f32 v4, v4, v80, v10
	v_fma_f32 v5, v5, v81, v11
	v_fma_f32 v6, v6, v82, v12
	v_fma_f32 v7, v7, v83, v13
	v_cvt_pk_bf16_f32 v14, v4, v5
	v_cvt_pk_bf16_f32 v15, v6, v7
	global_store_dwordx2 v1, v[14:15], s[12:13] nt
	s_add_u32 s12, s12, 0x40000
	s_addc_u32 s13, s13, 0
	v_lshlrev_b32_e32 v10, 16, v66
	v_and_b32_e32 v11, 0xffff0000, v66
	v_lshlrev_b32_e32 v12, 16, v67
	v_and_b32_e32 v13, 0xffff0000, v67
	v_fma_f32 v4, v4, v84, v10
	v_fma_f32 v5, v5, v85, v11
	v_fma_f32 v6, v6, v86, v12
	v_fma_f32 v7, v7, v87, v13
	v_cvt_pk_bf16_f32 v8, v4, v5
	v_cvt_pk_bf16_f32 v9, v6, v7
	global_store_dwordx2 v1, v[8:9], s[12:13] nt
	s_add_u32 s12, s12, 0x40000
	s_addc_u32 s13, s13, 0
	v_lshlrev_b32_e32 v10, 16, v68
	v_and_b32_e32 v11, 0xffff0000, v68
	v_lshlrev_b32_e32 v12, 16, v69
	v_and_b32_e32 v13, 0xffff0000, v69
	v_fma_f32 v4, v4, v88, v10
	v_fma_f32 v5, v5, v89, v11
	v_fma_f32 v6, v6, v90, v12
	v_fma_f32 v7, v7, v91, v13
	v_cvt_pk_bf16_f32 v14, v4, v5
	v_cvt_pk_bf16_f32 v15, v6, v7
	global_store_dwordx2 v1, v[14:15], s[12:13] nt
	s_add_u32 s12, s12, 0x40000
	s_addc_u32 s13, s13, 0
	v_lshlrev_b32_e32 v10, 16, v70
	v_and_b32_e32 v11, 0xffff0000, v70
	v_lshlrev_b32_e32 v12, 16, v71
	v_and_b32_e32 v13, 0xffff0000, v71
	v_fma_f32 v4, v4, v92, v10
	v_fma_f32 v5, v5, v93, v11
	v_fma_f32 v6, v6, v94, v12
	v_fma_f32 v7, v7, v95, v13
	v_cvt_pk_bf16_f32 v8, v4, v5
	v_cvt_pk_bf16_f32 v9, v6, v7
	global_store_dwordx2 v1, v[8:9], s[12:13] nt
	s_add_u32 s12, s12, 0x40000
	s_addc_u32 s13, s13, 0
	v_lshlrev_b32_e32 v10, 16, v72
	v_and_b32_e32 v11, 0xffff0000, v72
	v_lshlrev_b32_e32 v12, 16, v73
	v_and_b32_e32 v13, 0xffff0000, v73
	v_fma_f32 v4, v4, v96, v10
	v_fma_f32 v5, v5, v97, v11
	v_fma_f32 v6, v6, v98, v12
	v_fma_f32 v7, v7, v99, v13
	v_cvt_pk_bf16_f32 v14, v4, v5
	v_cvt_pk_bf16_f32 v15, v6, v7
	global_store_dwordx2 v1, v[14:15], s[12:13] nt
	s_add_u32 s12, s12, 0x40000
	s_addc_u32 s13, s13, 0
	v_lshlrev_b32_e32 v10, 16, v74
	v_and_b32_e32 v11, 0xffff0000, v74
	v_lshlrev_b32_e32 v12, 16, v75
	v_and_b32_e32 v13, 0xffff0000, v75
	v_fma_f32 v4, v4, v100, v10
	v_fma_f32 v5, v5, v101, v11
	v_fma_f32 v6, v6, v102, v12
	v_fma_f32 v7, v7, v103, v13
	v_cvt_pk_bf16_f32 v8, v4, v5
	v_cvt_pk_bf16_f32 v9, v6, v7
	global_store_dwordx2 v1, v[8:9], s[12:13] nt
	s_add_u32 s12, s12, 0x40000
	s_addc_u32 s13, s13, 0
	v_lshlrev_b32_e32 v10, 16, v76
	v_and_b32_e32 v11, 0xffff0000, v76
	v_lshlrev_b32_e32 v12, 16, v77
	v_and_b32_e32 v13, 0xffff0000, v77
	v_fma_f32 v4, v4, v104, v10
	v_fma_f32 v5, v5, v105, v11
	v_fma_f32 v6, v6, v106, v12
	v_fma_f32 v7, v7, v107, v13
	v_cvt_pk_bf16_f32 v14, v4, v5
	v_cvt_pk_bf16_f32 v15, v6, v7
	global_store_dwordx2 v1, v[14:15], s[12:13] nt
	s_add_u32 s12, s12, 0x40000
	s_addc_u32 s13, s13, 0
	v_lshlrev_b32_e32 v10, 16, v78
	v_and_b32_e32 v11, 0xffff0000, v78
	v_lshlrev_b32_e32 v12, 16, v79
	v_and_b32_e32 v13, 0xffff0000, v79
	v_fma_f32 v4, v4, v108, v10
	v_fma_f32 v5, v5, v109, v11
	v_fma_f32 v6, v6, v110, v12
	v_fma_f32 v7, v7, v111, v13
	global_load_dwordx2 v[64:65], v1, s[6:7] nt
	global_load_dwordx4 v[80:83], v2, s[8:9] offset:0
	s_add_u32 s6, s6, 0x40000
	s_addc_u32 s7, s7, 0
	global_load_dwordx2 v[66:67], v1, s[6:7] nt
	global_load_dwordx4 v[84:87], v2, s[8:9] offset:2048
	s_add_u32 s8, s8, 0x1000
	s_addc_u32 s9, s9, 0
	s_add_u32 s6, s6, 0x40000
	s_addc_u32 s7, s7, 0
	global_load_dwordx2 v[68:69], v1, s[6:7] nt
	global_load_dwordx4 v[88:91], v2, s[8:9] offset:0
	s_add_u32 s6, s6, 0x40000
	s_addc_u32 s7, s7, 0
	global_load_dwordx2 v[70:71], v1, s[6:7] nt
	global_load_dwordx4 v[92:95], v2, s[8:9] offset:2048
	s_add_u32 s8, s8, 0x1000
	s_addc_u32 s9, s9, 0
	s_add_u32 s6, s6, 0x40000
	s_addc_u32 s7, s7, 0
	global_load_dwordx2 v[72:73], v1, s[6:7] nt
	global_load_dwordx4 v[96:99], v2, s[8:9] offset:0
	s_add_u32 s6, s6, 0x40000
	s_addc_u32 s7, s7, 0
	global_load_dwordx2 v[74:75], v1, s[6:7] nt
	global_load_dwordx4 v[100:103], v2, s[8:9] offset:2048
	s_add_u32 s8, s8, 0x1000
	s_addc_u32 s9, s9, 0
	s_add_u32 s6, s6, 0x40000
	s_addc_u32 s7, s7, 0
	global_load_dwordx2 v[76:77], v1, s[6:7] nt
	global_load_dwordx4 v[104:107], v2, s[8:9] offset:0
	s_add_u32 s6, s6, 0x40000
	s_addc_u32 s7, s7, 0
	global_load_dwordx2 v[78:79], v1, s[6:7] nt
	global_load_dwordx4 v[108:111], v2, s[8:9] offset:2048
	s_add_u32 s8, s8, 0x1000
	s_addc_u32 s9, s9, 0
	s_add_u32 s6, s6, 0x40000
	s_addc_u32 s7, s7, 0
	s_waitcnt vmcnt(24)
; __device__ __forceinline__ u32x2 pk4(f32x4 v) { u32x2 r; r.x = pk2(v[0], v[1]); r.y = pk2(v[2], v[3]); return r; }
; __device__ __forceinline__ f32x4 up4(u32x2 u) { return (f32x4){lo16(u.x), hi16(u.x), lo16(u.y), hi16(u.y)}; }
; __device__ void scan_gla(const Ctx& c, int idx) {
;     ...
;     for (int ck = 0; ck < NCH; ++ck) { u32x2* ad = (u32x2*)(gSt + (size_t)ck * 131072 + e4);
;         const f32x4 st = up4(__builtin_nontemporal_load(ad)); const f32x4 d = *(const f32x4*)(gDec + (size_t)ck * 512 + h * 128 + k4);
;         __builtin_nontemporal_store(pk4(S), ad); S = S * d + st; }
	v_cvt_pk_bf16_f32 v8, v4, v5
	v_cvt_pk_bf16_f32 v9, v6, v7
	global_store_dwordx2 v1, v[8:9], s[12:13] nt
	s_add_u32 s12, s12, 0x40000
	s_addc_u32 s13, s13, 0
	v_lshlrev_b32_e32 v10, 16, v16
	v_and_b32_e32 v11, 0xffff0000, v16
	v_lshlrev_b32_e32 v12, 16, v17
	v_and_b32_e32 v13, 0xffff0000, v17
	v_fma_f32 v4, v4, v32, v10
	v_fma_f32 v5, v5, v33, v11
	v_fma_f32 v6, v6, v34, v12
	v_fma_f32 v7, v7, v35, v13
	v_cvt_pk_bf16_f32 v14, v4, v5
	v_cvt_pk_bf16_f32 v15, v6, v7
	global_store_dwordx2 v1, v[14:15], s[12:13] nt
	s_add_u32 s12, s12, 0x40000
	s_addc_u32 s13, s13, 0
	v_lshlrev_b32_e32 v10, 16, v18
	v_and_b32_e32 v11, 0xffff0000, v18
	v_lshlrev_b32_e32 v12, 16, v19
	v_and_b32_e32 v13, 0xffff0000, v19
	v_fma_f32 v4, v4, v36, v10
	v_fma_f32 v5, v5, v37, v11
	v_fma_f32 v6, v6, v38, v12
	v_fma_f32 v7, v7, v39, v13
	v_cvt_pk_bf16_f32 v8, v4, v5
	v_cvt_pk_bf16_f32 v9, v6, v7
	global_store_dwordx2 v1, v[8:9], s[12:13] nt
	s_add_u32 s12, s12, 0x40000
	s_addc_u32 s13, s13, 0
	v_lshlrev_b32_e32 v10, 16, v20
	v_and_b32_e32 v11, 0xffff0000, v20
	v_lshlrev_b32_e32 v12, 16, v21
	v_and_b32_e32 v13, 0xffff0000, v21
	v_fma_f32 v4, v4, v40, v10
	v_fma_f32 v5, v5, v41, v11
	v_fma_f32 v6, v6, v42, v12
	v_fma_f32 v7, v7, v43, v13
	v_cvt_pk_bf16_f32 v14, v4, v5
	v_cvt_pk_bf16_f32 v15, v6, v7
	global_store_dwordx2 v1, v[14:15], s[12:13] nt
	s_add_u32 s12, s12, 0x40000
	s_addc_u32 s13, s13, 0
	v_lshlrev_b32_e32 v10, 16, v22
	v_and_b32_e32 v11, 0xffff0000, v22
	v_lshlrev_b32_e32 v12, 16, v23
	v_and_b32_e32 v13, 0xffff0000, v23
	v_fma_f32 v4, v4, v44, v10
	v_fma_f32 v5, v5, v45, v11
	v_fma_f32 v6, v6, v46, v12
	v_fma_f32 v7, v7, v47, v13
	v_cvt_pk_bf16_f32 v8, v4, v5
	v_cvt_pk_bf16_f32 v9, v6, v7
	global_store_dwordx2 v1, v[8:9], s[12:13] nt
	s_add_u32 s12, s12, 0x40000
	s_addc_u32 s13, s13, 0
	v_lshlrev_b32_e32 v10, 16, v24
	v_and_b32_e32 v11, 0xffff0000, v24
	v_lshlrev_b32_e32 v12, 16, v25
	v_and_b32_e32 v13, 0xffff0000, v25
	v_fma_f32 v4, v4, v48, v10
	v_fma_f32 v5, v5, v49, v11
	v_fma_f32 v6, v6, v50, v12
	v_fma_f32 v7, v7, v51, v13
	v_cvt_pk_bf16_f32 v14, v4, v5
	v_cvt_pk_bf16_f32 v15, v6, v7
	global_store_dwordx2 v1, v[14:15], s[12:13] nt
	s_add_u32 s12, s12, 0x40000
	s_addc_u32 s13, s13, 0
	v_lshlrev_b32_e32 v10, 16, v26
	v_and_b32_e32 v11, 0xffff0000, v26
	v_lshlrev_b32_e32 v12, 16, v27
	v_and_b32_e32 v13, 0xffff0000, v27
	v_fma_f32 v4, v4, v52, v10
	v_fma_f32 v5, v5, v53, v11
	v_fma_f32 v6, v6, v54, v12
	v_fma_f32 v7, v7, v55, v13
	v_cvt_pk_bf16_f32 v8, v4, v5
	v_cvt_pk_bf16_f32 v9, v6, v7
	global_store_dwordx2 v1, v[8:9], s[12:13] nt
	s_add_u32 s12, s12, 0x40000
	s_addc_u32 s13, s13, 0
	v_lshlrev_b32_e32 v10, 16, v28
	v_and_b32_e32 v11, 0xffff0000, v28
	v_lshlrev_b32_e32 v12, 16, v29
	v_and_b32_e32 v13, 0xffff0000, v29
	v_fma_f32 v4, v4, v56, v10
	v_fma_f32 v5, v5, v57, v11
	v_fma_f32 v6, v6, v58, v12
	v_fma_f32 v7, v7, v59, v13
	v_cvt_pk_bf16_f32 v14, v4, v5
	v_cvt_pk_bf16_f32 v15, v6, v7
	global_store_dwordx2 v1, v[14:15], s[12:13] nt
	s_add_u32 s12, s12, 0x40000
	s_addc_u32 s13, s13, 0
	v_lshlrev_b32_e32 v10, 16, v30
	v_and_b32_e32 v11, 0xffff0000, v30
	v_lshlrev_b32_e32 v12, 16, v31
	v_and_b32_e32 v13, 0xffff0000, v31
	v_fma_f32 v4, v4, v60, v10
	v_fma_f32 v5, v5, v61, v11
	v_fma_f32 v6, v6, v62, v12
	v_fma_f32 v7, v7, v63, v13
	s_waitcnt vmcnt(8)
	v_cvt_pk_bf16_f32 v8, v4, v5
	v_cvt_pk_bf16_f32 v9, v6, v7
	global_store_dwordx2 v1, v[8:9], s[12:13] nt
	s_add_u32 s12, s12, 0x40000
	s_addc_u32 s13, s13, 0
	v_lshlrev_b32_e32 v10, 16, v64
	v_and_b32_e32 v11, 0xffff0000, v64
	v_lshlrev_b32_e32 v12, 16, v65
	v_and_b32_e32 v13, 0xffff0000, v65
	v_fma_f32 v4, v4, v80, v10
	v_fma_f32 v5, v5, v81, v11
	v_fma_f32 v6, v6, v82, v12
	v_fma_f32 v7, v7, v83, v13
	v_cvt_pk_bf16_f32 v14, v4, v5
	v_cvt_pk_bf16_f32 v15, v6, v7
	global_store_dwordx2 v1, v[14:15], s[12:13] nt
	s_add_u32 s12, s12, 0x40000
	s_addc_u32 s13, s13, 0
	v_lshlrev_b32_e32 v10, 16, v66
	v_and_b32_e32 v11, 0xffff0000, v66
	v_lshlrev_b32_e32 v12, 16, v67
	v_and_b32_e32 v13, 0xffff0000, v67
	v_fma_f32 v4, v4, v84, v10
	v_fma_f32 v5, v5, v85, v11
	v_fma_f32 v6, v6, v86, v12
	v_fma_f32 v7, v7, v87, v13
	v_cvt_pk_bf16_f32 v8, v4, v5
	v_cvt_pk_bf16_f32 v9, v6, v7
	global_store_dwordx2 v1, v[8:9], s[12:13] nt
	s_add_u32 s12, s12, 0x40000
	s_addc_u32 s13, s13, 0
	v_lshlrev_b32_e32 v10, 16, v68
	v_and_b32_e32 v11, 0xffff0000, v68
	v_lshlrev_b32_e32 v12, 16, v69
	v_and_b32_e32 v13, 0xffff0000, v69
	v_fma_f32 v4, v4, v88, v10
	v_fma_f32 v5, v5, v89, v11
	v_fma_f32 v6, v6, v90, v12
	v_fma_f32 v7, v7, v91, v13
	v_cvt_pk_bf16_f32 v14, v4, v5
	v_cvt_pk_bf16_f32 v15, v6, v7
	global_store_dwordx2 v1, v[14:15], s[12:13] nt
	s_add_u32 s12, s12, 0x40000
	s_addc_u32 s13, s13, 0
	v_lshlrev_b32_e32 v10, 16, v70
	v_and_b32_e32 v11, 0xffff0000, v70
	v_lshlrev_b32_e32 v12, 16, v71
	v_and_b32_e32 v13, 0xffff0000, v71
	v_fma_f32 v4, v4, v92, v10
	v_fma_f32 v5, v5, v93, v11
	v_fma_f32 v6, v6, v94, v12
	v_fma_f32 v7, v7, v95, v13
	v_cvt_pk_bf16_f32 v8, v4, v5
	v_cvt_pk_bf16_f32 v9, v6, v7
	global_store_dwordx2 v1, v[8:9], s[12:13] nt
	s_add_u32 s12, s12, 0x40000
	s_addc_u32 s13, s13, 0
	v_lshlrev_b32_e32 v10, 16, v72
	v_and_b32_e32 v11, 0xffff0000, v72
	v_lshlrev_b32_e32 v12, 16, v73
	v_and_b32_e32 v13, 0xffff0000, v73
	v_fma_f32 v4, v4, v96, v10
	v_fma_f32 v5, v5, v97, v11
	v_fma_f32 v6, v6, v98, v12
	v_fma_f32 v7, v7, v99, v13
	v_cvt_pk_bf16_f32 v14, v4, v5
	v_cvt_pk_bf16_f32 v15, v6, v7
	global_store_dwordx2 v1, v[14:15], s[12:13] nt
	s_add_u32 s12, s12, 0x40000
	s_addc_u32 s13, s13, 0
	v_lshlrev_b32_e32 v10, 16, v74
	v_and_b32_e32 v11, 0xffff0000, v74
	v_lshlrev_b32_e32 v12, 16, v75
	v_and_b32_e32 v13, 0xffff0000, v75
	v_fma_f32 v4, v4, v100, v10
	v_fma_f32 v5, v5, v101, v11
	v_fma_f32 v6, v6, v102, v12
	v_fma_f32 v7, v7, v103, v13
	v_cvt_pk_bf16_f32 v8, v4, v5
	v_cvt_pk_bf16_f32 v9, v6, v7
	global_store_dwordx2 v1, v[8:9], s[12:13] nt
	s_add_u32 s12, s12, 0x40000
	s_addc_u32 s13, s13, 0
	v_lshlrev_b32_e32 v10, 16, v76
	v_and_b32_e32 v11, 0xffff0000, v76
	v_lshlrev_b32_e32 v12, 16, v77
	v_and_b32_e32 v13, 0xffff0000, v77
	v_fma_f32 v4, v4, v104, v10
	v_fma_f32 v5, v5, v105, v11
	v_fma_f32 v6, v6, v106, v12
	v_fma_f32 v7, v7, v107, v13
	v_cvt_pk_bf16_f32 v14, v4, v5
	v_cvt_pk_bf16_f32 v15, v6, v7
	global_store_dwordx2 v1, v[14:15], s[12:13] nt
	s_add_u32 s12, s12, 0x40000
	s_addc_u32 s13, s13, 0
	v_lshlrev_b32_e32 v10, 16, v78
	v_and_b32_e32 v11, 0xffff0000, v78
	v_lshlrev_b32_e32 v12, 16, v79
	v_and_b32_e32 v13, 0xffff0000, v79
	v_fma_f32 v4, v4, v108, v10
	v_fma_f32 v5, v5, v109, v11
	v_fma_f32 v6, v6, v110, v12
	v_fma_f32 v7, v7, v111, v13
	s_branch .Lscan_done
.Lscan_done:
	s_waitcnt vmcnt(0)
	s_mov_b64 s[0:1], exec

; __device__ __forceinline__ u32x2 pk4(f32x4 v) { u32x2 r; r.x = pk2(v[0], v[1]); r.y = pk2(v[2], v[3]); return r; }
; __device__ __forceinline__ f32x4 mfma16(bf16x8 a, bf16x8 b, f32x4 c) { return __builtin_amdgcn_mfma_f32_16x16x32_bf16(a, b, c, 0, 0, 0); }
; __device__ __forceinline__ void dn_stage_load(DnStage& S, const bf16_t* dW, const bf16_t* dUT, const bf16_t* dKdT, const float* dGl, int ck, int h, int vs, int wave, int r, int q) {
;     ...
; #pragma unroll
;         for (int t = 0; t < 2; ++t)
; #pragma unroll
;             for (int kk = 0; kk < 2; ++kk) S.f[t * 2 + kk] = ldfrag(dKdT + (ch * 128 + ((wave - 4) * 2 + t) * 16 + r) * 64 + kk * 32 + q * 8);
;         S.gl = dGl[ch];
; __device__ __forceinline__ void dn_step(const DnStage& S, f32x4 (&Sacc)[2], bf16_t* ST, bf16_t* VN, bf16_t* dVnT, bf16_t* dST, int ck, int h, int vs, int wave, int r, int q) {
;     ...
;     if (wave >= 4) {
;         bf16x8 vf[2];
; #pragma unroll
;         for (int kk = 0; kk < 2; ++kk) vf[kk] = *(const bf16x8*)(VN + r * 72 + kk * 32 + q * 8);
; #pragma unroll
;         for (int t = 0; t < 2; ++t) { const int kb = (wave - 4) * 2 + t;
;             f32x4 a = Sacc[t] * S.gl;
; #pragma unroll
;             for (int kk = 0; kk < 2; ++kk) a = mfma16(S.f[t * 2 + kk], vf[kk], a);
;             Sacc[t] = a; const u32x2 ps = pk4(a);
;             *(u32x2*)(ST + r * 136 + kb * 16 + 4 * q) = ps;
;             if (ck + 1 < NCH) *(u32x2*)(dST + (((size_t)(ck + 1) * 8 + h) * 128 + vs * 16 + r) * 128 + kb * 16 + 4 * q) = ps; }
;     }
;     asm volatile("s_waitcnt lgkmcnt(0)" ::: "memory"); __builtin_amdgcn_s_barrier(); asm volatile("" ::: "memory");
.Ldq_B:
	s_sub_u32 s0, s22, 4
	s_lshl_b32 s1, s0, 12
	v_and_b32_e32 v10, 63, v234
	v_lshlrev_b32_e32 v10, 4, v10
	v_add_u32_e32 v10, s1, v10
	v_and_b32_e32 v0, 63, v234
	v_lshlrev_b32_e32 v11, 5, v0
	v_mul_u32_u24_e32 v12, 0x90, v1
	v_lshl_add_u32 v12, v2, 4, v12
	v_add_u32_e32 v12, 0x1100, v12
	s_lshl_b32 s1, s0, 6
	v_add_u32_e32 v13, s1, v4
	v_lshl_add_u32 v13, v2, 3, v3
	v_add_u32_e32 v13, s1, v13
	v_add_u32_e32 v14, s1, v6
	s_add_u32 s14, s4, 0x24100000
	s_addc_u32 s15, s5, 0
	s_add_u32 s14, s14, s3
	s_addc_u32 s15, s15, 0
	s_lshl_b32 s1, s11, 2
	s_add_u32 s16, s4, 0x29900000
	s_addc_u32 s17, s5, 0
	s_add_u32 s16, s16, s1
	s_addc_u32 s17, s17, 0
	v_mov_b32_e32 v128, 0
	v_mov_b32_e32 v129, 0
	v_mov_b32_e32 v130, 0
	v_mov_b32_e32 v131, 0
	v_mov_b32_e32 v132, 0
	v_mov_b32_e32 v133, 0
	v_mov_b32_e32 v134, 0
	v_mov_b32_e32 v135, 0
	global_load_dword v152, v11, s[16:17]
	global_load_dword v153, v11, s[16:17] offset:2048
	s_mov_b32 s41, 0
	global_load_dwordx4 v[16:19], v10, s[14:15] offset:0
	global_load_dwordx4 v[20:23], v10, s[14:15] offset:1024
	global_load_dwordx4 v[24:27], v10, s[14:15] offset:2048
	global_load_dwordx4 v[28:31], v10, s[14:15] offset:3072
	s_add_u32 s14, s14, 0x20000
	s_addc_u32 s15, s15, 0
	global_load_dwordx4 v[34:37], v10, s[14:15] offset:0
	global_load_dwordx4 v[38:41], v10, s[14:15] offset:1024
	global_load_dwordx4 v[42:45], v10, s[14:15] offset:2048
	global_load_dwordx4 v[46:49], v10, s[14:15] offset:3072
	s_add_u32 s14, s14, 0x20000
	s_addc_u32 s15, s15, 0
	global_load_dwordx4 v[52:55], v10, s[14:15] offset:0
	global_load_dwordx4 v[56:59], v10, s[14:15] offset:1024
	global_load_dwordx4 v[60:63], v10, s[14:15] offset:2048
	global_load_dwordx4 v[64:67], v10, s[14:15] offset:3072
	s_add_u32 s14, s14, 0x20000
	s_addc_u32 s15, s15, 0
	global_load_dwordx4 v[70:73], v10, s[14:15] offset:0
	global_load_dwordx4 v[74:77], v10, s[14:15] offset:1024
	global_load_dwordx4 v[78:81], v10, s[14:15] offset:2048
	global_load_dwordx4 v[82:85], v10, s[14:15] offset:3072
	s_add_u32 s14, s14, 0x20000
	s_addc_u32 s15, s15, 0
	global_load_dwordx4 v[88:91], v10, s[14:15] offset:0
	global_load_dwordx4 v[92:95], v10, s[14:15] offset:1024
	global_load_dwordx4 v[96:99], v10, s[14:15] offset:2048
	global_load_dwordx4 v[100:103], v10, s[14:15] offset:3072
	s_add_u32 s14, s14, 0x20000
	s_addc_u32 s15, s15, 0
	global_load_dwordx4 v[106:109], v10, s[14:15] offset:0
	global_load_dwordx4 v[110:113], v10, s[14:15] offset:1024
	global_load_dwordx4 v[114:117], v10, s[14:15] offset:2048
	global_load_dwordx4 v[118:121], v10, s[14:15] offset:3072
	s_add_u32 s14, s14, 0x20000
	s_addc_u32 s15, s15, 0
	s_waitcnt vmcnt(20)
	v_readlane_b32 s40, v152, 0
	s_nop 1
	v_mul_f32_e32 v128, s40, v128
	v_mul_f32_e32 v129, s40, v129
	v_mul_f32_e32 v130, s40, v130
	v_mul_f32_e32 v131, s40, v131
	v_mul_f32_e32 v132, s40, v132
	v_mul_f32_e32 v133, s40, v133
	v_mul_f32_e32 v134, s40, v134
	v_mul_f32_e32 v135, s40, v135
	s_barrier
	ds_read_b128 v[144:147], v12
	ds_read_b128 v[148:151], v12 offset:64
	s_waitcnt lgkmcnt(1)
	v_mfma_f32_16x16x32_bf16 v[128:131], v[16:19], v[144:147], v[128:131]
	v_mfma_f32_16x16x32_bf16 v[132:135], v[24:27], v[144:147], v[132:135]
	s_waitcnt lgkmcnt(0)
	v_mfma_f32_16x16x32_bf16 v[128:131], v[20:23], v[148:151], v[128:131]
	v_mfma_f32_16x16x32_bf16 v[132:135], v[28:31], v[148:151], v[132:135]
	s_nop 7
	v_cvt_pk_bf16_f32 v136, v128, v129
	v_cvt_pk_bf16_f32 v137, v130, v131
	s_nop 1
	v_cvt_pk_bf16_f32 v138, v132, v133
	v_cvt_pk_bf16_f32 v139, v134, v135
	ds_write_b64 v13, v[136:137]
	ds_write_b64 v13, v[138:139] offset:32
	s_waitcnt lgkmcnt(0)
	s_barrier
	global_load_dwordx4 v[16:19], v10, s[14:15] offset:0
	global_load_dwordx4 v[20:23], v10, s[14:15] offset:1024
	global_load_dwordx4 v[24:27], v10, s[14:15] offset:2048
	global_load_dwordx4 v[28:31], v10, s[14:15] offset:3072
	s_add_u32 s14, s14, 0x20000
	s_addc_u32 s15, s15, 0
	s_waitcnt vmcnt(20)
	v_readlane_b32 s40, v152, 1
	s_nop 1
	v_mul_f32_e32 v128, s40, v128
	v_mul_f32_e32 v129, s40, v129
	v_mul_f32_e32 v130, s40, v130
	v_mul_f32_e32 v131, s40, v131
	v_mul_f32_e32 v132, s40, v132
	v_mul_f32_e32 v133, s40, v133
	v_mul_f32_e32 v134, s40, v134
	v_mul_f32_e32 v135, s40, v135
	s_barrier
	ds_read_b128 v[144:147], v12
	ds_read_b128 v[148:151], v12 offset:64
	s_waitcnt lgkmcnt(1)
	v_mfma_f32_16x16x32_bf16 v[128:131], v[34:37], v[144:147], v[128:131]
	v_mfma_f32_16x16x32_bf16 v[132:135], v[42:45], v[144:147], v[132:135]
	s_waitcnt lgkmcnt(0)
	v_mfma_f32_16x16x32_bf16 v[128:131], v[38:41], v[148:151], v[128:131]
	v_mfma_f32_16x16x32_bf16 v[132:135], v[46:49], v[148:151], v[132:135]
	s_nop 7
	v_cvt_pk_bf16_f32 v136, v128, v129
	v_cvt_pk_bf16_f32 v137, v130, v131
	s_nop 1
	v_cvt_pk_bf16_f32 v138, v132, v133
	v_cvt_pk_bf16_f32 v139, v134, v135
	ds_write_b64 v13, v[136:137]
	ds_write_b64 v13, v[138:139] offset:32
	s_waitcnt lgkmcnt(0)
	s_barrier
	global_load_dwordx4 v[34:37], v10, s[14:15] offset:0
	global_load_dwordx4 v[38:41], v10, s[14:15] offset:1024
	global_load_dwordx4 v[42:45], v10, s[14:15] offset:2048
	global_load_dwordx4 v[46:49], v10, s[14:15] offset:3072
	s_add_u32 s14, s14, 0x20000
	s_addc_u32 s15, s15, 0
	s_waitcnt vmcnt(20)
	v_readlane_b32 s40, v152, 2
	s_nop 1
	v_mul_f32_e32 v128, s40, v128
	v_mul_f32_e32 v129, s40, v129
	v_mul_f32_e32 v130, s40, v130
	v_mul_f32_e32 v131, s40, v131
	v_mul_f32_e32 v132, s40, v132
	v_mul_f32_e32 v133, s40, v133
	v_mul_f32_e32 v134, s40, v134
	v_mul_f32_e32 v135, s40, v135
	s_barrier
; __device__ __forceinline__ u32x2 pk4(f32x4 v) { u32x2 r; r.x = pk2(v[0], v[1]); r.y = pk2(v[2], v[3]); return r; }
; __device__ __forceinline__ f32x4 mfma16(bf16x8 a, bf16x8 b, f32x4 c) { return __builtin_amdgcn_mfma_f32_16x16x32_bf16(a, b, c, 0, 0, 0); }
; __device__ __forceinline__ void dn_stage_load(DnStage& S, const bf16_t* dW, const bf16_t* dUT, const bf16_t* dKdT, const float* dGl, int ck, int h, int vs, int wave, int r, int q) {
;     ...
; #pragma unroll
;         for (int t = 0; t < 2; ++t)
; #pragma unroll
;             for (int kk = 0; kk < 2; ++kk) S.f[t * 2 + kk] = ldfrag(dKdT + (ch * 128 + ((wave - 4) * 2 + t) * 16 + r) * 64 + kk * 32 + q * 8);
;         S.gl = dGl[ch];
; __device__ __forceinline__ void dn_step(const DnStage& S, f32x4 (&Sacc)[2], bf16_t* ST, bf16_t* VN, bf16_t* dVnT, bf16_t* dST, int ck, int h, int vs, int wave, int r, int q) {
;     ...
;     if (wave >= 4) {
;         bf16x8 vf[2];
; #pragma unroll
;         for (int kk = 0; kk < 2; ++kk) vf[kk] = *(const bf16x8*)(VN + r * 72 + kk * 32 + q * 8);
; #pragma unroll
;         for (int t = 0; t < 2; ++t) { const int kb = (wave - 4) * 2 + t;
;             f32x4 a = Sacc[t] * S.gl;
; #pragma unroll
;             for (int kk = 0; kk < 2; ++kk) a = mfma16(S.f[t * 2 + kk], vf[kk], a);
;             Sacc[t] = a; const u32x2 ps = pk4(a);
;             *(u32x2*)(ST + r * 136 + kb * 16 + 4 * q) = ps;
;             if (ck + 1 < NCH) *(u32x2*)(dST + (((size_t)(ck + 1) * 8 + h) * 128 + vs * 16 + r) * 128 + kb * 16 + 4 * q) = ps; }
;     }
;     asm volatile("s_waitcnt lgkmcnt(0)" ::: "memory"); __builtin_amdgcn_s_barrier(); asm volatile("" ::: "memory");
	ds_read_b128 v[144:147], v12
	ds_read_b128 v[148:151], v12 offset:64
	s_waitcnt lgkmcnt(1)
	v_mfma_f32_16x16x32_bf16 v[128:131], v[52:55], v[144:147], v[128:131]
	v_mfma_f32_16x16x32_bf16 v[132:135], v[60:63], v[144:147], v[132:135]
	s_waitcnt lgkmcnt(0)
	v_mfma_f32_16x16x32_bf16 v[128:131], v[56:59], v[148:151], v[128:131]
	v_mfma_f32_16x16x32_bf16 v[132:135], v[64:67], v[148:151], v[132:135]
	s_nop 7
	v_cvt_pk_bf16_f32 v136, v128, v129
	v_cvt_pk_bf16_f32 v137, v130, v131
	s_nop 1
	v_cvt_pk_bf16_f32 v138, v132, v133
	v_cvt_pk_bf16_f32 v139, v134, v135
	ds_write_b64 v13, v[136:137]
	ds_write_b64 v13, v[138:139] offset:32
	s_waitcnt lgkmcnt(0)
	s_barrier
	global_load_dwordx4 v[52:55], v10, s[14:15] offset:0
	global_load_dwordx4 v[56:59], v10, s[14:15] offset:1024
	global_load_dwordx4 v[60:63], v10, s[14:15] offset:2048
	global_load_dwordx4 v[64:67], v10, s[14:15] offset:3072
	s_add_u32 s14, s14, 0x20000
	s_addc_u32 s15, s15, 0
	s_waitcnt vmcnt(20)
	v_readlane_b32 s40, v152, 3
	s_nop 1
	v_mul_f32_e32 v128, s40, v128
	v_mul_f32_e32 v129, s40, v129
	v_mul_f32_e32 v130, s40, v130
	v_mul_f32_e32 v131, s40, v131
	v_mul_f32_e32 v132, s40, v132
	v_mul_f32_e32 v133, s40, v133
	v_mul_f32_e32 v134, s40, v134
	v_mul_f32_e32 v135, s40, v135
	s_barrier
	ds_read_b128 v[144:147], v12
	ds_read_b128 v[148:151], v12 offset:64
	s_waitcnt lgkmcnt(1)
	v_mfma_f32_16x16x32_bf16 v[128:131], v[70:73], v[144:147], v[128:131]
	v_mfma_f32_16x16x32_bf16 v[132:135], v[78:81], v[144:147], v[132:135]
	s_waitcnt lgkmcnt(0)
	v_mfma_f32_16x16x32_bf16 v[128:131], v[74:77], v[148:151], v[128:131]
	v_mfma_f32_16x16x32_bf16 v[132:135], v[82:85], v[148:151], v[132:135]
	s_nop 7
	v_cvt_pk_bf16_f32 v136, v128, v129
	v_cvt_pk_bf16_f32 v137, v130, v131
	s_nop 1
	v_cvt_pk_bf16_f32 v138, v132, v133
	v_cvt_pk_bf16_f32 v139, v134, v135
	ds_write_b64 v13, v[136:137]
	ds_write_b64 v13, v[138:139] offset:32
	s_waitcnt lgkmcnt(0)
	s_barrier
	global_load_dwordx4 v[70:73], v10, s[14:15] offset:0
	global_load_dwordx4 v[74:77], v10, s[14:15] offset:1024
	global_load_dwordx4 v[78:81], v10, s[14:15] offset:2048
	global_load_dwordx4 v[82:85], v10, s[14:15] offset:3072
	s_add_u32 s14, s14, 0x20000
	s_addc_u32 s15, s15, 0
	s_waitcnt vmcnt(20)
	v_readlane_b32 s40, v152, 4
	s_nop 1
	v_mul_f32_e32 v128, s40, v128
	v_mul_f32_e32 v129, s40, v129
	v_mul_f32_e32 v130, s40, v130
	v_mul_f32_e32 v131, s40, v131
	v_mul_f32_e32 v132, s40, v132
	v_mul_f32_e32 v133, s40, v133
	v_mul_f32_e32 v134, s40, v134
	v_mul_f32_e32 v135, s40, v135
	s_barrier
	ds_read_b128 v[144:147], v12
	ds_read_b128 v[148:151], v12 offset:64
	s_waitcnt lgkmcnt(1)
	v_mfma_f32_16x16x32_bf16 v[128:131], v[88:91], v[144:147], v[128:131]
	v_mfma_f32_16x16x32_bf16 v[132:135], v[96:99], v[144:147], v[132:135]
	s_waitcnt lgkmcnt(0)
	v_mfma_f32_16x16x32_bf16 v[128:131], v[92:95], v[148:151], v[128:131]
	v_mfma_f32_16x16x32_bf16 v[132:135], v[100:103], v[148:151], v[132:135]
	s_nop 7
	v_cvt_pk_bf16_f32 v136, v128, v129
	v_cvt_pk_bf16_f32 v137, v130, v131
	s_nop 1
	v_cvt_pk_bf16_f32 v138, v132, v133
	v_cvt_pk_bf16_f32 v139, v134, v135
	ds_write_b64 v13, v[136:137]
	ds_write_b64 v13, v[138:139] offset:32
	s_waitcnt lgkmcnt(0)
	s_barrier
	global_load_dwordx4 v[88:91], v10, s[14:15] offset:0
	global_load_dwordx4 v[92:95], v10, s[14:15] offset:1024
	global_load_dwordx4 v[96:99], v10, s[14:15] offset:2048
	global_load_dwordx4 v[100:103], v10, s[14:15] offset:3072
	s_add_u32 s14, s14, 0x20000
	s_addc_u32 s15, s15, 0
	s_waitcnt vmcnt(20)
	v_readlane_b32 s40, v152, 5
	s_nop 1
	v_mul_f32_e32 v128, s40, v128
	v_mul_f32_e32 v129, s40, v129
	v_mul_f32_e32 v130, s40, v130
	v_mul_f32_e32 v131, s40, v131
	v_mul_f32_e32 v132, s40, v132
	v_mul_f32_e32 v133, s40, v133
	v_mul_f32_e32 v134, s40, v134
	v_mul_f32_e32 v135, s40, v135
	s_barrier
	ds_read_b128 v[144:147], v12
	ds_read_b128 v[148:151], v12 offset:64
	s_waitcnt lgkmcnt(1)
	v_mfma_f32_16x16x32_bf16 v[128:131], v[106:109], v[144:147], v[128:131]
	v_mfma_f32_16x16x32_bf16 v[132:135], v[114:117], v[144:147], v[132:135]
	s_waitcnt lgkmcnt(0)
	v_mfma_f32_16x16x32_bf16 v[128:131], v[110:113], v[148:151], v[128:131]
	v_mfma_f32_16x16x32_bf16 v[132:135], v[118:121], v[148:151], v[132:135]
	s_nop 7
	v_cvt_pk_bf16_f32 v136, v128, v129
	v_cvt_pk_bf16_f32 v137, v130, v131
	s_nop 1
	v_cvt_pk_bf16_f32 v138, v132, v133
	v_cvt_pk_bf16_f32 v139, v134, v135
	ds_write_b64 v13, v[136:137]
	ds_write_b64 v13, v[138:139] offset:32
	s_waitcnt lgkmcnt(0)
	s_barrier
	global_load_dwordx4 v[106:109], v10, s[14:15] offset:0
	global_load_dwordx4 v[110:113], v10, s[14:15] offset:1024
	global_load_dwordx4 v[114:117], v10, s[14:15] offset:2048
	global_load_dwordx4 v[118:121], v10, s[14:15] offset:3072
	s_add_u32 s14, s14, 0x20000
	s_addc_u32 s15, s15, 0
	s_waitcnt vmcnt(20)
	v_readlane_b32 s40, v152, 6
	s_nop 1
	v_mul_f32_e32 v128, s40, v128
	v_mul_f32_e32 v129, s40, v129
	v_mul_f32_e32 v130, s40, v130
	v_mul_f32_e32 v131, s40, v131
	v_mul_f32_e32 v132, s40, v132
	v_mul_f32_e32 v133, s40, v133
	v_mul_f32_e32 v134, s40, v134
	v_mul_f32_e32 v135, s40, v135
	s_barrier
	ds_read_b128 v[144:147], v12
	ds_read_b128 v[148:151], v12 offset:64
	s_waitcnt lgkmcnt(1)
	v_mfma_f32_16x16x32_bf16 v[128:131], v[16:19], v[144:147], v[128:131]
	v_mfma_f32_16x16x32_bf16 v[132:135], v[24:27], v[144:147], v[132:135]
	s_waitcnt lgkmcnt(0)
	v_mfma_f32_16x16x32_bf16 v[128:131], v[20:23], v[148:151], v[128:131]
	v_mfma_f32_16x16x32_bf16 v[132:135], v[28:31], v[148:151], v[132:135]
	s_nop 7
	v_cvt_pk_bf16_f32 v136, v128, v129
	v_cvt_pk_bf16_f32 v137, v130, v131
	s_nop 1
	v_cvt_pk_bf16_f32 v138, v132, v133
	v_cvt_pk_bf16_f32 v139, v134, v135
	ds_write_b64 v13, v[136:137]
	ds_write_b64 v13, v[138:139] offset:32
	s_waitcnt lgkmcnt(0)
	s_barrier
	global_load_dwordx4 v[16:19], v10, s[14:15] offset:0
	global_load_dwordx4 v[20:23], v10, s[14:15] offset:1024
	global_load_dwordx4 v[24:27], v10, s[14:15] offset:2048
	global_load_dwordx4 v[28:31], v10, s[14:15] offset:3072
	s_add_u32 s14, s14, 0x20000
	s_addc_u32 s15, s15, 0
	s_waitcnt vmcnt(20)
	v_readlane_b32 s40, v152, 7
	s_nop 1
	v_mul_f32_e32 v128, s40, v128
	v_mul_f32_e32 v129, s40, v129
	v_mul_f32_e32 v130, s40, v130
	v_mul_f32_e32 v131, s40, v131
	v_mul_f32_e32 v132, s40, v132
	v_mul_f32_e32 v133, s40, v133
	v_mul_f32_e32 v134, s40, v134
	v_mul_f32_e32 v135, s40, v135
	s_barrier
	ds_read_b128 v[144:147], v12
	ds_read_b128 v[148:151], v12 offset:64
	s_waitcnt lgkmcnt(1)
	v_mfma_f32_16x16x32_bf16 v[128:131], v[34:37], v[144:147], v[128:131]
	v_mfma_f32_16x16x32_bf16 v[132:135], v[42:45], v[144:147], v[132:135]
	s_waitcnt lgkmcnt(0)
	v_mfma_f32_16x16x32_bf16 v[128:131], v[38:41], v[148:151], v[128:131]
	v_mfma_f32_16x16x32_bf16 v[132:135], v[46:49], v[148:151], v[132:135]
	s_nop 7
	v_cvt_pk_bf16_f32 v136, v128, v129
	v_cvt_pk_bf16_f32 v137, v130, v131
	s_nop 1
	v_cvt_pk_bf16_f32 v138, v132, v133
	v_cvt_pk_bf16_f32 v139, v134, v135
	ds_write_b64 v13, v[136:137]
	ds_write_b64 v13, v[138:139] offset:32
	s_waitcnt lgkmcnt(0)
	s_barrier
	s_mov_b32 s20, 19
	s_mov_b32 s41, 8
; __device__ __forceinline__ u32x2 pk4(f32x4 v) { u32x2 r; r.x = pk2(v[0], v[1]); r.y = pk2(v[2], v[3]); return r; }
; __device__ __forceinline__ f32x4 mfma16(bf16x8 a, bf16x8 b, f32x4 c) { return __builtin_amdgcn_mfma_f32_16x16x32_bf16(a, b, c, 0, 0, 0); }
; __device__ __forceinline__ void dn_stage_load(DnStage& S, const bf16_t* dW, const bf16_t* dUT, const bf16_t* dKdT, const float* dGl, int ck, int h, int vs, int wave, int r, int q) {
;     ...
; #pragma unroll
;         for (int t = 0; t < 2; ++t)
; #pragma unroll
;             for (int kk = 0; kk < 2; ++kk) S.f[t * 2 + kk] = ldfrag(dKdT + (ch * 128 + ((wave - 4) * 2 + t) * 16 + r) * 64 + kk * 32 + q * 8);
;         S.gl = dGl[ch];
; __device__ __forceinline__ void dn_step(const DnStage& S, f32x4 (&Sacc)[2], bf16_t* ST, bf16_t* VN, bf16_t* dVnT, bf16_t* dST, int ck, int h, int vs, int wave, int r, int q) {
;     ...
;     if (wave >= 4) {
;         bf16x8 vf[2];
; #pragma unroll
;         for (int kk = 0; kk < 2; ++kk) vf[kk] = *(const bf16x8*)(VN + r * 72 + kk * 32 + q * 8);
; #pragma unroll
;         for (int t = 0; t < 2; ++t) { const int kb = (wave - 4) * 2 + t;
;             f32x4 a = Sacc[t] * S.gl;
; #pragma unroll
;             for (int kk = 0; kk < 2; ++kk) a = mfma16(S.f[t * 2 + kk], vf[kk], a);
;             Sacc[t] = a; const u32x2 ps = pk4(a);
;             *(u32x2*)(ST + r * 136 + kb * 16 + 4 * q) = ps;
;             if (ck + 1 < NCH) *(u32x2*)(dST + (((size_t)(ck + 1) * 8 + h) * 128 + vs * 16 + r) * 128 + kb * 16 + 4 * q) = ps; }
;     }
;     asm volatile("s_waitcnt lgkmcnt(0)" ::: "memory"); __builtin_amdgcn_s_barrier(); asm volatile("" ::: "memory");
.Ldq_B_loop:
	global_load_dwordx4 v[34:37], v10, s[14:15] offset:0
	global_load_dwordx4 v[38:41], v10, s[14:15] offset:1024
	global_load_dwordx4 v[42:45], v10, s[14:15] offset:2048
	global_load_dwordx4 v[46:49], v10, s[14:15] offset:3072
	s_add_u32 s14, s14, 0x20000
	s_addc_u32 s15, s15, 0
	s_waitcnt vmcnt(20)
	v_readlane_b32 s40, v152, s41
	v_readlane_b32 s42, v153, s41
	s_cmp_lt_u32 s41, 64
	s_cselect_b32 s40, s40, s42
	s_add_u32 s41, s41, 1
	v_mul_f32_e32 v128, s40, v128
	v_mul_f32_e32 v129, s40, v129
	v_mul_f32_e32 v130, s40, v130
	v_mul_f32_e32 v131, s40, v131
	v_mul_f32_e32 v132, s40, v132
	v_mul_f32_e32 v133, s40, v133
	v_mul_f32_e32 v134, s40, v134
	v_mul_f32_e32 v135, s40, v135
	s_barrier
	ds_read_b128 v[144:147], v12
	ds_read_b128 v[148:151], v12 offset:64
	s_waitcnt lgkmcnt(1)
	v_mfma_f32_16x16x32_bf16 v[128:131], v[52:55], v[144:147], v[128:131]
	v_mfma_f32_16x16x32_bf16 v[132:135], v[60:63], v[144:147], v[132:135]
	s_waitcnt lgkmcnt(0)
	v_mfma_f32_16x16x32_bf16 v[128:131], v[56:59], v[148:151], v[128:131]
	v_mfma_f32_16x16x32_bf16 v[132:135], v[64:67], v[148:151], v[132:135]
	s_nop 7
	v_cvt_pk_bf16_f32 v136, v128, v129
	v_cvt_pk_bf16_f32 v137, v130, v131
	s_nop 1
	v_cvt_pk_bf16_f32 v138, v132, v133
	v_cvt_pk_bf16_f32 v139, v134, v135
	ds_write_b64 v13, v[136:137]
	ds_write_b64 v13, v[138:139] offset:32
	s_waitcnt lgkmcnt(0)
	s_barrier
	global_load_dwordx4 v[52:55], v10, s[14:15] offset:0
	global_load_dwordx4 v[56:59], v10, s[14:15] offset:1024
	global_load_dwordx4 v[60:63], v10, s[14:15] offset:2048
	global_load_dwordx4 v[64:67], v10, s[14:15] offset:3072
	s_add_u32 s14, s14, 0x20000
	s_addc_u32 s15, s15, 0
	s_waitcnt vmcnt(20)
	v_readlane_b32 s40, v152, s41
	v_readlane_b32 s42, v153, s41
	s_cmp_lt_u32 s41, 64
	s_cselect_b32 s40, s40, s42
	s_add_u32 s41, s41, 1
	v_mul_f32_e32 v128, s40, v128
	v_mul_f32_e32 v129, s40, v129
	v_mul_f32_e32 v130, s40, v130
	v_mul_f32_e32 v131, s40, v131
	v_mul_f32_e32 v132, s40, v132
	v_mul_f32_e32 v133, s40, v133
	v_mul_f32_e32 v134, s40, v134
	v_mul_f32_e32 v135, s40, v135
	s_barrier
	ds_read_b128 v[144:147], v12
	ds_read_b128 v[148:151], v12 offset:64
	s_waitcnt lgkmcnt(1)
	v_mfma_f32_16x16x32_bf16 v[128:131], v[70:73], v[144:147], v[128:131]
	v_mfma_f32_16x16x32_bf16 v[132:135], v[78:81], v[144:147], v[132:135]
	s_waitcnt lgkmcnt(0)
	v_mfma_f32_16x16x32_bf16 v[128:131], v[74:77], v[148:151], v[128:131]
	v_mfma_f32_16x16x32_bf16 v[132:135], v[82:85], v[148:151], v[132:135]
	s_nop 7
	v_cvt_pk_bf16_f32 v136, v128, v129
	v_cvt_pk_bf16_f32 v137, v130, v131
	s_nop 1
	v_cvt_pk_bf16_f32 v138, v132, v133
	v_cvt_pk_bf16_f32 v139, v134, v135
	ds_write_b64 v13, v[136:137]
	ds_write_b64 v13, v[138:139] offset:32
	s_waitcnt lgkmcnt(0)
	s_barrier
	global_load_dwordx4 v[70:73], v10, s[14:15] offset:0
	global_load_dwordx4 v[74:77], v10, s[14:15] offset:1024
	global_load_dwordx4 v[78:81], v10, s[14:15] offset:2048
	global_load_dwordx4 v[82:85], v10, s[14:15] offset:3072
	s_add_u32 s14, s14, 0x20000
	s_addc_u32 s15, s15, 0
	s_waitcnt vmcnt(20)
	v_readlane_b32 s40, v152, s41
	v_readlane_b32 s42, v153, s41
	s_cmp_lt_u32 s41, 64
	s_cselect_b32 s40, s40, s42
	s_add_u32 s41, s41, 1
	v_mul_f32_e32 v128, s40, v128
	v_mul_f32_e32 v129, s40, v129
	v_mul_f32_e32 v130, s40, v130
	v_mul_f32_e32 v131, s40, v131
	v_mul_f32_e32 v132, s40, v132
	v_mul_f32_e32 v133, s40, v133
	v_mul_f32_e32 v134, s40, v134
	v_mul_f32_e32 v135, s40, v135
	s_barrier
	ds_read_b128 v[144:147], v12
	ds_read_b128 v[148:151], v12 offset:64
	s_waitcnt lgkmcnt(1)
	v_mfma_f32_16x16x32_bf16 v[128:131], v[88:91], v[144:147], v[128:131]
	v_mfma_f32_16x16x32_bf16 v[132:135], v[96:99], v[144:147], v[132:135]
	s_waitcnt lgkmcnt(0)
	v_mfma_f32_16x16x32_bf16 v[128:131], v[92:95], v[148:151], v[128:131]
	v_mfma_f32_16x16x32_bf16 v[132:135], v[100:103], v[148:151], v[132:135]
	s_nop 7
	v_cvt_pk_bf16_f32 v136, v128, v129
	v_cvt_pk_bf16_f32 v137, v130, v131
	s_nop 1
	v_cvt_pk_bf16_f32 v138, v132, v133
	v_cvt_pk_bf16_f32 v139, v134, v135
	ds_write_b64 v13, v[136:137]
	ds_write_b64 v13, v[138:139] offset:32
	s_waitcnt lgkmcnt(0)
	s_barrier
	global_load_dwordx4 v[88:91], v10, s[14:15] offset:0
	global_load_dwordx4 v[92:95], v10, s[14:15] offset:1024
	global_load_dwordx4 v[96:99], v10, s[14:15] offset:2048
	global_load_dwordx4 v[100:103], v10, s[14:15] offset:3072
	s_add_u32 s14, s14, 0x20000
	s_addc_u32 s15, s15, 0
	s_waitcnt vmcnt(20)
	v_readlane_b32 s40, v152, s41
	v_readlane_b32 s42, v153, s41
	s_cmp_lt_u32 s41, 64
	s_cselect_b32 s40, s40, s42
	s_add_u32 s41, s41, 1
	v_mul_f32_e32 v128, s40, v128
	v_mul_f32_e32 v129, s40, v129
	v_mul_f32_e32 v130, s40, v130
	v_mul_f32_e32 v131, s40, v131
	v_mul_f32_e32 v132, s40, v132
	v_mul_f32_e32 v133, s40, v133
	v_mul_f32_e32 v134, s40, v134
	v_mul_f32_e32 v135, s40, v135
	s_barrier
	ds_read_b128 v[144:147], v12
	ds_read_b128 v[148:151], v12 offset:64
	s_waitcnt lgkmcnt(1)
	v_mfma_f32_16x16x32_bf16 v[128:131], v[106:109], v[144:147], v[128:131]
	v_mfma_f32_16x16x32_bf16 v[132:135], v[114:117], v[144:147], v[132:135]
	s_waitcnt lgkmcnt(0)
	v_mfma_f32_16x16x32_bf16 v[128:131], v[110:113], v[148:151], v[128:131]
	v_mfma_f32_16x16x32_bf16 v[132:135], v[118:121], v[148:151], v[132:135]
	s_nop 7
	v_cvt_pk_bf16_f32 v136, v128, v129
	v_cvt_pk_bf16_f32 v137, v130, v131
	s_nop 1
	v_cvt_pk_bf16_f32 v138, v132, v133
	v_cvt_pk_bf16_f32 v139, v134, v135
	ds_write_b64 v13, v[136:137]
	ds_write_b64 v13, v[138:139] offset:32
	s_waitcnt lgkmcnt(0)
	s_barrier
; __device__ __forceinline__ u32x2 pk4(f32x4 v) { u32x2 r; r.x = pk2(v[0], v[1]); r.y = pk2(v[2], v[3]); return r; }
; __device__ __forceinline__ f32x4 mfma16(bf16x8 a, bf16x8 b, f32x4 c) { return __builtin_amdgcn_mfma_f32_16x16x32_bf16(a, b, c, 0, 0, 0); }
; __device__ __forceinline__ void dn_stage_load(DnStage& S, const bf16_t* dW, const bf16_t* dUT, const bf16_t* dKdT, const float* dGl, int ck, int h, int vs, int wave, int r, int q) {
;     ...
; #pragma unroll
;         for (int t = 0; t < 2; ++t)
; #pragma unroll
;             for (int kk = 0; kk < 2; ++kk) S.f[t * 2 + kk] = ldfrag(dKdT + (ch * 128 + ((wave - 4) * 2 + t) * 16 + r) * 64 + kk * 32 + q * 8);
;         S.gl = dGl[ch];
; __device__ __forceinline__ void dn_step(const DnStage& S, f32x4 (&Sacc)[2], bf16_t* ST, bf16_t* VN, bf16_t* dVnT, bf16_t* dST, int ck, int h, int vs, int wave, int r, int q) {
;     ...
;     if (wave >= 4) {
;         bf16x8 vf[2];
; #pragma unroll
;         for (int kk = 0; kk < 2; ++kk) vf[kk] = *(const bf16x8*)(VN + r * 72 + kk * 32 + q * 8);
; #pragma unroll
;         for (int t = 0; t < 2; ++t) { const int kb = (wave - 4) * 2 + t;
;             f32x4 a = Sacc[t] * S.gl;
; #pragma unroll
;             for (int kk = 0; kk < 2; ++kk) a = mfma16(S.f[t * 2 + kk], vf[kk], a);
;             Sacc[t] = a; const u32x2 ps = pk4(a);
;             *(u32x2*)(ST + r * 136 + kb * 16 + 4 * q) = ps;
;             if (ck + 1 < NCH) *(u32x2*)(dST + (((size_t)(ck + 1) * 8 + h) * 128 + vs * 16 + r) * 128 + kb * 16 + 4 * q) = ps; }
;     }
;     asm volatile("s_waitcnt lgkmcnt(0)" ::: "memory"); __builtin_amdgcn_s_barrier(); asm volatile("" ::: "memory");
	global_load_dwordx4 v[106:109], v10, s[14:15] offset:0
	global_load_dwordx4 v[110:113], v10, s[14:15] offset:1024
	global_load_dwordx4 v[114:117], v10, s[14:15] offset:2048
	global_load_dwordx4 v[118:121], v10, s[14:15] offset:3072
	s_add_u32 s14, s14, 0x20000
	s_addc_u32 s15, s15, 0
	s_waitcnt vmcnt(20)
	v_readlane_b32 s40, v152, s41
	v_readlane_b32 s42, v153, s41
	s_cmp_lt_u32 s41, 64
	s_cselect_b32 s40, s40, s42
	s_add_u32 s41, s41, 1
	v_mul_f32_e32 v128, s40, v128
	v_mul_f32_e32 v129, s40, v129
	v_mul_f32_e32 v130, s40, v130
	v_mul_f32_e32 v131, s40, v131
	v_mul_f32_e32 v132, s40, v132
	v_mul_f32_e32 v133, s40, v133
	v_mul_f32_e32 v134, s40, v134
	v_mul_f32_e32 v135, s40, v135
	s_barrier
	ds_read_b128 v[144:147], v12
	ds_read_b128 v[148:151], v12 offset:64
	s_waitcnt lgkmcnt(1)
	v_mfma_f32_16x16x32_bf16 v[128:131], v[16:19], v[144:147], v[128:131]
	v_mfma_f32_16x16x32_bf16 v[132:135], v[24:27], v[144:147], v[132:135]
	s_waitcnt lgkmcnt(0)
	v_mfma_f32_16x16x32_bf16 v[128:131], v[20:23], v[148:151], v[128:131]
	v_mfma_f32_16x16x32_bf16 v[132:135], v[28:31], v[148:151], v[132:135]
	s_nop 7
	v_cvt_pk_bf16_f32 v136, v128, v129
	v_cvt_pk_bf16_f32 v137, v130, v131
	s_nop 1
	v_cvt_pk_bf16_f32 v138, v132, v133
	v_cvt_pk_bf16_f32 v139, v134, v135
	ds_write_b64 v13, v[136:137]
	ds_write_b64 v13, v[138:139] offset:32
	s_waitcnt lgkmcnt(0)
	s_barrier
	global_load_dwordx4 v[16:19], v10, s[14:15] offset:0
	global_load_dwordx4 v[20:23], v10, s[14:15] offset:1024
	global_load_dwordx4 v[24:27], v10, s[14:15] offset:2048
	global_load_dwordx4 v[28:31], v10, s[14:15] offset:3072
	s_add_u32 s14, s14, 0x20000
	s_addc_u32 s15, s15, 0
	s_waitcnt vmcnt(20)
	v_readlane_b32 s40, v152, s41
	v_readlane_b32 s42, v153, s41
	s_cmp_lt_u32 s41, 64
	s_cselect_b32 s40, s40, s42
	s_add_u32 s41, s41, 1
	v_mul_f32_e32 v128, s40, v128
	v_mul_f32_e32 v129, s40, v129
	v_mul_f32_e32 v130, s40, v130
	v_mul_f32_e32 v131, s40, v131
	v_mul_f32_e32 v132, s40, v132
	v_mul_f32_e32 v133, s40, v133
	v_mul_f32_e32 v134, s40, v134
	v_mul_f32_e32 v135, s40, v135
	s_barrier
	ds_read_b128 v[144:147], v12
	ds_read_b128 v[148:151], v12 offset:64
	s_waitcnt lgkmcnt(1)
	v_mfma_f32_16x16x32_bf16 v[128:131], v[34:37], v[144:147], v[128:131]
	v_mfma_f32_16x16x32_bf16 v[132:135], v[42:45], v[144:147], v[132:135]
	s_waitcnt lgkmcnt(0)
	v_mfma_f32_16x16x32_bf16 v[128:131], v[38:41], v[148:151], v[128:131]
	v_mfma_f32_16x16x32_bf16 v[132:135], v[46:49], v[148:151], v[132:135]
	s_nop 7
	v_cvt_pk_bf16_f32 v136, v128, v129
	v_cvt_pk_bf16_f32 v137, v130, v131
	s_nop 1
	v_cvt_pk_bf16_f32 v138, v132, v133
	v_cvt_pk_bf16_f32 v139, v134, v135
	ds_write_b64 v13, v[136:137]
	ds_write_b64 v13, v[138:139] offset:32
	s_waitcnt lgkmcnt(0)
	s_barrier
	s_sub_u32 s20, s20, 1
	s_cmp_lg_u32 s20, 0
	s_cbranch_scc1 .Ldq_B_loop
	global_load_dwordx4 v[34:37], v10, s[14:15] offset:0
	global_load_dwordx4 v[38:41], v10, s[14:15] offset:1024
	global_load_dwordx4 v[42:45], v10, s[14:15] offset:2048
	global_load_dwordx4 v[46:49], v10, s[14:15] offset:3072
	s_waitcnt vmcnt(20)
	v_readlane_b32 s40, v153, 58
	s_nop 1
	v_mul_f32_e32 v128, s40, v128
	v_mul_f32_e32 v129, s40, v129
	v_mul_f32_e32 v130, s40, v130
	v_mul_f32_e32 v131, s40, v131
	v_mul_f32_e32 v132, s40, v132
	v_mul_f32_e32 v133, s40, v133
	v_mul_f32_e32 v134, s40, v134
	v_mul_f32_e32 v135, s40, v135
	s_barrier
	ds_read_b128 v[144:147], v12
	ds_read_b128 v[148:151], v12 offset:64
	s_waitcnt lgkmcnt(1)
	v_mfma_f32_16x16x32_bf16 v[128:131], v[52:55], v[144:147], v[128:131]
	v_mfma_f32_16x16x32_bf16 v[132:135], v[60:63], v[144:147], v[132:135]
	s_waitcnt lgkmcnt(0)
	v_mfma_f32_16x16x32_bf16 v[128:131], v[56:59], v[148:151], v[128:131]
	v_mfma_f32_16x16x32_bf16 v[132:135], v[64:67], v[148:151], v[132:135]
	s_nop 7
	v_cvt_pk_bf16_f32 v136, v128, v129
	v_cvt_pk_bf16_f32 v137, v130, v131
	s_nop 1
	v_cvt_pk_bf16_f32 v138, v132, v133
	v_cvt_pk_bf16_f32 v139, v134, v135
	ds_write_b64 v13, v[136:137]
	ds_write_b64 v13, v[138:139] offset:32
	s_waitcnt lgkmcnt(0)
	s_barrier
	s_waitcnt vmcnt(16)
	v_readlane_b32 s40, v153, 59
	s_nop 1
	v_mul_f32_e32 v128, s40, v128
	v_mul_f32_e32 v129, s40, v129
	v_mul_f32_e32 v130, s40, v130
	v_mul_f32_e32 v131, s40, v131
	v_mul_f32_e32 v132, s40, v132
	v_mul_f32_e32 v133, s40, v133
	v_mul_f32_e32 v134, s40, v134
	v_mul_f32_e32 v135, s40, v135
	s_barrier
; __device__ __forceinline__ u32x2 pk4(f32x4 v) { u32x2 r; r.x = pk2(v[0], v[1]); r.y = pk2(v[2], v[3]); return r; }
; __device__ __forceinline__ f32x4 mfma16(bf16x8 a, bf16x8 b, f32x4 c) { return __builtin_amdgcn_mfma_f32_16x16x32_bf16(a, b, c, 0, 0, 0); }
; __device__ __forceinline__ void dn_step(const DnStage& S, f32x4 (&Sacc)[2], bf16_t* ST, bf16_t* VN, bf16_t* dVnT, bf16_t* dST, int ck, int h, int vs, int wave, int r, int q) {
;     ...
;     if (wave >= 4) {
;         bf16x8 vf[2];
; #pragma unroll
;         for (int kk = 0; kk < 2; ++kk) vf[kk] = *(const bf16x8*)(VN + r * 72 + kk * 32 + q * 8);
; #pragma unroll
;         for (int t = 0; t < 2; ++t) { const int kb = (wave - 4) * 2 + t;
;             f32x4 a = Sacc[t] * S.gl;
; #pragma unroll
;             for (int kk = 0; kk < 2; ++kk) a = mfma16(S.f[t * 2 + kk], vf[kk], a);
;             Sacc[t] = a; const u32x2 ps = pk4(a);
;             *(u32x2*)(ST + r * 136 + kb * 16 + 4 * q) = ps;
;             if (ck + 1 < NCH) *(u32x2*)(dST + (((size_t)(ck + 1) * 8 + h) * 128 + vs * 16 + r) * 128 + kb * 16 + 4 * q) = ps; }
;     }
;     asm volatile("s_waitcnt lgkmcnt(0)" ::: "memory"); __builtin_amdgcn_s_barrier(); asm volatile("" ::: "memory");
	ds_read_b128 v[144:147], v12
	ds_read_b128 v[148:151], v12 offset:64
	s_waitcnt lgkmcnt(1)
	v_mfma_f32_16x16x32_bf16 v[128:131], v[70:73], v[144:147], v[128:131]
	v_mfma_f32_16x16x32_bf16 v[132:135], v[78:81], v[144:147], v[132:135]
	s_waitcnt lgkmcnt(0)
	v_mfma_f32_16x16x32_bf16 v[128:131], v[74:77], v[148:151], v[128:131]
	v_mfma_f32_16x16x32_bf16 v[132:135], v[82:85], v[148:151], v[132:135]
	s_nop 7
	v_cvt_pk_bf16_f32 v136, v128, v129
	v_cvt_pk_bf16_f32 v137, v130, v131
	s_nop 1
	v_cvt_pk_bf16_f32 v138, v132, v133
	v_cvt_pk_bf16_f32 v139, v134, v135
	ds_write_b64 v13, v[136:137]
	ds_write_b64 v13, v[138:139] offset:32
	s_waitcnt lgkmcnt(0)
	s_barrier
	s_waitcnt vmcnt(12)
	v_readlane_b32 s40, v153, 60
	s_nop 1
	v_mul_f32_e32 v128, s40, v128
	v_mul_f32_e32 v129, s40, v129
	v_mul_f32_e32 v130, s40, v130
	v_mul_f32_e32 v131, s40, v131
	v_mul_f32_e32 v132, s40, v132
	v_mul_f32_e32 v133, s40, v133
	v_mul_f32_e32 v134, s40, v134
	v_mul_f32_e32 v135, s40, v135
	s_barrier
	ds_read_b128 v[144:147], v12
	ds_read_b128 v[148:151], v12 offset:64
	s_waitcnt lgkmcnt(1)
	v_mfma_f32_16x16x32_bf16 v[128:131], v[88:91], v[144:147], v[128:131]
	v_mfma_f32_16x16x32_bf16 v[132:135], v[96:99], v[144:147], v[132:135]
	s_waitcnt lgkmcnt(0)
	v_mfma_f32_16x16x32_bf16 v[128:131], v[92:95], v[148:151], v[128:131]
	v_mfma_f32_16x16x32_bf16 v[132:135], v[100:103], v[148:151], v[132:135]
	s_nop 7
	v_cvt_pk_bf16_f32 v136, v128, v129
	v_cvt_pk_bf16_f32 v137, v130, v131
	s_nop 1
	v_cvt_pk_bf16_f32 v138, v132, v133
	v_cvt_pk_bf16_f32 v139, v134, v135
	ds_write_b64 v13, v[136:137]
	ds_write_b64 v13, v[138:139] offset:32
	s_waitcnt lgkmcnt(0)
	s_barrier
	s_waitcnt vmcnt(8)
	v_readlane_b32 s40, v153, 61
	s_nop 1
	v_mul_f32_e32 v128, s40, v128
	v_mul_f32_e32 v129, s40, v129
	v_mul_f32_e32 v130, s40, v130
	v_mul_f32_e32 v131, s40, v131
	v_mul_f32_e32 v132, s40, v132
	v_mul_f32_e32 v133, s40, v133
	v_mul_f32_e32 v134, s40, v134
	v_mul_f32_e32 v135, s40, v135
	s_barrier
	ds_read_b128 v[144:147], v12
	ds_read_b128 v[148:151], v12 offset:64
	s_waitcnt lgkmcnt(1)
	v_mfma_f32_16x16x32_bf16 v[128:131], v[106:109], v[144:147], v[128:131]
	v_mfma_f32_16x16x32_bf16 v[132:135], v[114:117], v[144:147], v[132:135]
	s_waitcnt lgkmcnt(0)
	v_mfma_f32_16x16x32_bf16 v[128:131], v[110:113], v[148:151], v[128:131]
	v_mfma_f32_16x16x32_bf16 v[132:135], v[118:121], v[148:151], v[132:135]
	s_nop 7
	v_cvt_pk_bf16_f32 v136, v128, v129
	v_cvt_pk_bf16_f32 v137, v130, v131
	s_nop 1
	v_cvt_pk_bf16_f32 v138, v132, v133
	v_cvt_pk_bf16_f32 v139, v134, v135
	ds_write_b64 v13, v[136:137]
	ds_write_b64 v13, v[138:139] offset:32
	s_waitcnt lgkmcnt(0)
	s_barrier
	s_waitcnt vmcnt(4)
	v_readlane_b32 s40, v153, 62
	s_nop 1
	v_mul_f32_e32 v128, s40, v128
	v_mul_f32_e32 v129, s40, v129
	v_mul_f32_e32 v130, s40, v130
	v_mul_f32_e32 v131, s40, v131
	v_mul_f32_e32 v132, s40, v132
	v_mul_f32_e32 v133, s40, v133
	v_mul_f32_e32 v134, s40, v134
	v_mul_f32_e32 v135, s40, v135
	s_barrier
	ds_read_b128 v[144:147], v12
	ds_read_b128 v[148:151], v12 offset:64
	s_waitcnt lgkmcnt(1)
	v_mfma_f32_16x16x32_bf16 v[128:131], v[16:19], v[144:147], v[128:131]
	v_mfma_f32_16x16x32_bf16 v[132:135], v[24:27], v[144:147], v[132:135]
	s_waitcnt lgkmcnt(0)
	v_mfma_f32_16x16x32_bf16 v[128:131], v[20:23], v[148:151], v[128:131]
	v_mfma_f32_16x16x32_bf16 v[132:135], v[28:31], v[148:151], v[132:135]
	s_nop 7
	v_cvt_pk_bf16_f32 v136, v128, v129
	v_cvt_pk_bf16_f32 v137, v130, v131
	s_nop 1
	v_cvt_pk_bf16_f32 v138, v132, v133
	v_cvt_pk_bf16_f32 v139, v134, v135
	ds_write_b64 v13, v[136:137]
	ds_write_b64 v13, v[138:139] offset:32
	s_waitcnt lgkmcnt(0)
	s_barrier
	s_waitcnt vmcnt(0)
	v_readlane_b32 s40, v153, 63
	s_nop 1
	v_mul_f32_e32 v128, s40, v128
	v_mul_f32_e32 v129, s40, v129
	v_mul_f32_e32 v130, s40, v130
	v_mul_f32_e32 v131, s40, v131
	v_mul_f32_e32 v132, s40, v132
	v_mul_f32_e32 v133, s40, v133
	v_mul_f32_e32 v134, s40, v134
	v_mul_f32_e32 v135, s40, v135
	s_barrier
	ds_read_b128 v[144:147], v12
	ds_read_b128 v[148:151], v12 offset:64
	s_waitcnt lgkmcnt(1)
	v_mfma_f32_16x16x32_bf16 v[128:131], v[34:37], v[144:147], v[128:131]
	v_mfma_f32_16x16x32_bf16 v[132:135], v[42:45], v[144:147], v[132:135]
	s_waitcnt lgkmcnt(0)
	v_mfma_f32_16x16x32_bf16 v[128:131], v[38:41], v[148:151], v[128:131]
	v_mfma_f32_16x16x32_bf16 v[132:135], v[46:49], v[148:151], v[132:135]
	s_nop 7
	v_cvt_pk_bf16_f32 v136, v128, v129
	v_cvt_pk_bf16_f32 v137, v130, v131
	s_nop 1
	v_cvt_pk_bf16_f32 v138, v132, v133
	v_cvt_pk_bf16_f32 v139, v134, v135
	ds_write_b64 v13, v[136:137]
	ds_write_b64 v13, v[138:139] offset:32
	s_waitcnt lgkmcnt(0)
	s_barrier

; __device__ __forceinline__ unsigned pk2(float lo, float hi) { const f32v2_t v = {lo, hi}; const bf16v2_t b = __builtin_convertvector(v, bf16v2_t); return __builtin_bit_cast(unsigned, b); }
;     template <class Tp> __device__ __forceinline__ Tp* W(size_t off) const { return (Tp*)(ws + off); }
; __device__ void dn_d1(const Ctx& c, int ip) {
;     ...
;           for (int i = 0; i < 64; ++i) x[i] = __uint_as_float(rw[i] << 16); }
;         if (isw) {
;             bf16_t* dKdT = c.W<bf16_t>(WS_DKDT);
; #pragma unroll
;             for (int l0 = 0; l0 < 64; l0 += 8) { u32x4 a;
;                 a.x = pk2(x[l0 + 0] * __expf(glast - gc_s[l0 + 0]), x[l0 + 1] * __expf(glast - gc_s[l0 + 1])); a.y = pk2(x[l0 + 2] * __expf(glast - gc_s[l0 + 2]), x[l0 + 3] * __expf(glast - gc_s[l0 + 3]));
;                 a.z = pk2(x[l0 + 4] * __expf(glast - gc_s[l0 + 4]), x[l0 + 5] * __expf(glast - gc_s[l0 + 5])); a.w = pk2(x[l0 + 6] * __expf(glast - gc_s[l0 + 6]), x[l0 + 7] * __expf(glast - gc_s[l0 + 7]));
;                 *(u32x4*)(dKdT + (ch * 128 + col) * 64 + l0) = a; }
.LBB0_740:
	s_or_saveexec_b64 s[18:19], s[18:19]
	v_lshlrev_b32_e32 v77, 16, v77
	v_lshlrev_b32_e32 v76, 16, v76
	v_lshlrev_b32_e32 v79, 16, v78
	v_lshlrev_b32_e32 v78, 16, v83
	v_lshlrev_b32_e32 v81, 16, v81
	v_lshlrev_b32_e32 v80, 16, v80
	v_lshlrev_b32_e32 v83, 16, v82
	v_lshlrev_b32_e32 v82, 16, v85
	v_lshlrev_b32_e32 v85, 16, v84
	v_lshlrev_b32_e32 v84, 16, v93
	v_lshlrev_b32_e32 v87, 16, v87
	v_lshlrev_b32_e32 v86, 16, v86
	v_lshlrev_b32_e32 v89, 16, v89
	v_lshlrev_b32_e32 v88, 16, v88
	v_lshlrev_b32_e32 v91, 16, v91
	v_lshlrev_b32_e32 v90, 16, v90
	v_lshlrev_b32_e32 v93, 16, v92
	v_lshlrev_b32_e32 v92, 16, v65
	v_lshlrev_b32_e32 v95, 16, v95
	v_lshlrev_b32_e32 v94, 16, v94
	v_lshlrev_b32_e32 v97, 16, v97
	v_lshlrev_b32_e32 v96, 16, v96
	v_lshlrev_b32_e32 v99, 16, v98
	v_lshlrev_b32_e32 v98, 16, v103
	v_lshlrev_b32_e32 v101, 16, v101
	v_lshlrev_b32_e32 v100, 16, v100
	v_lshlrev_b32_e32 v103, 16, v133
	v_lshlrev_b32_e32 v102, 16, v102
	v_lshlrev_b32_e32 v105, 16, v105
	v_lshlrev_b32_e32 v104, 16, v104
	v_lshlrev_b32_e32 v107, 16, v107
	v_lshlrev_b32_e32 v106, 16, v106
	v_lshlrev_b32_e32 v109, 16, v109
	v_lshlrev_b32_e32 v108, 16, v108
	v_lshlrev_b32_e32 v111, 16, v111
	v_lshlrev_b32_e32 v110, 16, v110
	v_lshlrev_b32_e32 v113, 16, v113
	v_lshlrev_b32_e32 v112, 16, v112
	v_lshlrev_b32_e32 v115, 16, v115
	v_lshlrev_b32_e32 v114, 16, v114
	v_lshlrev_b32_e32 v117, 16, v117
	v_lshlrev_b32_e32 v116, 16, v116
	v_lshlrev_b32_e32 v119, 16, v119
	v_lshlrev_b32_e32 v118, 16, v118
	v_lshlrev_b32_e32 v121, 16, v121
	v_lshlrev_b32_e32 v120, 16, v120
	v_lshlrev_b32_e32 v123, 16, v123
	v_lshlrev_b32_e32 v122, 16, v122
	v_lshlrev_b32_e32 v125, 16, v125
	v_lshlrev_b32_e32 v124, 16, v124
	v_lshlrev_b32_e32 v127, 16, v127
	v_lshlrev_b32_e32 v126, 16, v126
	v_lshlrev_b32_e32 v129, 16, v129
	v_lshlrev_b32_e32 v128, 16, v128
	v_lshlrev_b32_e32 v133, 16, v130
	v_lshlrev_b32_e32 v132, 16, v132
	v_lshlrev_b32_e32 v139, 16, v138
	v_lshlrev_b32_e32 v138, 16, v131
	v_lshlrev_b32_e32 v131, 16, v141
	v_lshlrev_b32_e32 v130, 16, v136
	v_lshlrev_b32_e32 v137, 16, v137
	v_lshlrev_b32_e32 v136, 16, v135
	v_lshlrev_b32_e32 v135, 16, v140
	v_lshlrev_b32_e32 v134, 16, v134
	s_xor_b64 exec, exec, s[18:19]
	s_cbranch_execz .LBB0_742
	s_waitcnt lgkmcnt(14)
	ds_read_b128 v[4:7], v157 offset:17664
	ds_read_b128 v[0:3], v157 offset:17680
	v_readlane_b32 s24, v249, 12
	v_readlane_b32 s25, v249, 13
	v_mov_b32_e32 v65, v177
	s_waitcnt lgkmcnt(14)
	v_lshl_add_u64 v[8:9], s[24:25], 0, v[74:75]
	v_lshl_add_u64 v[140:141], v[8:9], 0, v[64:65]
	v_and_b32_e32 v8, 15, v234
	v_mul_u32_u24_e32 v8, 0x70, v8
	v_sub_co_u32_e64 v140, s[100:101], v140, v8
	s_nop 1
	v_subb_co_u32_e64 v141, s[100:101], v141, 0, s[100:101]
	s_waitcnt lgkmcnt(1)
	v_sub_f32_e32 v8, v142, v4
	v_mul_f32_e32 v8, 0x3fb8aa3b, v8
	v_exp_f32_e32 v16, v8
	v_sub_f32_e32 v8, v142, v5
	v_mul_f32_e32 v8, 0x3fb8aa3b, v8
	v_exp_f32_e32 v17, v8
	v_sub_f32_e32 v8, v142, v6
	v_mul_f32_e32 v8, 0x3fb8aa3b, v8
	v_exp_f32_e32 v18, v8
	v_pk_mul_f32 v[16:17], v[16:17], v[76:77]
	v_sub_f32_e32 v8, v142, v7
	v_cvt_pk_bf16_f32 v16, v16, v17
	s_waitcnt lgkmcnt(0)
	v_sub_f32_e32 v17, v142, v0
	v_mul_f32_e32 v17, 0x3fb8aa3b, v17
	v_exp_f32_e32 v20, v17
	v_sub_f32_e32 v17, v142, v1
	v_mul_f32_e32 v17, 0x3fb8aa3b, v17
	v_exp_f32_e32 v21, v17
	v_sub_f32_e32 v17, v142, v2
	v_mul_f32_e32 v17, 0x3fb8aa3b, v17
	v_mul_f32_e32 v8, 0x3fb8aa3b, v8
	v_exp_f32_e32 v22, v17
	v_sub_f32_e32 v17, v142, v3
	v_exp_f32_e32 v19, v8
	v_mul_f32_e32 v17, 0x3fb8aa3b, v17
	v_exp_f32_e32 v23, v17
	ds_read_b128 v[12:15], v157 offset:17696
	ds_read_b128 v[8:11], v157 offset:17712
	v_pk_mul_f32 v[18:19], v[18:19], v[78:79]
	v_mul_f32_e32 v0, 0x3fb8aa3b, v0
	v_cvt_pk_bf16_f32 v17, v18, v19
	v_pk_mul_f32 v[18:19], v[20:21], v[80:81]
	v_pk_mul_f32 v[20:21], v[22:23], v[82:83]
	v_cvt_pk_bf16_f32 v18, v18, v19
	v_cvt_pk_bf16_f32 v19, v20, v21
	s_waitcnt lgkmcnt(1)
	v_sub_f32_e32 v20, v142, v12
	v_sub_f32_e32 v21, v142, v13
	v_mul_f32_e32 v20, 0x3fb8aa3b, v20
	v_mul_f32_e32 v21, 0x3fb8aa3b, v21
	v_sub_f32_e32 v22, v142, v14
	v_sub_f32_e32 v23, v142, v15
	v_exp_f32_e32 v20, v20
	v_exp_f32_e32 v21, v21
	v_mul_f32_e32 v22, 0x3fb8aa3b, v22
	v_mul_f32_e32 v23, 0x3fb8aa3b, v23
	v_exp_f32_e32 v22, v22
	v_exp_f32_e32 v23, v23
	global_store_dwordx4 v[140:141], v[16:19], off
	v_mul_f32_e32 v4, 0x3fb8aa3b, v4
	v_mul_f32_e32 v5, 0x3fb8aa3b, v5
	v_pk_mul_f32 v[16:17], v[20:21], v[84:85]
	s_waitcnt lgkmcnt(0)
	v_sub_f32_e32 v18, v142, v10
	v_cvt_pk_bf16_f32 v24, v16, v17
	v_pk_mul_f32 v[16:17], v[22:23], v[86:87]
	v_mul_f32_e32 v18, 0x3fb8aa3b, v18
	v_cvt_pk_bf16_f32 v25, v16, v17
	v_sub_f32_e32 v16, v142, v8
	v_sub_f32_e32 v17, v142, v9
	v_mul_f32_e32 v16, 0x3fb8aa3b, v16
	v_mul_f32_e32 v17, 0x3fb8aa3b, v17
	v_exp_f32_e32 v16, v16
	v_exp_f32_e32 v17, v17
	v_exp_f32_e32 v20, v18
	v_sub_f32_e32 v18, v142, v11
	v_mul_f32_e32 v18, 0x3fb8aa3b, v18
	v_exp_f32_e32 v21, v18
	v_pk_mul_f32 v[22:23], v[16:17], v[88:89]
	ds_read_b128 v[16:19], v157 offset:17728
	v_cvt_pk_bf16_f32 v26, v22, v23
	v_pk_mul_f32 v[20:21], v[20:21], v[90:91]
	v_exp_f32_e32 v4, v4
	v_cvt_pk_bf16_f32 v27, v20, v21
	ds_read_b128 v[20:23], v157 offset:17744
	s_waitcnt lgkmcnt(1)
	v_sub_f32_e32 v28, v142, v16
	v_sub_f32_e32 v29, v142, v17
	v_mul_f32_e32 v28, 0x3fb8aa3b, v28
	v_mul_f32_e32 v29, 0x3fb8aa3b, v29
	v_sub_f32_e32 v30, v142, v18
	v_sub_f32_e32 v31, v142, v19
	v_exp_f32_e32 v28, v28
	v_exp_f32_e32 v29, v29
	v_mul_f32_e32 v30, 0x3fb8aa3b, v30
	v_mul_f32_e32 v31, 0x3fb8aa3b, v31
	v_exp_f32_e32 v30, v30
	v_exp_f32_e32 v31, v31
	global_store_dwordx4 v[140:141], v[24:27], off offset:256
	v_exp_f32_e32 v5, v5
	v_mul_f32_e32 v8, 0x3fb8aa3b, v8
	v_pk_mul_f32 v[24:25], v[28:29], v[92:93]
	s_waitcnt lgkmcnt(0)
; __device__ __forceinline__ unsigned pk2(float lo, float hi) { const f32v2_t v = {lo, hi}; const bf16v2_t b = __builtin_convertvector(v, bf16v2_t); return __builtin_bit_cast(unsigned, b); }
; __device__ void dn_d1(const Ctx& c, int ip) {
;     ...
;             for (int l0 = 0; l0 < 64; l0 += 8) { u32x4 a;
;                 a.x = pk2(x[l0 + 0] * __expf(glast - gc_s[l0 + 0]), x[l0 + 1] * __expf(glast - gc_s[l0 + 1])); a.y = pk2(x[l0 + 2] * __expf(glast - gc_s[l0 + 2]), x[l0 + 3] * __expf(glast - gc_s[l0 + 3]));
;                 a.z = pk2(x[l0 + 4] * __expf(glast - gc_s[l0 + 4]), x[l0 + 5] * __expf(glast - gc_s[l0 + 5])); a.w = pk2(x[l0 + 6] * __expf(glast - gc_s[l0 + 6]), x[l0 + 7] * __expf(glast - gc_s[l0 + 7]));
;                 *(u32x4*)(dKdT + (ch * 128 + col) * 64 + l0) = a; }
	v_sub_f32_e32 v26, v142, v22
	v_cvt_pk_bf16_f32 v32, v24, v25
	v_pk_mul_f32 v[24:25], v[30:31], v[94:95]
	v_mul_f32_e32 v26, 0x3fb8aa3b, v26
	v_cvt_pk_bf16_f32 v33, v24, v25
	v_sub_f32_e32 v24, v142, v20
	v_sub_f32_e32 v25, v142, v21
	v_mul_f32_e32 v24, 0x3fb8aa3b, v24
	v_mul_f32_e32 v25, 0x3fb8aa3b, v25
	v_exp_f32_e32 v24, v24
	v_exp_f32_e32 v25, v25
	v_exp_f32_e32 v28, v26
	v_sub_f32_e32 v26, v142, v23
	v_mul_f32_e32 v26, 0x3fb8aa3b, v26
	v_exp_f32_e32 v29, v26
	v_pk_mul_f32 v[30:31], v[24:25], v[96:97]
	ds_read_b128 v[24:27], v157 offset:17760
	v_cvt_pk_bf16_f32 v34, v30, v31
	v_pk_mul_f32 v[28:29], v[28:29], v[98:99]
	v_mul_f32_e32 v12, 0x3fb8aa3b, v12
	v_cvt_pk_bf16_f32 v35, v28, v29
	ds_read_b128 v[28:31], v157 offset:17776
	s_waitcnt lgkmcnt(1)
	v_sub_f32_e32 v36, v142, v24
	v_sub_f32_e32 v37, v142, v25
	v_mul_f32_e32 v36, 0x3fb8aa3b, v36
	v_mul_f32_e32 v37, 0x3fb8aa3b, v37
	v_sub_f32_e32 v38, v142, v26
	v_sub_f32_e32 v39, v142, v27
	v_exp_f32_e32 v36, v36
	v_exp_f32_e32 v37, v37
	v_mul_f32_e32 v38, 0x3fb8aa3b, v38
	v_mul_f32_e32 v39, 0x3fb8aa3b, v39
	v_exp_f32_e32 v38, v38
	v_exp_f32_e32 v39, v39
	global_store_dwordx4 v[140:141], v[32:35], off offset:512
	v_mul_f32_e32 v13, 0x3fb8aa3b, v13
	v_exp_f32_e32 v12, v12
	v_pk_mul_f32 v[32:33], v[36:37], v[100:101]
	s_waitcnt lgkmcnt(0)
	v_sub_f32_e32 v34, v142, v30
	v_cvt_pk_bf16_f32 v40, v32, v33
	v_pk_mul_f32 v[32:33], v[38:39], v[102:103]
	v_mul_f32_e32 v34, 0x3fb8aa3b, v34
	v_cvt_pk_bf16_f32 v41, v32, v33
	v_sub_f32_e32 v32, v142, v28
	v_sub_f32_e32 v33, v142, v29
	v_mul_f32_e32 v32, 0x3fb8aa3b, v32
	v_mul_f32_e32 v33, 0x3fb8aa3b, v33
	v_exp_f32_e32 v32, v32
	v_exp_f32_e32 v33, v33
	v_exp_f32_e32 v36, v34
	v_sub_f32_e32 v34, v142, v31
	v_mul_f32_e32 v34, 0x3fb8aa3b, v34
	v_exp_f32_e32 v37, v34
	v_pk_mul_f32 v[38:39], v[32:33], v[104:105]
	ds_read_b128 v[32:35], v157 offset:17792
	v_cvt_pk_bf16_f32 v42, v38, v39
	v_pk_mul_f32 v[36:37], v[36:37], v[106:107]
	v_exp_f32_e32 v13, v13
	v_cvt_pk_bf16_f32 v43, v36, v37
	ds_read_b128 v[36:39], v157 offset:17808
	s_waitcnt lgkmcnt(1)
	v_sub_f32_e32 v44, v142, v32
	v_sub_f32_e32 v45, v142, v33
	v_mul_f32_e32 v44, 0x3fb8aa3b, v44
	v_mul_f32_e32 v45, 0x3fb8aa3b, v45
	v_sub_f32_e32 v46, v142, v34
	v_sub_f32_e32 v47, v142, v35
	v_exp_f32_e32 v44, v44
	v_exp_f32_e32 v45, v45
	v_mul_f32_e32 v46, 0x3fb8aa3b, v46
	v_mul_f32_e32 v47, 0x3fb8aa3b, v47
	v_exp_f32_e32 v46, v46
	v_exp_f32_e32 v47, v47
	global_store_dwordx4 v[140:141], v[40:43], off offset:768
	v_mul_f32_e32 v6, 0x3fb8aa3b, v6
	v_mul_f32_e32 v7, 0x3fb8aa3b, v7
	v_pk_mul_f32 v[40:41], v[44:45], v[108:109]
	s_waitcnt lgkmcnt(0)
	v_sub_f32_e32 v42, v142, v38
	v_cvt_pk_bf16_f32 v48, v40, v41
	v_pk_mul_f32 v[40:41], v[46:47], v[110:111]
	v_mul_f32_e32 v42, 0x3fb8aa3b, v42
	v_cvt_pk_bf16_f32 v49, v40, v41
	v_sub_f32_e32 v40, v142, v36
	v_sub_f32_e32 v41, v142, v37
	v_mul_f32_e32 v40, 0x3fb8aa3b, v40
	v_mul_f32_e32 v41, 0x3fb8aa3b, v41
	v_exp_f32_e32 v40, v40
	v_exp_f32_e32 v41, v41
	v_exp_f32_e32 v44, v42
	v_sub_f32_e32 v42, v142, v39
	v_mul_f32_e32 v42, 0x3fb8aa3b, v42
	v_exp_f32_e32 v45, v42
	v_pk_mul_f32 v[46:47], v[40:41], v[112:113]
	ds_read_b128 v[40:43], v157 offset:17824
	v_cvt_pk_bf16_f32 v50, v46, v47
	v_pk_mul_f32 v[44:45], v[44:45], v[114:115]
	v_mul_f32_e32 v14, 0x3fb8aa3b, v14
	v_cvt_pk_bf16_f32 v51, v44, v45
	ds_read_b128 v[44:47], v157 offset:17840
	s_waitcnt lgkmcnt(1)
	v_sub_f32_e32 v52, v142, v40
	v_sub_f32_e32 v53, v142, v41
	v_mul_f32_e32 v52, 0x3fb8aa3b, v52
	v_mul_f32_e32 v53, 0x3fb8aa3b, v53
	v_sub_f32_e32 v54, v142, v42
	v_sub_f32_e32 v55, v142, v43
	v_exp_f32_e32 v52, v52
	v_exp_f32_e32 v53, v53
	v_mul_f32_e32 v54, 0x3fb8aa3b, v54
	v_mul_f32_e32 v55, 0x3fb8aa3b, v55
	v_exp_f32_e32 v54, v54
	v_exp_f32_e32 v55, v55
	global_store_dwordx4 v[140:141], v[48:51], off offset:1024
	v_mul_f32_e32 v15, 0x3fb8aa3b, v15
	v_mul_f32_e32 v16, 0x3fb8aa3b, v16
	v_pk_mul_f32 v[48:49], v[52:53], v[116:117]
	s_waitcnt lgkmcnt(0)
	v_sub_f32_e32 v50, v142, v46
	v_cvt_pk_bf16_f32 v56, v48, v49
	v_pk_mul_f32 v[48:49], v[54:55], v[118:119]
	v_mul_f32_e32 v50, 0x3fb8aa3b, v50
	v_cvt_pk_bf16_f32 v57, v48, v49
	v_sub_f32_e32 v48, v142, v44
	v_sub_f32_e32 v49, v142, v45
	v_mul_f32_e32 v48, 0x3fb8aa3b, v48
	v_mul_f32_e32 v49, 0x3fb8aa3b, v49
	v_exp_f32_e32 v48, v48
	v_exp_f32_e32 v49, v49
	v_exp_f32_e32 v52, v50
	v_sub_f32_e32 v50, v142, v47
	v_mul_f32_e32 v50, 0x3fb8aa3b, v50
	v_exp_f32_e32 v53, v50
	v_pk_mul_f32 v[54:55], v[48:49], v[120:121]
	ds_read_b128 v[48:51], v157 offset:17856
	v_cvt_pk_bf16_f32 v58, v54, v55
	v_pk_mul_f32 v[52:53], v[52:53], v[122:123]
	v_exp_f32_e32 v6, v6
	v_cvt_pk_bf16_f32 v59, v52, v53
	ds_read_b128 v[52:55], v157 offset:17872
	s_waitcnt lgkmcnt(1)
	v_sub_f32_e32 v60, v142, v48
	v_sub_f32_e32 v61, v142, v49
	v_mul_f32_e32 v60, 0x3fb8aa3b, v60
	v_mul_f32_e32 v61, 0x3fb8aa3b, v61
	v_sub_f32_e32 v62, v142, v50
	v_sub_f32_e32 v63, v142, v51
	v_exp_f32_e32 v60, v60
	v_exp_f32_e32 v61, v61
	v_mul_f32_e32 v62, 0x3fb8aa3b, v62
	v_mul_f32_e32 v63, 0x3fb8aa3b, v63
	v_exp_f32_e32 v62, v62
	v_exp_f32_e32 v63, v63
	global_store_dwordx4 v[140:141], v[56:59], off offset:1280
	v_exp_f32_e32 v7, v7
	v_exp_f32_e32 v14, v14
	v_pk_mul_f32 v[56:57], v[60:61], v[124:125]
	s_waitcnt lgkmcnt(0)
	v_sub_f32_e32 v58, v142, v54
	v_cvt_pk_bf16_f32 v202, v56, v57
	v_pk_mul_f32 v[56:57], v[62:63], v[126:127]
	v_mul_f32_e32 v58, 0x3fb8aa3b, v58
	v_cvt_pk_bf16_f32 v203, v56, v57
	v_sub_f32_e32 v56, v142, v52
	v_sub_f32_e32 v57, v142, v53
	v_mul_f32_e32 v56, 0x3fb8aa3b, v56
	v_mul_f32_e32 v57, 0x3fb8aa3b, v57
	v_exp_f32_e32 v56, v56
	v_exp_f32_e32 v57, v57
	v_exp_f32_e32 v60, v58
	v_sub_f32_e32 v58, v142, v55
	v_mul_f32_e32 v58, 0x3fb8aa3b, v58
	v_exp_f32_e32 v61, v58
	v_pk_mul_f32 v[62:63], v[56:57], v[128:129]
	ds_read_b128 v[56:59], v157 offset:17888
	v_cvt_pk_bf16_f32 v204, v62, v63
	v_pk_mul_f32 v[60:61], v[60:61], v[132:133]
	v_exp_f32_e32 v15, v15
	v_cvt_pk_bf16_f32 v205, v60, v61
	ds_read_b128 v[60:63], v157 offset:17904
	s_waitcnt lgkmcnt(1)
; __device__ __forceinline__ unsigned pk2(float lo, float hi) { const f32v2_t v = {lo, hi}; const bf16v2_t b = __builtin_convertvector(v, bf16v2_t); return __builtin_bit_cast(unsigned, b); }
; __device__ void dn_d1(const Ctx& c, int ip) {
;     ...
;             for (int l0 = 0; l0 < 64; l0 += 8) { u32x4 a;
;                 a.x = pk2(x[l0 + 0] * __expf(glast - gc_s[l0 + 0]), x[l0 + 1] * __expf(glast - gc_s[l0 + 1])); a.y = pk2(x[l0 + 2] * __expf(glast - gc_s[l0 + 2]), x[l0 + 3] * __expf(glast - gc_s[l0 + 3]));
;                 a.z = pk2(x[l0 + 4] * __expf(glast - gc_s[l0 + 4]), x[l0 + 5] * __expf(glast - gc_s[l0 + 5])); a.w = pk2(x[l0 + 6] * __expf(glast - gc_s[l0 + 6]), x[l0 + 7] * __expf(glast - gc_s[l0 + 7]));
;                 *(u32x4*)(dKdT + (ch * 128 + col) * 64 + l0) = a; }
; #pragma unroll
;             for (int i = 0; i < 64; ++i) x[i] *= beta_s[i] * __expf(gc_s[i]);
	v_sub_f32_e32 v65, v142, v56
	v_mul_f32_e32 v65, 0x3fb8aa3b, v65
	v_exp_f32_e32 v206, v65
	v_sub_f32_e32 v65, v142, v57
	v_mul_f32_e32 v65, 0x3fb8aa3b, v65
	v_exp_f32_e32 v207, v65
	v_sub_f32_e32 v65, v142, v58
	v_mul_f32_e32 v65, 0x3fb8aa3b, v65
	v_exp_f32_e32 v208, v65
	v_sub_f32_e32 v65, v142, v59
	v_mul_f32_e32 v65, 0x3fb8aa3b, v65
	v_exp_f32_e32 v209, v65
	s_waitcnt lgkmcnt(0)
	v_sub_f32_e32 v65, v142, v60
	v_mul_f32_e32 v65, 0x3fb8aa3b, v65
	global_store_dwordx4 v[140:141], v[202:205], off offset:1536
	v_mul_f32_e32 v21, 0x3fb8aa3b, v21
	v_mul_f32_e32 v22, 0x3fb8aa3b, v22
	v_pk_mul_f32 v[202:203], v[206:207], v[138:139]
	v_exp_f32_e32 v206, v65
	v_sub_f32_e32 v65, v142, v61
	v_mul_f32_e32 v65, 0x3fb8aa3b, v65
	v_exp_f32_e32 v207, v65
	v_sub_f32_e32 v65, v142, v62
	v_mul_f32_e32 v65, 0x3fb8aa3b, v65
	v_pk_mul_f32 v[204:205], v[208:209], v[130:131]
	v_exp_f32_e32 v208, v65
	v_sub_f32_e32 v65, v142, v63
	v_mul_f32_e32 v65, 0x3fb8aa3b, v65
	v_exp_f32_e32 v209, v65
	v_cvt_pk_bf16_f32 v202, v202, v203
	v_cvt_pk_bf16_f32 v203, v204, v205
	v_pk_mul_f32 v[204:205], v[206:207], v[136:137]
	v_pk_mul_f32 v[206:207], v[208:209], v[134:135]
	v_cvt_pk_bf16_f32 v204, v204, v205
	v_cvt_pk_bf16_f32 v205, v206, v207
	global_store_dwordx4 v[140:141], v[202:205], off offset:1792
	v_exp_f32_e32 v140, v0
	v_mul_f32_e32 v0, 0x3fb8aa3b, v1
	v_exp_f32_e32 v141, v0
	ds_read_b128 v[202:205], v157 offset:17408
	ds_read_b128 v[206:209], v157 offset:17424
	ds_read_b128 v[210:213], v157 offset:17440
	ds_read_b128 v[214:217], v157 offset:17456
	v_mul_f32_e32 v0, 0x3fb8aa3b, v2
	v_exp_f32_e32 v218, v0
	v_mul_f32_e32 v0, 0x3fb8aa3b, v3
	v_exp_f32_e32 v219, v0
	s_waitcnt lgkmcnt(3)
	v_pk_mul_f32 v[0:1], v[4:5], v[202:203]
	s_waitcnt lgkmcnt(2)
	v_pk_mul_f32 v[4:5], v[140:141], v[206:207]
	v_exp_f32_e32 v140, v8
	v_mul_f32_e32 v8, 0x3fb8aa3b, v9
	v_exp_f32_e32 v141, v8
	v_mul_f32_e32 v8, 0x3fb8aa3b, v10
	v_exp_f32_e32 v202, v8
	v_mul_f32_e32 v8, 0x3fb8aa3b, v11
	v_exp_f32_e32 v203, v8
	s_waitcnt lgkmcnt(1)
	v_pk_mul_f32 v[8:9], v[12:13], v[210:211]
	s_waitcnt lgkmcnt(0)
	v_pk_mul_f32 v[12:13], v[140:141], v[214:215]
	v_exp_f32_e32 v140, v16
	v_mul_f32_e32 v16, 0x3fb8aa3b, v17
	v_exp_f32_e32 v141, v16
	v_mul_f32_e32 v16, 0x3fb8aa3b, v18
	v_exp_f32_e32 v206, v16
	v_mul_f32_e32 v16, 0x3fb8aa3b, v19
	v_exp_f32_e32 v207, v16
	v_mul_f32_e32 v16, 0x3fb8aa3b, v20
	v_pk_mul_f32 v[2:3], v[6:7], v[204:205]
	v_pk_mul_f32 v[10:11], v[14:15], v[212:213]
	v_pk_mul_f32 v[14:15], v[202:203], v[216:217]
	v_exp_f32_e32 v20, v16
	ds_read_b128 v[16:19], v157 offset:17472
	ds_read_b128 v[202:205], v157 offset:17488
	v_mul_f32_e32 v23, 0x3fb8aa3b, v23
	v_mul_f32_e32 v24, 0x3fb8aa3b, v24
	v_exp_f32_e32 v21, v21
	v_exp_f32_e32 v22, v22
	v_exp_f32_e32 v23, v23
	s_waitcnt lgkmcnt(1)
	v_pk_mul_f32 v[16:17], v[140:141], v[16:17]
	v_exp_f32_e32 v140, v24
	v_mul_f32_e32 v24, 0x3fb8aa3b, v25
	v_exp_f32_e32 v141, v24
	v_mul_f32_e32 v24, 0x3fb8aa3b, v26
	v_pk_mul_f32 v[18:19], v[206:207], v[18:19]
	v_exp_f32_e32 v206, v24
	v_mul_f32_e32 v24, 0x3fb8aa3b, v27
	v_exp_f32_e32 v207, v24
	v_mul_f32_e32 v24, 0x3fb8aa3b, v28
	s_waitcnt lgkmcnt(0)
	v_pk_mul_f32 v[20:21], v[20:21], v[202:203]
	v_pk_mul_f32 v[22:23], v[22:23], v[204:205]
	v_exp_f32_e32 v28, v24
	ds_read_b128 v[24:27], v157 offset:17504
	ds_read_b128 v[202:205], v157 offset:17520
	v_mul_f32_e32 v29, 0x3fb8aa3b, v29
	v_mul_f32_e32 v30, 0x3fb8aa3b, v30
	v_mul_f32_e32 v31, 0x3fb8aa3b, v31
	v_mul_f32_e32 v32, 0x3fb8aa3b, v32
	v_exp_f32_e32 v29, v29
	v_exp_f32_e32 v30, v30
	v_exp_f32_e32 v31, v31
	s_waitcnt lgkmcnt(1)
	v_pk_mul_f32 v[24:25], v[140:141], v[24:25]
	v_exp_f32_e32 v140, v32
	v_mul_f32_e32 v32, 0x3fb8aa3b, v33
	v_exp_f32_e32 v141, v32
	v_mul_f32_e32 v32, 0x3fb8aa3b, v34
	v_pk_mul_f32 v[26:27], v[206:207], v[26:27]
	v_exp_f32_e32 v206, v32
	v_mul_f32_e32 v32, 0x3fb8aa3b, v35
	v_exp_f32_e32 v207, v32
	v_mul_f32_e32 v32, 0x3fb8aa3b, v36
	s_waitcnt lgkmcnt(0)
	v_pk_mul_f32 v[28:29], v[28:29], v[202:203]
	v_pk_mul_f32 v[30:31], v[30:31], v[204:205]
	v_exp_f32_e32 v36, v32
	ds_read_b128 v[32:35], v157 offset:17536
	ds_read_b128 v[202:205], v157 offset:17552
	v_mul_f32_e32 v37, 0x3fb8aa3b, v37
	v_mul_f32_e32 v38, 0x3fb8aa3b, v38
	v_mul_f32_e32 v39, 0x3fb8aa3b, v39
	v_mul_f32_e32 v40, 0x3fb8aa3b, v40
	v_exp_f32_e32 v37, v37
	v_exp_f32_e32 v38, v38
	v_exp_f32_e32 v39, v39
	s_waitcnt lgkmcnt(1)
	v_pk_mul_f32 v[32:33], v[140:141], v[32:33]
	v_exp_f32_e32 v140, v40
	v_mul_f32_e32 v40, 0x3fb8aa3b, v41
	v_exp_f32_e32 v141, v40
	v_mul_f32_e32 v40, 0x3fb8aa3b, v42
	v_pk_mul_f32 v[34:35], v[206:207], v[34:35]
	v_exp_f32_e32 v206, v40
	v_mul_f32_e32 v40, 0x3fb8aa3b, v43
	v_exp_f32_e32 v207, v40
	v_mul_f32_e32 v40, 0x3fb8aa3b, v44
	s_waitcnt lgkmcnt(0)
	v_pk_mul_f32 v[36:37], v[36:37], v[202:203]
	v_pk_mul_f32 v[38:39], v[38:39], v[204:205]
	v_exp_f32_e32 v44, v40
	ds_read_b128 v[40:43], v157 offset:17568
	ds_read_b128 v[202:205], v157 offset:17584
	v_mul_f32_e32 v45, 0x3fb8aa3b, v45
	v_mul_f32_e32 v46, 0x3fb8aa3b, v46
	v_mul_f32_e32 v47, 0x3fb8aa3b, v47
	v_mul_f32_e32 v48, 0x3fb8aa3b, v48
	v_exp_f32_e32 v45, v45
	v_exp_f32_e32 v46, v46
	v_exp_f32_e32 v47, v47
	s_waitcnt lgkmcnt(1)
	v_pk_mul_f32 v[40:41], v[140:141], v[40:41]
	v_exp_f32_e32 v140, v48
	v_mul_f32_e32 v48, 0x3fb8aa3b, v49
	v_exp_f32_e32 v141, v48
	v_mul_f32_e32 v48, 0x3fb8aa3b, v50
	v_pk_mul_f32 v[42:43], v[206:207], v[42:43]
	v_exp_f32_e32 v206, v48
	v_mul_f32_e32 v48, 0x3fb8aa3b, v51
	v_exp_f32_e32 v207, v48
	v_mul_f32_e32 v48, 0x3fb8aa3b, v52
	s_waitcnt lgkmcnt(0)
	v_pk_mul_f32 v[44:45], v[44:45], v[202:203]
	v_pk_mul_f32 v[46:47], v[46:47], v[204:205]
	v_exp_f32_e32 v52, v48
	ds_read_b128 v[48:51], v157 offset:17600
	ds_read_b128 v[202:205], v157 offset:17616
	v_mul_f32_e32 v53, 0x3fb8aa3b, v53
	v_mul_f32_e32 v54, 0x3fb8aa3b, v54
	v_mul_f32_e32 v55, 0x3fb8aa3b, v55
	v_mul_f32_e32 v56, 0x3fb8aa3b, v56
	v_exp_f32_e32 v53, v53
	v_exp_f32_e32 v54, v54
	v_exp_f32_e32 v55, v55
	s_waitcnt lgkmcnt(1)
	v_pk_mul_f32 v[48:49], v[140:141], v[48:49]
	v_exp_f32_e32 v140, v56
	v_mul_f32_e32 v56, 0x3fb8aa3b, v57
	v_exp_f32_e32 v141, v56
	v_mul_f32_e32 v56, 0x3fb8aa3b, v58
	v_pk_mul_f32 v[50:51], v[206:207], v[50:51]
	v_exp_f32_e32 v206, v56
	v_mul_f32_e32 v56, 0x3fb8aa3b, v59
	v_exp_f32_e32 v207, v56
	v_mul_f32_e32 v56, 0x3fb8aa3b, v60
	s_waitcnt lgkmcnt(0)
	v_pk_mul_f32 v[52:53], v[52:53], v[202:203]
	v_pk_mul_f32 v[54:55], v[54:55], v[204:205]
	v_exp_f32_e32 v60, v56
	ds_read_b128 v[56:59], v157 offset:17632
	ds_read_b128 v[202:205], v157 offset:17648
	v_mul_f32_e32 v61, 0x3fb8aa3b, v61
	v_mul_f32_e32 v62, 0x3fb8aa3b, v62
	v_mul_f32_e32 v63, 0x3fb8aa3b, v63
	v_exp_f32_e32 v61, v61
	v_exp_f32_e32 v62, v62
	v_exp_f32_e32 v63, v63
	v_pk_mul_f32 v[6:7], v[218:219], v[208:209]
	s_waitcnt lgkmcnt(1)
	v_pk_mul_f32 v[56:57], v[140:141], v[56:57]
	v_pk_mul_f32 v[58:59], v[206:207], v[58:59]
	s_waitcnt lgkmcnt(0)
	v_pk_mul_f32 v[60:61], v[60:61], v[202:203]
	v_pk_mul_f32 v[62:63], v[62:63], v[204:205]

; __device__ __forceinline__ unsigned pk2(float lo, float hi) { const f32v2_t v = {lo, hi}; const bf16v2_t b = __builtin_convertvector(v, bf16v2_t); return __builtin_bit_cast(unsigned, b); }
;     template <class Tp> __device__ __forceinline__ Tp* W(size_t off) const { return (Tp*)(ws + off); }
; __device__ void dn_d1(const Ctx& c, int ip) {
;     ...
;           for (int i = 0; i < 64; ++i) x[i] = __uint_as_float(rw[i] << 16); }
;         if (isw) {
;             bf16_t* dKdT = c.W<bf16_t>(WS_DKDT);
; #pragma unroll
;             for (int l0 = 0; l0 < 64; l0 += 8) { u32x4 a;
;                 a.x = pk2(x[l0 + 0] * __expf(glast - gc_s[l0 + 0]), x[l0 + 1] * __expf(glast - gc_s[l0 + 1])); a.y = pk2(x[l0 + 2] * __expf(glast - gc_s[l0 + 2]), x[l0 + 3] * __expf(glast - gc_s[l0 + 3]));
;                 a.z = pk2(x[l0 + 4] * __expf(glast - gc_s[l0 + 4]), x[l0 + 5] * __expf(glast - gc_s[l0 + 5])); a.w = pk2(x[l0 + 6] * __expf(glast - gc_s[l0 + 6]), x[l0 + 7] * __expf(glast - gc_s[l0 + 7]));
;                 *(u32x4*)(dKdT + (ch * 128 + col) * 64 + l0) = a; }
.LBB0_818:
	s_or_saveexec_b64 s[0:1], s[0:1]
	v_lshlrev_b32_e32 v77, 16, v77
	v_lshlrev_b32_e32 v76, 16, v76
	v_lshlrev_b32_e32 v79, 16, v78
	v_lshlrev_b32_e32 v78, 16, v83
	v_lshlrev_b32_e32 v81, 16, v81
	v_lshlrev_b32_e32 v80, 16, v80
	v_lshlrev_b32_e32 v83, 16, v82
	v_lshlrev_b32_e32 v82, 16, v85
	v_lshlrev_b32_e32 v85, 16, v84
	v_lshlrev_b32_e32 v84, 16, v93
	v_lshlrev_b32_e32 v87, 16, v87
	v_lshlrev_b32_e32 v86, 16, v86
	v_lshlrev_b32_e32 v89, 16, v89
	v_lshlrev_b32_e32 v88, 16, v88
	v_lshlrev_b32_e32 v91, 16, v91
	v_lshlrev_b32_e32 v90, 16, v90
	v_lshlrev_b32_e32 v93, 16, v92
	v_lshlrev_b32_e32 v92, 16, v65
	v_lshlrev_b32_e32 v95, 16, v94
	v_lshlrev_b32_e32 v94, 16, v71
	v_lshlrev_b32_e32 v97, 16, v97
	v_lshlrev_b32_e32 v96, 16, v96
	v_lshlrev_b32_e32 v99, 16, v98
	v_lshlrev_b32_e32 v98, 16, v103
	v_lshlrev_b32_e32 v101, 16, v101
	v_lshlrev_b32_e32 v100, 16, v100
	v_lshlrev_b32_e32 v103, 16, v133
	v_lshlrev_b32_e32 v102, 16, v102
	v_lshlrev_b32_e32 v105, 16, v105
	v_lshlrev_b32_e32 v104, 16, v104
	v_lshlrev_b32_e32 v107, 16, v107
	v_lshlrev_b32_e32 v106, 16, v106
	v_lshlrev_b32_e32 v109, 16, v109
	v_lshlrev_b32_e32 v108, 16, v108
	v_lshlrev_b32_e32 v111, 16, v111
	v_lshlrev_b32_e32 v110, 16, v110
	v_lshlrev_b32_e32 v113, 16, v113
	v_lshlrev_b32_e32 v112, 16, v112
	v_lshlrev_b32_e32 v115, 16, v115
	v_lshlrev_b32_e32 v114, 16, v114
	v_lshlrev_b32_e32 v117, 16, v117
	v_lshlrev_b32_e32 v116, 16, v116
	v_lshlrev_b32_e32 v119, 16, v119
	v_lshlrev_b32_e32 v118, 16, v118
	v_lshlrev_b32_e32 v121, 16, v121
	v_lshlrev_b32_e32 v120, 16, v120
	v_lshlrev_b32_e32 v123, 16, v123
	v_lshlrev_b32_e32 v122, 16, v122
	v_lshlrev_b32_e32 v125, 16, v125
	v_lshlrev_b32_e32 v124, 16, v124
	v_lshlrev_b32_e32 v127, 16, v127
	v_lshlrev_b32_e32 v126, 16, v126
	v_lshlrev_b32_e32 v129, 16, v129
	v_lshlrev_b32_e32 v128, 16, v128
	v_lshlrev_b32_e32 v133, 16, v130
	v_lshlrev_b32_e32 v132, 16, v132
	v_lshlrev_b32_e32 v139, 16, v138
	v_lshlrev_b32_e32 v138, 16, v131
	v_lshlrev_b32_e32 v131, 16, v141
	v_lshlrev_b32_e32 v130, 16, v136
	v_lshlrev_b32_e32 v137, 16, v137
	v_lshlrev_b32_e32 v136, 16, v135
	v_lshlrev_b32_e32 v135, 16, v140
	v_lshlrev_b32_e32 v134, 16, v134
	s_xor_b64 exec, exec, s[0:1]
	s_cbranch_execz .LBB0_820
	s_waitcnt lgkmcnt(14)
	ds_read_b128 v[4:7], v157 offset:17664
	ds_read_b128 v[0:3], v157 offset:17680
	v_readlane_b32 s2, v249, 12
	v_readlane_b32 s3, v249, 13
	v_mov_b32_e32 v65, v177
	s_waitcnt lgkmcnt(14)
	v_lshl_add_u64 v[8:9], s[2:3], 0, v[72:73]
	v_lshl_add_u64 v[140:141], v[8:9], 0, v[64:65]
	v_and_b32_e32 v8, 15, v234
	v_mul_u32_u24_e32 v8, 0x70, v8
	v_sub_co_u32_e64 v140, s[100:101], v140, v8
	s_nop 1
	v_subb_co_u32_e64 v141, s[100:101], v141, 0, s[100:101]
	s_waitcnt lgkmcnt(1)
	v_sub_f32_e32 v8, v67, v4
	v_mul_f32_e32 v8, 0x3fb8aa3b, v8
	v_exp_f32_e32 v16, v8
	v_sub_f32_e32 v8, v67, v5
	v_mul_f32_e32 v8, 0x3fb8aa3b, v8
	v_exp_f32_e32 v17, v8
	v_sub_f32_e32 v8, v67, v6
	v_mul_f32_e32 v8, 0x3fb8aa3b, v8
	v_exp_f32_e32 v18, v8
	v_pk_mul_f32 v[16:17], v[16:17], v[76:77]
	v_sub_f32_e32 v8, v67, v7
	v_cvt_pk_bf16_f32 v16, v16, v17
	s_waitcnt lgkmcnt(0)
	v_sub_f32_e32 v17, v67, v0
	v_mul_f32_e32 v17, 0x3fb8aa3b, v17
	v_exp_f32_e32 v20, v17
	v_sub_f32_e32 v17, v67, v1
	v_mul_f32_e32 v17, 0x3fb8aa3b, v17
	v_exp_f32_e32 v21, v17
	v_sub_f32_e32 v17, v67, v2
	v_mul_f32_e32 v17, 0x3fb8aa3b, v17
	v_mul_f32_e32 v8, 0x3fb8aa3b, v8
	v_exp_f32_e32 v22, v17
	v_sub_f32_e32 v17, v67, v3
	v_exp_f32_e32 v19, v8
	v_mul_f32_e32 v17, 0x3fb8aa3b, v17
	v_exp_f32_e32 v23, v17
	ds_read_b128 v[12:15], v157 offset:17696
	ds_read_b128 v[8:11], v157 offset:17712
	v_pk_mul_f32 v[18:19], v[18:19], v[78:79]
	v_mul_f32_e32 v4, 0x3fb8aa3b, v4
	v_cvt_pk_bf16_f32 v17, v18, v19
	v_pk_mul_f32 v[18:19], v[20:21], v[80:81]
	v_pk_mul_f32 v[20:21], v[22:23], v[82:83]
	v_cvt_pk_bf16_f32 v18, v18, v19
	v_cvt_pk_bf16_f32 v19, v20, v21
	s_waitcnt lgkmcnt(1)
	v_sub_f32_e32 v20, v67, v12
	v_sub_f32_e32 v21, v67, v13
	v_mul_f32_e32 v20, 0x3fb8aa3b, v20
	v_mul_f32_e32 v21, 0x3fb8aa3b, v21
	v_sub_f32_e32 v22, v67, v14
	v_sub_f32_e32 v23, v67, v15
	v_exp_f32_e32 v20, v20
	v_exp_f32_e32 v21, v21
	v_mul_f32_e32 v22, 0x3fb8aa3b, v22
	v_mul_f32_e32 v23, 0x3fb8aa3b, v23
	v_exp_f32_e32 v22, v22
	v_exp_f32_e32 v23, v23
	global_store_dwordx4 v[140:141], v[16:19], off
	v_mul_f32_e32 v5, 0x3fb8aa3b, v5
	v_exp_f32_e32 v4, v4
	v_pk_mul_f32 v[16:17], v[20:21], v[84:85]
	s_waitcnt lgkmcnt(0)
	v_sub_f32_e32 v18, v67, v10
	v_cvt_pk_bf16_f32 v24, v16, v17
	v_pk_mul_f32 v[16:17], v[22:23], v[86:87]
	v_mul_f32_e32 v18, 0x3fb8aa3b, v18
	v_cvt_pk_bf16_f32 v25, v16, v17
	v_sub_f32_e32 v16, v67, v8
	v_sub_f32_e32 v17, v67, v9
	v_mul_f32_e32 v16, 0x3fb8aa3b, v16
	v_mul_f32_e32 v17, 0x3fb8aa3b, v17
	v_exp_f32_e32 v16, v16
	v_exp_f32_e32 v17, v17
	v_exp_f32_e32 v20, v18
	v_sub_f32_e32 v18, v67, v11
	v_mul_f32_e32 v18, 0x3fb8aa3b, v18
	v_exp_f32_e32 v21, v18
	v_pk_mul_f32 v[22:23], v[16:17], v[88:89]
	ds_read_b128 v[16:19], v157 offset:17728
	v_cvt_pk_bf16_f32 v26, v22, v23
	v_pk_mul_f32 v[20:21], v[20:21], v[90:91]
	v_exp_f32_e32 v5, v5
	v_cvt_pk_bf16_f32 v27, v20, v21
	ds_read_b128 v[20:23], v157 offset:17744
	s_waitcnt lgkmcnt(1)
	v_sub_f32_e32 v28, v67, v16
	v_sub_f32_e32 v29, v67, v17
	v_mul_f32_e32 v28, 0x3fb8aa3b, v28
	v_mul_f32_e32 v29, 0x3fb8aa3b, v29
	v_sub_f32_e32 v30, v67, v18
	v_sub_f32_e32 v31, v67, v19
	v_exp_f32_e32 v28, v28
	v_exp_f32_e32 v29, v29
	v_mul_f32_e32 v30, 0x3fb8aa3b, v30
	v_mul_f32_e32 v31, 0x3fb8aa3b, v31
	v_exp_f32_e32 v30, v30
	v_exp_f32_e32 v31, v31
	global_store_dwordx4 v[140:141], v[24:27], off offset:256
	v_mul_f32_e32 v0, 0x3fb8aa3b, v0
	v_mul_f32_e32 v6, 0x3fb8aa3b, v6
	v_pk_mul_f32 v[24:25], v[28:29], v[92:93]
	s_waitcnt lgkmcnt(0)
; __device__ __forceinline__ unsigned pk2(float lo, float hi) { const f32v2_t v = {lo, hi}; const bf16v2_t b = __builtin_convertvector(v, bf16v2_t); return __builtin_bit_cast(unsigned, b); }
; __device__ void dn_d1(const Ctx& c, int ip) {
;     ...
;             for (int l0 = 0; l0 < 64; l0 += 8) { u32x4 a;
;                 a.x = pk2(x[l0 + 0] * __expf(glast - gc_s[l0 + 0]), x[l0 + 1] * __expf(glast - gc_s[l0 + 1])); a.y = pk2(x[l0 + 2] * __expf(glast - gc_s[l0 + 2]), x[l0 + 3] * __expf(glast - gc_s[l0 + 3]));
;                 a.z = pk2(x[l0 + 4] * __expf(glast - gc_s[l0 + 4]), x[l0 + 5] * __expf(glast - gc_s[l0 + 5])); a.w = pk2(x[l0 + 6] * __expf(glast - gc_s[l0 + 6]), x[l0 + 7] * __expf(glast - gc_s[l0 + 7]));
;                 *(u32x4*)(dKdT + (ch * 128 + col) * 64 + l0) = a; }
	v_sub_f32_e32 v26, v67, v22
	v_cvt_pk_bf16_f32 v32, v24, v25
	v_pk_mul_f32 v[24:25], v[30:31], v[94:95]
	v_mul_f32_e32 v26, 0x3fb8aa3b, v26
	v_cvt_pk_bf16_f32 v33, v24, v25
	v_sub_f32_e32 v24, v67, v20
	v_sub_f32_e32 v25, v67, v21
	v_mul_f32_e32 v24, 0x3fb8aa3b, v24
	v_mul_f32_e32 v25, 0x3fb8aa3b, v25
	v_exp_f32_e32 v24, v24
	v_exp_f32_e32 v25, v25
	v_exp_f32_e32 v28, v26
	v_sub_f32_e32 v26, v67, v23
	v_mul_f32_e32 v26, 0x3fb8aa3b, v26
	v_exp_f32_e32 v29, v26
	v_pk_mul_f32 v[30:31], v[24:25], v[96:97]
	ds_read_b128 v[24:27], v157 offset:17760
	v_cvt_pk_bf16_f32 v34, v30, v31
	v_pk_mul_f32 v[28:29], v[28:29], v[98:99]
	v_mul_f32_e32 v7, 0x3fb8aa3b, v7
	v_cvt_pk_bf16_f32 v35, v28, v29
	ds_read_b128 v[28:31], v157 offset:17776
	s_waitcnt lgkmcnt(1)
	v_sub_f32_e32 v36, v67, v24
	v_sub_f32_e32 v37, v67, v25
	v_mul_f32_e32 v36, 0x3fb8aa3b, v36
	v_mul_f32_e32 v37, 0x3fb8aa3b, v37
	v_sub_f32_e32 v38, v67, v26
	v_sub_f32_e32 v39, v67, v27
	v_exp_f32_e32 v36, v36
	v_exp_f32_e32 v37, v37
	v_mul_f32_e32 v38, 0x3fb8aa3b, v38
	v_mul_f32_e32 v39, 0x3fb8aa3b, v39
	v_exp_f32_e32 v38, v38
	v_exp_f32_e32 v39, v39
	global_store_dwordx4 v[140:141], v[32:35], off offset:512
	v_exp_f32_e32 v174, v0
	v_mul_f32_e32 v0, 0x3fb8aa3b, v1
	v_pk_mul_f32 v[32:33], v[36:37], v[100:101]
	s_waitcnt lgkmcnt(0)
	v_sub_f32_e32 v34, v67, v30
	v_cvt_pk_bf16_f32 v40, v32, v33
	v_pk_mul_f32 v[32:33], v[38:39], v[102:103]
	v_mul_f32_e32 v34, 0x3fb8aa3b, v34
	v_cvt_pk_bf16_f32 v41, v32, v33
	v_sub_f32_e32 v32, v67, v28
	v_sub_f32_e32 v33, v67, v29
	v_mul_f32_e32 v32, 0x3fb8aa3b, v32
	v_mul_f32_e32 v33, 0x3fb8aa3b, v33
	v_exp_f32_e32 v32, v32
	v_exp_f32_e32 v33, v33
	v_exp_f32_e32 v36, v34
	v_sub_f32_e32 v34, v67, v31
	v_mul_f32_e32 v34, 0x3fb8aa3b, v34
	v_exp_f32_e32 v37, v34
	v_pk_mul_f32 v[38:39], v[32:33], v[104:105]
	ds_read_b128 v[32:35], v157 offset:17792
	v_cvt_pk_bf16_f32 v42, v38, v39
	v_pk_mul_f32 v[36:37], v[36:37], v[106:107]
	v_exp_f32_e32 v6, v6
	v_cvt_pk_bf16_f32 v43, v36, v37
	ds_read_b128 v[36:39], v157 offset:17808
	s_waitcnt lgkmcnt(1)
	v_sub_f32_e32 v44, v67, v32
	v_sub_f32_e32 v45, v67, v33
	v_mul_f32_e32 v44, 0x3fb8aa3b, v44
	v_mul_f32_e32 v45, 0x3fb8aa3b, v45
	v_sub_f32_e32 v46, v67, v34
	v_sub_f32_e32 v47, v67, v35
	v_exp_f32_e32 v44, v44
	v_exp_f32_e32 v45, v45
	v_mul_f32_e32 v46, 0x3fb8aa3b, v46
	v_mul_f32_e32 v47, 0x3fb8aa3b, v47
	v_exp_f32_e32 v46, v46
	v_exp_f32_e32 v47, v47
	global_store_dwordx4 v[140:141], v[40:43], off offset:768
	v_exp_f32_e32 v7, v7
	v_exp_f32_e32 v175, v0
	v_pk_mul_f32 v[40:41], v[44:45], v[108:109]
	s_waitcnt lgkmcnt(0)
	v_sub_f32_e32 v42, v67, v38
	v_cvt_pk_bf16_f32 v48, v40, v41
	v_pk_mul_f32 v[40:41], v[46:47], v[110:111]
	v_mul_f32_e32 v42, 0x3fb8aa3b, v42
	v_cvt_pk_bf16_f32 v49, v40, v41
	v_sub_f32_e32 v40, v67, v36
	v_sub_f32_e32 v41, v67, v37
	v_mul_f32_e32 v40, 0x3fb8aa3b, v40
	v_mul_f32_e32 v41, 0x3fb8aa3b, v41
	v_exp_f32_e32 v40, v40
	v_exp_f32_e32 v41, v41
	v_exp_f32_e32 v44, v42
	v_sub_f32_e32 v42, v67, v39
	v_mul_f32_e32 v42, 0x3fb8aa3b, v42
	v_exp_f32_e32 v45, v42
	v_pk_mul_f32 v[46:47], v[40:41], v[112:113]
	ds_read_b128 v[40:43], v157 offset:17824
	v_cvt_pk_bf16_f32 v50, v46, v47
	v_pk_mul_f32 v[44:45], v[44:45], v[114:115]
	v_mul_f32_e32 v0, 0x3fb8aa3b, v2
	v_cvt_pk_bf16_f32 v51, v44, v45
	ds_read_b128 v[44:47], v157 offset:17840
	s_waitcnt lgkmcnt(1)
	v_sub_f32_e32 v52, v67, v40
	v_sub_f32_e32 v53, v67, v41
	v_mul_f32_e32 v52, 0x3fb8aa3b, v52
	v_mul_f32_e32 v53, 0x3fb8aa3b, v53
	v_sub_f32_e32 v54, v67, v42
	v_sub_f32_e32 v55, v67, v43
	v_exp_f32_e32 v52, v52
	v_exp_f32_e32 v53, v53
	v_mul_f32_e32 v54, 0x3fb8aa3b, v54
	v_mul_f32_e32 v55, 0x3fb8aa3b, v55
	v_exp_f32_e32 v54, v54
	v_exp_f32_e32 v55, v55
	global_store_dwordx4 v[140:141], v[48:51], off offset:1024
	v_exp_f32_e32 v196, v0
	v_mul_f32_e32 v0, 0x3fb8aa3b, v3
	v_pk_mul_f32 v[48:49], v[52:53], v[116:117]
	s_waitcnt lgkmcnt(0)
	v_sub_f32_e32 v50, v67, v46
	v_cvt_pk_bf16_f32 v56, v48, v49
	v_pk_mul_f32 v[48:49], v[54:55], v[118:119]
	v_mul_f32_e32 v50, 0x3fb8aa3b, v50
	v_cvt_pk_bf16_f32 v57, v48, v49
	v_sub_f32_e32 v48, v67, v44
	v_sub_f32_e32 v49, v67, v45
	v_mul_f32_e32 v48, 0x3fb8aa3b, v48
	v_mul_f32_e32 v49, 0x3fb8aa3b, v49
	v_exp_f32_e32 v48, v48
	v_exp_f32_e32 v49, v49
	v_exp_f32_e32 v52, v50
	v_sub_f32_e32 v50, v67, v47
	v_mul_f32_e32 v50, 0x3fb8aa3b, v50
	v_exp_f32_e32 v53, v50
	v_pk_mul_f32 v[54:55], v[48:49], v[120:121]
	ds_read_b128 v[48:51], v157 offset:17856
	v_cvt_pk_bf16_f32 v58, v54, v55
	v_pk_mul_f32 v[52:53], v[52:53], v[122:123]
	v_mul_f32_e32 v8, 0x3fb8aa3b, v8
	v_cvt_pk_bf16_f32 v59, v52, v53
	ds_read_b128 v[52:55], v157 offset:17872
	s_waitcnt lgkmcnt(1)
	v_sub_f32_e32 v60, v67, v48
	v_sub_f32_e32 v61, v67, v49
	v_mul_f32_e32 v60, 0x3fb8aa3b, v60
	v_mul_f32_e32 v61, 0x3fb8aa3b, v61
	v_sub_f32_e32 v62, v67, v50
	v_sub_f32_e32 v63, v67, v51
	v_exp_f32_e32 v60, v60
	v_exp_f32_e32 v61, v61
	v_mul_f32_e32 v62, 0x3fb8aa3b, v62
	v_mul_f32_e32 v63, 0x3fb8aa3b, v63
	v_exp_f32_e32 v62, v62
	v_exp_f32_e32 v63, v63
	global_store_dwordx4 v[140:141], v[56:59], off offset:1280
	v_exp_f32_e32 v197, v0
	v_mul_f32_e32 v12, 0x3fb8aa3b, v12
	v_pk_mul_f32 v[56:57], v[60:61], v[124:125]
	s_waitcnt lgkmcnt(0)
	v_sub_f32_e32 v58, v67, v54
	v_cvt_pk_bf16_f32 v146, v56, v57
	v_pk_mul_f32 v[56:57], v[62:63], v[126:127]
	v_mul_f32_e32 v58, 0x3fb8aa3b, v58
	v_cvt_pk_bf16_f32 v147, v56, v57
	v_sub_f32_e32 v56, v67, v52
	v_sub_f32_e32 v57, v67, v53
	v_mul_f32_e32 v56, 0x3fb8aa3b, v56
	v_mul_f32_e32 v57, 0x3fb8aa3b, v57
	v_exp_f32_e32 v56, v56
	v_exp_f32_e32 v57, v57
	v_exp_f32_e32 v60, v58
	v_sub_f32_e32 v58, v67, v55
	v_mul_f32_e32 v58, 0x3fb8aa3b, v58
	v_exp_f32_e32 v61, v58
	v_pk_mul_f32 v[62:63], v[56:57], v[128:129]
	ds_read_b128 v[56:59], v157 offset:17888
	v_cvt_pk_bf16_f32 v148, v62, v63
	v_pk_mul_f32 v[60:61], v[60:61], v[132:133]
	v_mul_f32_e32 v13, 0x3fb8aa3b, v13
	v_cvt_pk_bf16_f32 v149, v60, v61
	ds_read_b128 v[60:63], v157 offset:17904
	s_waitcnt lgkmcnt(1)
; __device__ __forceinline__ unsigned pk2(float lo, float hi) { const f32v2_t v = {lo, hi}; const bf16v2_t b = __builtin_convertvector(v, bf16v2_t); return __builtin_bit_cast(unsigned, b); }
; __device__ void dn_d1(const Ctx& c, int ip) {
;     ...
;             for (int l0 = 0; l0 < 64; l0 += 8) { u32x4 a;
;                 a.x = pk2(x[l0 + 0] * __expf(glast - gc_s[l0 + 0]), x[l0 + 1] * __expf(glast - gc_s[l0 + 1])); a.y = pk2(x[l0 + 2] * __expf(glast - gc_s[l0 + 2]), x[l0 + 3] * __expf(glast - gc_s[l0 + 3]));
;                 a.z = pk2(x[l0 + 4] * __expf(glast - gc_s[l0 + 4]), x[l0 + 5] * __expf(glast - gc_s[l0 + 5])); a.w = pk2(x[l0 + 6] * __expf(glast - gc_s[l0 + 6]), x[l0 + 7] * __expf(glast - gc_s[l0 + 7]));
;                 *(u32x4*)(dKdT + (ch * 128 + col) * 64 + l0) = a; }
; #pragma unroll
;             for (int i = 0; i < 64; ++i) x[i] *= beta_s[i] * __expf(gc_s[i]);
	v_sub_f32_e32 v65, v67, v56
	v_mul_f32_e32 v65, 0x3fb8aa3b, v65
	v_exp_f32_e32 v142, v65
	v_sub_f32_e32 v65, v67, v57
	v_mul_f32_e32 v65, 0x3fb8aa3b, v65
	v_exp_f32_e32 v143, v65
	v_sub_f32_e32 v65, v67, v58
	v_mul_f32_e32 v65, 0x3fb8aa3b, v65
	v_exp_f32_e32 v170, v65
	v_sub_f32_e32 v65, v67, v59
	v_mul_f32_e32 v65, 0x3fb8aa3b, v65
	v_exp_f32_e32 v171, v65
	s_waitcnt lgkmcnt(0)
	v_sub_f32_e32 v65, v67, v60
	v_mul_f32_e32 v65, 0x3fb8aa3b, v65
	global_store_dwordx4 v[140:141], v[146:149], off offset:1536
	v_pk_mul_f32 v[142:143], v[142:143], v[138:139]
	v_mul_f32_e32 v14, 0x3fb8aa3b, v14
	v_exp_f32_e32 v148, v65
	v_sub_f32_e32 v65, v67, v61
	v_mul_f32_e32 v65, 0x3fb8aa3b, v65
	v_exp_f32_e32 v149, v65
	v_sub_f32_e32 v65, v67, v62
	v_mul_f32_e32 v65, 0x3fb8aa3b, v65
	v_cvt_pk_bf16_f32 v146, v142, v143
	v_pk_mul_f32 v[142:143], v[170:171], v[130:131]
	v_exp_f32_e32 v170, v65
	v_sub_f32_e32 v65, v67, v63
	v_mul_f32_e32 v65, 0x3fb8aa3b, v65
	v_exp_f32_e32 v171, v65
	v_cvt_pk_bf16_f32 v147, v142, v143
	v_pk_mul_f32 v[142:143], v[148:149], v[136:137]
	v_mul_f32_e32 v15, 0x3fb8aa3b, v15
	v_cvt_pk_bf16_f32 v148, v142, v143
	v_pk_mul_f32 v[142:143], v[170:171], v[134:135]
	v_mul_f32_e32 v16, 0x3fb8aa3b, v16
	v_cvt_pk_bf16_f32 v149, v142, v143
	global_store_dwordx4 v[140:141], v[146:149], off offset:1792
	ds_read_b128 v[140:143], v157 offset:17408
	ds_read_b128 v[146:149], v157 offset:17424
	ds_read_b128 v[170:173], v157 offset:17440
	ds_read_b128 v[192:195], v157 offset:17456
	v_exp_f32_e32 v12, v12
	s_waitcnt lgkmcnt(3)
	v_pk_mul_f32 v[0:1], v[4:5], v[140:141]
	v_exp_f32_e32 v140, v8
	v_mul_f32_e32 v8, 0x3fb8aa3b, v9
	v_exp_f32_e32 v141, v8
	v_mul_f32_e32 v8, 0x3fb8aa3b, v10
	v_pk_mul_f32 v[2:3], v[6:7], v[142:143]
	v_exp_f32_e32 v142, v8
	v_mul_f32_e32 v8, 0x3fb8aa3b, v11
	s_waitcnt lgkmcnt(2)
	v_pk_mul_f32 v[4:5], v[174:175], v[146:147]
	v_exp_f32_e32 v13, v13
	v_exp_f32_e32 v14, v14
	v_exp_f32_e32 v15, v15
	v_exp_f32_e32 v143, v8
	v_exp_f32_e32 v146, v16
	v_mul_f32_e32 v16, 0x3fb8aa3b, v17
	v_exp_f32_e32 v147, v16
	v_mul_f32_e32 v16, 0x3fb8aa3b, v18
	v_pk_mul_f32 v[6:7], v[196:197], v[148:149]
	v_exp_f32_e32 v148, v16
	v_mul_f32_e32 v16, 0x3fb8aa3b, v19
	v_exp_f32_e32 v149, v16
	v_mul_f32_e32 v16, 0x3fb8aa3b, v20
	s_waitcnt lgkmcnt(1)
	v_pk_mul_f32 v[8:9], v[12:13], v[170:171]
	v_pk_mul_f32 v[10:11], v[14:15], v[172:173]
	s_waitcnt lgkmcnt(0)
	v_pk_mul_f32 v[12:13], v[140:141], v[192:193]
	v_pk_mul_f32 v[14:15], v[142:143], v[194:195]
	v_exp_f32_e32 v20, v16
	ds_read_b128 v[16:19], v157 offset:17472
	ds_read_b128 v[140:143], v157 offset:17488
	v_mul_f32_e32 v21, 0x3fb8aa3b, v21
	v_mul_f32_e32 v22, 0x3fb8aa3b, v22
	v_mul_f32_e32 v23, 0x3fb8aa3b, v23
	v_mul_f32_e32 v24, 0x3fb8aa3b, v24
	v_exp_f32_e32 v21, v21
	v_exp_f32_e32 v22, v22
	v_exp_f32_e32 v23, v23
	s_waitcnt lgkmcnt(1)
	v_pk_mul_f32 v[16:17], v[146:147], v[16:17]
	v_exp_f32_e32 v146, v24
	v_mul_f32_e32 v24, 0x3fb8aa3b, v25
	v_exp_f32_e32 v147, v24
	v_mul_f32_e32 v24, 0x3fb8aa3b, v26
	v_pk_mul_f32 v[18:19], v[148:149], v[18:19]
	v_exp_f32_e32 v148, v24
	v_mul_f32_e32 v24, 0x3fb8aa3b, v27
	v_exp_f32_e32 v149, v24
	v_mul_f32_e32 v24, 0x3fb8aa3b, v28
	s_waitcnt lgkmcnt(0)
	v_pk_mul_f32 v[20:21], v[20:21], v[140:141]
	v_pk_mul_f32 v[22:23], v[22:23], v[142:143]
	v_exp_f32_e32 v28, v24
	ds_read_b128 v[24:27], v157 offset:17504
	ds_read_b128 v[140:143], v157 offset:17520
	v_mul_f32_e32 v29, 0x3fb8aa3b, v29
	v_mul_f32_e32 v30, 0x3fb8aa3b, v30
	v_mul_f32_e32 v31, 0x3fb8aa3b, v31
	v_mul_f32_e32 v32, 0x3fb8aa3b, v32
	v_exp_f32_e32 v29, v29
	v_exp_f32_e32 v30, v30
	v_exp_f32_e32 v31, v31
	s_waitcnt lgkmcnt(1)
	v_pk_mul_f32 v[24:25], v[146:147], v[24:25]
	v_exp_f32_e32 v146, v32
	v_mul_f32_e32 v32, 0x3fb8aa3b, v33
	v_exp_f32_e32 v147, v32
	v_mul_f32_e32 v32, 0x3fb8aa3b, v34
	v_pk_mul_f32 v[26:27], v[148:149], v[26:27]
	v_exp_f32_e32 v148, v32
	v_mul_f32_e32 v32, 0x3fb8aa3b, v35
	v_exp_f32_e32 v149, v32
	v_mul_f32_e32 v32, 0x3fb8aa3b, v36
	s_waitcnt lgkmcnt(0)
	v_pk_mul_f32 v[28:29], v[28:29], v[140:141]
	v_pk_mul_f32 v[30:31], v[30:31], v[142:143]
	v_exp_f32_e32 v36, v32
	ds_read_b128 v[32:35], v157 offset:17536
	ds_read_b128 v[140:143], v157 offset:17552
	v_mul_f32_e32 v37, 0x3fb8aa3b, v37
	v_mul_f32_e32 v38, 0x3fb8aa3b, v38
	v_mul_f32_e32 v39, 0x3fb8aa3b, v39
	v_mul_f32_e32 v40, 0x3fb8aa3b, v40
	v_exp_f32_e32 v37, v37
	v_exp_f32_e32 v38, v38
	v_exp_f32_e32 v39, v39
	s_waitcnt lgkmcnt(1)
	v_pk_mul_f32 v[32:33], v[146:147], v[32:33]
	v_exp_f32_e32 v146, v40
	v_mul_f32_e32 v40, 0x3fb8aa3b, v41
	v_exp_f32_e32 v147, v40
	v_mul_f32_e32 v40, 0x3fb8aa3b, v42
	v_pk_mul_f32 v[34:35], v[148:149], v[34:35]
	v_exp_f32_e32 v148, v40
	v_mul_f32_e32 v40, 0x3fb8aa3b, v43
	v_exp_f32_e32 v149, v40
	v_mul_f32_e32 v40, 0x3fb8aa3b, v44
	s_waitcnt lgkmcnt(0)
	v_pk_mul_f32 v[36:37], v[36:37], v[140:141]
	v_pk_mul_f32 v[38:39], v[38:39], v[142:143]
	v_exp_f32_e32 v44, v40
	ds_read_b128 v[40:43], v157 offset:17568
	ds_read_b128 v[140:143], v157 offset:17584
	v_mul_f32_e32 v45, 0x3fb8aa3b, v45
	v_mul_f32_e32 v46, 0x3fb8aa3b, v46
	v_mul_f32_e32 v47, 0x3fb8aa3b, v47
	v_mul_f32_e32 v48, 0x3fb8aa3b, v48
	v_exp_f32_e32 v45, v45
	v_exp_f32_e32 v46, v46
	v_exp_f32_e32 v47, v47
	s_waitcnt lgkmcnt(1)
	v_pk_mul_f32 v[40:41], v[146:147], v[40:41]
	v_exp_f32_e32 v146, v48
	v_mul_f32_e32 v48, 0x3fb8aa3b, v49
	v_exp_f32_e32 v147, v48
	v_mul_f32_e32 v48, 0x3fb8aa3b, v50
	v_pk_mul_f32 v[42:43], v[148:149], v[42:43]
	v_exp_f32_e32 v148, v48
	v_mul_f32_e32 v48, 0x3fb8aa3b, v51
	v_exp_f32_e32 v149, v48
	v_mul_f32_e32 v48, 0x3fb8aa3b, v52
	s_waitcnt lgkmcnt(0)
	v_pk_mul_f32 v[44:45], v[44:45], v[140:141]
	v_pk_mul_f32 v[46:47], v[46:47], v[142:143]
	v_exp_f32_e32 v52, v48
	ds_read_b128 v[48:51], v157 offset:17600
	ds_read_b128 v[140:143], v157 offset:17616
	v_mul_f32_e32 v53, 0x3fb8aa3b, v53
	v_mul_f32_e32 v54, 0x3fb8aa3b, v54
	v_mul_f32_e32 v55, 0x3fb8aa3b, v55
	v_mul_f32_e32 v56, 0x3fb8aa3b, v56
	v_exp_f32_e32 v53, v53
	v_exp_f32_e32 v54, v54
	v_exp_f32_e32 v55, v55
	s_waitcnt lgkmcnt(1)
	v_pk_mul_f32 v[48:49], v[146:147], v[48:49]
	v_exp_f32_e32 v146, v56
	v_mul_f32_e32 v56, 0x3fb8aa3b, v57
	v_exp_f32_e32 v147, v56
	v_mul_f32_e32 v56, 0x3fb8aa3b, v58
	v_pk_mul_f32 v[50:51], v[148:149], v[50:51]
	v_exp_f32_e32 v148, v56
	v_mul_f32_e32 v56, 0x3fb8aa3b, v59
	v_exp_f32_e32 v149, v56
	v_mul_f32_e32 v56, 0x3fb8aa3b, v60
	s_waitcnt lgkmcnt(0)
	v_pk_mul_f32 v[52:53], v[52:53], v[140:141]
	v_pk_mul_f32 v[54:55], v[54:55], v[142:143]
	v_exp_f32_e32 v60, v56
	ds_read_b128 v[56:59], v157 offset:17632
	ds_read_b128 v[140:143], v157 offset:17648
	v_mul_f32_e32 v61, 0x3fb8aa3b, v61
	v_mul_f32_e32 v62, 0x3fb8aa3b, v62
	v_mul_f32_e32 v63, 0x3fb8aa3b, v63
	v_exp_f32_e32 v61, v61
	v_exp_f32_e32 v62, v62
	v_exp_f32_e32 v63, v63
	s_waitcnt lgkmcnt(1)
	v_pk_mul_f32 v[56:57], v[146:147], v[56:57]
	v_pk_mul_f32 v[58:59], v[148:149], v[58:59]
	s_waitcnt lgkmcnt(0)
	v_pk_mul_f32 v[60:61], v[60:61], v[140:141]
	v_pk_mul_f32 v[62:63], v[62:63], v[142:143]

; __global__ void __launch_bounds__(512, 2) mega(Params P, int ph_lo, int ph_hi) {
;     extern __shared__ __attribute__((aligned(16))) unsigned char lds[];
;     cg::grid_group grid = cg::this_grid();
	.amdhsa_kernel _Z4mega6Paramsii
		.amdhsa_group_segment_fixed_size 0
		.amdhsa_private_segment_fixed_size 0
		.amdhsa_kernarg_size 504
		.amdhsa_user_sgpr_count 2
		.amdhsa_user_sgpr_dispatch_ptr 0
		.amdhsa_user_sgpr_queue_ptr 0
		.amdhsa_user_sgpr_kernarg_segment_ptr 1
		.amdhsa_user_sgpr_dispatch_id 0
		.amdhsa_user_sgpr_kernarg_preload_length 0
		.amdhsa_user_sgpr_kernarg_preload_offset 0
		.amdhsa_user_sgpr_private_segment_size 0
		.amdhsa_uses_dynamic_stack 0
		.amdhsa_enable_private_segment 0
		.amdhsa_system_sgpr_workgroup_id_x 1
		.amdhsa_system_sgpr_workgroup_id_y 0
		.amdhsa_system_sgpr_workgroup_id_z 0
		.amdhsa_system_sgpr_workgroup_info 0
		.amdhsa_system_vgpr_workitem_id 2
		.amdhsa_next_free_vgpr 256
		.amdhsa_next_free_sgpr 102
		.amdhsa_accum_offset 256
		.amdhsa_reserve_vcc 1
		.amdhsa_float_round_mode_32 0
		.amdhsa_float_round_mode_16_64 0
		.amdhsa_float_denorm_mode_32 3
		.amdhsa_float_denorm_mode_16_64 3
		.amdhsa_dx10_clamp 1
		.amdhsa_ieee_mode 1
		.amdhsa_fp16_overflow 0
		.amdhsa_tg_split 0
		.amdhsa_exception_fp_ieee_invalid_op 0
		.amdhsa_exception_fp_denorm_src 0
		.amdhsa_exception_fp_ieee_div_zero 0
		.amdhsa_exception_fp_ieee_overflow 0
		.amdhsa_exception_fp_ieee_underflow 0
		.amdhsa_exception_fp_ieee_inexact 0
		.amdhsa_exception_int_div_zero 0
	.end_amdhsa_kernel

; __global__ void __launch_bounds__(512, 2) mega(Params P, int ph_lo, int ph_hi) {
;     extern __shared__ __attribute__((aligned(16))) unsigned char lds[];
;     cg::grid_group grid = cg::this_grid();
amdhsa.kernels:
  - .agpr_count:     0
    .args:
      - .offset:         0
        .size:           240
        .value_kind:     by_value
      - .offset:         240
        .size:           4
        .value_kind:     by_value
      - .offset:         244
        .size:           4
        .value_kind:     by_value
      - .offset:         248
        .size:           4
        .value_kind:     hidden_block_count_x
      - .offset:         252
        .size:           4
        .value_kind:     hidden_block_count_y
      - .offset:         256
        .size:           4
        .value_kind:     hidden_block_count_z
      - .offset:         260
        .size:           2
        .value_kind:     hidden_group_size_x
      - .offset:         262
        .size:           2
        .value_kind:     hidden_group_size_y
      - .offset:         264
        .size:           2
        .value_kind:     hidden_group_size_z
      - .offset:         266
        .size:           2
        .value_kind:     hidden_remainder_x
      - .offset:         268
        .size:           2
        .value_kind:     hidden_remainder_y
      - .offset:         270
        .size:           2
        .value_kind:     hidden_remainder_z
      - .offset:         288
        .size:           8
        .value_kind:     hidden_global_offset_x
      - .offset:         296
        .size:           8
        .value_kind:     hidden_global_offset_y
      - .offset:         304
        .size:           8
        .value_kind:     hidden_global_offset_z
      - .offset:         312
        .size:           2
        .value_kind:     hidden_grid_dims
      - .offset:         336
        .size:           8
        .value_kind:     hidden_multigrid_sync_arg
      - .offset:         368
        .size:           4
        .value_kind:     hidden_dynamic_lds_size
    .group_segment_fixed_size: 0
    .kernarg_segment_align: 8
    .kernarg_segment_size: 504
    .language:       OpenCL C
    .language_version:
      - 2
      - 0
    .max_flat_workgroup_size: 512
    .name:           _Z4mega6Paramsii
    .private_segment_fixed_size: 0
    .sgpr_count:     108
    .sgpr_spill_count: 592
    .symbol:         _Z4mega6Paramsii.kd
    .uniform_work_group_size: 1
    .uses_dynamic_stack: false
    .vgpr_count:     256
    .vgpr_spill_count: 0
    .wavefront_size: 64
